# GEMM K-loops: loading half at raised priority, MFMA half at base priority (inverted segment priorities)
# speedup vs baseline: 1.0044x; 1.0014x over previous
; #define PG8_STAGE(bufoff, gbase, voff) do { _Pragma("unroll") for (int _i = 0; _i < 2; ++_i) \
;         __builtin_amdgcn_global_load_lds((const unsigned*)((const char*)(gbase) + (voff)[_i]), (PG8_LAS unsigned*)(lds + (bufoff) + ldsw + _i * 8192), 16, 0, 0); } while (0)
; #define PG8_LDA(dst, b, h) do { _Pragma("unroll") for (int m = 0; m < 4; ++m) _Pragma("unroll") for (int k = 0; k < 2; ++k) dst[m][k] = *(const PG8_LAS bf16x8*)(lds + PG8_SA(b, h) + aoff + m * 2048 + k * 1024); } while (0)
; #define PG8_LDB(dst, b, h) do { _Pragma("unroll") for (int n = 0; n < 2; ++n) _Pragma("unroll") for (int k = 0; k < 2; ++k) dst[n][k] = *(const PG8_LAS bf16x8*)(lds + PG8_SB(b, h) + boff + n * 2048 + k * 1024); } while (0)
; #define PG8_WAIT_V(n) asm volatile("s_waitcnt vmcnt(" #n ")" ::: "memory")
; #define PG8_WAIT_L(n) asm volatile("s_waitcnt lgkmcnt(" #n ")" ::: "memory")
; #define PG8_BAR __builtin_amdgcn_s_barrier()
; #define PG8_SCHED __builtin_amdgcn_sched_barrier(0)
; template <class Epi, class Sched, bool ALIGN_EPI = false, bool SP2 = false>
; __device__ __forceinline__ void gemm_phase(PG8_LAS unsigned char* lds, const Gemm g, const Sched& S, const Epi& E, const int wid) {
;     ...
;         const bool has_next = S.next(ui + 1, nxt);
;         const char* nA = has_next ? (const char*)g.A + (size_t)nxt.pm * tstep : cA; const char* nB = has_next ? (const char*)g.Bt + (size_t)nxt.pn * tstep : cB;
;         for (int t = 0; t < nt; t += 2) {
;             const bool last = (t == nt - 2);
;             const char* a1 = cA + (size_t)(t + 1) * kstep;
;             const char* a2 = last ? nA : cA + (size_t)(t + 2) * kstep; const char* b2 = last ? nB : cB + (size_t)(t + 2) * kstep;
;             const char* a3 = a2 + kstep; const char* b3 = b2 + kstep;
;             if (last && has_next) S.a_ready(nxt);
;             if constexpr (SP2) {
;             PG8_LDB(B0, 0, 0); PG8_LDB(B1, 0, 1); PG8_SCHED; PG8_LDA(At, 0, 0); PG8_STAGE(PG8_SA(1, 1), a1 + hstep, voffA);
;             PG8_WAIT_V(8); PG8_WAIT_L(0); PG8_BAR; PG8_MMA(0, 0, At, B0); PG8_MMA(0, 1, At, B1); PG8_BAR; PG8_SCHED;
;             PG8_LDA(At, 0, 1); PG8_STAGE(PG8_SB(0, 0), b2, voffB); PG8_STAGE(PG8_SB(0, 1), b2 + hstep, voffB); PG8_STAGE(PG8_SA(0, 0), a2, voffA);
;             PG8_WAIT_V(8); PG8_WAIT_L(0); PG8_BAR; PG8_MMA(1, 0, At, B0); PG8_MMA(1, 1, At, B1); PG8_BAR; PG8_SCHED;
.LBB0_18:
	s_andn2_b64 vcc, exec, s[24:25]
	s_cbranch_vccnz .Lz_G1A
	s_add_u32 s4, s38, 0x80
	s_addc_u32 s5, s39, 0
	s_add_u32 s0, s36, 0x100
	s_addc_u32 s1, s37, 0
	s_mov_b32 s36, 0
	ds_read_b128 v[128:131], v165
	ds_read_b128 v[146:149], v165 offset:1024
	ds_read_b128 v[150:153], v165 offset:2048
	ds_read_b128 v[154:157], v165 offset:3072
	ds_read_b128 v[158:161], v166
	ds_read_b128 v[172:175], v166 offset:1024
	ds_read_b128 v[176:179], v166 offset:2048
	ds_read_b128 v[180:183], v166 offset:3072
	s_add_i32 s38, s36, 2
	s_add_u32 s33, s4, 0x80
	s_addc_u32 s37, s5, 0
	s_cmp_eq_u32 s57, s36
	s_cselect_b32 s36, s30, s33
	s_cselect_b32 s37, s31, s37
	s_cselect_b32 s71, s35, s1
	s_cselect_b32 s70, s34, s0
	v_lshl_add_u64 v[216:217], s[4:5], 0, v[140:141]
	s_add_i32 m0, s47, 0xc000
	ds_read_b128 v[184:187], v167
	ds_read_b128 v[188:191], v167 offset:1024
	ds_read_b128 v[192:195], v167 offset:2048
	ds_read_b128 v[196:199], v167 offset:3072
	ds_read_b128 v[200:203], v167 offset:4096
	ds_read_b128 v[204:207], v167 offset:5120
	ds_read_b128 v[208:211], v167 offset:6144
	ds_read_b128 v[212:215], v167 offset:7168
	global_load_lds_dwordx4 v[216:217], off
	v_lshl_add_u64 v[216:217], s[4:5], 0, v[142:143]
	s_add_i32 m0, s47, 0xe000
	s_nop 0
	global_load_lds_dwordx4 v[216:217], off
	s_waitcnt vmcnt(8)
	s_waitcnt lgkmcnt(0)
	s_setprio 0
	s_barrier
	v_mfma_f32_16x16x32_bf16 v[124:127], v[128:131], v[184:187], 0
	v_mfma_f32_16x16x32_bf16 v[120:123], v[150:153], v[184:187], 0
	v_mfma_f32_16x16x32_bf16 v[108:111], v[128:131], v[192:195], 0
	v_mfma_f32_16x16x32_bf16 v[104:107], v[150:153], v[192:195], 0
	v_mfma_f32_16x16x32_bf16 v[92:95], v[128:131], v[200:203], 0
	v_mfma_f32_16x16x32_bf16 v[88:91], v[150:153], v[200:203], 0
	v_mfma_f32_16x16x32_bf16 v[76:79], v[128:131], v[208:211], 0
	v_mfma_f32_16x16x32_bf16 v[72:75], v[150:153], v[208:211], 0
	v_mfma_f32_16x16x32_bf16 v[124:127], v[146:149], v[188:191], v[124:127]
	v_mfma_f32_16x16x32_bf16 v[120:123], v[154:157], v[188:191], v[120:123]
	v_mfma_f32_16x16x32_bf16 v[108:111], v[146:149], v[196:199], v[108:111]
	v_mfma_f32_16x16x32_bf16 v[104:107], v[154:157], v[196:199], v[104:107]
	v_mfma_f32_16x16x32_bf16 v[92:95], v[146:149], v[204:207], v[92:95]
	v_mfma_f32_16x16x32_bf16 v[88:91], v[154:157], v[204:207], v[88:91]
	v_mfma_f32_16x16x32_bf16 v[76:79], v[146:149], v[212:215], v[76:79]
	v_mfma_f32_16x16x32_bf16 v[72:75], v[154:157], v[212:215], v[72:75]
	v_mfma_f32_16x16x32_bf16 v[116:119], v[158:161], v[184:187], 0
	v_mfma_f32_16x16x32_bf16 v[112:115], v[176:179], v[184:187], 0
	v_mfma_f32_16x16x32_bf16 v[100:103], v[158:161], v[192:195], 0
	v_mfma_f32_16x16x32_bf16 v[96:99], v[176:179], v[192:195], 0
	v_mfma_f32_16x16x32_bf16 v[84:87], v[158:161], v[200:203], 0
	v_mfma_f32_16x16x32_bf16 v[80:83], v[176:179], v[200:203], 0
	v_mfma_f32_16x16x32_bf16 v[68:71], v[158:161], v[208:211], 0
	v_mfma_f32_16x16x32_bf16 v[64:67], v[176:179], v[208:211], 0
	v_mfma_f32_16x16x32_bf16 v[116:119], v[172:175], v[188:191], v[116:119]
	v_mfma_f32_16x16x32_bf16 v[112:115], v[180:183], v[188:191], v[112:115]
	v_mfma_f32_16x16x32_bf16 v[100:103], v[172:175], v[196:199], v[100:103]
	v_mfma_f32_16x16x32_bf16 v[96:99], v[180:183], v[196:199], v[96:99]
	v_mfma_f32_16x16x32_bf16 v[84:87], v[172:175], v[204:207], v[84:87]
	v_mfma_f32_16x16x32_bf16 v[80:83], v[180:183], v[204:207], v[80:83]
	v_mfma_f32_16x16x32_bf16 v[68:71], v[172:175], v[212:215], v[68:71]
	v_mfma_f32_16x16x32_bf16 v[64:67], v[180:183], v[212:215], v[64:67]
	s_barrier
	s_setprio 1
	s_add_i32 s33, s60, s40
	v_lshl_add_u64 v[216:217], s[70:71], 0, v[136:137]
	s_mov_b32 m0, s33
	ds_read_b128 v[184:187], v167 offset:16384
	ds_read_b128 v[188:191], v167 offset:17408
	ds_read_b128 v[192:195], v167 offset:18432
	ds_read_b128 v[196:199], v167 offset:19456
	ds_read_b128 v[200:203], v167 offset:20480
	ds_read_b128 v[204:207], v167 offset:21504
	ds_read_b128 v[208:211], v167 offset:22528
	ds_read_b128 v[212:215], v167 offset:23552
	global_load_lds_dwordx4 v[216:217], off
	s_add_i32 m0, s33, 0x2000
	v_lshl_add_u64 v[218:219], s[70:71], 0, v[132:133]
	s_add_u32 s70, s70, s6
	s_addc_u32 s71, s71, s7
	s_add_i32 s33, s61, s40
	global_load_lds_dwordx4 v[218:219], off
	v_lshl_add_u64 v[220:221], s[70:71], 0, v[136:137]
	s_mov_b32 m0, s33
	v_lshl_add_u64 v[222:223], s[70:71], 0, v[132:133]
	global_load_lds_dwordx4 v[220:221], off
	s_add_i32 m0, s33, 0x2000
	v_lshl_add_u64 v[224:225], s[36:37], 0, v[138:139]
	global_load_lds_dwordx4 v[222:223], off
	s_mov_b32 m0, s47
	v_lshl_add_u64 v[226:227], s[36:37], 0, v[134:135]
	global_load_lds_dwordx4 v[224:225], off
	s_mov_b32 m0, s49
	s_nop 0
	global_load_lds_dwordx4 v[226:227], off
	s_waitcnt vmcnt(8)
	s_waitcnt lgkmcnt(0)
	s_setprio 0
	s_barrier
; #define PG8_STAGE(bufoff, gbase, voff) do { _Pragma("unroll") for (int _i = 0; _i < 2; ++_i) \
;         __builtin_amdgcn_global_load_lds((const unsigned*)((const char*)(gbase) + (voff)[_i]), (PG8_LAS unsigned*)(lds + (bufoff) + ldsw + _i * 8192), 16, 0, 0); } while (0)
; #define PG8_LDA(dst, b, h) do { _Pragma("unroll") for (int m = 0; m < 4; ++m) _Pragma("unroll") for (int k = 0; k < 2; ++k) dst[m][k] = *(const PG8_LAS bf16x8*)(lds + PG8_SA(b, h) + aoff + m * 2048 + k * 1024); } while (0)
; #define PG8_LDB(dst, b, h) do { _Pragma("unroll") for (int n = 0; n < 2; ++n) _Pragma("unroll") for (int k = 0; k < 2; ++k) dst[n][k] = *(const PG8_LAS bf16x8*)(lds + PG8_SB(b, h) + boff + n * 2048 + k * 1024); } while (0)
; #define PG8_MMA(ai, bj, At, Bt) do { __builtin_amdgcn_s_setprio(1); _Pragma("unroll") for (int m = 0; m < 4; ++m) _Pragma("unroll") for (int n = 0; n < 2; ++n) _Pragma("unroll") for (int k = 0; k < 2; ++k) \
;         acc[ai][bj][m][n] = __builtin_amdgcn_mfma_f32_16x16x32_bf16(Bt[n][k], At[m][k], acc[ai][bj][m][n], 0, 0, 0); __builtin_amdgcn_s_setprio(0); } while (0)
; #define PG8_WAIT_V(n) asm volatile("s_waitcnt vmcnt(" #n ")" ::: "memory")
; #define PG8_WAIT_L(n) asm volatile("s_waitcnt lgkmcnt(" #n ")" ::: "memory")
; #define PG8_BAR __builtin_amdgcn_s_barrier()
; #define PG8_SCHED __builtin_amdgcn_sched_barrier(0)
; template <class Epi, class Sched, bool ALIGN_EPI = false, bool SP2 = false>
; __device__ __forceinline__ void gemm_phase(PG8_LAS unsigned char* lds, const Gemm g, const Sched& S, const Epi& E, const int wid) {
;     ...
;             PG8_WAIT_V(8); PG8_WAIT_L(0); PG8_BAR; PG8_MMA(0, 0, At, B0); PG8_MMA(0, 1, At, B1); PG8_BAR; PG8_SCHED;
;             PG8_LDA(At, 0, 1); PG8_STAGE(PG8_SB(0, 0), b2, voffB); PG8_STAGE(PG8_SB(0, 1), b2 + hstep, voffB); PG8_STAGE(PG8_SA(0, 0), a2, voffA);
;             PG8_WAIT_V(8); PG8_WAIT_L(0); PG8_BAR; PG8_MMA(1, 0, At, B0); PG8_MMA(1, 1, At, B1); PG8_BAR; PG8_SCHED;
;             PG8_LDB(B0, 1, 0); PG8_LDB(B1, 1, 1); PG8_SCHED; PG8_LDA(At, 1, 0); PG8_STAGE(PG8_SA(0, 1), a2 + hstep, voffA);
;             PG8_WAIT_V(8); PG8_WAIT_L(0); PG8_BAR; PG8_MMA(0, 0, At, B0); PG8_MMA(0, 1, At, B1); PG8_BAR; PG8_SCHED;
	v_mfma_f32_16x16x32_bf16 v[60:63], v[128:131], v[184:187], 0
	v_mfma_f32_16x16x32_bf16 v[56:59], v[150:153], v[184:187], 0
	v_mfma_f32_16x16x32_bf16 v[44:47], v[128:131], v[192:195], 0
	v_mfma_f32_16x16x32_bf16 v[40:43], v[150:153], v[192:195], 0
	v_mfma_f32_16x16x32_bf16 v[28:31], v[128:131], v[200:203], 0
	v_mfma_f32_16x16x32_bf16 v[24:27], v[150:153], v[200:203], 0
	v_mfma_f32_16x16x32_bf16 v[12:15], v[128:131], v[208:211], 0
	v_mfma_f32_16x16x32_bf16 v[8:11], v[150:153], v[208:211], 0
	v_mfma_f32_16x16x32_bf16 v[60:63], v[146:149], v[188:191], v[60:63]
	v_mfma_f32_16x16x32_bf16 v[56:59], v[154:157], v[188:191], v[56:59]
	v_mfma_f32_16x16x32_bf16 v[44:47], v[146:149], v[196:199], v[44:47]
	v_mfma_f32_16x16x32_bf16 v[40:43], v[154:157], v[196:199], v[40:43]
	v_mfma_f32_16x16x32_bf16 v[28:31], v[146:149], v[204:207], v[28:31]
	v_mfma_f32_16x16x32_bf16 v[24:27], v[154:157], v[204:207], v[24:27]
	v_mfma_f32_16x16x32_bf16 v[12:15], v[146:149], v[212:215], v[12:15]
	v_mfma_f32_16x16x32_bf16 v[8:11], v[154:157], v[212:215], v[8:11]
	v_mfma_f32_16x16x32_bf16 v[52:55], v[158:161], v[184:187], 0
	v_mfma_f32_16x16x32_bf16 v[48:51], v[176:179], v[184:187], 0
	v_mfma_f32_16x16x32_bf16 v[36:39], v[158:161], v[192:195], 0
	v_mfma_f32_16x16x32_bf16 v[32:35], v[176:179], v[192:195], 0
	v_mfma_f32_16x16x32_bf16 v[20:23], v[158:161], v[200:203], 0
	v_mfma_f32_16x16x32_bf16 v[16:19], v[176:179], v[200:203], 0
	v_mfma_f32_16x16x32_bf16 v[4:7], v[158:161], v[208:211], 0
	v_mfma_f32_16x16x32_bf16 v[0:3], v[176:179], v[208:211], 0
	v_mfma_f32_16x16x32_bf16 v[52:55], v[172:175], v[188:191], v[52:55]
	v_mfma_f32_16x16x32_bf16 v[48:51], v[180:183], v[188:191], v[48:51]
	v_mfma_f32_16x16x32_bf16 v[36:39], v[172:175], v[196:199], v[36:39]
	v_mfma_f32_16x16x32_bf16 v[32:35], v[180:183], v[196:199], v[32:35]
	v_mfma_f32_16x16x32_bf16 v[20:23], v[172:175], v[204:207], v[20:23]
	v_mfma_f32_16x16x32_bf16 v[16:19], v[180:183], v[204:207], v[16:19]
	v_mfma_f32_16x16x32_bf16 v[4:7], v[172:175], v[212:215], v[4:7]
	v_mfma_f32_16x16x32_bf16 v[0:3], v[180:183], v[212:215], v[0:3]
	s_barrier
	s_setprio 1
	s_add_i32 s33, 0, 0x18000
	s_add_i32 s39, 0, 0x1c000
	v_add_u32_e32 v154, s33, v164
	v_add_u32_e32 v180, s39, v164
	ds_read_b128 v[128:131], v154
	ds_read_b128 v[146:149], v154 offset:1024
	ds_read_b128 v[150:153], v154 offset:2048
	ds_read_b128 v[154:157], v154 offset:3072
	ds_read_b128 v[158:161], v180
	ds_read_b128 v[172:175], v180 offset:1024
	ds_read_b128 v[176:179], v180 offset:2048
	ds_read_b128 v[180:183], v180 offset:3072
	s_add_u32 s36, s36, s6
	s_addc_u32 s37, s37, s7
	s_mov_b32 m0, s50
	v_lshl_add_u64 v[228:229], s[36:37], 0, v[138:139]
	ds_read_b128 v[184:187], v167 offset:32768
	ds_read_b128 v[188:191], v167 offset:33792
	ds_read_b128 v[192:195], v167 offset:34816
	ds_read_b128 v[196:199], v167 offset:35840
	ds_read_b128 v[200:203], v167 offset:36864
	ds_read_b128 v[204:207], v167 offset:37888
	ds_read_b128 v[208:211], v167 offset:38912
	ds_read_b128 v[212:215], v167 offset:39936
	global_load_lds_dwordx4 v[228:229], off
	v_lshl_add_u64 v[228:229], s[36:37], 0, v[134:135]
	s_mov_b32 m0, s51
	s_nop 0
	global_load_lds_dwordx4 v[228:229], off
	s_waitcnt vmcnt(8)
	s_waitcnt lgkmcnt(0)
	s_setprio 0
	s_barrier
	v_mfma_f32_16x16x32_bf16 v[124:127], v[128:131], v[184:187], v[124:127]
	v_mfma_f32_16x16x32_bf16 v[120:123], v[150:153], v[184:187], v[120:123]
	v_mfma_f32_16x16x32_bf16 v[108:111], v[128:131], v[192:195], v[108:111]
	v_mfma_f32_16x16x32_bf16 v[104:107], v[150:153], v[192:195], v[104:107]
	v_mfma_f32_16x16x32_bf16 v[92:95], v[128:131], v[200:203], v[92:95]
	v_mfma_f32_16x16x32_bf16 v[88:91], v[150:153], v[200:203], v[88:91]
	v_mfma_f32_16x16x32_bf16 v[76:79], v[128:131], v[208:211], v[76:79]
	v_mfma_f32_16x16x32_bf16 v[72:75], v[150:153], v[208:211], v[72:75]
	v_mfma_f32_16x16x32_bf16 v[124:127], v[146:149], v[188:191], v[124:127]
	v_mfma_f32_16x16x32_bf16 v[120:123], v[154:157], v[188:191], v[120:123]
	v_mfma_f32_16x16x32_bf16 v[108:111], v[146:149], v[196:199], v[108:111]
	v_mfma_f32_16x16x32_bf16 v[104:107], v[154:157], v[196:199], v[104:107]
	v_mfma_f32_16x16x32_bf16 v[92:95], v[146:149], v[204:207], v[92:95]
	v_mfma_f32_16x16x32_bf16 v[88:91], v[154:157], v[204:207], v[88:91]
	v_mfma_f32_16x16x32_bf16 v[76:79], v[146:149], v[212:215], v[76:79]
	v_mfma_f32_16x16x32_bf16 v[72:75], v[154:157], v[212:215], v[72:75]
	v_mfma_f32_16x16x32_bf16 v[116:119], v[158:161], v[184:187], v[116:119]
	v_mfma_f32_16x16x32_bf16 v[112:115], v[176:179], v[184:187], v[112:115]
	v_mfma_f32_16x16x32_bf16 v[100:103], v[158:161], v[192:195], v[100:103]
	v_mfma_f32_16x16x32_bf16 v[96:99], v[176:179], v[192:195], v[96:99]
	v_mfma_f32_16x16x32_bf16 v[84:87], v[158:161], v[200:203], v[84:87]
	v_mfma_f32_16x16x32_bf16 v[80:83], v[176:179], v[200:203], v[80:83]
	v_mfma_f32_16x16x32_bf16 v[68:71], v[158:161], v[208:211], v[68:71]
	v_mfma_f32_16x16x32_bf16 v[64:67], v[176:179], v[208:211], v[64:67]
	v_mfma_f32_16x16x32_bf16 v[116:119], v[172:175], v[188:191], v[116:119]
	v_mfma_f32_16x16x32_bf16 v[112:115], v[180:183], v[188:191], v[112:115]
	v_mfma_f32_16x16x32_bf16 v[100:103], v[172:175], v[196:199], v[100:103]
	v_mfma_f32_16x16x32_bf16 v[96:99], v[180:183], v[196:199], v[96:99]
	v_mfma_f32_16x16x32_bf16 v[84:87], v[172:175], v[204:207], v[84:87]
	v_mfma_f32_16x16x32_bf16 v[80:83], v[180:183], v[204:207], v[80:83]
	v_mfma_f32_16x16x32_bf16 v[68:71], v[172:175], v[212:215], v[68:71]
	v_mfma_f32_16x16x32_bf16 v[64:67], v[180:183], v[212:215], v[64:67]
	s_barrier
; #define PG8_STAGE(bufoff, gbase, voff) do { _Pragma("unroll") for (int _i = 0; _i < 2; ++_i) \
;         __builtin_amdgcn_global_load_lds((const unsigned*)((const char*)(gbase) + (voff)[_i]), (PG8_LAS unsigned*)(lds + (bufoff) + ldsw + _i * 8192), 16, 0, 0); } while (0)
; #define PG8_LDA(dst, b, h) do { _Pragma("unroll") for (int m = 0; m < 4; ++m) _Pragma("unroll") for (int k = 0; k < 2; ++k) dst[m][k] = *(const PG8_LAS bf16x8*)(lds + PG8_SA(b, h) + aoff + m * 2048 + k * 1024); } while (0)
; #define PG8_WAIT_V(n) asm volatile("s_waitcnt vmcnt(" #n ")" ::: "memory")
; #define PG8_WAIT_L(n) asm volatile("s_waitcnt lgkmcnt(" #n ")" ::: "memory")
; #define PG8_BAR __builtin_amdgcn_s_barrier()
; template <class Epi, class Sched, bool ALIGN_EPI = false, bool SP2 = false>
; __device__ __forceinline__ void gemm_phase(PG8_LAS unsigned char* lds, const Gemm g, const Sched& S, const Epi& E, const int wid) {
;     ...
;         for (int t = 0; t < nt; t += 2) {
;             const bool last = (t == nt - 2);
;             const char* a1 = cA + (size_t)(t + 1) * kstep;
;             const char* a2 = last ? nA : cA + (size_t)(t + 2) * kstep; const char* b2 = last ? nB : cB + (size_t)(t + 2) * kstep;
;             const char* a3 = a2 + kstep; const char* b3 = b2 + kstep;
;             if (last && has_next) S.a_ready(nxt);
;             if constexpr (SP2) {
;             PG8_LDB(B0, 0, 0); PG8_LDB(B1, 0, 1); PG8_SCHED; PG8_LDA(At, 0, 0); PG8_STAGE(PG8_SA(1, 1), a1 + hstep, voffA);
;             PG8_WAIT_V(8); PG8_WAIT_L(0); PG8_BAR; PG8_MMA(0, 0, At, B0); PG8_MMA(0, 1, At, B1); PG8_BAR; PG8_SCHED;
;             PG8_LDA(At, 0, 1); PG8_STAGE(PG8_SB(0, 0), b2, voffB); PG8_STAGE(PG8_SB(0, 1), b2 + hstep, voffB); PG8_STAGE(PG8_SA(0, 0), a2, voffA);
;             PG8_WAIT_V(8); PG8_WAIT_L(0); PG8_BAR; PG8_MMA(1, 0, At, B0); PG8_MMA(1, 1, At, B1); PG8_BAR; PG8_SCHED;
;             PG8_LDB(B0, 1, 0); PG8_LDB(B1, 1, 1); PG8_SCHED; PG8_LDA(At, 1, 0); PG8_STAGE(PG8_SA(0, 1), a2 + hstep, voffA);
;             PG8_WAIT_V(8); PG8_WAIT_L(0); PG8_BAR; PG8_MMA(0, 0, At, B0); PG8_MMA(0, 1, At, B1); PG8_BAR; PG8_SCHED;
;             PG8_LDA(At, 1, 1); PG8_STAGE(PG8_SB(1, 0), b3, voffB); PG8_STAGE(PG8_SB(1, 1), b3 + hstep, voffB); PG8_STAGE(PG8_SA(1, 0), a3, voffA);
;             PG8_WAIT_V(8); PG8_WAIT_L(0); PG8_BAR; PG8_MMA(1, 0, At, B0); PG8_MMA(1, 1, At, B1); PG8_BAR; PG8_SCHED;
	s_setprio 1
	s_add_i32 s33, s33, s40
	v_lshl_add_u64 v[216:217], v[216:217], 0, s[22:23]
	s_mov_b32 m0, s33
	ds_read_b128 v[184:187], v167 offset:49152
	ds_read_b128 v[188:191], v167 offset:50176
	ds_read_b128 v[192:195], v167 offset:51200
	ds_read_b128 v[196:199], v167 offset:52224
	ds_read_b128 v[200:203], v167 offset:53248
	ds_read_b128 v[204:207], v167 offset:54272
	ds_read_b128 v[208:211], v167 offset:55296
	ds_read_b128 v[212:215], v167 offset:56320
	global_load_lds_dwordx4 v[216:217], off
	v_lshl_add_u64 v[216:217], v[218:219], 0, s[22:23]
	s_add_i32 m0, s33, 0x2000
	s_add_i32 s33, s39, s40
	global_load_lds_dwordx4 v[216:217], off
	v_lshl_add_u64 v[216:217], v[220:221], 0, s[22:23]
	s_mov_b32 m0, s33
	s_nop 0
	global_load_lds_dwordx4 v[216:217], off
	v_lshl_add_u64 v[216:217], v[222:223], 0, s[22:23]
	s_add_i32 m0, s33, 0x2000
	s_nop 0
	global_load_lds_dwordx4 v[216:217], off
	v_lshl_add_u64 v[216:217], v[224:225], 0, s[22:23]
	s_mov_b32 m0, s53
	s_nop 0
	global_load_lds_dwordx4 v[216:217], off
	v_lshl_add_u64 v[216:217], v[226:227], 0, s[22:23]
	s_mov_b32 m0, s54
	s_nop 0
	global_load_lds_dwordx4 v[216:217], off
	s_waitcnt vmcnt(8)
	s_waitcnt lgkmcnt(0)
	s_setprio 0
	s_barrier
	v_mfma_f32_16x16x32_bf16 v[60:63], v[128:131], v[184:187], v[60:63]
	v_mfma_f32_16x16x32_bf16 v[56:59], v[150:153], v[184:187], v[56:59]
	v_mfma_f32_16x16x32_bf16 v[44:47], v[128:131], v[192:195], v[44:47]
	v_mfma_f32_16x16x32_bf16 v[40:43], v[150:153], v[192:195], v[40:43]
	v_mfma_f32_16x16x32_bf16 v[28:31], v[128:131], v[200:203], v[28:31]
	v_mfma_f32_16x16x32_bf16 v[24:27], v[150:153], v[200:203], v[24:27]
	v_mfma_f32_16x16x32_bf16 v[12:15], v[128:131], v[208:211], v[12:15]
	v_mfma_f32_16x16x32_bf16 v[8:11], v[150:153], v[208:211], v[8:11]
	v_mfma_f32_16x16x32_bf16 v[60:63], v[146:149], v[188:191], v[60:63]
	v_mfma_f32_16x16x32_bf16 v[56:59], v[154:157], v[188:191], v[56:59]
	v_mfma_f32_16x16x32_bf16 v[44:47], v[146:149], v[196:199], v[44:47]
	v_mfma_f32_16x16x32_bf16 v[40:43], v[154:157], v[196:199], v[40:43]
	v_mfma_f32_16x16x32_bf16 v[28:31], v[146:149], v[204:207], v[28:31]
	v_mfma_f32_16x16x32_bf16 v[24:27], v[154:157], v[204:207], v[24:27]
	v_mfma_f32_16x16x32_bf16 v[12:15], v[146:149], v[212:215], v[12:15]
	v_mfma_f32_16x16x32_bf16 v[8:11], v[154:157], v[212:215], v[8:11]
	v_mfma_f32_16x16x32_bf16 v[52:55], v[158:161], v[184:187], v[52:55]
	v_mfma_f32_16x16x32_bf16 v[48:51], v[176:179], v[184:187], v[48:51]
	v_mfma_f32_16x16x32_bf16 v[36:39], v[158:161], v[192:195], v[36:39]
	v_mfma_f32_16x16x32_bf16 v[32:35], v[176:179], v[192:195], v[32:35]
	v_mfma_f32_16x16x32_bf16 v[20:23], v[158:161], v[200:203], v[20:23]
	v_mfma_f32_16x16x32_bf16 v[16:19], v[176:179], v[200:203], v[16:19]
	v_mfma_f32_16x16x32_bf16 v[4:7], v[158:161], v[208:211], v[4:7]
	v_mfma_f32_16x16x32_bf16 v[0:3], v[176:179], v[208:211], v[0:3]
	v_mfma_f32_16x16x32_bf16 v[52:55], v[172:175], v[188:191], v[52:55]
	v_mfma_f32_16x16x32_bf16 v[48:51], v[180:183], v[188:191], v[48:51]
	v_mfma_f32_16x16x32_bf16 v[36:39], v[172:175], v[196:199], v[36:39]
	v_mfma_f32_16x16x32_bf16 v[32:35], v[180:183], v[196:199], v[32:35]
	v_mfma_f32_16x16x32_bf16 v[20:23], v[172:175], v[204:207], v[20:23]
	v_mfma_f32_16x16x32_bf16 v[16:19], v[180:183], v[204:207], v[16:19]
	v_mfma_f32_16x16x32_bf16 v[4:7], v[172:175], v[212:215], v[4:7]
	v_mfma_f32_16x16x32_bf16 v[0:3], v[180:183], v[212:215], v[0:3]
	s_barrier
	s_setprio 1
	s_add_u32 s4, s4, 0x100
	s_addc_u32 s5, s5, 0
	s_add_u32 s0, s0, 0x100
	s_addc_u32 s1, s1, 0
	s_cmp_ge_i32 s38, s55
	s_mov_b32 s36, s38
	s_cbranch_scc1 .LBB0_21
.LBB0_20:
	ds_read_b128 v[128:131], v165
	ds_read_b128 v[146:149], v165 offset:1024
	ds_read_b128 v[150:153], v165 offset:2048
	ds_read_b128 v[154:157], v165 offset:3072
	ds_read_b128 v[158:161], v166
	ds_read_b128 v[172:175], v166 offset:1024
	ds_read_b128 v[176:179], v166 offset:2048
	ds_read_b128 v[180:183], v166 offset:3072
	s_add_i32 s38, s36, 2
	s_add_u32 s33, s4, 0x80
	s_addc_u32 s37, s5, 0
	s_cmp_eq_u32 s57, s36
	s_cselect_b32 s36, s30, s33
	s_cselect_b32 s37, s31, s37
	s_cselect_b32 s71, s35, s1
	s_cselect_b32 s70, s34, s0
	v_lshl_add_u64 v[216:217], s[4:5], 0, v[140:141]
	s_add_i32 m0, s47, 0xc000
	ds_read_b128 v[184:187], v167
	ds_read_b128 v[188:191], v167 offset:1024
	ds_read_b128 v[192:195], v167 offset:2048
	ds_read_b128 v[196:199], v167 offset:3072
	ds_read_b128 v[200:203], v167 offset:4096
	ds_read_b128 v[204:207], v167 offset:5120
	ds_read_b128 v[208:211], v167 offset:6144
	ds_read_b128 v[212:215], v167 offset:7168
	global_load_lds_dwordx4 v[216:217], off
	v_lshl_add_u64 v[216:217], s[4:5], 0, v[142:143]
	s_add_i32 m0, s47, 0xe000
	s_nop 0
	global_load_lds_dwordx4 v[216:217], off
	s_waitcnt vmcnt(8)
	s_waitcnt lgkmcnt(0)
	s_setprio 0
	s_barrier
; #define PG8_STAGE(bufoff, gbase, voff) do { _Pragma("unroll") for (int _i = 0; _i < 2; ++_i) \
;         __builtin_amdgcn_global_load_lds((const unsigned*)((const char*)(gbase) + (voff)[_i]), (PG8_LAS unsigned*)(lds + (bufoff) + ldsw + _i * 8192), 16, 0, 0); } while (0)
; #define PG8_LDA(dst, b, h) do { _Pragma("unroll") for (int m = 0; m < 4; ++m) _Pragma("unroll") for (int k = 0; k < 2; ++k) dst[m][k] = *(const PG8_LAS bf16x8*)(lds + PG8_SA(b, h) + aoff + m * 2048 + k * 1024); } while (0)
; #define PG8_LDB(dst, b, h) do { _Pragma("unroll") for (int n = 0; n < 2; ++n) _Pragma("unroll") for (int k = 0; k < 2; ++k) dst[n][k] = *(const PG8_LAS bf16x8*)(lds + PG8_SB(b, h) + boff + n * 2048 + k * 1024); } while (0)
; #define PG8_MMA(ai, bj, At, Bt) do { __builtin_amdgcn_s_setprio(1); _Pragma("unroll") for (int m = 0; m < 4; ++m) _Pragma("unroll") for (int n = 0; n < 2; ++n) _Pragma("unroll") for (int k = 0; k < 2; ++k) \
;         acc[ai][bj][m][n] = __builtin_amdgcn_mfma_f32_16x16x32_bf16(Bt[n][k], At[m][k], acc[ai][bj][m][n], 0, 0, 0); __builtin_amdgcn_s_setprio(0); } while (0)
; #define PG8_WAIT_V(n) asm volatile("s_waitcnt vmcnt(" #n ")" ::: "memory")
; #define PG8_WAIT_L(n) asm volatile("s_waitcnt lgkmcnt(" #n ")" ::: "memory")
; #define PG8_BAR __builtin_amdgcn_s_barrier()
; #define PG8_SCHED __builtin_amdgcn_sched_barrier(0)
; template <class Epi, class Sched, bool ALIGN_EPI = false, bool SP2 = false>
; __device__ __forceinline__ void gemm_phase(PG8_LAS unsigned char* lds, const Gemm g, const Sched& S, const Epi& E, const int wid) {
;     ...
;             if constexpr (SP2) {
;             PG8_LDB(B0, 0, 0); PG8_LDB(B1, 0, 1); PG8_SCHED; PG8_LDA(At, 0, 0); PG8_STAGE(PG8_SA(1, 1), a1 + hstep, voffA);
;             PG8_WAIT_V(8); PG8_WAIT_L(0); PG8_BAR; PG8_MMA(0, 0, At, B0); PG8_MMA(0, 1, At, B1); PG8_BAR; PG8_SCHED;
;             PG8_LDA(At, 0, 1); PG8_STAGE(PG8_SB(0, 0), b2, voffB); PG8_STAGE(PG8_SB(0, 1), b2 + hstep, voffB); PG8_STAGE(PG8_SA(0, 0), a2, voffA);
;             PG8_WAIT_V(8); PG8_WAIT_L(0); PG8_BAR; PG8_MMA(1, 0, At, B0); PG8_MMA(1, 1, At, B1); PG8_BAR; PG8_SCHED;
	v_mfma_f32_16x16x32_bf16 v[124:127], v[128:131], v[184:187], v[124:127]
	v_mfma_f32_16x16x32_bf16 v[120:123], v[150:153], v[184:187], v[120:123]
	v_mfma_f32_16x16x32_bf16 v[108:111], v[128:131], v[192:195], v[108:111]
	v_mfma_f32_16x16x32_bf16 v[104:107], v[150:153], v[192:195], v[104:107]
	v_mfma_f32_16x16x32_bf16 v[92:95], v[128:131], v[200:203], v[92:95]
	v_mfma_f32_16x16x32_bf16 v[88:91], v[150:153], v[200:203], v[88:91]
	v_mfma_f32_16x16x32_bf16 v[76:79], v[128:131], v[208:211], v[76:79]
	v_mfma_f32_16x16x32_bf16 v[72:75], v[150:153], v[208:211], v[72:75]
	v_mfma_f32_16x16x32_bf16 v[124:127], v[146:149], v[188:191], v[124:127]
	v_mfma_f32_16x16x32_bf16 v[120:123], v[154:157], v[188:191], v[120:123]
	v_mfma_f32_16x16x32_bf16 v[108:111], v[146:149], v[196:199], v[108:111]
	v_mfma_f32_16x16x32_bf16 v[104:107], v[154:157], v[196:199], v[104:107]
	v_mfma_f32_16x16x32_bf16 v[92:95], v[146:149], v[204:207], v[92:95]
	v_mfma_f32_16x16x32_bf16 v[88:91], v[154:157], v[204:207], v[88:91]
	v_mfma_f32_16x16x32_bf16 v[76:79], v[146:149], v[212:215], v[76:79]
	v_mfma_f32_16x16x32_bf16 v[72:75], v[154:157], v[212:215], v[72:75]
	v_mfma_f32_16x16x32_bf16 v[116:119], v[158:161], v[184:187], v[116:119]
	v_mfma_f32_16x16x32_bf16 v[112:115], v[176:179], v[184:187], v[112:115]
	v_mfma_f32_16x16x32_bf16 v[100:103], v[158:161], v[192:195], v[100:103]
	v_mfma_f32_16x16x32_bf16 v[96:99], v[176:179], v[192:195], v[96:99]
	v_mfma_f32_16x16x32_bf16 v[84:87], v[158:161], v[200:203], v[84:87]
	v_mfma_f32_16x16x32_bf16 v[80:83], v[176:179], v[200:203], v[80:83]
	v_mfma_f32_16x16x32_bf16 v[68:71], v[158:161], v[208:211], v[68:71]
	v_mfma_f32_16x16x32_bf16 v[64:67], v[176:179], v[208:211], v[64:67]
	v_mfma_f32_16x16x32_bf16 v[116:119], v[172:175], v[188:191], v[116:119]
	v_mfma_f32_16x16x32_bf16 v[112:115], v[180:183], v[188:191], v[112:115]
	v_mfma_f32_16x16x32_bf16 v[100:103], v[172:175], v[196:199], v[100:103]
	v_mfma_f32_16x16x32_bf16 v[96:99], v[180:183], v[196:199], v[96:99]
	v_mfma_f32_16x16x32_bf16 v[84:87], v[172:175], v[204:207], v[84:87]
	v_mfma_f32_16x16x32_bf16 v[80:83], v[180:183], v[204:207], v[80:83]
	v_mfma_f32_16x16x32_bf16 v[68:71], v[172:175], v[212:215], v[68:71]
	v_mfma_f32_16x16x32_bf16 v[64:67], v[180:183], v[212:215], v[64:67]
	s_barrier
	s_setprio 1
	s_add_i32 s33, s60, s40
	v_lshl_add_u64 v[216:217], s[70:71], 0, v[136:137]
	s_mov_b32 m0, s33
	ds_read_b128 v[184:187], v167 offset:16384
	ds_read_b128 v[188:191], v167 offset:17408
	ds_read_b128 v[192:195], v167 offset:18432
	ds_read_b128 v[196:199], v167 offset:19456
	ds_read_b128 v[200:203], v167 offset:20480
	ds_read_b128 v[204:207], v167 offset:21504
	ds_read_b128 v[208:211], v167 offset:22528
	ds_read_b128 v[212:215], v167 offset:23552
	global_load_lds_dwordx4 v[216:217], off
	s_add_i32 m0, s33, 0x2000
	v_lshl_add_u64 v[218:219], s[70:71], 0, v[132:133]
	s_add_u32 s70, s70, s6
	s_addc_u32 s71, s71, s7
	s_add_i32 s33, s61, s40
	global_load_lds_dwordx4 v[218:219], off
	v_lshl_add_u64 v[220:221], s[70:71], 0, v[136:137]
	s_mov_b32 m0, s33
	v_lshl_add_u64 v[222:223], s[70:71], 0, v[132:133]
	global_load_lds_dwordx4 v[220:221], off
	s_add_i32 m0, s33, 0x2000
	v_lshl_add_u64 v[224:225], s[36:37], 0, v[138:139]
	global_load_lds_dwordx4 v[222:223], off
	s_mov_b32 m0, s47
	v_lshl_add_u64 v[226:227], s[36:37], 0, v[134:135]
	global_load_lds_dwordx4 v[224:225], off
	s_mov_b32 m0, s49
	s_nop 0
	global_load_lds_dwordx4 v[226:227], off
	s_waitcnt vmcnt(8)
	s_waitcnt lgkmcnt(0)
	s_setprio 0
	s_barrier
	v_mfma_f32_16x16x32_bf16 v[60:63], v[128:131], v[184:187], v[60:63]
	v_mfma_f32_16x16x32_bf16 v[56:59], v[150:153], v[184:187], v[56:59]
	v_mfma_f32_16x16x32_bf16 v[44:47], v[128:131], v[192:195], v[44:47]
	v_mfma_f32_16x16x32_bf16 v[40:43], v[150:153], v[192:195], v[40:43]
	v_mfma_f32_16x16x32_bf16 v[28:31], v[128:131], v[200:203], v[28:31]
	v_mfma_f32_16x16x32_bf16 v[24:27], v[150:153], v[200:203], v[24:27]
	v_mfma_f32_16x16x32_bf16 v[12:15], v[128:131], v[208:211], v[12:15]
	v_mfma_f32_16x16x32_bf16 v[8:11], v[150:153], v[208:211], v[8:11]
	v_mfma_f32_16x16x32_bf16 v[60:63], v[146:149], v[188:191], v[60:63]
	v_mfma_f32_16x16x32_bf16 v[56:59], v[154:157], v[188:191], v[56:59]
	v_mfma_f32_16x16x32_bf16 v[44:47], v[146:149], v[196:199], v[44:47]
	v_mfma_f32_16x16x32_bf16 v[40:43], v[154:157], v[196:199], v[40:43]
	v_mfma_f32_16x16x32_bf16 v[28:31], v[146:149], v[204:207], v[28:31]
	v_mfma_f32_16x16x32_bf16 v[24:27], v[154:157], v[204:207], v[24:27]
	v_mfma_f32_16x16x32_bf16 v[12:15], v[146:149], v[212:215], v[12:15]
	v_mfma_f32_16x16x32_bf16 v[8:11], v[154:157], v[212:215], v[8:11]
	v_mfma_f32_16x16x32_bf16 v[52:55], v[158:161], v[184:187], v[52:55]
	v_mfma_f32_16x16x32_bf16 v[48:51], v[176:179], v[184:187], v[48:51]
	v_mfma_f32_16x16x32_bf16 v[36:39], v[158:161], v[192:195], v[36:39]
	v_mfma_f32_16x16x32_bf16 v[32:35], v[176:179], v[192:195], v[32:35]
	v_mfma_f32_16x16x32_bf16 v[20:23], v[158:161], v[200:203], v[20:23]
	v_mfma_f32_16x16x32_bf16 v[16:19], v[176:179], v[200:203], v[16:19]
	v_mfma_f32_16x16x32_bf16 v[4:7], v[158:161], v[208:211], v[4:7]
	v_mfma_f32_16x16x32_bf16 v[0:3], v[176:179], v[208:211], v[0:3]
	v_mfma_f32_16x16x32_bf16 v[52:55], v[172:175], v[188:191], v[52:55]
	v_mfma_f32_16x16x32_bf16 v[48:51], v[180:183], v[188:191], v[48:51]
	v_mfma_f32_16x16x32_bf16 v[36:39], v[172:175], v[196:199], v[36:39]
	v_mfma_f32_16x16x32_bf16 v[32:35], v[180:183], v[196:199], v[32:35]
	v_mfma_f32_16x16x32_bf16 v[20:23], v[172:175], v[204:207], v[20:23]
	v_mfma_f32_16x16x32_bf16 v[16:19], v[180:183], v[204:207], v[16:19]
	v_mfma_f32_16x16x32_bf16 v[4:7], v[172:175], v[212:215], v[4:7]
	v_mfma_f32_16x16x32_bf16 v[0:3], v[180:183], v[212:215], v[0:3]
	s_barrier
; #define PG8_STAGE(bufoff, gbase, voff) do { _Pragma("unroll") for (int _i = 0; _i < 2; ++_i) \
;         __builtin_amdgcn_global_load_lds((const unsigned*)((const char*)(gbase) + (voff)[_i]), (PG8_LAS unsigned*)(lds + (bufoff) + ldsw + _i * 8192), 16, 0, 0); } while (0)
; #define PG8_LDA(dst, b, h) do { _Pragma("unroll") for (int m = 0; m < 4; ++m) _Pragma("unroll") for (int k = 0; k < 2; ++k) dst[m][k] = *(const PG8_LAS bf16x8*)(lds + PG8_SA(b, h) + aoff + m * 2048 + k * 1024); } while (0)
; #define PG8_WAIT_V(n) asm volatile("s_waitcnt vmcnt(" #n ")" ::: "memory")
; #define PG8_WAIT_L(n) asm volatile("s_waitcnt lgkmcnt(" #n ")" ::: "memory")
; #define PG8_BAR __builtin_amdgcn_s_barrier()
; template <class Epi, class Sched, bool ALIGN_EPI = false, bool SP2 = false>
; __device__ __forceinline__ void gemm_phase(PG8_LAS unsigned char* lds, const Gemm g, const Sched& S, const Epi& E, const int wid) {
;     ...
;         for (int t = 0; t < nt; t += 2) {
;             const bool last = (t == nt - 2);
;             const char* a1 = cA + (size_t)(t + 1) * kstep;
;             const char* a2 = last ? nA : cA + (size_t)(t + 2) * kstep; const char* b2 = last ? nB : cB + (size_t)(t + 2) * kstep;
;             const char* a3 = a2 + kstep; const char* b3 = b2 + kstep;
;             if (last && has_next) S.a_ready(nxt);
;             if constexpr (SP2) {
;             PG8_LDB(B0, 0, 0); PG8_LDB(B1, 0, 1); PG8_SCHED; PG8_LDA(At, 0, 0); PG8_STAGE(PG8_SA(1, 1), a1 + hstep, voffA);
;             PG8_WAIT_V(8); PG8_WAIT_L(0); PG8_BAR; PG8_MMA(0, 0, At, B0); PG8_MMA(0, 1, At, B1); PG8_BAR; PG8_SCHED;
;             PG8_LDA(At, 0, 1); PG8_STAGE(PG8_SB(0, 0), b2, voffB); PG8_STAGE(PG8_SB(0, 1), b2 + hstep, voffB); PG8_STAGE(PG8_SA(0, 0), a2, voffA);
;             PG8_WAIT_V(8); PG8_WAIT_L(0); PG8_BAR; PG8_MMA(1, 0, At, B0); PG8_MMA(1, 1, At, B1); PG8_BAR; PG8_SCHED;
;             PG8_LDB(B0, 1, 0); PG8_LDB(B1, 1, 1); PG8_SCHED; PG8_LDA(At, 1, 0); PG8_STAGE(PG8_SA(0, 1), a2 + hstep, voffA);
;             PG8_WAIT_V(8); PG8_WAIT_L(0); PG8_BAR; PG8_MMA(0, 0, At, B0); PG8_MMA(0, 1, At, B1); PG8_BAR; PG8_SCHED;
;             PG8_LDA(At, 1, 1); PG8_STAGE(PG8_SB(1, 0), b3, voffB); PG8_STAGE(PG8_SB(1, 1), b3 + hstep, voffB); PG8_STAGE(PG8_SA(1, 0), a3, voffA);
;             PG8_WAIT_V(8); PG8_WAIT_L(0); PG8_BAR; PG8_MMA(1, 0, At, B0); PG8_MMA(1, 1, At, B1); PG8_BAR; PG8_SCHED;
	s_setprio 1
	s_add_i32 s33, 0, 0x18000
	s_add_i32 s39, 0, 0x1c000
	v_add_u32_e32 v154, s33, v164
	v_add_u32_e32 v180, s39, v164
	ds_read_b128 v[128:131], v154
	ds_read_b128 v[146:149], v154 offset:1024
	ds_read_b128 v[150:153], v154 offset:2048
	ds_read_b128 v[154:157], v154 offset:3072
	ds_read_b128 v[158:161], v180
	ds_read_b128 v[172:175], v180 offset:1024
	ds_read_b128 v[176:179], v180 offset:2048
	ds_read_b128 v[180:183], v180 offset:3072
	s_add_u32 s36, s36, s6
	s_addc_u32 s37, s37, s7
	s_mov_b32 m0, s50
	v_lshl_add_u64 v[228:229], s[36:37], 0, v[138:139]
	ds_read_b128 v[184:187], v167 offset:32768
	ds_read_b128 v[188:191], v167 offset:33792
	ds_read_b128 v[192:195], v167 offset:34816
	ds_read_b128 v[196:199], v167 offset:35840
	ds_read_b128 v[200:203], v167 offset:36864
	ds_read_b128 v[204:207], v167 offset:37888
	ds_read_b128 v[208:211], v167 offset:38912
	ds_read_b128 v[212:215], v167 offset:39936
	global_load_lds_dwordx4 v[228:229], off
	v_lshl_add_u64 v[228:229], s[36:37], 0, v[134:135]
	s_mov_b32 m0, s51
	s_nop 0
	global_load_lds_dwordx4 v[228:229], off
	s_waitcnt vmcnt(8)
	s_waitcnt lgkmcnt(0)
	s_setprio 0
	s_barrier
	v_mfma_f32_16x16x32_bf16 v[124:127], v[128:131], v[184:187], v[124:127]
	v_mfma_f32_16x16x32_bf16 v[120:123], v[150:153], v[184:187], v[120:123]
	v_mfma_f32_16x16x32_bf16 v[108:111], v[128:131], v[192:195], v[108:111]
	v_mfma_f32_16x16x32_bf16 v[104:107], v[150:153], v[192:195], v[104:107]
	v_mfma_f32_16x16x32_bf16 v[92:95], v[128:131], v[200:203], v[92:95]
	v_mfma_f32_16x16x32_bf16 v[88:91], v[150:153], v[200:203], v[88:91]
	v_mfma_f32_16x16x32_bf16 v[76:79], v[128:131], v[208:211], v[76:79]
	v_mfma_f32_16x16x32_bf16 v[72:75], v[150:153], v[208:211], v[72:75]
	v_mfma_f32_16x16x32_bf16 v[124:127], v[146:149], v[188:191], v[124:127]
	v_mfma_f32_16x16x32_bf16 v[120:123], v[154:157], v[188:191], v[120:123]
	v_mfma_f32_16x16x32_bf16 v[108:111], v[146:149], v[196:199], v[108:111]
	v_mfma_f32_16x16x32_bf16 v[104:107], v[154:157], v[196:199], v[104:107]
	v_mfma_f32_16x16x32_bf16 v[92:95], v[146:149], v[204:207], v[92:95]
	v_mfma_f32_16x16x32_bf16 v[88:91], v[154:157], v[204:207], v[88:91]
	v_mfma_f32_16x16x32_bf16 v[76:79], v[146:149], v[212:215], v[76:79]
	v_mfma_f32_16x16x32_bf16 v[72:75], v[154:157], v[212:215], v[72:75]
	v_mfma_f32_16x16x32_bf16 v[116:119], v[158:161], v[184:187], v[116:119]
	v_mfma_f32_16x16x32_bf16 v[112:115], v[176:179], v[184:187], v[112:115]
	v_mfma_f32_16x16x32_bf16 v[100:103], v[158:161], v[192:195], v[100:103]
	v_mfma_f32_16x16x32_bf16 v[96:99], v[176:179], v[192:195], v[96:99]
	v_mfma_f32_16x16x32_bf16 v[84:87], v[158:161], v[200:203], v[84:87]
	v_mfma_f32_16x16x32_bf16 v[80:83], v[176:179], v[200:203], v[80:83]
	v_mfma_f32_16x16x32_bf16 v[68:71], v[158:161], v[208:211], v[68:71]
	v_mfma_f32_16x16x32_bf16 v[64:67], v[176:179], v[208:211], v[64:67]
	v_mfma_f32_16x16x32_bf16 v[116:119], v[172:175], v[188:191], v[116:119]
	v_mfma_f32_16x16x32_bf16 v[112:115], v[180:183], v[188:191], v[112:115]
	v_mfma_f32_16x16x32_bf16 v[100:103], v[172:175], v[196:199], v[100:103]
	v_mfma_f32_16x16x32_bf16 v[96:99], v[180:183], v[196:199], v[96:99]
	v_mfma_f32_16x16x32_bf16 v[84:87], v[172:175], v[204:207], v[84:87]
	v_mfma_f32_16x16x32_bf16 v[80:83], v[180:183], v[204:207], v[80:83]
	v_mfma_f32_16x16x32_bf16 v[68:71], v[172:175], v[212:215], v[68:71]
	v_mfma_f32_16x16x32_bf16 v[64:67], v[180:183], v[212:215], v[64:67]
	s_barrier
	s_setprio 1
	s_add_i32 s33, s33, s40
	v_lshl_add_u64 v[216:217], v[216:217], 0, s[22:23]
	s_mov_b32 m0, s33
	ds_read_b128 v[184:187], v167 offset:49152
	ds_read_b128 v[188:191], v167 offset:50176
	ds_read_b128 v[192:195], v167 offset:51200
	ds_read_b128 v[196:199], v167 offset:52224
	ds_read_b128 v[200:203], v167 offset:53248
	ds_read_b128 v[204:207], v167 offset:54272
	ds_read_b128 v[208:211], v167 offset:55296
	ds_read_b128 v[212:215], v167 offset:56320
	global_load_lds_dwordx4 v[216:217], off
	v_lshl_add_u64 v[216:217], v[218:219], 0, s[22:23]
	s_add_i32 m0, s33, 0x2000
	s_add_i32 s33, s39, s40
	global_load_lds_dwordx4 v[216:217], off
	v_lshl_add_u64 v[216:217], v[220:221], 0, s[22:23]
	s_mov_b32 m0, s33
	s_nop 0
	global_load_lds_dwordx4 v[216:217], off
	v_lshl_add_u64 v[216:217], v[222:223], 0, s[22:23]
	s_add_i32 m0, s33, 0x2000
	s_nop 0
	global_load_lds_dwordx4 v[216:217], off
	v_lshl_add_u64 v[216:217], v[224:225], 0, s[22:23]
	s_mov_b32 m0, s53
	s_nop 0
	global_load_lds_dwordx4 v[216:217], off
	v_lshl_add_u64 v[216:217], v[226:227], 0, s[22:23]
	s_mov_b32 m0, s54
	s_nop 0
	global_load_lds_dwordx4 v[216:217], off
	s_waitcnt vmcnt(8)
	s_waitcnt lgkmcnt(0)
	s_setprio 0
	s_barrier
	v_mfma_f32_16x16x32_bf16 v[60:63], v[128:131], v[184:187], v[60:63]
	v_mfma_f32_16x16x32_bf16 v[56:59], v[150:153], v[184:187], v[56:59]
	v_mfma_f32_16x16x32_bf16 v[44:47], v[128:131], v[192:195], v[44:47]
	v_mfma_f32_16x16x32_bf16 v[40:43], v[150:153], v[192:195], v[40:43]
	v_mfma_f32_16x16x32_bf16 v[28:31], v[128:131], v[200:203], v[28:31]
	v_mfma_f32_16x16x32_bf16 v[24:27], v[150:153], v[200:203], v[24:27]
	v_mfma_f32_16x16x32_bf16 v[12:15], v[128:131], v[208:211], v[12:15]
	v_mfma_f32_16x16x32_bf16 v[8:11], v[150:153], v[208:211], v[8:11]
	v_mfma_f32_16x16x32_bf16 v[60:63], v[146:149], v[188:191], v[60:63]
	v_mfma_f32_16x16x32_bf16 v[56:59], v[154:157], v[188:191], v[56:59]
	v_mfma_f32_16x16x32_bf16 v[44:47], v[146:149], v[196:199], v[44:47]
	v_mfma_f32_16x16x32_bf16 v[40:43], v[154:157], v[196:199], v[40:43]
	v_mfma_f32_16x16x32_bf16 v[28:31], v[146:149], v[204:207], v[28:31]
	v_mfma_f32_16x16x32_bf16 v[24:27], v[154:157], v[204:207], v[24:27]
	v_mfma_f32_16x16x32_bf16 v[12:15], v[146:149], v[212:215], v[12:15]
	v_mfma_f32_16x16x32_bf16 v[8:11], v[154:157], v[212:215], v[8:11]
	v_mfma_f32_16x16x32_bf16 v[52:55], v[158:161], v[184:187], v[52:55]
	v_mfma_f32_16x16x32_bf16 v[48:51], v[176:179], v[184:187], v[48:51]
	v_mfma_f32_16x16x32_bf16 v[36:39], v[158:161], v[192:195], v[36:39]
	v_mfma_f32_16x16x32_bf16 v[32:35], v[176:179], v[192:195], v[32:35]
	v_mfma_f32_16x16x32_bf16 v[20:23], v[158:161], v[200:203], v[20:23]
	v_mfma_f32_16x16x32_bf16 v[16:19], v[176:179], v[200:203], v[16:19]
	v_mfma_f32_16x16x32_bf16 v[4:7], v[158:161], v[208:211], v[4:7]
	v_mfma_f32_16x16x32_bf16 v[0:3], v[176:179], v[208:211], v[0:3]
	v_mfma_f32_16x16x32_bf16 v[52:55], v[172:175], v[188:191], v[52:55]
	v_mfma_f32_16x16x32_bf16 v[48:51], v[180:183], v[188:191], v[48:51]
	v_mfma_f32_16x16x32_bf16 v[36:39], v[172:175], v[196:199], v[36:39]
	v_mfma_f32_16x16x32_bf16 v[32:35], v[180:183], v[196:199], v[32:35]
	v_mfma_f32_16x16x32_bf16 v[20:23], v[172:175], v[204:207], v[20:23]
	v_mfma_f32_16x16x32_bf16 v[16:19], v[180:183], v[204:207], v[16:19]
	v_mfma_f32_16x16x32_bf16 v[4:7], v[172:175], v[212:215], v[4:7]
	v_mfma_f32_16x16x32_bf16 v[0:3], v[180:183], v[212:215], v[0:3]
	s_barrier
	s_setprio 1
	s_add_u32 s4, s4, 0x100
	s_addc_u32 s5, s5, 0
	s_add_u32 s0, s0, 0x100
	s_addc_u32 s1, s1, 0
	s_cmp_ge_i32 s38, s55
	s_mov_b32 s36, s38
	s_cbranch_scc0 .LBB0_20

; #define PG8_STAGE(bufoff, gbase, voff) do { _Pragma("unroll") for (int _i = 0; _i < 2; ++_i) \
;         __builtin_amdgcn_global_load_lds((const unsigned*)((const char*)(gbase) + (voff)[_i]), (PG8_LAS unsigned*)(lds + (bufoff) + ldsw + _i * 8192), 16, 0, 0); } while (0)
; #define PG8_LDA(dst, b, h) do { _Pragma("unroll") for (int m = 0; m < 4; ++m) _Pragma("unroll") for (int k = 0; k < 2; ++k) dst[m][k] = *(const PG8_LAS bf16x8*)(lds + PG8_SA(b, h) + aoff + m * 2048 + k * 1024); } while (0)
; #define PG8_LDB(dst, b, h) do { _Pragma("unroll") for (int n = 0; n < 2; ++n) _Pragma("unroll") for (int k = 0; k < 2; ++k) dst[n][k] = *(const PG8_LAS bf16x8*)(lds + PG8_SB(b, h) + boff + n * 2048 + k * 1024); } while (0)
; #define PG8_WAIT_V(n) asm volatile("s_waitcnt vmcnt(" #n ")" ::: "memory")
; #define PG8_WAIT_L(n) asm volatile("s_waitcnt lgkmcnt(" #n ")" ::: "memory")
; #define PG8_BAR __builtin_amdgcn_s_barrier()
; #define PG8_SCHED __builtin_amdgcn_sched_barrier(0)
; template <class Epi, class Sched, bool ALIGN_EPI = false, bool SP2 = false>
; __device__ __forceinline__ void gemm_phase(PG8_LAS unsigned char* lds, const Gemm g, const Sched& S, const Epi& E, const int wid) {
;     ...
;         const bool has_next = S.next(ui + 1, nxt);
;         const char* nA = has_next ? (const char*)g.A + (size_t)nxt.pm * tstep : cA; const char* nB = has_next ? (const char*)g.Bt + (size_t)nxt.pn * tstep : cB;
;         for (int t = 0; t < nt; t += 2) {
;             const bool last = (t == nt - 2);
;             const char* a1 = cA + (size_t)(t + 1) * kstep;
;             const char* a2 = last ? nA : cA + (size_t)(t + 2) * kstep; const char* b2 = last ? nB : cB + (size_t)(t + 2) * kstep;
;             const char* a3 = a2 + kstep; const char* b3 = b2 + kstep;
;             if (last && has_next) S.a_ready(nxt);
;             if constexpr (SP2) {
;             PG8_LDB(B0, 0, 0); PG8_LDB(B1, 0, 1); PG8_SCHED; PG8_LDA(At, 0, 0); PG8_STAGE(PG8_SA(1, 1), a1 + hstep, voffA);
;             PG8_WAIT_V(8); PG8_WAIT_L(0); PG8_BAR; PG8_MMA(0, 0, At, B0); PG8_MMA(0, 1, At, B1); PG8_BAR; PG8_SCHED;
;             PG8_LDA(At, 0, 1); PG8_STAGE(PG8_SB(0, 0), b2, voffB); PG8_STAGE(PG8_SB(0, 1), b2 + hstep, voffB); PG8_STAGE(PG8_SA(0, 0), a2, voffA);
;             PG8_WAIT_V(8); PG8_WAIT_L(0); PG8_BAR; PG8_MMA(1, 0, At, B0); PG8_MMA(1, 1, At, B1); PG8_BAR; PG8_SCHED;
.LBB0_1098:
	s_andn2_b64 vcc, exec, s[28:29]
	s_cbranch_vccnz .Lz_G1B
	s_add_u32 s4, s8, 0x80
	s_addc_u32 s5, s9, 0
	s_add_u32 s0, s6, 0x100
	s_addc_u32 s1, s7, 0
	s_mov_b32 s6, 0
	ds_read_b128 v[44:47], v163
	ds_read_b128 v[52:55], v163 offset:1024
	ds_read_b128 v[60:63], v163 offset:2048
	ds_read_b128 v[68:71], v163 offset:3072
	ds_read_b128 v[166:169], v164
	ds_read_b128 v[170:173], v164 offset:1024
	ds_read_b128 v[174:177], v164 offset:2048
	ds_read_b128 v[178:181], v164 offset:3072
	s_add_i32 s8, s6, 2
	s_add_u32 s9, s4, 0x80
	s_addc_u32 s7, s5, 0
	s_cmp_eq_u32 s72, s6
	s_cselect_b32 s6, s48, s9
	s_cselect_b32 s7, s49, s7
	s_cselect_b32 s77, s51, s1
	s_cselect_b32 s76, s50, s0
	v_lshl_add_u64 v[158:159], s[4:5], 0, v[152:153]
	s_add_i32 m0, s63, 0xc000
	ds_read_b128 v[182:185], v165
	ds_read_b128 v[186:189], v165 offset:1024
	ds_read_b128 v[190:193], v165 offset:2048
	ds_read_b128 v[194:197], v165 offset:3072
	ds_read_b128 v[198:201], v165 offset:4096
	ds_read_b128 v[202:205], v165 offset:5120
	ds_read_b128 v[206:209], v165 offset:6144
	ds_read_b128 v[210:213], v165 offset:7168
	global_load_lds_dwordx4 v[158:159], off
	v_lshl_add_u64 v[158:159], s[4:5], 0, v[154:155]
	s_add_i32 m0, s63, 0xe000
	s_nop 0
	global_load_lds_dwordx4 v[158:159], off
	s_waitcnt vmcnt(8)
	s_waitcnt lgkmcnt(0)
	s_setprio 0
	s_barrier
	v_mfma_f32_16x16x32_bf16 v[140:143], v[44:47], v[182:185], 0
	v_mfma_f32_16x16x32_bf16 v[136:139], v[60:63], v[182:185], 0
	v_mfma_f32_16x16x32_bf16 v[124:127], v[44:47], v[190:193], 0
	v_mfma_f32_16x16x32_bf16 v[120:123], v[60:63], v[190:193], 0
	v_mfma_f32_16x16x32_bf16 v[108:111], v[44:47], v[198:201], 0
	v_mfma_f32_16x16x32_bf16 v[104:107], v[60:63], v[198:201], 0
	v_mfma_f32_16x16x32_bf16 v[92:95], v[44:47], v[206:209], 0
	v_mfma_f32_16x16x32_bf16 v[88:91], v[60:63], v[206:209], 0
	v_mfma_f32_16x16x32_bf16 v[140:143], v[52:55], v[186:189], v[140:143]
	v_mfma_f32_16x16x32_bf16 v[136:139], v[68:71], v[186:189], v[136:139]
	v_mfma_f32_16x16x32_bf16 v[124:127], v[52:55], v[194:197], v[124:127]
	v_mfma_f32_16x16x32_bf16 v[120:123], v[68:71], v[194:197], v[120:123]
	v_mfma_f32_16x16x32_bf16 v[108:111], v[52:55], v[202:205], v[108:111]
	v_mfma_f32_16x16x32_bf16 v[104:107], v[68:71], v[202:205], v[104:107]
	v_mfma_f32_16x16x32_bf16 v[92:95], v[52:55], v[210:213], v[92:95]
	v_mfma_f32_16x16x32_bf16 v[88:91], v[68:71], v[210:213], v[88:91]
	v_mfma_f32_16x16x32_bf16 v[132:135], v[166:169], v[182:185], 0
	v_mfma_f32_16x16x32_bf16 v[128:131], v[174:177], v[182:185], 0
	v_mfma_f32_16x16x32_bf16 v[116:119], v[166:169], v[190:193], 0
	v_mfma_f32_16x16x32_bf16 v[112:115], v[174:177], v[190:193], 0
	v_mfma_f32_16x16x32_bf16 v[100:103], v[166:169], v[198:201], 0
	v_mfma_f32_16x16x32_bf16 v[96:99], v[174:177], v[198:201], 0
	v_mfma_f32_16x16x32_bf16 v[84:87], v[166:169], v[206:209], 0
	v_mfma_f32_16x16x32_bf16 v[80:83], v[174:177], v[206:209], 0
	v_mfma_f32_16x16x32_bf16 v[132:135], v[170:173], v[186:189], v[132:135]
	v_mfma_f32_16x16x32_bf16 v[128:131], v[178:181], v[186:189], v[128:131]
	v_mfma_f32_16x16x32_bf16 v[116:119], v[170:173], v[194:197], v[116:119]
	v_mfma_f32_16x16x32_bf16 v[112:115], v[178:181], v[194:197], v[112:115]
	v_mfma_f32_16x16x32_bf16 v[100:103], v[170:173], v[202:205], v[100:103]
	v_mfma_f32_16x16x32_bf16 v[96:99], v[178:181], v[202:205], v[96:99]
	v_mfma_f32_16x16x32_bf16 v[84:87], v[170:173], v[210:213], v[84:87]
	v_mfma_f32_16x16x32_bf16 v[80:83], v[178:181], v[210:213], v[80:83]
	s_barrier
	s_setprio 1
	s_add_i32 s9, s75, s55
	v_lshl_add_u64 v[158:159], s[76:77], 0, v[148:149]
	s_mov_b32 m0, s9
	ds_read_b128 v[182:185], v165 offset:16384
	ds_read_b128 v[186:189], v165 offset:17408
	ds_read_b128 v[190:193], v165 offset:18432
	ds_read_b128 v[194:197], v165 offset:19456
	ds_read_b128 v[198:201], v165 offset:20480
	ds_read_b128 v[202:205], v165 offset:21504
	ds_read_b128 v[206:209], v165 offset:22528
	ds_read_b128 v[210:213], v165 offset:23552
	global_load_lds_dwordx4 v[158:159], off
	s_add_i32 m0, s9, 0x2000
	v_lshl_add_u64 v[214:215], s[76:77], 0, v[144:145]
	s_add_u32 s76, s76, s12
	s_addc_u32 s77, s77, s13
	s_add_i32 s9, s78, s55
	global_load_lds_dwordx4 v[214:215], off
	v_lshl_add_u64 v[216:217], s[76:77], 0, v[148:149]
	s_mov_b32 m0, s9
	v_lshl_add_u64 v[218:219], s[76:77], 0, v[144:145]
	global_load_lds_dwordx4 v[216:217], off
	s_add_i32 m0, s9, 0x2000
	v_lshl_add_u64 v[220:221], s[6:7], 0, v[150:151]
	global_load_lds_dwordx4 v[218:219], off
	s_mov_b32 m0, s63
	v_lshl_add_u64 v[222:223], s[6:7], 0, v[146:147]
	global_load_lds_dwordx4 v[220:221], off
	s_mov_b32 m0, s64
	s_nop 0
	global_load_lds_dwordx4 v[222:223], off
	s_waitcnt vmcnt(8)
	s_waitcnt lgkmcnt(0)
	s_setprio 0
	s_barrier
; #define PG8_STAGE(bufoff, gbase, voff) do { _Pragma("unroll") for (int _i = 0; _i < 2; ++_i) \
;         __builtin_amdgcn_global_load_lds((const unsigned*)((const char*)(gbase) + (voff)[_i]), (PG8_LAS unsigned*)(lds + (bufoff) + ldsw + _i * 8192), 16, 0, 0); } while (0)
; #define PG8_LDA(dst, b, h) do { _Pragma("unroll") for (int m = 0; m < 4; ++m) _Pragma("unroll") for (int k = 0; k < 2; ++k) dst[m][k] = *(const PG8_LAS bf16x8*)(lds + PG8_SA(b, h) + aoff + m * 2048 + k * 1024); } while (0)
; #define PG8_LDB(dst, b, h) do { _Pragma("unroll") for (int n = 0; n < 2; ++n) _Pragma("unroll") for (int k = 0; k < 2; ++k) dst[n][k] = *(const PG8_LAS bf16x8*)(lds + PG8_SB(b, h) + boff + n * 2048 + k * 1024); } while (0)
; #define PG8_MMA(ai, bj, At, Bt) do { __builtin_amdgcn_s_setprio(1); _Pragma("unroll") for (int m = 0; m < 4; ++m) _Pragma("unroll") for (int n = 0; n < 2; ++n) _Pragma("unroll") for (int k = 0; k < 2; ++k) \
;         acc[ai][bj][m][n] = __builtin_amdgcn_mfma_f32_16x16x32_bf16(Bt[n][k], At[m][k], acc[ai][bj][m][n], 0, 0, 0); __builtin_amdgcn_s_setprio(0); } while (0)
; #define PG8_WAIT_V(n) asm volatile("s_waitcnt vmcnt(" #n ")" ::: "memory")
; #define PG8_WAIT_L(n) asm volatile("s_waitcnt lgkmcnt(" #n ")" ::: "memory")
; #define PG8_BAR __builtin_amdgcn_s_barrier()
; #define PG8_SCHED __builtin_amdgcn_sched_barrier(0)
; template <class Epi, class Sched, bool ALIGN_EPI = false, bool SP2 = false>
; __device__ __forceinline__ void gemm_phase(PG8_LAS unsigned char* lds, const Gemm g, const Sched& S, const Epi& E, const int wid) {
;     ...
;             PG8_WAIT_V(8); PG8_WAIT_L(0); PG8_BAR; PG8_MMA(0, 0, At, B0); PG8_MMA(0, 1, At, B1); PG8_BAR; PG8_SCHED;
;             PG8_LDA(At, 0, 1); PG8_STAGE(PG8_SB(0, 0), b2, voffB); PG8_STAGE(PG8_SB(0, 1), b2 + hstep, voffB); PG8_STAGE(PG8_SA(0, 0), a2, voffA);
;             PG8_WAIT_V(8); PG8_WAIT_L(0); PG8_BAR; PG8_MMA(1, 0, At, B0); PG8_MMA(1, 1, At, B1); PG8_BAR; PG8_SCHED;
;             PG8_LDB(B0, 1, 0); PG8_LDB(B1, 1, 1); PG8_SCHED; PG8_LDA(At, 1, 0); PG8_STAGE(PG8_SA(0, 1), a2 + hstep, voffA);
;             PG8_WAIT_V(8); PG8_WAIT_L(0); PG8_BAR; PG8_MMA(0, 0, At, B0); PG8_MMA(0, 1, At, B1); PG8_BAR; PG8_SCHED;
	v_mfma_f32_16x16x32_bf16 v[76:79], v[44:47], v[182:185], 0
	v_mfma_f32_16x16x32_bf16 v[72:75], v[60:63], v[182:185], 0
	v_mfma_f32_16x16x32_bf16 v[48:51], v[44:47], v[190:193], 0
	v_mfma_f32_16x16x32_bf16 v[40:43], v[60:63], v[190:193], 0
	v_mfma_f32_16x16x32_bf16 v[28:31], v[44:47], v[198:201], 0
	v_mfma_f32_16x16x32_bf16 v[24:27], v[60:63], v[198:201], 0
	v_mfma_f32_16x16x32_bf16 v[12:15], v[44:47], v[206:209], 0
	v_mfma_f32_16x16x32_bf16 v[8:11], v[60:63], v[206:209], 0
	v_mfma_f32_16x16x32_bf16 v[76:79], v[52:55], v[186:189], v[76:79]
	v_mfma_f32_16x16x32_bf16 v[72:75], v[68:71], v[186:189], v[72:75]
	v_mfma_f32_16x16x32_bf16 v[48:51], v[52:55], v[194:197], v[48:51]
	v_mfma_f32_16x16x32_bf16 v[40:43], v[68:71], v[194:197], v[40:43]
	v_mfma_f32_16x16x32_bf16 v[28:31], v[52:55], v[202:205], v[28:31]
	v_mfma_f32_16x16x32_bf16 v[24:27], v[68:71], v[202:205], v[24:27]
	v_mfma_f32_16x16x32_bf16 v[12:15], v[52:55], v[210:213], v[12:15]
	v_mfma_f32_16x16x32_bf16 v[8:11], v[68:71], v[210:213], v[8:11]
	v_mfma_f32_16x16x32_bf16 v[36:39], v[166:169], v[190:193], 0
	v_mfma_f32_16x16x32_bf16 v[32:35], v[174:177], v[190:193], 0
	v_mfma_f32_16x16x32_bf16 v[20:23], v[166:169], v[198:201], 0
	v_mfma_f32_16x16x32_bf16 v[16:19], v[174:177], v[198:201], 0
	v_mfma_f32_16x16x32_bf16 v[4:7], v[166:169], v[206:209], 0
	v_mfma_f32_16x16x32_bf16 v[0:3], v[174:177], v[206:209], 0
	v_mfma_f32_16x16x32_bf16 v[44:47], v[166:169], v[182:185], 0
	v_mfma_f32_16x16x32_bf16 v[52:55], v[174:177], v[182:185], 0
	v_mfma_f32_16x16x32_bf16 v[36:39], v[170:173], v[194:197], v[36:39]
	v_mfma_f32_16x16x32_bf16 v[32:35], v[178:181], v[194:197], v[32:35]
	v_mfma_f32_16x16x32_bf16 v[20:23], v[170:173], v[202:205], v[20:23]
	v_mfma_f32_16x16x32_bf16 v[16:19], v[178:181], v[202:205], v[16:19]
	v_mfma_f32_16x16x32_bf16 v[4:7], v[170:173], v[210:213], v[4:7]
	v_mfma_f32_16x16x32_bf16 v[0:3], v[178:181], v[210:213], v[0:3]
	v_mfma_f32_16x16x32_bf16 v[44:47], v[170:173], v[186:189], v[44:47]
	v_mfma_f32_16x16x32_bf16 v[52:55], v[178:181], v[186:189], v[52:55]
	s_barrier
	s_setprio 1
	s_add_i32 s9, 0, 0x18000
	s_add_i32 s33, 0, 0x1c000
	v_add_u32_e32 v68, s9, v162
	v_add_u32_e32 v178, s33, v162
	ds_read_b128 v[56:59], v68
	ds_read_b128 v[60:63], v68 offset:1024
	ds_read_b128 v[64:67], v68 offset:2048
	ds_read_b128 v[68:71], v68 offset:3072
	ds_read_b128 v[166:169], v178
	ds_read_b128 v[170:173], v178 offset:1024
	ds_read_b128 v[174:177], v178 offset:2048
	ds_read_b128 v[178:181], v178 offset:3072
	s_add_u32 s6, s6, s12
	s_addc_u32 s7, s7, s13
	s_mov_b32 m0, s65
	v_lshl_add_u64 v[224:225], s[6:7], 0, v[150:151]
	ds_read_b128 v[182:185], v165 offset:32768
	ds_read_b128 v[186:189], v165 offset:33792
	ds_read_b128 v[190:193], v165 offset:34816
	ds_read_b128 v[194:197], v165 offset:35840
	ds_read_b128 v[198:201], v165 offset:36864
	ds_read_b128 v[202:205], v165 offset:37888
	ds_read_b128 v[206:209], v165 offset:38912
	ds_read_b128 v[210:213], v165 offset:39936
	global_load_lds_dwordx4 v[224:225], off
	v_lshl_add_u64 v[224:225], s[6:7], 0, v[146:147]
	s_mov_b32 m0, s66
	s_nop 0
	global_load_lds_dwordx4 v[224:225], off
	s_waitcnt vmcnt(8)
	s_waitcnt lgkmcnt(0)
	s_setprio 0
	s_barrier
	v_mfma_f32_16x16x32_bf16 v[140:143], v[56:59], v[182:185], v[140:143]
	v_mfma_f32_16x16x32_bf16 v[136:139], v[64:67], v[182:185], v[136:139]
	v_mfma_f32_16x16x32_bf16 v[124:127], v[56:59], v[190:193], v[124:127]
	v_mfma_f32_16x16x32_bf16 v[120:123], v[64:67], v[190:193], v[120:123]
	v_mfma_f32_16x16x32_bf16 v[108:111], v[56:59], v[198:201], v[108:111]
	v_mfma_f32_16x16x32_bf16 v[104:107], v[64:67], v[198:201], v[104:107]
	v_mfma_f32_16x16x32_bf16 v[92:95], v[56:59], v[206:209], v[92:95]
	v_mfma_f32_16x16x32_bf16 v[88:91], v[64:67], v[206:209], v[88:91]
	v_mfma_f32_16x16x32_bf16 v[140:143], v[60:63], v[186:189], v[140:143]
	v_mfma_f32_16x16x32_bf16 v[136:139], v[68:71], v[186:189], v[136:139]
	v_mfma_f32_16x16x32_bf16 v[124:127], v[60:63], v[194:197], v[124:127]
	v_mfma_f32_16x16x32_bf16 v[120:123], v[68:71], v[194:197], v[120:123]
	v_mfma_f32_16x16x32_bf16 v[108:111], v[60:63], v[202:205], v[108:111]
	v_mfma_f32_16x16x32_bf16 v[104:107], v[68:71], v[202:205], v[104:107]
	v_mfma_f32_16x16x32_bf16 v[92:95], v[60:63], v[210:213], v[92:95]
	v_mfma_f32_16x16x32_bf16 v[88:91], v[68:71], v[210:213], v[88:91]
	v_mfma_f32_16x16x32_bf16 v[132:135], v[166:169], v[182:185], v[132:135]
	v_mfma_f32_16x16x32_bf16 v[128:131], v[174:177], v[182:185], v[128:131]
	v_mfma_f32_16x16x32_bf16 v[116:119], v[166:169], v[190:193], v[116:119]
	v_mfma_f32_16x16x32_bf16 v[112:115], v[174:177], v[190:193], v[112:115]
	v_mfma_f32_16x16x32_bf16 v[100:103], v[166:169], v[198:201], v[100:103]
	v_mfma_f32_16x16x32_bf16 v[96:99], v[174:177], v[198:201], v[96:99]
	v_mfma_f32_16x16x32_bf16 v[84:87], v[166:169], v[206:209], v[84:87]
	v_mfma_f32_16x16x32_bf16 v[80:83], v[174:177], v[206:209], v[80:83]
	v_mfma_f32_16x16x32_bf16 v[132:135], v[170:173], v[186:189], v[132:135]
	v_mfma_f32_16x16x32_bf16 v[128:131], v[178:181], v[186:189], v[128:131]
	v_mfma_f32_16x16x32_bf16 v[116:119], v[170:173], v[194:197], v[116:119]
	v_mfma_f32_16x16x32_bf16 v[112:115], v[178:181], v[194:197], v[112:115]
	v_mfma_f32_16x16x32_bf16 v[100:103], v[170:173], v[202:205], v[100:103]
	v_mfma_f32_16x16x32_bf16 v[96:99], v[178:181], v[202:205], v[96:99]
	v_mfma_f32_16x16x32_bf16 v[84:87], v[170:173], v[210:213], v[84:87]
	v_mfma_f32_16x16x32_bf16 v[80:83], v[178:181], v[210:213], v[80:83]
	s_barrier
; #define PG8_STAGE(bufoff, gbase, voff) do { _Pragma("unroll") for (int _i = 0; _i < 2; ++_i) \
;         __builtin_amdgcn_global_load_lds((const unsigned*)((const char*)(gbase) + (voff)[_i]), (PG8_LAS unsigned*)(lds + (bufoff) + ldsw + _i * 8192), 16, 0, 0); } while (0)
; #define PG8_LDA(dst, b, h) do { _Pragma("unroll") for (int m = 0; m < 4; ++m) _Pragma("unroll") for (int k = 0; k < 2; ++k) dst[m][k] = *(const PG8_LAS bf16x8*)(lds + PG8_SA(b, h) + aoff + m * 2048 + k * 1024); } while (0)
; #define PG8_WAIT_V(n) asm volatile("s_waitcnt vmcnt(" #n ")" ::: "memory")
; #define PG8_WAIT_L(n) asm volatile("s_waitcnt lgkmcnt(" #n ")" ::: "memory")
; #define PG8_BAR __builtin_amdgcn_s_barrier()
; template <class Epi, class Sched, bool ALIGN_EPI = false, bool SP2 = false>
; __device__ __forceinline__ void gemm_phase(PG8_LAS unsigned char* lds, const Gemm g, const Sched& S, const Epi& E, const int wid) {
;     ...
;         for (int t = 0; t < nt; t += 2) {
;             const bool last = (t == nt - 2);
;             const char* a1 = cA + (size_t)(t + 1) * kstep;
;             const char* a2 = last ? nA : cA + (size_t)(t + 2) * kstep; const char* b2 = last ? nB : cB + (size_t)(t + 2) * kstep;
;             const char* a3 = a2 + kstep; const char* b3 = b2 + kstep;
;             if (last && has_next) S.a_ready(nxt);
;             if constexpr (SP2) {
;             PG8_LDB(B0, 0, 0); PG8_LDB(B1, 0, 1); PG8_SCHED; PG8_LDA(At, 0, 0); PG8_STAGE(PG8_SA(1, 1), a1 + hstep, voffA);
;             PG8_WAIT_V(8); PG8_WAIT_L(0); PG8_BAR; PG8_MMA(0, 0, At, B0); PG8_MMA(0, 1, At, B1); PG8_BAR; PG8_SCHED;
;             PG8_LDA(At, 0, 1); PG8_STAGE(PG8_SB(0, 0), b2, voffB); PG8_STAGE(PG8_SB(0, 1), b2 + hstep, voffB); PG8_STAGE(PG8_SA(0, 0), a2, voffA);
;             PG8_WAIT_V(8); PG8_WAIT_L(0); PG8_BAR; PG8_MMA(1, 0, At, B0); PG8_MMA(1, 1, At, B1); PG8_BAR; PG8_SCHED;
;             PG8_LDB(B0, 1, 0); PG8_LDB(B1, 1, 1); PG8_SCHED; PG8_LDA(At, 1, 0); PG8_STAGE(PG8_SA(0, 1), a2 + hstep, voffA);
;             PG8_WAIT_V(8); PG8_WAIT_L(0); PG8_BAR; PG8_MMA(0, 0, At, B0); PG8_MMA(0, 1, At, B1); PG8_BAR; PG8_SCHED;
;             PG8_LDA(At, 1, 1); PG8_STAGE(PG8_SB(1, 0), b3, voffB); PG8_STAGE(PG8_SB(1, 1), b3 + hstep, voffB); PG8_STAGE(PG8_SA(1, 0), a3, voffA);
;             PG8_WAIT_V(8); PG8_WAIT_L(0); PG8_BAR; PG8_MMA(1, 0, At, B0); PG8_MMA(1, 1, At, B1); PG8_BAR; PG8_SCHED;
	s_setprio 1
	s_add_i32 s6, s9, s55
	v_lshl_add_u64 v[158:159], v[158:159], 0, s[26:27]
	s_mov_b32 m0, s6
	ds_read_b128 v[182:185], v165 offset:49152
	ds_read_b128 v[186:189], v165 offset:50176
	ds_read_b128 v[190:193], v165 offset:51200
	ds_read_b128 v[194:197], v165 offset:52224
	ds_read_b128 v[198:201], v165 offset:53248
	ds_read_b128 v[202:205], v165 offset:54272
	ds_read_b128 v[206:209], v165 offset:55296
	ds_read_b128 v[210:213], v165 offset:56320
	global_load_lds_dwordx4 v[158:159], off
	v_lshl_add_u64 v[158:159], v[214:215], 0, s[26:27]
	s_add_i32 m0, s6, 0x2000
	s_add_i32 s6, s33, s55
	global_load_lds_dwordx4 v[158:159], off
	v_lshl_add_u64 v[158:159], v[216:217], 0, s[26:27]
	s_mov_b32 m0, s6
	s_nop 0
	global_load_lds_dwordx4 v[158:159], off
	v_lshl_add_u64 v[158:159], v[218:219], 0, s[26:27]
	s_add_i32 m0, s6, 0x2000
	s_nop 0
	global_load_lds_dwordx4 v[158:159], off
	v_lshl_add_u64 v[158:159], v[220:221], 0, s[26:27]
	s_mov_b32 m0, s68
	s_nop 0
	global_load_lds_dwordx4 v[158:159], off
	v_lshl_add_u64 v[158:159], v[222:223], 0, s[26:27]
	s_mov_b32 m0, s69
	s_nop 0
	global_load_lds_dwordx4 v[158:159], off
	s_waitcnt vmcnt(8)
	s_waitcnt lgkmcnt(0)
	s_setprio 0
	s_barrier
	v_mfma_f32_16x16x32_bf16 v[76:79], v[56:59], v[182:185], v[76:79]
	v_mfma_f32_16x16x32_bf16 v[72:75], v[64:67], v[182:185], v[72:75]
	v_mfma_f32_16x16x32_bf16 v[48:51], v[56:59], v[190:193], v[48:51]
	v_mfma_f32_16x16x32_bf16 v[40:43], v[64:67], v[190:193], v[40:43]
	v_mfma_f32_16x16x32_bf16 v[28:31], v[56:59], v[198:201], v[28:31]
	v_mfma_f32_16x16x32_bf16 v[24:27], v[64:67], v[198:201], v[24:27]
	v_mfma_f32_16x16x32_bf16 v[12:15], v[56:59], v[206:209], v[12:15]
	v_mfma_f32_16x16x32_bf16 v[8:11], v[64:67], v[206:209], v[8:11]
	v_mfma_f32_16x16x32_bf16 v[76:79], v[60:63], v[186:189], v[76:79]
	v_mfma_f32_16x16x32_bf16 v[72:75], v[68:71], v[186:189], v[72:75]
	v_mfma_f32_16x16x32_bf16 v[48:51], v[60:63], v[194:197], v[48:51]
	v_mfma_f32_16x16x32_bf16 v[40:43], v[68:71], v[194:197], v[40:43]
	v_mfma_f32_16x16x32_bf16 v[28:31], v[60:63], v[202:205], v[28:31]
	v_mfma_f32_16x16x32_bf16 v[24:27], v[68:71], v[202:205], v[24:27]
	v_mfma_f32_16x16x32_bf16 v[12:15], v[60:63], v[210:213], v[12:15]
	v_mfma_f32_16x16x32_bf16 v[8:11], v[68:71], v[210:213], v[8:11]
	v_mfma_f32_16x16x32_bf16 v[44:47], v[166:169], v[182:185], v[44:47]
	v_mfma_f32_16x16x32_bf16 v[64:67], v[170:173], v[186:189], v[44:47]
	v_mfma_f32_16x16x32_bf16 v[44:47], v[174:177], v[182:185], v[52:55]
	v_mfma_f32_16x16x32_bf16 v[36:39], v[166:169], v[190:193], v[36:39]
	v_mfma_f32_16x16x32_bf16 v[32:35], v[174:177], v[190:193], v[32:35]
	v_mfma_f32_16x16x32_bf16 v[20:23], v[166:169], v[198:201], v[20:23]
	v_mfma_f32_16x16x32_bf16 v[16:19], v[174:177], v[198:201], v[16:19]
	v_mfma_f32_16x16x32_bf16 v[4:7], v[166:169], v[206:209], v[4:7]
	v_mfma_f32_16x16x32_bf16 v[0:3], v[174:177], v[206:209], v[0:3]
	v_mfma_f32_16x16x32_bf16 v[56:59], v[178:181], v[186:189], v[44:47]
	v_mfma_f32_16x16x32_bf16 v[36:39], v[170:173], v[194:197], v[36:39]
	v_mfma_f32_16x16x32_bf16 v[32:35], v[178:181], v[194:197], v[32:35]
	v_mfma_f32_16x16x32_bf16 v[20:23], v[170:173], v[202:205], v[20:23]
	v_mfma_f32_16x16x32_bf16 v[16:19], v[178:181], v[202:205], v[16:19]
	v_mfma_f32_16x16x32_bf16 v[4:7], v[170:173], v[210:213], v[4:7]
	v_mfma_f32_16x16x32_bf16 v[0:3], v[178:181], v[210:213], v[0:3]
	s_barrier
	s_setprio 1
	s_add_u32 s4, s4, 0x100
	s_addc_u32 s5, s5, 0
	s_add_u32 s0, s0, 0x100
	s_addc_u32 s1, s1, 0
	s_cmp_ge_i32 s8, s70
	s_mov_b32 s6, s8
	s_cbranch_scc1 .LBB0_1101
.LBB0_1100:
	ds_read_b128 v[44:47], v163
	ds_read_b128 v[52:55], v163 offset:1024
	ds_read_b128 v[60:63], v163 offset:2048
	ds_read_b128 v[68:71], v163 offset:3072
	ds_read_b128 v[166:169], v164
	ds_read_b128 v[170:173], v164 offset:1024
	ds_read_b128 v[174:177], v164 offset:2048
	ds_read_b128 v[178:181], v164 offset:3072
	s_add_i32 s8, s6, 2
	s_add_u32 s9, s4, 0x80
	s_addc_u32 s7, s5, 0
	s_cmp_eq_u32 s72, s6
	s_cselect_b32 s6, s48, s9
	s_cselect_b32 s7, s49, s7
	s_cselect_b32 s77, s51, s1
	s_cselect_b32 s76, s50, s0
	v_lshl_add_u64 v[158:159], s[4:5], 0, v[152:153]
	s_add_i32 m0, s63, 0xc000
	ds_read_b128 v[182:185], v165
	ds_read_b128 v[186:189], v165 offset:1024
	ds_read_b128 v[190:193], v165 offset:2048
	ds_read_b128 v[194:197], v165 offset:3072
	ds_read_b128 v[198:201], v165 offset:4096
	ds_read_b128 v[202:205], v165 offset:5120
	ds_read_b128 v[206:209], v165 offset:6144
	ds_read_b128 v[210:213], v165 offset:7168
	global_load_lds_dwordx4 v[158:159], off
	v_lshl_add_u64 v[158:159], s[4:5], 0, v[154:155]
	s_add_i32 m0, s63, 0xe000
	s_nop 0
	global_load_lds_dwordx4 v[158:159], off
	s_waitcnt vmcnt(8)
	s_waitcnt lgkmcnt(0)
	s_setprio 0
	s_barrier
; #define PG8_STAGE(bufoff, gbase, voff) do { _Pragma("unroll") for (int _i = 0; _i < 2; ++_i) \
;         __builtin_amdgcn_global_load_lds((const unsigned*)((const char*)(gbase) + (voff)[_i]), (PG8_LAS unsigned*)(lds + (bufoff) + ldsw + _i * 8192), 16, 0, 0); } while (0)
; #define PG8_LDA(dst, b, h) do { _Pragma("unroll") for (int m = 0; m < 4; ++m) _Pragma("unroll") for (int k = 0; k < 2; ++k) dst[m][k] = *(const PG8_LAS bf16x8*)(lds + PG8_SA(b, h) + aoff + m * 2048 + k * 1024); } while (0)
; #define PG8_LDB(dst, b, h) do { _Pragma("unroll") for (int n = 0; n < 2; ++n) _Pragma("unroll") for (int k = 0; k < 2; ++k) dst[n][k] = *(const PG8_LAS bf16x8*)(lds + PG8_SB(b, h) + boff + n * 2048 + k * 1024); } while (0)
; #define PG8_MMA(ai, bj, At, Bt) do { __builtin_amdgcn_s_setprio(1); _Pragma("unroll") for (int m = 0; m < 4; ++m) _Pragma("unroll") for (int n = 0; n < 2; ++n) _Pragma("unroll") for (int k = 0; k < 2; ++k) \
;         acc[ai][bj][m][n] = __builtin_amdgcn_mfma_f32_16x16x32_bf16(Bt[n][k], At[m][k], acc[ai][bj][m][n], 0, 0, 0); __builtin_amdgcn_s_setprio(0); } while (0)
; #define PG8_WAIT_V(n) asm volatile("s_waitcnt vmcnt(" #n ")" ::: "memory")
; #define PG8_WAIT_L(n) asm volatile("s_waitcnt lgkmcnt(" #n ")" ::: "memory")
; #define PG8_BAR __builtin_amdgcn_s_barrier()
; #define PG8_SCHED __builtin_amdgcn_sched_barrier(0)
; template <class Epi, class Sched, bool ALIGN_EPI = false, bool SP2 = false>
; __device__ __forceinline__ void gemm_phase(PG8_LAS unsigned char* lds, const Gemm g, const Sched& S, const Epi& E, const int wid) {
;     ...
;             if constexpr (SP2) {
;             PG8_LDB(B0, 0, 0); PG8_LDB(B1, 0, 1); PG8_SCHED; PG8_LDA(At, 0, 0); PG8_STAGE(PG8_SA(1, 1), a1 + hstep, voffA);
;             PG8_WAIT_V(8); PG8_WAIT_L(0); PG8_BAR; PG8_MMA(0, 0, At, B0); PG8_MMA(0, 1, At, B1); PG8_BAR; PG8_SCHED;
;             PG8_LDA(At, 0, 1); PG8_STAGE(PG8_SB(0, 0), b2, voffB); PG8_STAGE(PG8_SB(0, 1), b2 + hstep, voffB); PG8_STAGE(PG8_SA(0, 0), a2, voffA);
;             PG8_WAIT_V(8); PG8_WAIT_L(0); PG8_BAR; PG8_MMA(1, 0, At, B0); PG8_MMA(1, 1, At, B1); PG8_BAR; PG8_SCHED;
	v_mfma_f32_16x16x32_bf16 v[140:143], v[44:47], v[182:185], v[140:143]
	v_mfma_f32_16x16x32_bf16 v[136:139], v[60:63], v[182:185], v[136:139]
	v_mfma_f32_16x16x32_bf16 v[124:127], v[44:47], v[190:193], v[124:127]
	v_mfma_f32_16x16x32_bf16 v[120:123], v[60:63], v[190:193], v[120:123]
	v_mfma_f32_16x16x32_bf16 v[108:111], v[44:47], v[198:201], v[108:111]
	v_mfma_f32_16x16x32_bf16 v[104:107], v[60:63], v[198:201], v[104:107]
	v_mfma_f32_16x16x32_bf16 v[92:95], v[44:47], v[206:209], v[92:95]
	v_mfma_f32_16x16x32_bf16 v[88:91], v[60:63], v[206:209], v[88:91]
	v_mfma_f32_16x16x32_bf16 v[140:143], v[52:55], v[186:189], v[140:143]
	v_mfma_f32_16x16x32_bf16 v[136:139], v[68:71], v[186:189], v[136:139]
	v_mfma_f32_16x16x32_bf16 v[124:127], v[52:55], v[194:197], v[124:127]
	v_mfma_f32_16x16x32_bf16 v[120:123], v[68:71], v[194:197], v[120:123]
	v_mfma_f32_16x16x32_bf16 v[108:111], v[52:55], v[202:205], v[108:111]
	v_mfma_f32_16x16x32_bf16 v[104:107], v[68:71], v[202:205], v[104:107]
	v_mfma_f32_16x16x32_bf16 v[92:95], v[52:55], v[210:213], v[92:95]
	v_mfma_f32_16x16x32_bf16 v[88:91], v[68:71], v[210:213], v[88:91]
	v_mfma_f32_16x16x32_bf16 v[132:135], v[166:169], v[182:185], v[132:135]
	v_mfma_f32_16x16x32_bf16 v[128:131], v[174:177], v[182:185], v[128:131]
	v_mfma_f32_16x16x32_bf16 v[116:119], v[166:169], v[190:193], v[116:119]
	v_mfma_f32_16x16x32_bf16 v[112:115], v[174:177], v[190:193], v[112:115]
	v_mfma_f32_16x16x32_bf16 v[100:103], v[166:169], v[198:201], v[100:103]
	v_mfma_f32_16x16x32_bf16 v[96:99], v[174:177], v[198:201], v[96:99]
	v_mfma_f32_16x16x32_bf16 v[84:87], v[166:169], v[206:209], v[84:87]
	v_mfma_f32_16x16x32_bf16 v[80:83], v[174:177], v[206:209], v[80:83]
	v_mfma_f32_16x16x32_bf16 v[132:135], v[170:173], v[186:189], v[132:135]
	v_mfma_f32_16x16x32_bf16 v[128:131], v[178:181], v[186:189], v[128:131]
	v_mfma_f32_16x16x32_bf16 v[116:119], v[170:173], v[194:197], v[116:119]
	v_mfma_f32_16x16x32_bf16 v[112:115], v[178:181], v[194:197], v[112:115]
	v_mfma_f32_16x16x32_bf16 v[100:103], v[170:173], v[202:205], v[100:103]
	v_mfma_f32_16x16x32_bf16 v[96:99], v[178:181], v[202:205], v[96:99]
	v_mfma_f32_16x16x32_bf16 v[84:87], v[170:173], v[210:213], v[84:87]
	v_mfma_f32_16x16x32_bf16 v[80:83], v[178:181], v[210:213], v[80:83]
	s_barrier
	s_setprio 1
	s_add_i32 s9, s75, s55
	v_lshl_add_u64 v[158:159], s[76:77], 0, v[148:149]
	s_mov_b32 m0, s9
	ds_read_b128 v[182:185], v165 offset:16384
	ds_read_b128 v[186:189], v165 offset:17408
	ds_read_b128 v[190:193], v165 offset:18432
	ds_read_b128 v[194:197], v165 offset:19456
	ds_read_b128 v[198:201], v165 offset:20480
	ds_read_b128 v[202:205], v165 offset:21504
	ds_read_b128 v[206:209], v165 offset:22528
	ds_read_b128 v[210:213], v165 offset:23552
	global_load_lds_dwordx4 v[158:159], off
	s_add_i32 m0, s9, 0x2000
	v_lshl_add_u64 v[214:215], s[76:77], 0, v[144:145]
	s_add_u32 s76, s76, s12
	s_addc_u32 s77, s77, s13
	s_add_i32 s9, s78, s55
	global_load_lds_dwordx4 v[214:215], off
	v_lshl_add_u64 v[216:217], s[76:77], 0, v[148:149]
	s_mov_b32 m0, s9
	v_lshl_add_u64 v[218:219], s[76:77], 0, v[144:145]
	global_load_lds_dwordx4 v[216:217], off
	s_add_i32 m0, s9, 0x2000
	v_lshl_add_u64 v[220:221], s[6:7], 0, v[150:151]
	global_load_lds_dwordx4 v[218:219], off
	s_mov_b32 m0, s63
	v_lshl_add_u64 v[222:223], s[6:7], 0, v[146:147]
	global_load_lds_dwordx4 v[220:221], off
	s_mov_b32 m0, s64
	s_nop 0
	global_load_lds_dwordx4 v[222:223], off
	s_waitcnt vmcnt(8)
	s_waitcnt lgkmcnt(0)
	s_setprio 0
	s_barrier
	v_mfma_f32_16x16x32_bf16 v[76:79], v[44:47], v[182:185], v[76:79]
	v_mfma_f32_16x16x32_bf16 v[72:75], v[60:63], v[182:185], v[72:75]
	v_mfma_f32_16x16x32_bf16 v[48:51], v[44:47], v[190:193], v[48:51]
	v_mfma_f32_16x16x32_bf16 v[40:43], v[60:63], v[190:193], v[40:43]
	v_mfma_f32_16x16x32_bf16 v[28:31], v[44:47], v[198:201], v[28:31]
	v_mfma_f32_16x16x32_bf16 v[24:27], v[60:63], v[198:201], v[24:27]
	v_mfma_f32_16x16x32_bf16 v[12:15], v[44:47], v[206:209], v[12:15]
	v_mfma_f32_16x16x32_bf16 v[8:11], v[60:63], v[206:209], v[8:11]
	v_mfma_f32_16x16x32_bf16 v[76:79], v[52:55], v[186:189], v[76:79]
	v_mfma_f32_16x16x32_bf16 v[72:75], v[68:71], v[186:189], v[72:75]
	v_mfma_f32_16x16x32_bf16 v[48:51], v[52:55], v[194:197], v[48:51]
	v_mfma_f32_16x16x32_bf16 v[40:43], v[68:71], v[194:197], v[40:43]
	v_mfma_f32_16x16x32_bf16 v[28:31], v[52:55], v[202:205], v[28:31]
	v_mfma_f32_16x16x32_bf16 v[24:27], v[68:71], v[202:205], v[24:27]
	v_mfma_f32_16x16x32_bf16 v[12:15], v[52:55], v[210:213], v[12:15]
	v_mfma_f32_16x16x32_bf16 v[8:11], v[68:71], v[210:213], v[8:11]
	v_mfma_f32_16x16x32_bf16 v[36:39], v[166:169], v[190:193], v[36:39]
	v_mfma_f32_16x16x32_bf16 v[32:35], v[174:177], v[190:193], v[32:35]
	v_mfma_f32_16x16x32_bf16 v[20:23], v[166:169], v[198:201], v[20:23]
	v_mfma_f32_16x16x32_bf16 v[16:19], v[174:177], v[198:201], v[16:19]
	v_mfma_f32_16x16x32_bf16 v[4:7], v[166:169], v[206:209], v[4:7]
	v_mfma_f32_16x16x32_bf16 v[0:3], v[174:177], v[206:209], v[0:3]
	v_mfma_f32_16x16x32_bf16 v[44:47], v[166:169], v[182:185], v[64:67]
	v_mfma_f32_16x16x32_bf16 v[52:55], v[174:177], v[182:185], v[56:59]
	v_mfma_f32_16x16x32_bf16 v[36:39], v[170:173], v[194:197], v[36:39]
	v_mfma_f32_16x16x32_bf16 v[32:35], v[178:181], v[194:197], v[32:35]
	v_mfma_f32_16x16x32_bf16 v[20:23], v[170:173], v[202:205], v[20:23]
	v_mfma_f32_16x16x32_bf16 v[16:19], v[178:181], v[202:205], v[16:19]
	v_mfma_f32_16x16x32_bf16 v[4:7], v[170:173], v[210:213], v[4:7]
	v_mfma_f32_16x16x32_bf16 v[0:3], v[178:181], v[210:213], v[0:3]
	v_mfma_f32_16x16x32_bf16 v[44:47], v[170:173], v[186:189], v[44:47]
	v_mfma_f32_16x16x32_bf16 v[52:55], v[178:181], v[186:189], v[52:55]
	s_barrier
; #define PG8_STAGE(bufoff, gbase, voff) do { _Pragma("unroll") for (int _i = 0; _i < 2; ++_i) \
;         __builtin_amdgcn_global_load_lds((const unsigned*)((const char*)(gbase) + (voff)[_i]), (PG8_LAS unsigned*)(lds + (bufoff) + ldsw + _i * 8192), 16, 0, 0); } while (0)
; #define PG8_LDA(dst, b, h) do { _Pragma("unroll") for (int m = 0; m < 4; ++m) _Pragma("unroll") for (int k = 0; k < 2; ++k) dst[m][k] = *(const PG8_LAS bf16x8*)(lds + PG8_SA(b, h) + aoff + m * 2048 + k * 1024); } while (0)
; #define PG8_WAIT_V(n) asm volatile("s_waitcnt vmcnt(" #n ")" ::: "memory")
; #define PG8_WAIT_L(n) asm volatile("s_waitcnt lgkmcnt(" #n ")" ::: "memory")
; #define PG8_BAR __builtin_amdgcn_s_barrier()
; template <class Epi, class Sched, bool ALIGN_EPI = false, bool SP2 = false>
; __device__ __forceinline__ void gemm_phase(PG8_LAS unsigned char* lds, const Gemm g, const Sched& S, const Epi& E, const int wid) {
;     ...
;         for (int t = 0; t < nt; t += 2) {
;             const bool last = (t == nt - 2);
;             const char* a1 = cA + (size_t)(t + 1) * kstep;
;             const char* a2 = last ? nA : cA + (size_t)(t + 2) * kstep; const char* b2 = last ? nB : cB + (size_t)(t + 2) * kstep;
;             const char* a3 = a2 + kstep; const char* b3 = b2 + kstep;
;             if (last && has_next) S.a_ready(nxt);
;             if constexpr (SP2) {
;             PG8_LDB(B0, 0, 0); PG8_LDB(B1, 0, 1); PG8_SCHED; PG8_LDA(At, 0, 0); PG8_STAGE(PG8_SA(1, 1), a1 + hstep, voffA);
;             PG8_WAIT_V(8); PG8_WAIT_L(0); PG8_BAR; PG8_MMA(0, 0, At, B0); PG8_MMA(0, 1, At, B1); PG8_BAR; PG8_SCHED;
;             PG8_LDA(At, 0, 1); PG8_STAGE(PG8_SB(0, 0), b2, voffB); PG8_STAGE(PG8_SB(0, 1), b2 + hstep, voffB); PG8_STAGE(PG8_SA(0, 0), a2, voffA);
;             PG8_WAIT_V(8); PG8_WAIT_L(0); PG8_BAR; PG8_MMA(1, 0, At, B0); PG8_MMA(1, 1, At, B1); PG8_BAR; PG8_SCHED;
;             PG8_LDB(B0, 1, 0); PG8_LDB(B1, 1, 1); PG8_SCHED; PG8_LDA(At, 1, 0); PG8_STAGE(PG8_SA(0, 1), a2 + hstep, voffA);
;             PG8_WAIT_V(8); PG8_WAIT_L(0); PG8_BAR; PG8_MMA(0, 0, At, B0); PG8_MMA(0, 1, At, B1); PG8_BAR; PG8_SCHED;
;             PG8_LDA(At, 1, 1); PG8_STAGE(PG8_SB(1, 0), b3, voffB); PG8_STAGE(PG8_SB(1, 1), b3 + hstep, voffB); PG8_STAGE(PG8_SA(1, 0), a3, voffA);
;             PG8_WAIT_V(8); PG8_WAIT_L(0); PG8_BAR; PG8_MMA(1, 0, At, B0); PG8_MMA(1, 1, At, B1); PG8_BAR; PG8_SCHED;
	s_setprio 1
	s_add_i32 s9, 0, 0x18000
	s_add_i32 s33, 0, 0x1c000
	v_add_u32_e32 v68, s9, v162
	v_add_u32_e32 v178, s33, v162
	ds_read_b128 v[56:59], v68
	ds_read_b128 v[60:63], v68 offset:1024
	ds_read_b128 v[64:67], v68 offset:2048
	ds_read_b128 v[68:71], v68 offset:3072
	ds_read_b128 v[166:169], v178
	ds_read_b128 v[170:173], v178 offset:1024
	ds_read_b128 v[174:177], v178 offset:2048
	ds_read_b128 v[178:181], v178 offset:3072
	s_add_u32 s6, s6, s12
	s_addc_u32 s7, s7, s13
	s_mov_b32 m0, s65
	v_lshl_add_u64 v[224:225], s[6:7], 0, v[150:151]
	ds_read_b128 v[182:185], v165 offset:32768
	ds_read_b128 v[186:189], v165 offset:33792
	ds_read_b128 v[190:193], v165 offset:34816
	ds_read_b128 v[194:197], v165 offset:35840
	ds_read_b128 v[198:201], v165 offset:36864
	ds_read_b128 v[202:205], v165 offset:37888
	ds_read_b128 v[206:209], v165 offset:38912
	ds_read_b128 v[210:213], v165 offset:39936
	global_load_lds_dwordx4 v[224:225], off
	v_lshl_add_u64 v[224:225], s[6:7], 0, v[146:147]
	s_mov_b32 m0, s66
	s_nop 0
	global_load_lds_dwordx4 v[224:225], off
	s_waitcnt vmcnt(8)
	s_waitcnt lgkmcnt(0)
	s_setprio 0
	s_barrier
	v_mfma_f32_16x16x32_bf16 v[140:143], v[56:59], v[182:185], v[140:143]
	v_mfma_f32_16x16x32_bf16 v[136:139], v[64:67], v[182:185], v[136:139]
	v_mfma_f32_16x16x32_bf16 v[124:127], v[56:59], v[190:193], v[124:127]
	v_mfma_f32_16x16x32_bf16 v[120:123], v[64:67], v[190:193], v[120:123]
	v_mfma_f32_16x16x32_bf16 v[108:111], v[56:59], v[198:201], v[108:111]
	v_mfma_f32_16x16x32_bf16 v[104:107], v[64:67], v[198:201], v[104:107]
	v_mfma_f32_16x16x32_bf16 v[92:95], v[56:59], v[206:209], v[92:95]
	v_mfma_f32_16x16x32_bf16 v[88:91], v[64:67], v[206:209], v[88:91]
	v_mfma_f32_16x16x32_bf16 v[140:143], v[60:63], v[186:189], v[140:143]
	v_mfma_f32_16x16x32_bf16 v[136:139], v[68:71], v[186:189], v[136:139]
	v_mfma_f32_16x16x32_bf16 v[124:127], v[60:63], v[194:197], v[124:127]
	v_mfma_f32_16x16x32_bf16 v[120:123], v[68:71], v[194:197], v[120:123]
	v_mfma_f32_16x16x32_bf16 v[108:111], v[60:63], v[202:205], v[108:111]
	v_mfma_f32_16x16x32_bf16 v[104:107], v[68:71], v[202:205], v[104:107]
	v_mfma_f32_16x16x32_bf16 v[92:95], v[60:63], v[210:213], v[92:95]
	v_mfma_f32_16x16x32_bf16 v[88:91], v[68:71], v[210:213], v[88:91]
	v_mfma_f32_16x16x32_bf16 v[132:135], v[166:169], v[182:185], v[132:135]
	v_mfma_f32_16x16x32_bf16 v[128:131], v[174:177], v[182:185], v[128:131]
	v_mfma_f32_16x16x32_bf16 v[116:119], v[166:169], v[190:193], v[116:119]
	v_mfma_f32_16x16x32_bf16 v[112:115], v[174:177], v[190:193], v[112:115]
	v_mfma_f32_16x16x32_bf16 v[100:103], v[166:169], v[198:201], v[100:103]
	v_mfma_f32_16x16x32_bf16 v[96:99], v[174:177], v[198:201], v[96:99]
	v_mfma_f32_16x16x32_bf16 v[84:87], v[166:169], v[206:209], v[84:87]
	v_mfma_f32_16x16x32_bf16 v[80:83], v[174:177], v[206:209], v[80:83]
	v_mfma_f32_16x16x32_bf16 v[132:135], v[170:173], v[186:189], v[132:135]
	v_mfma_f32_16x16x32_bf16 v[128:131], v[178:181], v[186:189], v[128:131]
	v_mfma_f32_16x16x32_bf16 v[116:119], v[170:173], v[194:197], v[116:119]
	v_mfma_f32_16x16x32_bf16 v[112:115], v[178:181], v[194:197], v[112:115]
	v_mfma_f32_16x16x32_bf16 v[100:103], v[170:173], v[202:205], v[100:103]
	v_mfma_f32_16x16x32_bf16 v[96:99], v[178:181], v[202:205], v[96:99]
	v_mfma_f32_16x16x32_bf16 v[84:87], v[170:173], v[210:213], v[84:87]
	v_mfma_f32_16x16x32_bf16 v[80:83], v[178:181], v[210:213], v[80:83]
	s_barrier
	s_setprio 1
	s_add_i32 s6, s9, s55
	v_lshl_add_u64 v[158:159], v[158:159], 0, s[26:27]
	s_mov_b32 m0, s6
	ds_read_b128 v[182:185], v165 offset:49152
	ds_read_b128 v[186:189], v165 offset:50176
	ds_read_b128 v[190:193], v165 offset:51200
	ds_read_b128 v[194:197], v165 offset:52224
	ds_read_b128 v[198:201], v165 offset:53248
	ds_read_b128 v[202:205], v165 offset:54272
	ds_read_b128 v[206:209], v165 offset:55296
	ds_read_b128 v[210:213], v165 offset:56320
	global_load_lds_dwordx4 v[158:159], off
	v_lshl_add_u64 v[158:159], v[214:215], 0, s[26:27]
	s_add_i32 m0, s6, 0x2000
	s_add_i32 s6, s33, s55
	global_load_lds_dwordx4 v[158:159], off
	v_lshl_add_u64 v[158:159], v[216:217], 0, s[26:27]
	s_mov_b32 m0, s6
	s_nop 0
	global_load_lds_dwordx4 v[158:159], off
	v_lshl_add_u64 v[158:159], v[218:219], 0, s[26:27]
	s_add_i32 m0, s6, 0x2000
	s_nop 0
	global_load_lds_dwordx4 v[158:159], off
	v_lshl_add_u64 v[158:159], v[220:221], 0, s[26:27]
	s_mov_b32 m0, s68
	s_nop 0
	global_load_lds_dwordx4 v[158:159], off
	v_lshl_add_u64 v[158:159], v[222:223], 0, s[26:27]
	s_mov_b32 m0, s69
	s_nop 0
	global_load_lds_dwordx4 v[158:159], off
	s_waitcnt vmcnt(8)
	s_waitcnt lgkmcnt(0)
	s_setprio 0
	s_barrier
	v_mfma_f32_16x16x32_bf16 v[76:79], v[56:59], v[182:185], v[76:79]
	v_mfma_f32_16x16x32_bf16 v[72:75], v[64:67], v[182:185], v[72:75]
	v_mfma_f32_16x16x32_bf16 v[48:51], v[56:59], v[190:193], v[48:51]
	v_mfma_f32_16x16x32_bf16 v[40:43], v[64:67], v[190:193], v[40:43]
	v_mfma_f32_16x16x32_bf16 v[28:31], v[56:59], v[198:201], v[28:31]
	v_mfma_f32_16x16x32_bf16 v[24:27], v[64:67], v[198:201], v[24:27]
	v_mfma_f32_16x16x32_bf16 v[12:15], v[56:59], v[206:209], v[12:15]
	v_mfma_f32_16x16x32_bf16 v[8:11], v[64:67], v[206:209], v[8:11]
	v_mfma_f32_16x16x32_bf16 v[76:79], v[60:63], v[186:189], v[76:79]
	v_mfma_f32_16x16x32_bf16 v[72:75], v[68:71], v[186:189], v[72:75]
	v_mfma_f32_16x16x32_bf16 v[48:51], v[60:63], v[194:197], v[48:51]
	v_mfma_f32_16x16x32_bf16 v[40:43], v[68:71], v[194:197], v[40:43]
	v_mfma_f32_16x16x32_bf16 v[28:31], v[60:63], v[202:205], v[28:31]
	v_mfma_f32_16x16x32_bf16 v[24:27], v[68:71], v[202:205], v[24:27]
	v_mfma_f32_16x16x32_bf16 v[12:15], v[60:63], v[210:213], v[12:15]
	v_mfma_f32_16x16x32_bf16 v[8:11], v[68:71], v[210:213], v[8:11]
	v_mfma_f32_16x16x32_bf16 v[44:47], v[166:169], v[182:185], v[44:47]
	v_mfma_f32_16x16x32_bf16 v[64:67], v[170:173], v[186:189], v[44:47]
	v_mfma_f32_16x16x32_bf16 v[44:47], v[174:177], v[182:185], v[52:55]
	v_mfma_f32_16x16x32_bf16 v[36:39], v[166:169], v[190:193], v[36:39]
	v_mfma_f32_16x16x32_bf16 v[32:35], v[174:177], v[190:193], v[32:35]
	v_mfma_f32_16x16x32_bf16 v[20:23], v[166:169], v[198:201], v[20:23]
	v_mfma_f32_16x16x32_bf16 v[16:19], v[174:177], v[198:201], v[16:19]
	v_mfma_f32_16x16x32_bf16 v[4:7], v[166:169], v[206:209], v[4:7]
	v_mfma_f32_16x16x32_bf16 v[0:3], v[174:177], v[206:209], v[0:3]
	v_mfma_f32_16x16x32_bf16 v[56:59], v[178:181], v[186:189], v[44:47]
	v_mfma_f32_16x16x32_bf16 v[36:39], v[170:173], v[194:197], v[36:39]
	v_mfma_f32_16x16x32_bf16 v[32:35], v[178:181], v[194:197], v[32:35]
	v_mfma_f32_16x16x32_bf16 v[20:23], v[170:173], v[202:205], v[20:23]
	v_mfma_f32_16x16x32_bf16 v[16:19], v[178:181], v[202:205], v[16:19]
	v_mfma_f32_16x16x32_bf16 v[4:7], v[170:173], v[210:213], v[4:7]
	v_mfma_f32_16x16x32_bf16 v[0:3], v[178:181], v[210:213], v[0:3]
	s_barrier
	s_setprio 1
	s_add_u32 s4, s4, 0x100
	s_addc_u32 s5, s5, 0
	s_add_u32 s0, s0, 0x100
	s_addc_u32 s1, s1, 0
	s_cmp_ge_i32 s8, s70
	s_mov_b32 s6, s8
	s_cbranch_scc0 .LBB0_1100

; #define PG8_STAGE(bufoff, gbase, voff) do { _Pragma("unroll") for (int _i = 0; _i < 2; ++_i) \
;         __builtin_amdgcn_global_load_lds((const unsigned*)((const char*)(gbase) + (voff)[_i]), (PG8_LAS unsigned*)(lds + (bufoff) + ldsw + _i * 8192), 16, 0, 0); } while (0)
; #define PG8_LDA(dst, b, h) do { _Pragma("unroll") for (int m = 0; m < 4; ++m) _Pragma("unroll") for (int k = 0; k < 2; ++k) dst[m][k] = *(const PG8_LAS bf16x8*)(lds + PG8_SA(b, h) + aoff + m * 2048 + k * 1024); } while (0)
; #define PG8_LDB(dst, b, h) do { _Pragma("unroll") for (int n = 0; n < 2; ++n) _Pragma("unroll") for (int k = 0; k < 2; ++k) dst[n][k] = *(const PG8_LAS bf16x8*)(lds + PG8_SB(b, h) + boff + n * 2048 + k * 1024); } while (0)
; #define PG8_WAIT_V(n) asm volatile("s_waitcnt vmcnt(" #n ")" ::: "memory")
; #define PG8_WAIT_L(n) asm volatile("s_waitcnt lgkmcnt(" #n ")" ::: "memory")
; #define PG8_BAR __builtin_amdgcn_s_barrier()
; #define PG8_SCHED __builtin_amdgcn_sched_barrier(0)
; template <class Epi, class Sched, bool ALIGN_EPI = false, bool SP2 = false>
; __device__ __forceinline__ void gemm_phase(PG8_LAS unsigned char* lds, const Gemm g, const Sched& S, const Epi& E, const int wid) {
;     ...
;         const bool has_next = S.next(ui + 1, nxt);
;         const char* nA = has_next ? (const char*)g.A + (size_t)nxt.pm * tstep : cA; const char* nB = has_next ? (const char*)g.Bt + (size_t)nxt.pn * tstep : cB;
;         for (int t = 0; t < nt; t += 2) {
;             const bool last = (t == nt - 2);
;             const char* a1 = cA + (size_t)(t + 1) * kstep;
;             const char* a2 = last ? nA : cA + (size_t)(t + 2) * kstep; const char* b2 = last ? nB : cB + (size_t)(t + 2) * kstep;
;             const char* a3 = a2 + kstep; const char* b3 = b2 + kstep;
;             if (last && has_next) S.a_ready(nxt);
;             if constexpr (SP2) {
;             PG8_LDB(B0, 0, 0); PG8_LDB(B1, 0, 1); PG8_SCHED; PG8_LDA(At, 0, 0); PG8_STAGE(PG8_SA(1, 1), a1 + hstep, voffA);
;             PG8_WAIT_V(8); PG8_WAIT_L(0); PG8_BAR; PG8_MMA(0, 0, At, B0); PG8_MMA(0, 1, At, B1); PG8_BAR; PG8_SCHED;
;             PG8_LDA(At, 0, 1); PG8_STAGE(PG8_SB(0, 0), b2, voffB); PG8_STAGE(PG8_SB(0, 1), b2 + hstep, voffB); PG8_STAGE(PG8_SA(0, 0), a2, voffA);
;             PG8_WAIT_V(8); PG8_WAIT_L(0); PG8_BAR; PG8_MMA(1, 0, At, B0); PG8_MMA(1, 1, At, B1); PG8_BAR; PG8_SCHED;
.LBB0_1177:
	s_andn2_b64 vcc, exec, s[20:21]
	s_cbranch_vccnz .Lz_GMA
	s_add_u32 s26, s26, 0x80
	s_addc_u32 s27, s27, 0
	s_add_u32 s0, s28, 0x100
	s_addc_u32 s1, s29, 0
	s_mov_b32 s28, 0
	ds_read_b128 v[142:145], v149
	ds_read_b128 v[152:155], v149 offset:1024
	ds_read_b128 v[156:159], v149 offset:2048
	ds_read_b128 v[160:163], v149 offset:3072
	ds_read_b128 v[164:167], v150
	ds_read_b128 v[168:171], v150 offset:1024
	ds_read_b128 v[172:175], v150 offset:2048
	ds_read_b128 v[176:179], v150 offset:3072
	s_add_i32 s61, s28, 2
	s_add_u32 s33, s26, 0x80
	s_addc_u32 s29, s27, 0
	s_cmp_eq_u32 s53, s28
	s_cselect_b32 s28, s4, s33
	s_cselect_b32 s29, s5, s29
	s_cselect_b32 s63, s25, s1
	s_cselect_b32 s62, s24, s0
	v_lshl_add_u64 v[212:213], s[26:27], 0, v[136:137]
	s_add_i32 m0, s42, 0xc000
	ds_read_b128 v[180:183], v151
	ds_read_b128 v[184:187], v151 offset:1024
	ds_read_b128 v[188:191], v151 offset:2048
	ds_read_b128 v[192:195], v151 offset:3072
	ds_read_b128 v[196:199], v151 offset:4096
	ds_read_b128 v[200:203], v151 offset:5120
	ds_read_b128 v[204:207], v151 offset:6144
	ds_read_b128 v[208:211], v151 offset:7168
	global_load_lds_dwordx4 v[212:213], off
	v_lshl_add_u64 v[212:213], s[26:27], 0, v[138:139]
	s_add_i32 m0, s42, 0xe000
	s_nop 0
	global_load_lds_dwordx4 v[212:213], off
	s_waitcnt vmcnt(8)
	s_waitcnt lgkmcnt(0)
	s_setprio 0
	s_barrier
	v_mfma_f32_16x16x32_bf16 v[124:127], v[142:145], v[180:183], 0
	v_mfma_f32_16x16x32_bf16 v[120:123], v[156:159], v[180:183], 0
	v_mfma_f32_16x16x32_bf16 v[108:111], v[142:145], v[188:191], 0
	v_mfma_f32_16x16x32_bf16 v[104:107], v[156:159], v[188:191], 0
	v_mfma_f32_16x16x32_bf16 v[92:95], v[142:145], v[196:199], 0
	v_mfma_f32_16x16x32_bf16 v[88:91], v[156:159], v[196:199], 0
	v_mfma_f32_16x16x32_bf16 v[76:79], v[142:145], v[204:207], 0
	v_mfma_f32_16x16x32_bf16 v[72:75], v[156:159], v[204:207], 0
	v_mfma_f32_16x16x32_bf16 v[124:127], v[152:155], v[184:187], v[124:127]
	v_mfma_f32_16x16x32_bf16 v[120:123], v[160:163], v[184:187], v[120:123]
	v_mfma_f32_16x16x32_bf16 v[108:111], v[152:155], v[192:195], v[108:111]
	v_mfma_f32_16x16x32_bf16 v[104:107], v[160:163], v[192:195], v[104:107]
	v_mfma_f32_16x16x32_bf16 v[92:95], v[152:155], v[200:203], v[92:95]
	v_mfma_f32_16x16x32_bf16 v[88:91], v[160:163], v[200:203], v[88:91]
	v_mfma_f32_16x16x32_bf16 v[76:79], v[152:155], v[208:211], v[76:79]
	v_mfma_f32_16x16x32_bf16 v[72:75], v[160:163], v[208:211], v[72:75]
	v_mfma_f32_16x16x32_bf16 v[116:119], v[164:167], v[180:183], 0
	v_mfma_f32_16x16x32_bf16 v[112:115], v[172:175], v[180:183], 0
	v_mfma_f32_16x16x32_bf16 v[100:103], v[164:167], v[188:191], 0
	v_mfma_f32_16x16x32_bf16 v[96:99], v[172:175], v[188:191], 0
	v_mfma_f32_16x16x32_bf16 v[84:87], v[164:167], v[196:199], 0
	v_mfma_f32_16x16x32_bf16 v[80:83], v[172:175], v[196:199], 0
	v_mfma_f32_16x16x32_bf16 v[68:71], v[164:167], v[204:207], 0
	v_mfma_f32_16x16x32_bf16 v[64:67], v[172:175], v[204:207], 0
	v_mfma_f32_16x16x32_bf16 v[116:119], v[168:171], v[184:187], v[116:119]
	v_mfma_f32_16x16x32_bf16 v[112:115], v[176:179], v[184:187], v[112:115]
	v_mfma_f32_16x16x32_bf16 v[100:103], v[168:171], v[192:195], v[100:103]
	v_mfma_f32_16x16x32_bf16 v[96:99], v[176:179], v[192:195], v[96:99]
	v_mfma_f32_16x16x32_bf16 v[84:87], v[168:171], v[200:203], v[84:87]
	v_mfma_f32_16x16x32_bf16 v[80:83], v[176:179], v[200:203], v[80:83]
	v_mfma_f32_16x16x32_bf16 v[68:71], v[168:171], v[208:211], v[68:71]
	v_mfma_f32_16x16x32_bf16 v[64:67], v[176:179], v[208:211], v[64:67]
	s_barrier
	s_setprio 1
	s_add_i32 s33, s55, s34
	v_lshl_add_u64 v[212:213], s[62:63], 0, v[132:133]
	s_mov_b32 m0, s33
	ds_read_b128 v[180:183], v151 offset:16384
	ds_read_b128 v[184:187], v151 offset:17408
	ds_read_b128 v[188:191], v151 offset:18432
	ds_read_b128 v[192:195], v151 offset:19456
	ds_read_b128 v[196:199], v151 offset:20480
	ds_read_b128 v[200:203], v151 offset:21504
	ds_read_b128 v[204:207], v151 offset:22528
	ds_read_b128 v[208:211], v151 offset:23552
	global_load_lds_dwordx4 v[212:213], off
	s_add_i32 m0, s33, 0x2000
	v_lshl_add_u64 v[214:215], s[62:63], 0, v[128:129]
	s_add_u32 s62, s62, s8
	s_addc_u32 s63, s63, s9
	s_add_i32 s33, s56, s34
	global_load_lds_dwordx4 v[214:215], off
	v_lshl_add_u64 v[216:217], s[62:63], 0, v[132:133]
	s_mov_b32 m0, s33
	v_lshl_add_u64 v[218:219], s[62:63], 0, v[128:129]
	global_load_lds_dwordx4 v[216:217], off
	s_add_i32 m0, s33, 0x2000
	v_lshl_add_u64 v[220:221], s[28:29], 0, v[134:135]
	global_load_lds_dwordx4 v[218:219], off
	s_mov_b32 m0, s42
	v_lshl_add_u64 v[222:223], s[28:29], 0, v[130:131]
	global_load_lds_dwordx4 v[220:221], off
	s_mov_b32 m0, s43
	s_nop 0
	global_load_lds_dwordx4 v[222:223], off
	s_waitcnt vmcnt(8)
	s_waitcnt lgkmcnt(0)
	s_setprio 0
	s_barrier
; #define PG8_STAGE(bufoff, gbase, voff) do { _Pragma("unroll") for (int _i = 0; _i < 2; ++_i) \
;         __builtin_amdgcn_global_load_lds((const unsigned*)((const char*)(gbase) + (voff)[_i]), (PG8_LAS unsigned*)(lds + (bufoff) + ldsw + _i * 8192), 16, 0, 0); } while (0)
; #define PG8_LDA(dst, b, h) do { _Pragma("unroll") for (int m = 0; m < 4; ++m) _Pragma("unroll") for (int k = 0; k < 2; ++k) dst[m][k] = *(const PG8_LAS bf16x8*)(lds + PG8_SA(b, h) + aoff + m * 2048 + k * 1024); } while (0)
; #define PG8_LDB(dst, b, h) do { _Pragma("unroll") for (int n = 0; n < 2; ++n) _Pragma("unroll") for (int k = 0; k < 2; ++k) dst[n][k] = *(const PG8_LAS bf16x8*)(lds + PG8_SB(b, h) + boff + n * 2048 + k * 1024); } while (0)
; #define PG8_MMA(ai, bj, At, Bt) do { __builtin_amdgcn_s_setprio(1); _Pragma("unroll") for (int m = 0; m < 4; ++m) _Pragma("unroll") for (int n = 0; n < 2; ++n) _Pragma("unroll") for (int k = 0; k < 2; ++k) \
;         acc[ai][bj][m][n] = __builtin_amdgcn_mfma_f32_16x16x32_bf16(Bt[n][k], At[m][k], acc[ai][bj][m][n], 0, 0, 0); __builtin_amdgcn_s_setprio(0); } while (0)
; #define PG8_WAIT_V(n) asm volatile("s_waitcnt vmcnt(" #n ")" ::: "memory")
; #define PG8_WAIT_L(n) asm volatile("s_waitcnt lgkmcnt(" #n ")" ::: "memory")
; #define PG8_BAR __builtin_amdgcn_s_barrier()
; #define PG8_SCHED __builtin_amdgcn_sched_barrier(0)
; template <class Epi, class Sched, bool ALIGN_EPI = false, bool SP2 = false>
; __device__ __forceinline__ void gemm_phase(PG8_LAS unsigned char* lds, const Gemm g, const Sched& S, const Epi& E, const int wid) {
;     ...
;             PG8_WAIT_V(8); PG8_WAIT_L(0); PG8_BAR; PG8_MMA(0, 0, At, B0); PG8_MMA(0, 1, At, B1); PG8_BAR; PG8_SCHED;
;             PG8_LDA(At, 0, 1); PG8_STAGE(PG8_SB(0, 0), b2, voffB); PG8_STAGE(PG8_SB(0, 1), b2 + hstep, voffB); PG8_STAGE(PG8_SA(0, 0), a2, voffA);
;             PG8_WAIT_V(8); PG8_WAIT_L(0); PG8_BAR; PG8_MMA(1, 0, At, B0); PG8_MMA(1, 1, At, B1); PG8_BAR; PG8_SCHED;
;             PG8_LDB(B0, 1, 0); PG8_LDB(B1, 1, 1); PG8_SCHED; PG8_LDA(At, 1, 0); PG8_STAGE(PG8_SA(0, 1), a2 + hstep, voffA);
;             PG8_WAIT_V(8); PG8_WAIT_L(0); PG8_BAR; PG8_MMA(0, 0, At, B0); PG8_MMA(0, 1, At, B1); PG8_BAR; PG8_SCHED;
	v_mfma_f32_16x16x32_bf16 v[60:63], v[142:145], v[180:183], 0
	v_mfma_f32_16x16x32_bf16 v[56:59], v[156:159], v[180:183], 0
	v_mfma_f32_16x16x32_bf16 v[44:47], v[142:145], v[188:191], 0
	v_mfma_f32_16x16x32_bf16 v[40:43], v[156:159], v[188:191], 0
	v_mfma_f32_16x16x32_bf16 v[28:31], v[142:145], v[196:199], 0
	v_mfma_f32_16x16x32_bf16 v[24:27], v[156:159], v[196:199], 0
	v_mfma_f32_16x16x32_bf16 v[12:15], v[142:145], v[204:207], 0
	v_mfma_f32_16x16x32_bf16 v[8:11], v[156:159], v[204:207], 0
	v_mfma_f32_16x16x32_bf16 v[60:63], v[152:155], v[184:187], v[60:63]
	v_mfma_f32_16x16x32_bf16 v[56:59], v[160:163], v[184:187], v[56:59]
	v_mfma_f32_16x16x32_bf16 v[44:47], v[152:155], v[192:195], v[44:47]
	v_mfma_f32_16x16x32_bf16 v[40:43], v[160:163], v[192:195], v[40:43]
	v_mfma_f32_16x16x32_bf16 v[28:31], v[152:155], v[200:203], v[28:31]
	v_mfma_f32_16x16x32_bf16 v[24:27], v[160:163], v[200:203], v[24:27]
	v_mfma_f32_16x16x32_bf16 v[12:15], v[152:155], v[208:211], v[12:15]
	v_mfma_f32_16x16x32_bf16 v[8:11], v[160:163], v[208:211], v[8:11]
	v_mfma_f32_16x16x32_bf16 v[52:55], v[164:167], v[180:183], 0
	v_mfma_f32_16x16x32_bf16 v[48:51], v[172:175], v[180:183], 0
	v_mfma_f32_16x16x32_bf16 v[36:39], v[164:167], v[188:191], 0
	v_mfma_f32_16x16x32_bf16 v[32:35], v[172:175], v[188:191], 0
	v_mfma_f32_16x16x32_bf16 v[20:23], v[164:167], v[196:199], 0
	v_mfma_f32_16x16x32_bf16 v[16:19], v[172:175], v[196:199], 0
	v_mfma_f32_16x16x32_bf16 v[4:7], v[164:167], v[204:207], 0
	v_mfma_f32_16x16x32_bf16 v[0:3], v[172:175], v[204:207], 0
	v_mfma_f32_16x16x32_bf16 v[52:55], v[168:171], v[184:187], v[52:55]
	v_mfma_f32_16x16x32_bf16 v[48:51], v[176:179], v[184:187], v[48:51]
	v_mfma_f32_16x16x32_bf16 v[36:39], v[168:171], v[192:195], v[36:39]
	v_mfma_f32_16x16x32_bf16 v[32:35], v[176:179], v[192:195], v[32:35]
	v_mfma_f32_16x16x32_bf16 v[20:23], v[168:171], v[200:203], v[20:23]
	v_mfma_f32_16x16x32_bf16 v[16:19], v[176:179], v[200:203], v[16:19]
	v_mfma_f32_16x16x32_bf16 v[4:7], v[168:171], v[208:211], v[4:7]
	v_mfma_f32_16x16x32_bf16 v[0:3], v[176:179], v[208:211], v[0:3]
	s_barrier
	s_setprio 1
	s_add_i32 s33, 0, 0x18000
	s_add_i32 s62, 0, 0x1c000
	v_add_u32_e32 v160, s33, v148
	v_add_u32_e32 v176, s62, v148
	ds_read_b128 v[142:145], v160
	ds_read_b128 v[152:155], v160 offset:1024
	ds_read_b128 v[156:159], v160 offset:2048
	ds_read_b128 v[160:163], v160 offset:3072
	ds_read_b128 v[164:167], v176
	ds_read_b128 v[168:171], v176 offset:1024
	ds_read_b128 v[172:175], v176 offset:2048
	ds_read_b128 v[176:179], v176 offset:3072
	s_add_u32 s28, s28, s8
	s_addc_u32 s29, s29, s9
	s_mov_b32 m0, s44
	v_lshl_add_u64 v[224:225], s[28:29], 0, v[134:135]
	ds_read_b128 v[180:183], v151 offset:32768
	ds_read_b128 v[184:187], v151 offset:33792
	ds_read_b128 v[188:191], v151 offset:34816
	ds_read_b128 v[192:195], v151 offset:35840
	ds_read_b128 v[196:199], v151 offset:36864
	ds_read_b128 v[200:203], v151 offset:37888
	ds_read_b128 v[204:207], v151 offset:38912
	ds_read_b128 v[208:211], v151 offset:39936
	global_load_lds_dwordx4 v[224:225], off
	v_lshl_add_u64 v[224:225], s[28:29], 0, v[130:131]
	s_mov_b32 m0, s45
	s_nop 0
	global_load_lds_dwordx4 v[224:225], off
	s_waitcnt vmcnt(8)
	s_waitcnt lgkmcnt(0)
	s_setprio 0
	s_barrier
	v_mfma_f32_16x16x32_bf16 v[124:127], v[142:145], v[180:183], v[124:127]
	v_mfma_f32_16x16x32_bf16 v[120:123], v[156:159], v[180:183], v[120:123]
	v_mfma_f32_16x16x32_bf16 v[108:111], v[142:145], v[188:191], v[108:111]
	v_mfma_f32_16x16x32_bf16 v[104:107], v[156:159], v[188:191], v[104:107]
	v_mfma_f32_16x16x32_bf16 v[92:95], v[142:145], v[196:199], v[92:95]
	v_mfma_f32_16x16x32_bf16 v[88:91], v[156:159], v[196:199], v[88:91]
	v_mfma_f32_16x16x32_bf16 v[76:79], v[142:145], v[204:207], v[76:79]
	v_mfma_f32_16x16x32_bf16 v[72:75], v[156:159], v[204:207], v[72:75]
	v_mfma_f32_16x16x32_bf16 v[124:127], v[152:155], v[184:187], v[124:127]
	v_mfma_f32_16x16x32_bf16 v[120:123], v[160:163], v[184:187], v[120:123]
	v_mfma_f32_16x16x32_bf16 v[108:111], v[152:155], v[192:195], v[108:111]
	v_mfma_f32_16x16x32_bf16 v[104:107], v[160:163], v[192:195], v[104:107]
	v_mfma_f32_16x16x32_bf16 v[92:95], v[152:155], v[200:203], v[92:95]
	v_mfma_f32_16x16x32_bf16 v[88:91], v[160:163], v[200:203], v[88:91]
	v_mfma_f32_16x16x32_bf16 v[76:79], v[152:155], v[208:211], v[76:79]
	v_mfma_f32_16x16x32_bf16 v[72:75], v[160:163], v[208:211], v[72:75]
	v_mfma_f32_16x16x32_bf16 v[116:119], v[164:167], v[180:183], v[116:119]
	v_mfma_f32_16x16x32_bf16 v[112:115], v[172:175], v[180:183], v[112:115]
	v_mfma_f32_16x16x32_bf16 v[100:103], v[164:167], v[188:191], v[100:103]
	v_mfma_f32_16x16x32_bf16 v[96:99], v[172:175], v[188:191], v[96:99]
	v_mfma_f32_16x16x32_bf16 v[84:87], v[164:167], v[196:199], v[84:87]
	v_mfma_f32_16x16x32_bf16 v[80:83], v[172:175], v[196:199], v[80:83]
	v_mfma_f32_16x16x32_bf16 v[68:71], v[164:167], v[204:207], v[68:71]
	v_mfma_f32_16x16x32_bf16 v[64:67], v[172:175], v[204:207], v[64:67]
	v_mfma_f32_16x16x32_bf16 v[116:119], v[168:171], v[184:187], v[116:119]
	v_mfma_f32_16x16x32_bf16 v[112:115], v[176:179], v[184:187], v[112:115]
	v_mfma_f32_16x16x32_bf16 v[100:103], v[168:171], v[192:195], v[100:103]
	v_mfma_f32_16x16x32_bf16 v[96:99], v[176:179], v[192:195], v[96:99]
	v_mfma_f32_16x16x32_bf16 v[84:87], v[168:171], v[200:203], v[84:87]
	v_mfma_f32_16x16x32_bf16 v[80:83], v[176:179], v[200:203], v[80:83]
	v_mfma_f32_16x16x32_bf16 v[68:71], v[168:171], v[208:211], v[68:71]
	v_mfma_f32_16x16x32_bf16 v[64:67], v[176:179], v[208:211], v[64:67]
	s_barrier
; #define PG8_STAGE(bufoff, gbase, voff) do { _Pragma("unroll") for (int _i = 0; _i < 2; ++_i) \
;         __builtin_amdgcn_global_load_lds((const unsigned*)((const char*)(gbase) + (voff)[_i]), (PG8_LAS unsigned*)(lds + (bufoff) + ldsw + _i * 8192), 16, 0, 0); } while (0)
; #define PG8_LDA(dst, b, h) do { _Pragma("unroll") for (int m = 0; m < 4; ++m) _Pragma("unroll") for (int k = 0; k < 2; ++k) dst[m][k] = *(const PG8_LAS bf16x8*)(lds + PG8_SA(b, h) + aoff + m * 2048 + k * 1024); } while (0)
; #define PG8_WAIT_V(n) asm volatile("s_waitcnt vmcnt(" #n ")" ::: "memory")
; #define PG8_WAIT_L(n) asm volatile("s_waitcnt lgkmcnt(" #n ")" ::: "memory")
; #define PG8_BAR __builtin_amdgcn_s_barrier()
; template <class Epi, class Sched, bool ALIGN_EPI = false, bool SP2 = false>
; __device__ __forceinline__ void gemm_phase(PG8_LAS unsigned char* lds, const Gemm g, const Sched& S, const Epi& E, const int wid) {
;     ...
;         for (int t = 0; t < nt; t += 2) {
;             const bool last = (t == nt - 2);
;             const char* a1 = cA + (size_t)(t + 1) * kstep;
;             const char* a2 = last ? nA : cA + (size_t)(t + 2) * kstep; const char* b2 = last ? nB : cB + (size_t)(t + 2) * kstep;
;             const char* a3 = a2 + kstep; const char* b3 = b2 + kstep;
;             if (last && has_next) S.a_ready(nxt);
;             if constexpr (SP2) {
;             PG8_LDB(B0, 0, 0); PG8_LDB(B1, 0, 1); PG8_SCHED; PG8_LDA(At, 0, 0); PG8_STAGE(PG8_SA(1, 1), a1 + hstep, voffA);
;             PG8_WAIT_V(8); PG8_WAIT_L(0); PG8_BAR; PG8_MMA(0, 0, At, B0); PG8_MMA(0, 1, At, B1); PG8_BAR; PG8_SCHED;
;             PG8_LDA(At, 0, 1); PG8_STAGE(PG8_SB(0, 0), b2, voffB); PG8_STAGE(PG8_SB(0, 1), b2 + hstep, voffB); PG8_STAGE(PG8_SA(0, 0), a2, voffA);
;             PG8_WAIT_V(8); PG8_WAIT_L(0); PG8_BAR; PG8_MMA(1, 0, At, B0); PG8_MMA(1, 1, At, B1); PG8_BAR; PG8_SCHED;
;             PG8_LDB(B0, 1, 0); PG8_LDB(B1, 1, 1); PG8_SCHED; PG8_LDA(At, 1, 0); PG8_STAGE(PG8_SA(0, 1), a2 + hstep, voffA);
;             PG8_WAIT_V(8); PG8_WAIT_L(0); PG8_BAR; PG8_MMA(0, 0, At, B0); PG8_MMA(0, 1, At, B1); PG8_BAR; PG8_SCHED;
;             PG8_LDA(At, 1, 1); PG8_STAGE(PG8_SB(1, 0), b3, voffB); PG8_STAGE(PG8_SB(1, 1), b3 + hstep, voffB); PG8_STAGE(PG8_SA(1, 0), a3, voffA);
;             PG8_WAIT_V(8); PG8_WAIT_L(0); PG8_BAR; PG8_MMA(1, 0, At, B0); PG8_MMA(1, 1, At, B1); PG8_BAR; PG8_SCHED;
	s_setprio 1
	s_add_i32 s28, s33, s34
	v_lshl_add_u64 v[212:213], v[212:213], 0, s[18:19]
	s_mov_b32 m0, s28
	ds_read_b128 v[180:183], v151 offset:49152
	ds_read_b128 v[184:187], v151 offset:50176
	ds_read_b128 v[188:191], v151 offset:51200
	ds_read_b128 v[192:195], v151 offset:52224
	ds_read_b128 v[196:199], v151 offset:53248
	ds_read_b128 v[200:203], v151 offset:54272
	ds_read_b128 v[204:207], v151 offset:55296
	ds_read_b128 v[208:211], v151 offset:56320
	global_load_lds_dwordx4 v[212:213], off
	v_lshl_add_u64 v[212:213], v[214:215], 0, s[18:19]
	s_add_i32 m0, s28, 0x2000
	s_add_i32 s28, s62, s34
	global_load_lds_dwordx4 v[212:213], off
	v_lshl_add_u64 v[212:213], v[216:217], 0, s[18:19]
	s_mov_b32 m0, s28
	s_nop 0
	global_load_lds_dwordx4 v[212:213], off
	v_lshl_add_u64 v[212:213], v[218:219], 0, s[18:19]
	s_add_i32 m0, s28, 0x2000
	s_nop 0
	global_load_lds_dwordx4 v[212:213], off
	v_lshl_add_u64 v[212:213], v[220:221], 0, s[18:19]
	s_mov_b32 m0, s47
	s_nop 0
	global_load_lds_dwordx4 v[212:213], off
	v_lshl_add_u64 v[212:213], v[222:223], 0, s[18:19]
	s_mov_b32 m0, s49
	s_nop 0
	global_load_lds_dwordx4 v[212:213], off
	s_waitcnt vmcnt(8)
	s_waitcnt lgkmcnt(0)
	s_setprio 0
	s_barrier
	v_mfma_f32_16x16x32_bf16 v[60:63], v[142:145], v[180:183], v[60:63]
	v_mfma_f32_16x16x32_bf16 v[56:59], v[156:159], v[180:183], v[56:59]
	v_mfma_f32_16x16x32_bf16 v[44:47], v[142:145], v[188:191], v[44:47]
	v_mfma_f32_16x16x32_bf16 v[40:43], v[156:159], v[188:191], v[40:43]
	v_mfma_f32_16x16x32_bf16 v[28:31], v[142:145], v[196:199], v[28:31]
	v_mfma_f32_16x16x32_bf16 v[24:27], v[156:159], v[196:199], v[24:27]
	v_mfma_f32_16x16x32_bf16 v[12:15], v[142:145], v[204:207], v[12:15]
	v_mfma_f32_16x16x32_bf16 v[8:11], v[156:159], v[204:207], v[8:11]
	v_mfma_f32_16x16x32_bf16 v[60:63], v[152:155], v[184:187], v[60:63]
	v_mfma_f32_16x16x32_bf16 v[56:59], v[160:163], v[184:187], v[56:59]
	v_mfma_f32_16x16x32_bf16 v[44:47], v[152:155], v[192:195], v[44:47]
	v_mfma_f32_16x16x32_bf16 v[40:43], v[160:163], v[192:195], v[40:43]
	v_mfma_f32_16x16x32_bf16 v[28:31], v[152:155], v[200:203], v[28:31]
	v_mfma_f32_16x16x32_bf16 v[24:27], v[160:163], v[200:203], v[24:27]
	v_mfma_f32_16x16x32_bf16 v[12:15], v[152:155], v[208:211], v[12:15]
	v_mfma_f32_16x16x32_bf16 v[8:11], v[160:163], v[208:211], v[8:11]
	v_mfma_f32_16x16x32_bf16 v[52:55], v[164:167], v[180:183], v[52:55]
	v_mfma_f32_16x16x32_bf16 v[48:51], v[172:175], v[180:183], v[48:51]
	v_mfma_f32_16x16x32_bf16 v[36:39], v[164:167], v[188:191], v[36:39]
	v_mfma_f32_16x16x32_bf16 v[32:35], v[172:175], v[188:191], v[32:35]
	v_mfma_f32_16x16x32_bf16 v[20:23], v[164:167], v[196:199], v[20:23]
	v_mfma_f32_16x16x32_bf16 v[16:19], v[172:175], v[196:199], v[16:19]
	v_mfma_f32_16x16x32_bf16 v[4:7], v[164:167], v[204:207], v[4:7]
	v_mfma_f32_16x16x32_bf16 v[0:3], v[172:175], v[204:207], v[0:3]
	v_mfma_f32_16x16x32_bf16 v[52:55], v[168:171], v[184:187], v[52:55]
	v_mfma_f32_16x16x32_bf16 v[48:51], v[176:179], v[184:187], v[48:51]
	v_mfma_f32_16x16x32_bf16 v[36:39], v[168:171], v[192:195], v[36:39]
	v_mfma_f32_16x16x32_bf16 v[32:35], v[176:179], v[192:195], v[32:35]
	v_mfma_f32_16x16x32_bf16 v[20:23], v[168:171], v[200:203], v[20:23]
	v_mfma_f32_16x16x32_bf16 v[16:19], v[176:179], v[200:203], v[16:19]
	v_mfma_f32_16x16x32_bf16 v[4:7], v[168:171], v[208:211], v[4:7]
	v_mfma_f32_16x16x32_bf16 v[0:3], v[176:179], v[208:211], v[0:3]
	s_barrier
	s_setprio 1
	s_add_u32 s26, s26, 0x100
	s_addc_u32 s27, s27, 0
	s_add_u32 s0, s0, 0x100
	s_addc_u32 s1, s1, 0
	s_cmp_ge_i32 s61, s50
	s_mov_b32 s28, s61
	s_cbranch_scc1 .LBB0_1180
.LBB0_1179:
	ds_read_b128 v[142:145], v149
	ds_read_b128 v[152:155], v149 offset:1024
	ds_read_b128 v[156:159], v149 offset:2048
	ds_read_b128 v[160:163], v149 offset:3072
	ds_read_b128 v[164:167], v150
	ds_read_b128 v[168:171], v150 offset:1024
	ds_read_b128 v[172:175], v150 offset:2048
	ds_read_b128 v[176:179], v150 offset:3072
	s_add_i32 s61, s28, 2
	s_add_u32 s33, s26, 0x80
	s_addc_u32 s29, s27, 0
	s_cmp_eq_u32 s53, s28
	s_cselect_b32 s28, s4, s33
	s_cselect_b32 s29, s5, s29
	s_cselect_b32 s63, s25, s1
	s_cselect_b32 s62, s24, s0
	v_lshl_add_u64 v[212:213], s[26:27], 0, v[136:137]
	s_add_i32 m0, s42, 0xc000
	ds_read_b128 v[180:183], v151
	ds_read_b128 v[184:187], v151 offset:1024
	ds_read_b128 v[188:191], v151 offset:2048
	ds_read_b128 v[192:195], v151 offset:3072
	ds_read_b128 v[196:199], v151 offset:4096
	ds_read_b128 v[200:203], v151 offset:5120
	ds_read_b128 v[204:207], v151 offset:6144
	ds_read_b128 v[208:211], v151 offset:7168
	global_load_lds_dwordx4 v[212:213], off
	v_lshl_add_u64 v[212:213], s[26:27], 0, v[138:139]
	s_add_i32 m0, s42, 0xe000
	s_nop 0
	global_load_lds_dwordx4 v[212:213], off
	s_waitcnt vmcnt(8)
	s_waitcnt lgkmcnt(0)
	s_setprio 0
	s_barrier
; #define PG8_STAGE(bufoff, gbase, voff) do { _Pragma("unroll") for (int _i = 0; _i < 2; ++_i) \
;         __builtin_amdgcn_global_load_lds((const unsigned*)((const char*)(gbase) + (voff)[_i]), (PG8_LAS unsigned*)(lds + (bufoff) + ldsw + _i * 8192), 16, 0, 0); } while (0)
; #define PG8_LDA(dst, b, h) do { _Pragma("unroll") for (int m = 0; m < 4; ++m) _Pragma("unroll") for (int k = 0; k < 2; ++k) dst[m][k] = *(const PG8_LAS bf16x8*)(lds + PG8_SA(b, h) + aoff + m * 2048 + k * 1024); } while (0)
; #define PG8_LDB(dst, b, h) do { _Pragma("unroll") for (int n = 0; n < 2; ++n) _Pragma("unroll") for (int k = 0; k < 2; ++k) dst[n][k] = *(const PG8_LAS bf16x8*)(lds + PG8_SB(b, h) + boff + n * 2048 + k * 1024); } while (0)
; #define PG8_MMA(ai, bj, At, Bt) do { __builtin_amdgcn_s_setprio(1); _Pragma("unroll") for (int m = 0; m < 4; ++m) _Pragma("unroll") for (int n = 0; n < 2; ++n) _Pragma("unroll") for (int k = 0; k < 2; ++k) \
;         acc[ai][bj][m][n] = __builtin_amdgcn_mfma_f32_16x16x32_bf16(Bt[n][k], At[m][k], acc[ai][bj][m][n], 0, 0, 0); __builtin_amdgcn_s_setprio(0); } while (0)
; #define PG8_BAR __builtin_amdgcn_s_barrier()
; template <class Epi, class Sched, bool ALIGN_EPI = false, bool SP2 = false>
; __device__ __forceinline__ void gemm_phase(PG8_LAS unsigned char* lds, const Gemm g, const Sched& S, const Epi& E, const int wid) {
;     ...
;             PG8_LDB(B0, 0, 0); PG8_LDB(B1, 0, 1); PG8_SCHED; PG8_LDA(At, 0, 0); PG8_STAGE(PG8_SA(1, 1), a1 + hstep, voffA);
;             PG8_WAIT_V(8); PG8_WAIT_L(0); PG8_BAR; PG8_MMA(0, 0, At, B0); PG8_MMA(0, 1, At, B1); PG8_BAR; PG8_SCHED;
;             PG8_LDA(At, 0, 1); PG8_STAGE(PG8_SB(0, 0), b2, voffB); PG8_STAGE(PG8_SB(0, 1), b2 + hstep, voffB); PG8_STAGE(PG8_SA(0, 0), a2, voffA);
;             PG8_WAIT_V(8); PG8_WAIT_L(0); PG8_BAR; PG8_MMA(1, 0, At, B0); PG8_MMA(1, 1, At, B1); PG8_BAR; PG8_SCHED;
;             PG8_LDB(B0, 1, 0); PG8_LDB(B1, 1, 1); PG8_SCHED; PG8_LDA(At, 1, 0); PG8_STAGE(PG8_SA(0, 1), a2 + hstep, voffA);
;             PG8_WAIT_V(8); PG8_WAIT_L(0); PG8_BAR; PG8_MMA(0, 0, At, B0); PG8_MMA(0, 1, At, B1); PG8_BAR; PG8_SCHED;
;             PG8_LDA(At, 1, 1); PG8_STAGE(PG8_SB(1, 0), b3, voffB); PG8_STAGE(PG8_SB(1, 1), b3 + hstep, voffB); PG8_STAGE(PG8_SA(1, 0), a3, voffA);
;             PG8_WAIT_V(8); PG8_WAIT_L(0); PG8_BAR; PG8_MMA(1, 0, At, B0); PG8_MMA(1, 1, At, B1); PG8_BAR; PG8_SCHED;
	v_mfma_f32_16x16x32_bf16 v[124:127], v[142:145], v[180:183], v[124:127]
	v_mfma_f32_16x16x32_bf16 v[120:123], v[156:159], v[180:183], v[120:123]
	v_mfma_f32_16x16x32_bf16 v[108:111], v[142:145], v[188:191], v[108:111]
	v_mfma_f32_16x16x32_bf16 v[104:107], v[156:159], v[188:191], v[104:107]
	v_mfma_f32_16x16x32_bf16 v[92:95], v[142:145], v[196:199], v[92:95]
	v_mfma_f32_16x16x32_bf16 v[88:91], v[156:159], v[196:199], v[88:91]
	v_mfma_f32_16x16x32_bf16 v[76:79], v[142:145], v[204:207], v[76:79]
	v_mfma_f32_16x16x32_bf16 v[72:75], v[156:159], v[204:207], v[72:75]
	v_mfma_f32_16x16x32_bf16 v[124:127], v[152:155], v[184:187], v[124:127]
	v_mfma_f32_16x16x32_bf16 v[120:123], v[160:163], v[184:187], v[120:123]
	v_mfma_f32_16x16x32_bf16 v[108:111], v[152:155], v[192:195], v[108:111]
	v_mfma_f32_16x16x32_bf16 v[104:107], v[160:163], v[192:195], v[104:107]
	v_mfma_f32_16x16x32_bf16 v[92:95], v[152:155], v[200:203], v[92:95]
	v_mfma_f32_16x16x32_bf16 v[88:91], v[160:163], v[200:203], v[88:91]
	v_mfma_f32_16x16x32_bf16 v[76:79], v[152:155], v[208:211], v[76:79]
	v_mfma_f32_16x16x32_bf16 v[72:75], v[160:163], v[208:211], v[72:75]
	v_mfma_f32_16x16x32_bf16 v[116:119], v[164:167], v[180:183], v[116:119]
	v_mfma_f32_16x16x32_bf16 v[112:115], v[172:175], v[180:183], v[112:115]
	v_mfma_f32_16x16x32_bf16 v[100:103], v[164:167], v[188:191], v[100:103]
	v_mfma_f32_16x16x32_bf16 v[96:99], v[172:175], v[188:191], v[96:99]
	v_mfma_f32_16x16x32_bf16 v[84:87], v[164:167], v[196:199], v[84:87]
	v_mfma_f32_16x16x32_bf16 v[80:83], v[172:175], v[196:199], v[80:83]
	v_mfma_f32_16x16x32_bf16 v[68:71], v[164:167], v[204:207], v[68:71]
	v_mfma_f32_16x16x32_bf16 v[64:67], v[172:175], v[204:207], v[64:67]
	v_mfma_f32_16x16x32_bf16 v[116:119], v[168:171], v[184:187], v[116:119]
	v_mfma_f32_16x16x32_bf16 v[112:115], v[176:179], v[184:187], v[112:115]
	v_mfma_f32_16x16x32_bf16 v[100:103], v[168:171], v[192:195], v[100:103]
	v_mfma_f32_16x16x32_bf16 v[96:99], v[176:179], v[192:195], v[96:99]
	v_mfma_f32_16x16x32_bf16 v[84:87], v[168:171], v[200:203], v[84:87]
	v_mfma_f32_16x16x32_bf16 v[80:83], v[176:179], v[200:203], v[80:83]
	v_mfma_f32_16x16x32_bf16 v[68:71], v[168:171], v[208:211], v[68:71]
	v_mfma_f32_16x16x32_bf16 v[64:67], v[176:179], v[208:211], v[64:67]
	s_barrier
	s_setprio 1
	s_add_i32 s33, s55, s34
	v_lshl_add_u64 v[212:213], s[62:63], 0, v[132:133]
	s_mov_b32 m0, s33
	ds_read_b128 v[180:183], v151 offset:16384
	ds_read_b128 v[184:187], v151 offset:17408
	ds_read_b128 v[188:191], v151 offset:18432
	ds_read_b128 v[192:195], v151 offset:19456
	ds_read_b128 v[196:199], v151 offset:20480
	ds_read_b128 v[200:203], v151 offset:21504
	ds_read_b128 v[204:207], v151 offset:22528
	ds_read_b128 v[208:211], v151 offset:23552
	global_load_lds_dwordx4 v[212:213], off
	s_add_i32 m0, s33, 0x2000
	v_lshl_add_u64 v[214:215], s[62:63], 0, v[128:129]
	s_add_u32 s62, s62, s8
	s_addc_u32 s63, s63, s9
	s_add_i32 s33, s56, s34
	global_load_lds_dwordx4 v[214:215], off
	v_lshl_add_u64 v[216:217], s[62:63], 0, v[132:133]
	s_mov_b32 m0, s33
	v_lshl_add_u64 v[218:219], s[62:63], 0, v[128:129]
	global_load_lds_dwordx4 v[216:217], off
	s_add_i32 m0, s33, 0x2000
	v_lshl_add_u64 v[220:221], s[28:29], 0, v[134:135]
	global_load_lds_dwordx4 v[218:219], off
	s_mov_b32 m0, s42
	v_lshl_add_u64 v[222:223], s[28:29], 0, v[130:131]
	global_load_lds_dwordx4 v[220:221], off
	s_mov_b32 m0, s43
	s_nop 0
	global_load_lds_dwordx4 v[222:223], off
	s_waitcnt vmcnt(8)
	s_waitcnt lgkmcnt(0)
	s_setprio 0
	s_barrier
	v_mfma_f32_16x16x32_bf16 v[60:63], v[142:145], v[180:183], v[60:63]
	v_mfma_f32_16x16x32_bf16 v[56:59], v[156:159], v[180:183], v[56:59]
	v_mfma_f32_16x16x32_bf16 v[44:47], v[142:145], v[188:191], v[44:47]
	v_mfma_f32_16x16x32_bf16 v[40:43], v[156:159], v[188:191], v[40:43]
	v_mfma_f32_16x16x32_bf16 v[28:31], v[142:145], v[196:199], v[28:31]
	v_mfma_f32_16x16x32_bf16 v[24:27], v[156:159], v[196:199], v[24:27]
	v_mfma_f32_16x16x32_bf16 v[12:15], v[142:145], v[204:207], v[12:15]
	v_mfma_f32_16x16x32_bf16 v[8:11], v[156:159], v[204:207], v[8:11]
	v_mfma_f32_16x16x32_bf16 v[60:63], v[152:155], v[184:187], v[60:63]
	v_mfma_f32_16x16x32_bf16 v[56:59], v[160:163], v[184:187], v[56:59]
	v_mfma_f32_16x16x32_bf16 v[44:47], v[152:155], v[192:195], v[44:47]
	v_mfma_f32_16x16x32_bf16 v[40:43], v[160:163], v[192:195], v[40:43]
	v_mfma_f32_16x16x32_bf16 v[28:31], v[152:155], v[200:203], v[28:31]
	v_mfma_f32_16x16x32_bf16 v[24:27], v[160:163], v[200:203], v[24:27]
	v_mfma_f32_16x16x32_bf16 v[12:15], v[152:155], v[208:211], v[12:15]
	v_mfma_f32_16x16x32_bf16 v[8:11], v[160:163], v[208:211], v[8:11]
	v_mfma_f32_16x16x32_bf16 v[52:55], v[164:167], v[180:183], v[52:55]
	v_mfma_f32_16x16x32_bf16 v[48:51], v[172:175], v[180:183], v[48:51]
	v_mfma_f32_16x16x32_bf16 v[36:39], v[164:167], v[188:191], v[36:39]
	v_mfma_f32_16x16x32_bf16 v[32:35], v[172:175], v[188:191], v[32:35]
	v_mfma_f32_16x16x32_bf16 v[20:23], v[164:167], v[196:199], v[20:23]
	v_mfma_f32_16x16x32_bf16 v[16:19], v[172:175], v[196:199], v[16:19]
	v_mfma_f32_16x16x32_bf16 v[4:7], v[164:167], v[204:207], v[4:7]
	v_mfma_f32_16x16x32_bf16 v[0:3], v[172:175], v[204:207], v[0:3]
	v_mfma_f32_16x16x32_bf16 v[52:55], v[168:171], v[184:187], v[52:55]
	v_mfma_f32_16x16x32_bf16 v[48:51], v[176:179], v[184:187], v[48:51]
	v_mfma_f32_16x16x32_bf16 v[36:39], v[168:171], v[192:195], v[36:39]
	v_mfma_f32_16x16x32_bf16 v[32:35], v[176:179], v[192:195], v[32:35]
	v_mfma_f32_16x16x32_bf16 v[20:23], v[168:171], v[200:203], v[20:23]
	v_mfma_f32_16x16x32_bf16 v[16:19], v[176:179], v[200:203], v[16:19]
	v_mfma_f32_16x16x32_bf16 v[4:7], v[168:171], v[208:211], v[4:7]
	v_mfma_f32_16x16x32_bf16 v[0:3], v[176:179], v[208:211], v[0:3]
	s_barrier
; #define PG8_STAGE(bufoff, gbase, voff) do { _Pragma("unroll") for (int _i = 0; _i < 2; ++_i) \
;         __builtin_amdgcn_global_load_lds((const unsigned*)((const char*)(gbase) + (voff)[_i]), (PG8_LAS unsigned*)(lds + (bufoff) + ldsw + _i * 8192), 16, 0, 0); } while (0)
; #define PG8_LDA(dst, b, h) do { _Pragma("unroll") for (int m = 0; m < 4; ++m) _Pragma("unroll") for (int k = 0; k < 2; ++k) dst[m][k] = *(const PG8_LAS bf16x8*)(lds + PG8_SA(b, h) + aoff + m * 2048 + k * 1024); } while (0)
; #define PG8_WAIT_V(n) asm volatile("s_waitcnt vmcnt(" #n ")" ::: "memory")
; #define PG8_WAIT_L(n) asm volatile("s_waitcnt lgkmcnt(" #n ")" ::: "memory")
; #define PG8_BAR __builtin_amdgcn_s_barrier()
; template <class Epi, class Sched, bool ALIGN_EPI = false, bool SP2 = false>
; __device__ __forceinline__ void gemm_phase(PG8_LAS unsigned char* lds, const Gemm g, const Sched& S, const Epi& E, const int wid) {
;     ...
;         for (int t = 0; t < nt; t += 2) {
;             const bool last = (t == nt - 2);
;             const char* a1 = cA + (size_t)(t + 1) * kstep;
;             const char* a2 = last ? nA : cA + (size_t)(t + 2) * kstep; const char* b2 = last ? nB : cB + (size_t)(t + 2) * kstep;
;             const char* a3 = a2 + kstep; const char* b3 = b2 + kstep;
;             if (last && has_next) S.a_ready(nxt);
;             if constexpr (SP2) {
;             PG8_LDB(B0, 0, 0); PG8_LDB(B1, 0, 1); PG8_SCHED; PG8_LDA(At, 0, 0); PG8_STAGE(PG8_SA(1, 1), a1 + hstep, voffA);
;             PG8_WAIT_V(8); PG8_WAIT_L(0); PG8_BAR; PG8_MMA(0, 0, At, B0); PG8_MMA(0, 1, At, B1); PG8_BAR; PG8_SCHED;
;             PG8_LDA(At, 0, 1); PG8_STAGE(PG8_SB(0, 0), b2, voffB); PG8_STAGE(PG8_SB(0, 1), b2 + hstep, voffB); PG8_STAGE(PG8_SA(0, 0), a2, voffA);
;             PG8_WAIT_V(8); PG8_WAIT_L(0); PG8_BAR; PG8_MMA(1, 0, At, B0); PG8_MMA(1, 1, At, B1); PG8_BAR; PG8_SCHED;
;             PG8_LDB(B0, 1, 0); PG8_LDB(B1, 1, 1); PG8_SCHED; PG8_LDA(At, 1, 0); PG8_STAGE(PG8_SA(0, 1), a2 + hstep, voffA);
;             PG8_WAIT_V(8); PG8_WAIT_L(0); PG8_BAR; PG8_MMA(0, 0, At, B0); PG8_MMA(0, 1, At, B1); PG8_BAR; PG8_SCHED;
;             PG8_LDA(At, 1, 1); PG8_STAGE(PG8_SB(1, 0), b3, voffB); PG8_STAGE(PG8_SB(1, 1), b3 + hstep, voffB); PG8_STAGE(PG8_SA(1, 0), a3, voffA);
;             PG8_WAIT_V(8); PG8_WAIT_L(0); PG8_BAR; PG8_MMA(1, 0, At, B0); PG8_MMA(1, 1, At, B1); PG8_BAR; PG8_SCHED;
	s_setprio 1
	s_add_i32 s33, 0, 0x18000
	s_add_i32 s62, 0, 0x1c000
	v_add_u32_e32 v160, s33, v148
	v_add_u32_e32 v176, s62, v148
	ds_read_b128 v[142:145], v160
	ds_read_b128 v[152:155], v160 offset:1024
	ds_read_b128 v[156:159], v160 offset:2048
	ds_read_b128 v[160:163], v160 offset:3072
	ds_read_b128 v[164:167], v176
	ds_read_b128 v[168:171], v176 offset:1024
	ds_read_b128 v[172:175], v176 offset:2048
	ds_read_b128 v[176:179], v176 offset:3072
	s_add_u32 s28, s28, s8
	s_addc_u32 s29, s29, s9
	s_mov_b32 m0, s44
	v_lshl_add_u64 v[224:225], s[28:29], 0, v[134:135]
	ds_read_b128 v[180:183], v151 offset:32768
	ds_read_b128 v[184:187], v151 offset:33792
	ds_read_b128 v[188:191], v151 offset:34816
	ds_read_b128 v[192:195], v151 offset:35840
	ds_read_b128 v[196:199], v151 offset:36864
	ds_read_b128 v[200:203], v151 offset:37888
	ds_read_b128 v[204:207], v151 offset:38912
	ds_read_b128 v[208:211], v151 offset:39936
	global_load_lds_dwordx4 v[224:225], off
	v_lshl_add_u64 v[224:225], s[28:29], 0, v[130:131]
	s_mov_b32 m0, s45
	s_nop 0
	global_load_lds_dwordx4 v[224:225], off
	s_waitcnt vmcnt(8)
	s_waitcnt lgkmcnt(0)
	s_setprio 0
	s_barrier
	v_mfma_f32_16x16x32_bf16 v[124:127], v[142:145], v[180:183], v[124:127]
	v_mfma_f32_16x16x32_bf16 v[120:123], v[156:159], v[180:183], v[120:123]
	v_mfma_f32_16x16x32_bf16 v[108:111], v[142:145], v[188:191], v[108:111]
	v_mfma_f32_16x16x32_bf16 v[104:107], v[156:159], v[188:191], v[104:107]
	v_mfma_f32_16x16x32_bf16 v[92:95], v[142:145], v[196:199], v[92:95]
	v_mfma_f32_16x16x32_bf16 v[88:91], v[156:159], v[196:199], v[88:91]
	v_mfma_f32_16x16x32_bf16 v[76:79], v[142:145], v[204:207], v[76:79]
	v_mfma_f32_16x16x32_bf16 v[72:75], v[156:159], v[204:207], v[72:75]
	v_mfma_f32_16x16x32_bf16 v[124:127], v[152:155], v[184:187], v[124:127]
	v_mfma_f32_16x16x32_bf16 v[120:123], v[160:163], v[184:187], v[120:123]
	v_mfma_f32_16x16x32_bf16 v[108:111], v[152:155], v[192:195], v[108:111]
	v_mfma_f32_16x16x32_bf16 v[104:107], v[160:163], v[192:195], v[104:107]
	v_mfma_f32_16x16x32_bf16 v[92:95], v[152:155], v[200:203], v[92:95]
	v_mfma_f32_16x16x32_bf16 v[88:91], v[160:163], v[200:203], v[88:91]
	v_mfma_f32_16x16x32_bf16 v[76:79], v[152:155], v[208:211], v[76:79]
	v_mfma_f32_16x16x32_bf16 v[72:75], v[160:163], v[208:211], v[72:75]
	v_mfma_f32_16x16x32_bf16 v[116:119], v[164:167], v[180:183], v[116:119]
	v_mfma_f32_16x16x32_bf16 v[112:115], v[172:175], v[180:183], v[112:115]
	v_mfma_f32_16x16x32_bf16 v[100:103], v[164:167], v[188:191], v[100:103]
	v_mfma_f32_16x16x32_bf16 v[96:99], v[172:175], v[188:191], v[96:99]
	v_mfma_f32_16x16x32_bf16 v[84:87], v[164:167], v[196:199], v[84:87]
	v_mfma_f32_16x16x32_bf16 v[80:83], v[172:175], v[196:199], v[80:83]
	v_mfma_f32_16x16x32_bf16 v[68:71], v[164:167], v[204:207], v[68:71]
	v_mfma_f32_16x16x32_bf16 v[64:67], v[172:175], v[204:207], v[64:67]
	v_mfma_f32_16x16x32_bf16 v[116:119], v[168:171], v[184:187], v[116:119]
	v_mfma_f32_16x16x32_bf16 v[112:115], v[176:179], v[184:187], v[112:115]
	v_mfma_f32_16x16x32_bf16 v[100:103], v[168:171], v[192:195], v[100:103]
	v_mfma_f32_16x16x32_bf16 v[96:99], v[176:179], v[192:195], v[96:99]
	v_mfma_f32_16x16x32_bf16 v[84:87], v[168:171], v[200:203], v[84:87]
	v_mfma_f32_16x16x32_bf16 v[80:83], v[176:179], v[200:203], v[80:83]
	v_mfma_f32_16x16x32_bf16 v[68:71], v[168:171], v[208:211], v[68:71]
	v_mfma_f32_16x16x32_bf16 v[64:67], v[176:179], v[208:211], v[64:67]
	s_barrier
	s_setprio 1
	s_add_i32 s28, s33, s34
	v_lshl_add_u64 v[212:213], v[212:213], 0, s[18:19]
	s_mov_b32 m0, s28
	ds_read_b128 v[180:183], v151 offset:49152
	ds_read_b128 v[184:187], v151 offset:50176
	ds_read_b128 v[188:191], v151 offset:51200
	ds_read_b128 v[192:195], v151 offset:52224
	ds_read_b128 v[196:199], v151 offset:53248
	ds_read_b128 v[200:203], v151 offset:54272
	ds_read_b128 v[204:207], v151 offset:55296
	ds_read_b128 v[208:211], v151 offset:56320
	global_load_lds_dwordx4 v[212:213], off
	v_lshl_add_u64 v[212:213], v[214:215], 0, s[18:19]
	s_add_i32 m0, s28, 0x2000
	s_add_i32 s28, s62, s34
	global_load_lds_dwordx4 v[212:213], off
	v_lshl_add_u64 v[212:213], v[216:217], 0, s[18:19]
	s_mov_b32 m0, s28
	s_nop 0
	global_load_lds_dwordx4 v[212:213], off
	v_lshl_add_u64 v[212:213], v[218:219], 0, s[18:19]
	s_add_i32 m0, s28, 0x2000
	s_nop 0
	global_load_lds_dwordx4 v[212:213], off
	v_lshl_add_u64 v[212:213], v[220:221], 0, s[18:19]
	s_mov_b32 m0, s47
	s_nop 0
	global_load_lds_dwordx4 v[212:213], off
	v_lshl_add_u64 v[212:213], v[222:223], 0, s[18:19]
	s_mov_b32 m0, s49
	s_nop 0
	global_load_lds_dwordx4 v[212:213], off
	s_waitcnt vmcnt(8)
	s_waitcnt lgkmcnt(0)
	s_setprio 0
	s_barrier
	v_mfma_f32_16x16x32_bf16 v[60:63], v[142:145], v[180:183], v[60:63]
	v_mfma_f32_16x16x32_bf16 v[56:59], v[156:159], v[180:183], v[56:59]
	v_mfma_f32_16x16x32_bf16 v[44:47], v[142:145], v[188:191], v[44:47]
	v_mfma_f32_16x16x32_bf16 v[40:43], v[156:159], v[188:191], v[40:43]
	v_mfma_f32_16x16x32_bf16 v[28:31], v[142:145], v[196:199], v[28:31]
	v_mfma_f32_16x16x32_bf16 v[24:27], v[156:159], v[196:199], v[24:27]
	v_mfma_f32_16x16x32_bf16 v[12:15], v[142:145], v[204:207], v[12:15]
	v_mfma_f32_16x16x32_bf16 v[8:11], v[156:159], v[204:207], v[8:11]
	v_mfma_f32_16x16x32_bf16 v[60:63], v[152:155], v[184:187], v[60:63]
	v_mfma_f32_16x16x32_bf16 v[56:59], v[160:163], v[184:187], v[56:59]
	v_mfma_f32_16x16x32_bf16 v[44:47], v[152:155], v[192:195], v[44:47]
	v_mfma_f32_16x16x32_bf16 v[40:43], v[160:163], v[192:195], v[40:43]
	v_mfma_f32_16x16x32_bf16 v[28:31], v[152:155], v[200:203], v[28:31]
	v_mfma_f32_16x16x32_bf16 v[24:27], v[160:163], v[200:203], v[24:27]
	v_mfma_f32_16x16x32_bf16 v[12:15], v[152:155], v[208:211], v[12:15]
	v_mfma_f32_16x16x32_bf16 v[8:11], v[160:163], v[208:211], v[8:11]
	v_mfma_f32_16x16x32_bf16 v[52:55], v[164:167], v[180:183], v[52:55]
	v_mfma_f32_16x16x32_bf16 v[48:51], v[172:175], v[180:183], v[48:51]
	v_mfma_f32_16x16x32_bf16 v[36:39], v[164:167], v[188:191], v[36:39]
	v_mfma_f32_16x16x32_bf16 v[32:35], v[172:175], v[188:191], v[32:35]
	v_mfma_f32_16x16x32_bf16 v[20:23], v[164:167], v[196:199], v[20:23]
	v_mfma_f32_16x16x32_bf16 v[16:19], v[172:175], v[196:199], v[16:19]
	v_mfma_f32_16x16x32_bf16 v[4:7], v[164:167], v[204:207], v[4:7]
	v_mfma_f32_16x16x32_bf16 v[0:3], v[172:175], v[204:207], v[0:3]
	v_mfma_f32_16x16x32_bf16 v[52:55], v[168:171], v[184:187], v[52:55]
	v_mfma_f32_16x16x32_bf16 v[48:51], v[176:179], v[184:187], v[48:51]
	v_mfma_f32_16x16x32_bf16 v[36:39], v[168:171], v[192:195], v[36:39]
	v_mfma_f32_16x16x32_bf16 v[32:35], v[176:179], v[192:195], v[32:35]
	v_mfma_f32_16x16x32_bf16 v[20:23], v[168:171], v[200:203], v[20:23]
	v_mfma_f32_16x16x32_bf16 v[16:19], v[176:179], v[200:203], v[16:19]
	v_mfma_f32_16x16x32_bf16 v[4:7], v[168:171], v[208:211], v[4:7]
	v_mfma_f32_16x16x32_bf16 v[0:3], v[176:179], v[208:211], v[0:3]
	s_barrier
	s_setprio 1
	s_add_u32 s26, s26, 0x100
	s_addc_u32 s27, s27, 0
	s_add_u32 s0, s0, 0x100
	s_addc_u32 s1, s1, 0
	s_cmp_ge_i32 s61, s50
	s_mov_b32 s28, s61
	s_cbranch_scc0 .LBB0_1179

; #define PG8_STAGE(bufoff, gbase, voff) do { _Pragma("unroll") for (int _i = 0; _i < 2; ++_i) \
;         __builtin_amdgcn_global_load_lds((const unsigned*)((const char*)(gbase) + (voff)[_i]), (PG8_LAS unsigned*)(lds + (bufoff) + ldsw + _i * 8192), 16, 0, 0); } while (0)
; #define PG8_WAIT_V(n) asm volatile("s_waitcnt vmcnt(" #n ")" ::: "memory")
; #define PG8_WAIT_L(n) asm volatile("s_waitcnt lgkmcnt(" #n ")" ::: "memory")
; #define PG8_BAR __builtin_amdgcn_s_barrier()
; template <class Epi, class Sched, bool ALIGN_EPI = false, bool SP2 = false>
; __device__ __forceinline__ void gemm_phase(PG8_LAS unsigned char* lds, const Gemm g, const Sched& S, const Epi& E, const int wid) {
;     ...
;     for (;;) {
;         const bool has_next = S.next(ui + 1, nxt);
;         const char* nA = has_next ? (const char*)g.A + (size_t)nxt.pm * tstep : cA; const char* nB = has_next ? (const char*)g.Bt + (size_t)nxt.pn * tstep : cB;
;         for (int t = 0; t < nt; t += 2) {
;             const bool last = (t == nt - 2);
;             const char* a1 = cA + (size_t)(t + 1) * kstep;
;             const char* a2 = last ? nA : cA + (size_t)(t + 2) * kstep; const char* b2 = last ? nB : cB + (size_t)(t + 2) * kstep;
;             const char* a3 = a2 + kstep; const char* b3 = b2 + kstep;
;             if (last && has_next) S.a_ready(nxt);
;             if constexpr (SP2) {
;             PG8_LDB(B0, 0, 0); PG8_LDB(B1, 0, 1); PG8_SCHED; PG8_LDA(At, 0, 0); PG8_STAGE(PG8_SA(1, 1), a1 + hstep, voffA);
;             PG8_WAIT_V(8); PG8_WAIT_L(0); PG8_BAR; PG8_MMA(0, 0, At, B0); PG8_MMA(0, 1, At, B1); PG8_BAR; PG8_SCHED;
;             PG8_LDA(At, 0, 1); PG8_STAGE(PG8_SB(0, 0), b2, voffB); PG8_STAGE(PG8_SB(0, 1), b2 + hstep, voffB); PG8_STAGE(PG8_SA(0, 0), a2, voffA);
;             PG8_WAIT_V(8); PG8_WAIT_L(0); PG8_BAR; PG8_MMA(1, 0, At, B0); PG8_MMA(1, 1, At, B1); PG8_BAR; PG8_SCHED;
;             PG8_LDB(B0, 1, 0); PG8_LDB(B1, 1, 1); PG8_SCHED; PG8_LDA(At, 1, 0); PG8_STAGE(PG8_SA(0, 1), a2 + hstep, voffA);
;             PG8_WAIT_V(8); PG8_WAIT_L(0); PG8_BAR; PG8_MMA(0, 0, At, B0); PG8_MMA(0, 1, At, B1); PG8_BAR; PG8_SCHED;
;             PG8_LDA(At, 1, 1); PG8_STAGE(PG8_SB(1, 0), b3, voffB); PG8_STAGE(PG8_SB(1, 1), b3 + hstep, voffB); PG8_STAGE(PG8_SA(1, 0), a3, voffA);
;             PG8_WAIT_V(8); PG8_WAIT_L(0); PG8_BAR; PG8_MMA(1, 0, At, B0); PG8_MMA(1, 1, At, B1); PG8_BAR; PG8_SCHED;
.LBB0_1256:
	s_andn2_b64 vcc, exec, s[20:21]
	s_cbranch_vccnz .Lz_GMB
	s_add_u32 s28, s28, 0x80
	s_addc_u32 s29, s29, 0
	s_add_u32 s0, s30, 0x100
	s_addc_u32 s1, s31, 0
	s_mov_b32 s30, 0
	ds_read_b128 v[142:145], v149
	ds_read_b128 v[152:155], v149 offset:1024
	ds_read_b128 v[156:159], v149 offset:2048
	ds_read_b128 v[160:163], v149 offset:3072
	ds_read_b128 v[164:167], v150
	ds_read_b128 v[168:171], v150 offset:1024
	ds_read_b128 v[172:175], v150 offset:2048
	ds_read_b128 v[176:179], v150 offset:3072
	s_add_i32 s66, s30, 2
	s_add_u32 s33, s28, 0x80
	s_addc_u32 s31, s29, 0
	s_cmp_eq_u32 s57, s30
	s_cselect_b32 s30, s4, s33
	s_cselect_b32 s31, s5, s31
	s_cselect_b32 s69, s27, s1
	s_cselect_b32 s68, s26, s0
	v_lshl_add_u64 v[212:213], s[28:29], 0, v[136:137]
	s_add_i32 m0, s46, 0xc000
	ds_read_b128 v[180:183], v151
	ds_read_b128 v[184:187], v151 offset:1024
	ds_read_b128 v[188:191], v151 offset:2048
	ds_read_b128 v[192:195], v151 offset:3072
	ds_read_b128 v[196:199], v151 offset:4096
	ds_read_b128 v[200:203], v151 offset:5120
	ds_read_b128 v[204:207], v151 offset:6144
	ds_read_b128 v[208:211], v151 offset:7168
	global_load_lds_dwordx4 v[212:213], off
	v_lshl_add_u64 v[212:213], s[28:29], 0, v[138:139]
	s_add_i32 m0, s46, 0xe000
	s_nop 0
	global_load_lds_dwordx4 v[212:213], off
	s_waitcnt vmcnt(8)
	s_waitcnt lgkmcnt(0)
	s_setprio 0
	s_barrier
	v_mfma_f32_16x16x32_bf16 v[124:127], v[142:145], v[180:183], 0
	v_mfma_f32_16x16x32_bf16 v[120:123], v[156:159], v[180:183], 0
	v_mfma_f32_16x16x32_bf16 v[108:111], v[142:145], v[188:191], 0
	v_mfma_f32_16x16x32_bf16 v[104:107], v[156:159], v[188:191], 0
	v_mfma_f32_16x16x32_bf16 v[92:95], v[142:145], v[196:199], 0
	v_mfma_f32_16x16x32_bf16 v[88:91], v[156:159], v[196:199], 0
	v_mfma_f32_16x16x32_bf16 v[76:79], v[142:145], v[204:207], 0
	v_mfma_f32_16x16x32_bf16 v[72:75], v[156:159], v[204:207], 0
	v_mfma_f32_16x16x32_bf16 v[124:127], v[152:155], v[184:187], v[124:127]
	v_mfma_f32_16x16x32_bf16 v[120:123], v[160:163], v[184:187], v[120:123]
	v_mfma_f32_16x16x32_bf16 v[108:111], v[152:155], v[192:195], v[108:111]
	v_mfma_f32_16x16x32_bf16 v[104:107], v[160:163], v[192:195], v[104:107]
	v_mfma_f32_16x16x32_bf16 v[92:95], v[152:155], v[200:203], v[92:95]
	v_mfma_f32_16x16x32_bf16 v[88:91], v[160:163], v[200:203], v[88:91]
	v_mfma_f32_16x16x32_bf16 v[76:79], v[152:155], v[208:211], v[76:79]
	v_mfma_f32_16x16x32_bf16 v[72:75], v[160:163], v[208:211], v[72:75]
	v_mfma_f32_16x16x32_bf16 v[116:119], v[164:167], v[180:183], 0
	v_mfma_f32_16x16x32_bf16 v[112:115], v[172:175], v[180:183], 0
	v_mfma_f32_16x16x32_bf16 v[100:103], v[164:167], v[188:191], 0
	v_mfma_f32_16x16x32_bf16 v[96:99], v[172:175], v[188:191], 0
	v_mfma_f32_16x16x32_bf16 v[84:87], v[164:167], v[196:199], 0
	v_mfma_f32_16x16x32_bf16 v[80:83], v[172:175], v[196:199], 0
	v_mfma_f32_16x16x32_bf16 v[68:71], v[164:167], v[204:207], 0
	v_mfma_f32_16x16x32_bf16 v[64:67], v[172:175], v[204:207], 0
	v_mfma_f32_16x16x32_bf16 v[116:119], v[168:171], v[184:187], v[116:119]
	v_mfma_f32_16x16x32_bf16 v[112:115], v[176:179], v[184:187], v[112:115]
	v_mfma_f32_16x16x32_bf16 v[100:103], v[168:171], v[192:195], v[100:103]
	v_mfma_f32_16x16x32_bf16 v[96:99], v[176:179], v[192:195], v[96:99]
	v_mfma_f32_16x16x32_bf16 v[84:87], v[168:171], v[200:203], v[84:87]
	v_mfma_f32_16x16x32_bf16 v[80:83], v[176:179], v[200:203], v[80:83]
	v_mfma_f32_16x16x32_bf16 v[68:71], v[168:171], v[208:211], v[68:71]
	v_mfma_f32_16x16x32_bf16 v[64:67], v[176:179], v[208:211], v[64:67]
	s_barrier
	s_setprio 1
	s_add_i32 s33, s59, s38
	v_lshl_add_u64 v[212:213], s[68:69], 0, v[132:133]
	s_mov_b32 m0, s33
	ds_read_b128 v[180:183], v151 offset:16384
	ds_read_b128 v[184:187], v151 offset:17408
	ds_read_b128 v[188:191], v151 offset:18432
	ds_read_b128 v[192:195], v151 offset:19456
	ds_read_b128 v[196:199], v151 offset:20480
	ds_read_b128 v[200:203], v151 offset:21504
	ds_read_b128 v[204:207], v151 offset:22528
	ds_read_b128 v[208:211], v151 offset:23552
	global_load_lds_dwordx4 v[212:213], off
	s_add_i32 m0, s33, 0x2000
	v_lshl_add_u64 v[214:215], s[68:69], 0, v[128:129]
	s_add_u32 s68, s68, s8
	s_addc_u32 s69, s69, s9
	s_add_i32 s33, s60, s38
	global_load_lds_dwordx4 v[214:215], off
	v_lshl_add_u64 v[216:217], s[68:69], 0, v[132:133]
	s_mov_b32 m0, s33
	v_lshl_add_u64 v[218:219], s[68:69], 0, v[128:129]
	global_load_lds_dwordx4 v[216:217], off
	s_add_i32 m0, s33, 0x2000
	v_lshl_add_u64 v[220:221], s[30:31], 0, v[134:135]
	global_load_lds_dwordx4 v[218:219], off
	s_mov_b32 m0, s46
	v_lshl_add_u64 v[222:223], s[30:31], 0, v[130:131]
	global_load_lds_dwordx4 v[220:221], off
	s_mov_b32 m0, s47
	s_nop 0
	global_load_lds_dwordx4 v[222:223], off
	s_waitcnt vmcnt(8)
	s_waitcnt lgkmcnt(0)
	s_setprio 0
	s_barrier
; #define PG8_STAGE(bufoff, gbase, voff) do { _Pragma("unroll") for (int _i = 0; _i < 2; ++_i) \
;         __builtin_amdgcn_global_load_lds((const unsigned*)((const char*)(gbase) + (voff)[_i]), (PG8_LAS unsigned*)(lds + (bufoff) + ldsw + _i * 8192), 16, 0, 0); } while (0)
; #define PG8_LDA(dst, b, h) do { _Pragma("unroll") for (int m = 0; m < 4; ++m) _Pragma("unroll") for (int k = 0; k < 2; ++k) dst[m][k] = *(const PG8_LAS bf16x8*)(lds + PG8_SA(b, h) + aoff + m * 2048 + k * 1024); } while (0)
; #define PG8_LDB(dst, b, h) do { _Pragma("unroll") for (int n = 0; n < 2; ++n) _Pragma("unroll") for (int k = 0; k < 2; ++k) dst[n][k] = *(const PG8_LAS bf16x8*)(lds + PG8_SB(b, h) + boff + n * 2048 + k * 1024); } while (0)
; #define PG8_MMA(ai, bj, At, Bt) do { __builtin_amdgcn_s_setprio(1); _Pragma("unroll") for (int m = 0; m < 4; ++m) _Pragma("unroll") for (int n = 0; n < 2; ++n) _Pragma("unroll") for (int k = 0; k < 2; ++k) \
;         acc[ai][bj][m][n] = __builtin_amdgcn_mfma_f32_16x16x32_bf16(Bt[n][k], At[m][k], acc[ai][bj][m][n], 0, 0, 0); __builtin_amdgcn_s_setprio(0); } while (0)
; #define PG8_BAR __builtin_amdgcn_s_barrier()
; template <class Epi, class Sched, bool ALIGN_EPI = false, bool SP2 = false>
; __device__ __forceinline__ void gemm_phase(PG8_LAS unsigned char* lds, const Gemm g, const Sched& S, const Epi& E, const int wid) {
;     ...
;             PG8_LDB(B0, 0, 0); PG8_LDB(B1, 0, 1); PG8_SCHED; PG8_LDA(At, 0, 0); PG8_STAGE(PG8_SA(1, 1), a1 + hstep, voffA);
;             PG8_WAIT_V(8); PG8_WAIT_L(0); PG8_BAR; PG8_MMA(0, 0, At, B0); PG8_MMA(0, 1, At, B1); PG8_BAR; PG8_SCHED;
;             PG8_LDA(At, 0, 1); PG8_STAGE(PG8_SB(0, 0), b2, voffB); PG8_STAGE(PG8_SB(0, 1), b2 + hstep, voffB); PG8_STAGE(PG8_SA(0, 0), a2, voffA);
;             PG8_WAIT_V(8); PG8_WAIT_L(0); PG8_BAR; PG8_MMA(1, 0, At, B0); PG8_MMA(1, 1, At, B1); PG8_BAR; PG8_SCHED;
;             PG8_LDB(B0, 1, 0); PG8_LDB(B1, 1, 1); PG8_SCHED; PG8_LDA(At, 1, 0); PG8_STAGE(PG8_SA(0, 1), a2 + hstep, voffA);
;             PG8_WAIT_V(8); PG8_WAIT_L(0); PG8_BAR; PG8_MMA(0, 0, At, B0); PG8_MMA(0, 1, At, B1); PG8_BAR; PG8_SCHED;
;             PG8_LDA(At, 1, 1); PG8_STAGE(PG8_SB(1, 0), b3, voffB); PG8_STAGE(PG8_SB(1, 1), b3 + hstep, voffB); PG8_STAGE(PG8_SA(1, 0), a3, voffA);
;             PG8_WAIT_V(8); PG8_WAIT_L(0); PG8_BAR; PG8_MMA(1, 0, At, B0); PG8_MMA(1, 1, At, B1); PG8_BAR; PG8_SCHED;
	v_mfma_f32_16x16x32_bf16 v[60:63], v[142:145], v[180:183], 0
	v_mfma_f32_16x16x32_bf16 v[56:59], v[156:159], v[180:183], 0
	v_mfma_f32_16x16x32_bf16 v[44:47], v[142:145], v[188:191], 0
	v_mfma_f32_16x16x32_bf16 v[40:43], v[156:159], v[188:191], 0
	v_mfma_f32_16x16x32_bf16 v[28:31], v[142:145], v[196:199], 0
	v_mfma_f32_16x16x32_bf16 v[24:27], v[156:159], v[196:199], 0
	v_mfma_f32_16x16x32_bf16 v[12:15], v[142:145], v[204:207], 0
	v_mfma_f32_16x16x32_bf16 v[8:11], v[156:159], v[204:207], 0
	v_mfma_f32_16x16x32_bf16 v[60:63], v[152:155], v[184:187], v[60:63]
	v_mfma_f32_16x16x32_bf16 v[56:59], v[160:163], v[184:187], v[56:59]
	v_mfma_f32_16x16x32_bf16 v[44:47], v[152:155], v[192:195], v[44:47]
	v_mfma_f32_16x16x32_bf16 v[40:43], v[160:163], v[192:195], v[40:43]
	v_mfma_f32_16x16x32_bf16 v[28:31], v[152:155], v[200:203], v[28:31]
	v_mfma_f32_16x16x32_bf16 v[24:27], v[160:163], v[200:203], v[24:27]
	v_mfma_f32_16x16x32_bf16 v[12:15], v[152:155], v[208:211], v[12:15]
	v_mfma_f32_16x16x32_bf16 v[8:11], v[160:163], v[208:211], v[8:11]
	v_mfma_f32_16x16x32_bf16 v[52:55], v[164:167], v[180:183], 0
	v_mfma_f32_16x16x32_bf16 v[48:51], v[172:175], v[180:183], 0
	v_mfma_f32_16x16x32_bf16 v[36:39], v[164:167], v[188:191], 0
	v_mfma_f32_16x16x32_bf16 v[32:35], v[172:175], v[188:191], 0
	v_mfma_f32_16x16x32_bf16 v[20:23], v[164:167], v[196:199], 0
	v_mfma_f32_16x16x32_bf16 v[16:19], v[172:175], v[196:199], 0
	v_mfma_f32_16x16x32_bf16 v[4:7], v[164:167], v[204:207], 0
	v_mfma_f32_16x16x32_bf16 v[0:3], v[172:175], v[204:207], 0
	v_mfma_f32_16x16x32_bf16 v[52:55], v[168:171], v[184:187], v[52:55]
	v_mfma_f32_16x16x32_bf16 v[48:51], v[176:179], v[184:187], v[48:51]
	v_mfma_f32_16x16x32_bf16 v[36:39], v[168:171], v[192:195], v[36:39]
	v_mfma_f32_16x16x32_bf16 v[32:35], v[176:179], v[192:195], v[32:35]
	v_mfma_f32_16x16x32_bf16 v[20:23], v[168:171], v[200:203], v[20:23]
	v_mfma_f32_16x16x32_bf16 v[16:19], v[176:179], v[200:203], v[16:19]
	v_mfma_f32_16x16x32_bf16 v[4:7], v[168:171], v[208:211], v[4:7]
	v_mfma_f32_16x16x32_bf16 v[0:3], v[176:179], v[208:211], v[0:3]
	s_barrier
	s_setprio 1
	s_add_i32 s33, 0, 0x18000
	s_add_i32 s67, 0, 0x1c000
	v_add_u32_e32 v160, s33, v148
	v_add_u32_e32 v176, s67, v148
	ds_read_b128 v[142:145], v160
	ds_read_b128 v[152:155], v160 offset:1024
	ds_read_b128 v[156:159], v160 offset:2048
	ds_read_b128 v[160:163], v160 offset:3072
	ds_read_b128 v[164:167], v176
	ds_read_b128 v[168:171], v176 offset:1024
	ds_read_b128 v[172:175], v176 offset:2048
	ds_read_b128 v[176:179], v176 offset:3072
	s_add_u32 s30, s30, s8
	s_addc_u32 s31, s31, s9
	s_mov_b32 m0, s49
	v_lshl_add_u64 v[224:225], s[30:31], 0, v[134:135]
	ds_read_b128 v[180:183], v151 offset:32768
	ds_read_b128 v[184:187], v151 offset:33792
	ds_read_b128 v[188:191], v151 offset:34816
	ds_read_b128 v[192:195], v151 offset:35840
	ds_read_b128 v[196:199], v151 offset:36864
	ds_read_b128 v[200:203], v151 offset:37888
	ds_read_b128 v[204:207], v151 offset:38912
	ds_read_b128 v[208:211], v151 offset:39936
	global_load_lds_dwordx4 v[224:225], off
	v_lshl_add_u64 v[224:225], s[30:31], 0, v[130:131]
	s_mov_b32 m0, s50
	s_nop 0
	global_load_lds_dwordx4 v[224:225], off
	s_waitcnt vmcnt(8)
	s_waitcnt lgkmcnt(0)
	s_setprio 0
	s_barrier
	v_mfma_f32_16x16x32_bf16 v[124:127], v[142:145], v[180:183], v[124:127]
	v_mfma_f32_16x16x32_bf16 v[120:123], v[156:159], v[180:183], v[120:123]
	v_mfma_f32_16x16x32_bf16 v[108:111], v[142:145], v[188:191], v[108:111]
	v_mfma_f32_16x16x32_bf16 v[104:107], v[156:159], v[188:191], v[104:107]
	v_mfma_f32_16x16x32_bf16 v[92:95], v[142:145], v[196:199], v[92:95]
	v_mfma_f32_16x16x32_bf16 v[88:91], v[156:159], v[196:199], v[88:91]
	v_mfma_f32_16x16x32_bf16 v[76:79], v[142:145], v[204:207], v[76:79]
	v_mfma_f32_16x16x32_bf16 v[72:75], v[156:159], v[204:207], v[72:75]
	v_mfma_f32_16x16x32_bf16 v[124:127], v[152:155], v[184:187], v[124:127]
	v_mfma_f32_16x16x32_bf16 v[120:123], v[160:163], v[184:187], v[120:123]
	v_mfma_f32_16x16x32_bf16 v[108:111], v[152:155], v[192:195], v[108:111]
	v_mfma_f32_16x16x32_bf16 v[104:107], v[160:163], v[192:195], v[104:107]
	v_mfma_f32_16x16x32_bf16 v[92:95], v[152:155], v[200:203], v[92:95]
	v_mfma_f32_16x16x32_bf16 v[88:91], v[160:163], v[200:203], v[88:91]
	v_mfma_f32_16x16x32_bf16 v[76:79], v[152:155], v[208:211], v[76:79]
	v_mfma_f32_16x16x32_bf16 v[72:75], v[160:163], v[208:211], v[72:75]
	v_mfma_f32_16x16x32_bf16 v[116:119], v[164:167], v[180:183], v[116:119]
	v_mfma_f32_16x16x32_bf16 v[112:115], v[172:175], v[180:183], v[112:115]
	v_mfma_f32_16x16x32_bf16 v[100:103], v[164:167], v[188:191], v[100:103]
	v_mfma_f32_16x16x32_bf16 v[96:99], v[172:175], v[188:191], v[96:99]
	v_mfma_f32_16x16x32_bf16 v[84:87], v[164:167], v[196:199], v[84:87]
	v_mfma_f32_16x16x32_bf16 v[80:83], v[172:175], v[196:199], v[80:83]
	v_mfma_f32_16x16x32_bf16 v[68:71], v[164:167], v[204:207], v[68:71]
	v_mfma_f32_16x16x32_bf16 v[64:67], v[172:175], v[204:207], v[64:67]
	v_mfma_f32_16x16x32_bf16 v[116:119], v[168:171], v[184:187], v[116:119]
	v_mfma_f32_16x16x32_bf16 v[112:115], v[176:179], v[184:187], v[112:115]
	v_mfma_f32_16x16x32_bf16 v[100:103], v[168:171], v[192:195], v[100:103]
	v_mfma_f32_16x16x32_bf16 v[96:99], v[176:179], v[192:195], v[96:99]
	v_mfma_f32_16x16x32_bf16 v[84:87], v[168:171], v[200:203], v[84:87]
	v_mfma_f32_16x16x32_bf16 v[80:83], v[176:179], v[200:203], v[80:83]
	v_mfma_f32_16x16x32_bf16 v[68:71], v[168:171], v[208:211], v[68:71]
	v_mfma_f32_16x16x32_bf16 v[64:67], v[176:179], v[208:211], v[64:67]
	s_barrier
; #define PG8_STAGE(bufoff, gbase, voff) do { _Pragma("unroll") for (int _i = 0; _i < 2; ++_i) \
;         __builtin_amdgcn_global_load_lds((const unsigned*)((const char*)(gbase) + (voff)[_i]), (PG8_LAS unsigned*)(lds + (bufoff) + ldsw + _i * 8192), 16, 0, 0); } while (0)
; #define PG8_LDA(dst, b, h) do { _Pragma("unroll") for (int m = 0; m < 4; ++m) _Pragma("unroll") for (int k = 0; k < 2; ++k) dst[m][k] = *(const PG8_LAS bf16x8*)(lds + PG8_SA(b, h) + aoff + m * 2048 + k * 1024); } while (0)
; #define PG8_WAIT_V(n) asm volatile("s_waitcnt vmcnt(" #n ")" ::: "memory")
; #define PG8_WAIT_L(n) asm volatile("s_waitcnt lgkmcnt(" #n ")" ::: "memory")
; #define PG8_BAR __builtin_amdgcn_s_barrier()
; template <class Epi, class Sched, bool ALIGN_EPI = false, bool SP2 = false>
; __device__ __forceinline__ void gemm_phase(PG8_LAS unsigned char* lds, const Gemm g, const Sched& S, const Epi& E, const int wid) {
;     ...
;         for (int t = 0; t < nt; t += 2) {
;             const bool last = (t == nt - 2);
;             const char* a1 = cA + (size_t)(t + 1) * kstep;
;             const char* a2 = last ? nA : cA + (size_t)(t + 2) * kstep; const char* b2 = last ? nB : cB + (size_t)(t + 2) * kstep;
;             const char* a3 = a2 + kstep; const char* b3 = b2 + kstep;
;             if (last && has_next) S.a_ready(nxt);
;             if constexpr (SP2) {
;             PG8_LDB(B0, 0, 0); PG8_LDB(B1, 0, 1); PG8_SCHED; PG8_LDA(At, 0, 0); PG8_STAGE(PG8_SA(1, 1), a1 + hstep, voffA);
;             PG8_WAIT_V(8); PG8_WAIT_L(0); PG8_BAR; PG8_MMA(0, 0, At, B0); PG8_MMA(0, 1, At, B1); PG8_BAR; PG8_SCHED;
;             PG8_LDA(At, 0, 1); PG8_STAGE(PG8_SB(0, 0), b2, voffB); PG8_STAGE(PG8_SB(0, 1), b2 + hstep, voffB); PG8_STAGE(PG8_SA(0, 0), a2, voffA);
;             PG8_WAIT_V(8); PG8_WAIT_L(0); PG8_BAR; PG8_MMA(1, 0, At, B0); PG8_MMA(1, 1, At, B1); PG8_BAR; PG8_SCHED;
;             PG8_LDB(B0, 1, 0); PG8_LDB(B1, 1, 1); PG8_SCHED; PG8_LDA(At, 1, 0); PG8_STAGE(PG8_SA(0, 1), a2 + hstep, voffA);
;             PG8_WAIT_V(8); PG8_WAIT_L(0); PG8_BAR; PG8_MMA(0, 0, At, B0); PG8_MMA(0, 1, At, B1); PG8_BAR; PG8_SCHED;
;             PG8_LDA(At, 1, 1); PG8_STAGE(PG8_SB(1, 0), b3, voffB); PG8_STAGE(PG8_SB(1, 1), b3 + hstep, voffB); PG8_STAGE(PG8_SA(1, 0), a3, voffA);
;             PG8_WAIT_V(8); PG8_WAIT_L(0); PG8_BAR; PG8_MMA(1, 0, At, B0); PG8_MMA(1, 1, At, B1); PG8_BAR; PG8_SCHED;
	s_setprio 1
	s_add_i32 s30, s33, s38
	v_lshl_add_u64 v[212:213], v[212:213], 0, s[18:19]
	s_mov_b32 m0, s30
	ds_read_b128 v[180:183], v151 offset:49152
	ds_read_b128 v[184:187], v151 offset:50176
	ds_read_b128 v[188:191], v151 offset:51200
	ds_read_b128 v[192:195], v151 offset:52224
	ds_read_b128 v[196:199], v151 offset:53248
	ds_read_b128 v[200:203], v151 offset:54272
	ds_read_b128 v[204:207], v151 offset:55296
	ds_read_b128 v[208:211], v151 offset:56320
	global_load_lds_dwordx4 v[212:213], off
	v_lshl_add_u64 v[212:213], v[214:215], 0, s[18:19]
	s_add_i32 m0, s30, 0x2000
	s_add_i32 s30, s67, s38
	global_load_lds_dwordx4 v[212:213], off
	v_lshl_add_u64 v[212:213], v[216:217], 0, s[18:19]
	s_mov_b32 m0, s30
	s_nop 0
	global_load_lds_dwordx4 v[212:213], off
	v_lshl_add_u64 v[212:213], v[218:219], 0, s[18:19]
	s_add_i32 m0, s30, 0x2000
	s_nop 0
	global_load_lds_dwordx4 v[212:213], off
	v_lshl_add_u64 v[212:213], v[220:221], 0, s[18:19]
	s_mov_b32 m0, s52
	s_nop 0
	global_load_lds_dwordx4 v[212:213], off
	v_lshl_add_u64 v[212:213], v[222:223], 0, s[18:19]
	s_mov_b32 m0, s53
	s_nop 0
	global_load_lds_dwordx4 v[212:213], off
	s_waitcnt vmcnt(8)
	s_waitcnt lgkmcnt(0)
	s_setprio 0
	s_barrier
	v_mfma_f32_16x16x32_bf16 v[60:63], v[142:145], v[180:183], v[60:63]
	v_mfma_f32_16x16x32_bf16 v[56:59], v[156:159], v[180:183], v[56:59]
	v_mfma_f32_16x16x32_bf16 v[44:47], v[142:145], v[188:191], v[44:47]
	v_mfma_f32_16x16x32_bf16 v[40:43], v[156:159], v[188:191], v[40:43]
	v_mfma_f32_16x16x32_bf16 v[28:31], v[142:145], v[196:199], v[28:31]
	v_mfma_f32_16x16x32_bf16 v[24:27], v[156:159], v[196:199], v[24:27]
	v_mfma_f32_16x16x32_bf16 v[12:15], v[142:145], v[204:207], v[12:15]
	v_mfma_f32_16x16x32_bf16 v[8:11], v[156:159], v[204:207], v[8:11]
	v_mfma_f32_16x16x32_bf16 v[60:63], v[152:155], v[184:187], v[60:63]
	v_mfma_f32_16x16x32_bf16 v[56:59], v[160:163], v[184:187], v[56:59]
	v_mfma_f32_16x16x32_bf16 v[44:47], v[152:155], v[192:195], v[44:47]
	v_mfma_f32_16x16x32_bf16 v[40:43], v[160:163], v[192:195], v[40:43]
	v_mfma_f32_16x16x32_bf16 v[28:31], v[152:155], v[200:203], v[28:31]
	v_mfma_f32_16x16x32_bf16 v[24:27], v[160:163], v[200:203], v[24:27]
	v_mfma_f32_16x16x32_bf16 v[12:15], v[152:155], v[208:211], v[12:15]
	v_mfma_f32_16x16x32_bf16 v[8:11], v[160:163], v[208:211], v[8:11]
	v_mfma_f32_16x16x32_bf16 v[52:55], v[164:167], v[180:183], v[52:55]
	v_mfma_f32_16x16x32_bf16 v[48:51], v[172:175], v[180:183], v[48:51]
	v_mfma_f32_16x16x32_bf16 v[36:39], v[164:167], v[188:191], v[36:39]
	v_mfma_f32_16x16x32_bf16 v[32:35], v[172:175], v[188:191], v[32:35]
	v_mfma_f32_16x16x32_bf16 v[20:23], v[164:167], v[196:199], v[20:23]
	v_mfma_f32_16x16x32_bf16 v[16:19], v[172:175], v[196:199], v[16:19]
	v_mfma_f32_16x16x32_bf16 v[4:7], v[164:167], v[204:207], v[4:7]
	v_mfma_f32_16x16x32_bf16 v[0:3], v[172:175], v[204:207], v[0:3]
	v_mfma_f32_16x16x32_bf16 v[52:55], v[168:171], v[184:187], v[52:55]
	v_mfma_f32_16x16x32_bf16 v[48:51], v[176:179], v[184:187], v[48:51]
	v_mfma_f32_16x16x32_bf16 v[36:39], v[168:171], v[192:195], v[36:39]
	v_mfma_f32_16x16x32_bf16 v[32:35], v[176:179], v[192:195], v[32:35]
	v_mfma_f32_16x16x32_bf16 v[20:23], v[168:171], v[200:203], v[20:23]
	v_mfma_f32_16x16x32_bf16 v[16:19], v[176:179], v[200:203], v[16:19]
	v_mfma_f32_16x16x32_bf16 v[4:7], v[168:171], v[208:211], v[4:7]
	v_mfma_f32_16x16x32_bf16 v[0:3], v[176:179], v[208:211], v[0:3]
	s_barrier
	s_setprio 1
	s_add_u32 s28, s28, 0x100
	s_addc_u32 s29, s29, 0
	s_add_u32 s0, s0, 0x100
	s_addc_u32 s1, s1, 0
	s_cmp_ge_i32 s66, s54
	s_mov_b32 s30, s66
	s_cbranch_scc1 .LBB0_1259
.LBB0_1258:
	ds_read_b128 v[142:145], v149
	ds_read_b128 v[152:155], v149 offset:1024
	ds_read_b128 v[156:159], v149 offset:2048
	ds_read_b128 v[160:163], v149 offset:3072
	ds_read_b128 v[164:167], v150
	ds_read_b128 v[168:171], v150 offset:1024
	ds_read_b128 v[172:175], v150 offset:2048
	ds_read_b128 v[176:179], v150 offset:3072
	s_add_i32 s66, s30, 2
	s_add_u32 s33, s28, 0x80
	s_addc_u32 s31, s29, 0
	s_cmp_eq_u32 s57, s30
	s_cselect_b32 s30, s4, s33
	s_cselect_b32 s31, s5, s31
	s_cselect_b32 s69, s27, s1
	s_cselect_b32 s68, s26, s0
	v_lshl_add_u64 v[212:213], s[28:29], 0, v[136:137]
	s_add_i32 m0, s46, 0xc000
	ds_read_b128 v[180:183], v151
	ds_read_b128 v[184:187], v151 offset:1024
	ds_read_b128 v[188:191], v151 offset:2048
	ds_read_b128 v[192:195], v151 offset:3072
	ds_read_b128 v[196:199], v151 offset:4096
	ds_read_b128 v[200:203], v151 offset:5120
	ds_read_b128 v[204:207], v151 offset:6144
	ds_read_b128 v[208:211], v151 offset:7168
	global_load_lds_dwordx4 v[212:213], off
	v_lshl_add_u64 v[212:213], s[28:29], 0, v[138:139]
	s_add_i32 m0, s46, 0xe000
	s_nop 0
	global_load_lds_dwordx4 v[212:213], off
	s_waitcnt vmcnt(8)
	s_waitcnt lgkmcnt(0)
	s_setprio 0
	s_barrier
; #define PG8_STAGE(bufoff, gbase, voff) do { _Pragma("unroll") for (int _i = 0; _i < 2; ++_i) \
;         __builtin_amdgcn_global_load_lds((const unsigned*)((const char*)(gbase) + (voff)[_i]), (PG8_LAS unsigned*)(lds + (bufoff) + ldsw + _i * 8192), 16, 0, 0); } while (0)
; #define PG8_LDA(dst, b, h) do { _Pragma("unroll") for (int m = 0; m < 4; ++m) _Pragma("unroll") for (int k = 0; k < 2; ++k) dst[m][k] = *(const PG8_LAS bf16x8*)(lds + PG8_SA(b, h) + aoff + m * 2048 + k * 1024); } while (0)
; #define PG8_LDB(dst, b, h) do { _Pragma("unroll") for (int n = 0; n < 2; ++n) _Pragma("unroll") for (int k = 0; k < 2; ++k) dst[n][k] = *(const PG8_LAS bf16x8*)(lds + PG8_SB(b, h) + boff + n * 2048 + k * 1024); } while (0)
; #define PG8_MMA(ai, bj, At, Bt) do { __builtin_amdgcn_s_setprio(1); _Pragma("unroll") for (int m = 0; m < 4; ++m) _Pragma("unroll") for (int n = 0; n < 2; ++n) _Pragma("unroll") for (int k = 0; k < 2; ++k) \
;         acc[ai][bj][m][n] = __builtin_amdgcn_mfma_f32_16x16x32_bf16(Bt[n][k], At[m][k], acc[ai][bj][m][n], 0, 0, 0); __builtin_amdgcn_s_setprio(0); } while (0)
; #define PG8_BAR __builtin_amdgcn_s_barrier()
; template <class Epi, class Sched, bool ALIGN_EPI = false, bool SP2 = false>
; __device__ __forceinline__ void gemm_phase(PG8_LAS unsigned char* lds, const Gemm g, const Sched& S, const Epi& E, const int wid) {
;     ...
;             PG8_LDB(B0, 0, 0); PG8_LDB(B1, 0, 1); PG8_SCHED; PG8_LDA(At, 0, 0); PG8_STAGE(PG8_SA(1, 1), a1 + hstep, voffA);
;             PG8_WAIT_V(8); PG8_WAIT_L(0); PG8_BAR; PG8_MMA(0, 0, At, B0); PG8_MMA(0, 1, At, B1); PG8_BAR; PG8_SCHED;
;             PG8_LDA(At, 0, 1); PG8_STAGE(PG8_SB(0, 0), b2, voffB); PG8_STAGE(PG8_SB(0, 1), b2 + hstep, voffB); PG8_STAGE(PG8_SA(0, 0), a2, voffA);
;             PG8_WAIT_V(8); PG8_WAIT_L(0); PG8_BAR; PG8_MMA(1, 0, At, B0); PG8_MMA(1, 1, At, B1); PG8_BAR; PG8_SCHED;
;             PG8_LDB(B0, 1, 0); PG8_LDB(B1, 1, 1); PG8_SCHED; PG8_LDA(At, 1, 0); PG8_STAGE(PG8_SA(0, 1), a2 + hstep, voffA);
;             PG8_WAIT_V(8); PG8_WAIT_L(0); PG8_BAR; PG8_MMA(0, 0, At, B0); PG8_MMA(0, 1, At, B1); PG8_BAR; PG8_SCHED;
;             PG8_LDA(At, 1, 1); PG8_STAGE(PG8_SB(1, 0), b3, voffB); PG8_STAGE(PG8_SB(1, 1), b3 + hstep, voffB); PG8_STAGE(PG8_SA(1, 0), a3, voffA);
;             PG8_WAIT_V(8); PG8_WAIT_L(0); PG8_BAR; PG8_MMA(1, 0, At, B0); PG8_MMA(1, 1, At, B1); PG8_BAR; PG8_SCHED;
	v_mfma_f32_16x16x32_bf16 v[124:127], v[142:145], v[180:183], v[124:127]
	v_mfma_f32_16x16x32_bf16 v[120:123], v[156:159], v[180:183], v[120:123]
	v_mfma_f32_16x16x32_bf16 v[108:111], v[142:145], v[188:191], v[108:111]
	v_mfma_f32_16x16x32_bf16 v[104:107], v[156:159], v[188:191], v[104:107]
	v_mfma_f32_16x16x32_bf16 v[92:95], v[142:145], v[196:199], v[92:95]
	v_mfma_f32_16x16x32_bf16 v[88:91], v[156:159], v[196:199], v[88:91]
	v_mfma_f32_16x16x32_bf16 v[76:79], v[142:145], v[204:207], v[76:79]
	v_mfma_f32_16x16x32_bf16 v[72:75], v[156:159], v[204:207], v[72:75]
	v_mfma_f32_16x16x32_bf16 v[124:127], v[152:155], v[184:187], v[124:127]
	v_mfma_f32_16x16x32_bf16 v[120:123], v[160:163], v[184:187], v[120:123]
	v_mfma_f32_16x16x32_bf16 v[108:111], v[152:155], v[192:195], v[108:111]
	v_mfma_f32_16x16x32_bf16 v[104:107], v[160:163], v[192:195], v[104:107]
	v_mfma_f32_16x16x32_bf16 v[92:95], v[152:155], v[200:203], v[92:95]
	v_mfma_f32_16x16x32_bf16 v[88:91], v[160:163], v[200:203], v[88:91]
	v_mfma_f32_16x16x32_bf16 v[76:79], v[152:155], v[208:211], v[76:79]
	v_mfma_f32_16x16x32_bf16 v[72:75], v[160:163], v[208:211], v[72:75]
	v_mfma_f32_16x16x32_bf16 v[116:119], v[164:167], v[180:183], v[116:119]
	v_mfma_f32_16x16x32_bf16 v[112:115], v[172:175], v[180:183], v[112:115]
	v_mfma_f32_16x16x32_bf16 v[100:103], v[164:167], v[188:191], v[100:103]
	v_mfma_f32_16x16x32_bf16 v[96:99], v[172:175], v[188:191], v[96:99]
	v_mfma_f32_16x16x32_bf16 v[84:87], v[164:167], v[196:199], v[84:87]
	v_mfma_f32_16x16x32_bf16 v[80:83], v[172:175], v[196:199], v[80:83]
	v_mfma_f32_16x16x32_bf16 v[68:71], v[164:167], v[204:207], v[68:71]
	v_mfma_f32_16x16x32_bf16 v[64:67], v[172:175], v[204:207], v[64:67]
	v_mfma_f32_16x16x32_bf16 v[116:119], v[168:171], v[184:187], v[116:119]
	v_mfma_f32_16x16x32_bf16 v[112:115], v[176:179], v[184:187], v[112:115]
	v_mfma_f32_16x16x32_bf16 v[100:103], v[168:171], v[192:195], v[100:103]
	v_mfma_f32_16x16x32_bf16 v[96:99], v[176:179], v[192:195], v[96:99]
	v_mfma_f32_16x16x32_bf16 v[84:87], v[168:171], v[200:203], v[84:87]
	v_mfma_f32_16x16x32_bf16 v[80:83], v[176:179], v[200:203], v[80:83]
	v_mfma_f32_16x16x32_bf16 v[68:71], v[168:171], v[208:211], v[68:71]
	v_mfma_f32_16x16x32_bf16 v[64:67], v[176:179], v[208:211], v[64:67]
	s_barrier
	s_setprio 1
	s_add_i32 s33, s59, s38
	v_lshl_add_u64 v[212:213], s[68:69], 0, v[132:133]
	s_mov_b32 m0, s33
	ds_read_b128 v[180:183], v151 offset:16384
	ds_read_b128 v[184:187], v151 offset:17408
	ds_read_b128 v[188:191], v151 offset:18432
	ds_read_b128 v[192:195], v151 offset:19456
	ds_read_b128 v[196:199], v151 offset:20480
	ds_read_b128 v[200:203], v151 offset:21504
	ds_read_b128 v[204:207], v151 offset:22528
	ds_read_b128 v[208:211], v151 offset:23552
	global_load_lds_dwordx4 v[212:213], off
	s_add_i32 m0, s33, 0x2000
	v_lshl_add_u64 v[214:215], s[68:69], 0, v[128:129]
	s_add_u32 s68, s68, s8
	s_addc_u32 s69, s69, s9
	s_add_i32 s33, s60, s38
	global_load_lds_dwordx4 v[214:215], off
	v_lshl_add_u64 v[216:217], s[68:69], 0, v[132:133]
	s_mov_b32 m0, s33
	v_lshl_add_u64 v[218:219], s[68:69], 0, v[128:129]
	global_load_lds_dwordx4 v[216:217], off
	s_add_i32 m0, s33, 0x2000
	v_lshl_add_u64 v[220:221], s[30:31], 0, v[134:135]
	global_load_lds_dwordx4 v[218:219], off
	s_mov_b32 m0, s46
	v_lshl_add_u64 v[222:223], s[30:31], 0, v[130:131]
	global_load_lds_dwordx4 v[220:221], off
	s_mov_b32 m0, s47
	s_nop 0
	global_load_lds_dwordx4 v[222:223], off
	s_waitcnt vmcnt(8)
	s_waitcnt lgkmcnt(0)
	s_setprio 0
	s_barrier
	v_mfma_f32_16x16x32_bf16 v[60:63], v[142:145], v[180:183], v[60:63]
	v_mfma_f32_16x16x32_bf16 v[56:59], v[156:159], v[180:183], v[56:59]
	v_mfma_f32_16x16x32_bf16 v[44:47], v[142:145], v[188:191], v[44:47]
	v_mfma_f32_16x16x32_bf16 v[40:43], v[156:159], v[188:191], v[40:43]
	v_mfma_f32_16x16x32_bf16 v[28:31], v[142:145], v[196:199], v[28:31]
	v_mfma_f32_16x16x32_bf16 v[24:27], v[156:159], v[196:199], v[24:27]
	v_mfma_f32_16x16x32_bf16 v[12:15], v[142:145], v[204:207], v[12:15]
	v_mfma_f32_16x16x32_bf16 v[8:11], v[156:159], v[204:207], v[8:11]
	v_mfma_f32_16x16x32_bf16 v[60:63], v[152:155], v[184:187], v[60:63]
	v_mfma_f32_16x16x32_bf16 v[56:59], v[160:163], v[184:187], v[56:59]
	v_mfma_f32_16x16x32_bf16 v[44:47], v[152:155], v[192:195], v[44:47]
	v_mfma_f32_16x16x32_bf16 v[40:43], v[160:163], v[192:195], v[40:43]
	v_mfma_f32_16x16x32_bf16 v[28:31], v[152:155], v[200:203], v[28:31]
	v_mfma_f32_16x16x32_bf16 v[24:27], v[160:163], v[200:203], v[24:27]
	v_mfma_f32_16x16x32_bf16 v[12:15], v[152:155], v[208:211], v[12:15]
	v_mfma_f32_16x16x32_bf16 v[8:11], v[160:163], v[208:211], v[8:11]
	v_mfma_f32_16x16x32_bf16 v[52:55], v[164:167], v[180:183], v[52:55]
	v_mfma_f32_16x16x32_bf16 v[48:51], v[172:175], v[180:183], v[48:51]
	v_mfma_f32_16x16x32_bf16 v[36:39], v[164:167], v[188:191], v[36:39]
	v_mfma_f32_16x16x32_bf16 v[32:35], v[172:175], v[188:191], v[32:35]
	v_mfma_f32_16x16x32_bf16 v[20:23], v[164:167], v[196:199], v[20:23]
	v_mfma_f32_16x16x32_bf16 v[16:19], v[172:175], v[196:199], v[16:19]
	v_mfma_f32_16x16x32_bf16 v[4:7], v[164:167], v[204:207], v[4:7]
	v_mfma_f32_16x16x32_bf16 v[0:3], v[172:175], v[204:207], v[0:3]
	v_mfma_f32_16x16x32_bf16 v[52:55], v[168:171], v[184:187], v[52:55]
	v_mfma_f32_16x16x32_bf16 v[48:51], v[176:179], v[184:187], v[48:51]
	v_mfma_f32_16x16x32_bf16 v[36:39], v[168:171], v[192:195], v[36:39]
	v_mfma_f32_16x16x32_bf16 v[32:35], v[176:179], v[192:195], v[32:35]
	v_mfma_f32_16x16x32_bf16 v[20:23], v[168:171], v[200:203], v[20:23]
	v_mfma_f32_16x16x32_bf16 v[16:19], v[176:179], v[200:203], v[16:19]
	v_mfma_f32_16x16x32_bf16 v[4:7], v[168:171], v[208:211], v[4:7]
	v_mfma_f32_16x16x32_bf16 v[0:3], v[176:179], v[208:211], v[0:3]
	s_barrier
; #define PG8_STAGE(bufoff, gbase, voff) do { _Pragma("unroll") for (int _i = 0; _i < 2; ++_i) \
;         __builtin_amdgcn_global_load_lds((const unsigned*)((const char*)(gbase) + (voff)[_i]), (PG8_LAS unsigned*)(lds + (bufoff) + ldsw + _i * 8192), 16, 0, 0); } while (0)
; #define PG8_LDA(dst, b, h) do { _Pragma("unroll") for (int m = 0; m < 4; ++m) _Pragma("unroll") for (int k = 0; k < 2; ++k) dst[m][k] = *(const PG8_LAS bf16x8*)(lds + PG8_SA(b, h) + aoff + m * 2048 + k * 1024); } while (0)
; #define PG8_WAIT_V(n) asm volatile("s_waitcnt vmcnt(" #n ")" ::: "memory")
; #define PG8_WAIT_L(n) asm volatile("s_waitcnt lgkmcnt(" #n ")" ::: "memory")
; #define PG8_BAR __builtin_amdgcn_s_barrier()
; template <class Epi, class Sched, bool ALIGN_EPI = false, bool SP2 = false>
; __device__ __forceinline__ void gemm_phase(PG8_LAS unsigned char* lds, const Gemm g, const Sched& S, const Epi& E, const int wid) {
;     ...
;         for (int t = 0; t < nt; t += 2) {
;             const bool last = (t == nt - 2);
;             const char* a1 = cA + (size_t)(t + 1) * kstep;
;             const char* a2 = last ? nA : cA + (size_t)(t + 2) * kstep; const char* b2 = last ? nB : cB + (size_t)(t + 2) * kstep;
;             const char* a3 = a2 + kstep; const char* b3 = b2 + kstep;
;             if (last && has_next) S.a_ready(nxt);
;             if constexpr (SP2) {
;             PG8_LDB(B0, 0, 0); PG8_LDB(B1, 0, 1); PG8_SCHED; PG8_LDA(At, 0, 0); PG8_STAGE(PG8_SA(1, 1), a1 + hstep, voffA);
;             PG8_WAIT_V(8); PG8_WAIT_L(0); PG8_BAR; PG8_MMA(0, 0, At, B0); PG8_MMA(0, 1, At, B1); PG8_BAR; PG8_SCHED;
;             PG8_LDA(At, 0, 1); PG8_STAGE(PG8_SB(0, 0), b2, voffB); PG8_STAGE(PG8_SB(0, 1), b2 + hstep, voffB); PG8_STAGE(PG8_SA(0, 0), a2, voffA);
;             PG8_WAIT_V(8); PG8_WAIT_L(0); PG8_BAR; PG8_MMA(1, 0, At, B0); PG8_MMA(1, 1, At, B1); PG8_BAR; PG8_SCHED;
;             PG8_LDB(B0, 1, 0); PG8_LDB(B1, 1, 1); PG8_SCHED; PG8_LDA(At, 1, 0); PG8_STAGE(PG8_SA(0, 1), a2 + hstep, voffA);
;             PG8_WAIT_V(8); PG8_WAIT_L(0); PG8_BAR; PG8_MMA(0, 0, At, B0); PG8_MMA(0, 1, At, B1); PG8_BAR; PG8_SCHED;
;             PG8_LDA(At, 1, 1); PG8_STAGE(PG8_SB(1, 0), b3, voffB); PG8_STAGE(PG8_SB(1, 1), b3 + hstep, voffB); PG8_STAGE(PG8_SA(1, 0), a3, voffA);
;             PG8_WAIT_V(8); PG8_WAIT_L(0); PG8_BAR; PG8_MMA(1, 0, At, B0); PG8_MMA(1, 1, At, B1); PG8_BAR; PG8_SCHED;
	s_setprio 1
	s_add_i32 s33, 0, 0x18000
	s_add_i32 s67, 0, 0x1c000
	v_add_u32_e32 v160, s33, v148
	v_add_u32_e32 v176, s67, v148
	ds_read_b128 v[142:145], v160
	ds_read_b128 v[152:155], v160 offset:1024
	ds_read_b128 v[156:159], v160 offset:2048
	ds_read_b128 v[160:163], v160 offset:3072
	ds_read_b128 v[164:167], v176
	ds_read_b128 v[168:171], v176 offset:1024
	ds_read_b128 v[172:175], v176 offset:2048
	ds_read_b128 v[176:179], v176 offset:3072
	s_add_u32 s30, s30, s8
	s_addc_u32 s31, s31, s9
	s_mov_b32 m0, s49
	v_lshl_add_u64 v[224:225], s[30:31], 0, v[134:135]
	ds_read_b128 v[180:183], v151 offset:32768
	ds_read_b128 v[184:187], v151 offset:33792
	ds_read_b128 v[188:191], v151 offset:34816
	ds_read_b128 v[192:195], v151 offset:35840
	ds_read_b128 v[196:199], v151 offset:36864
	ds_read_b128 v[200:203], v151 offset:37888
	ds_read_b128 v[204:207], v151 offset:38912
	ds_read_b128 v[208:211], v151 offset:39936
	global_load_lds_dwordx4 v[224:225], off
	v_lshl_add_u64 v[224:225], s[30:31], 0, v[130:131]
	s_mov_b32 m0, s50
	s_nop 0
	global_load_lds_dwordx4 v[224:225], off
	s_waitcnt vmcnt(8)
	s_waitcnt lgkmcnt(0)
	s_setprio 0
	s_barrier
	v_mfma_f32_16x16x32_bf16 v[124:127], v[142:145], v[180:183], v[124:127]
	v_mfma_f32_16x16x32_bf16 v[120:123], v[156:159], v[180:183], v[120:123]
	v_mfma_f32_16x16x32_bf16 v[108:111], v[142:145], v[188:191], v[108:111]
	v_mfma_f32_16x16x32_bf16 v[104:107], v[156:159], v[188:191], v[104:107]
	v_mfma_f32_16x16x32_bf16 v[92:95], v[142:145], v[196:199], v[92:95]
	v_mfma_f32_16x16x32_bf16 v[88:91], v[156:159], v[196:199], v[88:91]
	v_mfma_f32_16x16x32_bf16 v[76:79], v[142:145], v[204:207], v[76:79]
	v_mfma_f32_16x16x32_bf16 v[72:75], v[156:159], v[204:207], v[72:75]
	v_mfma_f32_16x16x32_bf16 v[124:127], v[152:155], v[184:187], v[124:127]
	v_mfma_f32_16x16x32_bf16 v[120:123], v[160:163], v[184:187], v[120:123]
	v_mfma_f32_16x16x32_bf16 v[108:111], v[152:155], v[192:195], v[108:111]
	v_mfma_f32_16x16x32_bf16 v[104:107], v[160:163], v[192:195], v[104:107]
	v_mfma_f32_16x16x32_bf16 v[92:95], v[152:155], v[200:203], v[92:95]
	v_mfma_f32_16x16x32_bf16 v[88:91], v[160:163], v[200:203], v[88:91]
	v_mfma_f32_16x16x32_bf16 v[76:79], v[152:155], v[208:211], v[76:79]
	v_mfma_f32_16x16x32_bf16 v[72:75], v[160:163], v[208:211], v[72:75]
	v_mfma_f32_16x16x32_bf16 v[116:119], v[164:167], v[180:183], v[116:119]
	v_mfma_f32_16x16x32_bf16 v[112:115], v[172:175], v[180:183], v[112:115]
	v_mfma_f32_16x16x32_bf16 v[100:103], v[164:167], v[188:191], v[100:103]
	v_mfma_f32_16x16x32_bf16 v[96:99], v[172:175], v[188:191], v[96:99]
	v_mfma_f32_16x16x32_bf16 v[84:87], v[164:167], v[196:199], v[84:87]
	v_mfma_f32_16x16x32_bf16 v[80:83], v[172:175], v[196:199], v[80:83]
	v_mfma_f32_16x16x32_bf16 v[68:71], v[164:167], v[204:207], v[68:71]
	v_mfma_f32_16x16x32_bf16 v[64:67], v[172:175], v[204:207], v[64:67]
	v_mfma_f32_16x16x32_bf16 v[116:119], v[168:171], v[184:187], v[116:119]
	v_mfma_f32_16x16x32_bf16 v[112:115], v[176:179], v[184:187], v[112:115]
	v_mfma_f32_16x16x32_bf16 v[100:103], v[168:171], v[192:195], v[100:103]
	v_mfma_f32_16x16x32_bf16 v[96:99], v[176:179], v[192:195], v[96:99]
	v_mfma_f32_16x16x32_bf16 v[84:87], v[168:171], v[200:203], v[84:87]
	v_mfma_f32_16x16x32_bf16 v[80:83], v[176:179], v[200:203], v[80:83]
	v_mfma_f32_16x16x32_bf16 v[68:71], v[168:171], v[208:211], v[68:71]
	v_mfma_f32_16x16x32_bf16 v[64:67], v[176:179], v[208:211], v[64:67]
	s_barrier
	s_setprio 1
	s_add_i32 s30, s33, s38
	v_lshl_add_u64 v[212:213], v[212:213], 0, s[18:19]
	s_mov_b32 m0, s30
	ds_read_b128 v[180:183], v151 offset:49152
	ds_read_b128 v[184:187], v151 offset:50176
	ds_read_b128 v[188:191], v151 offset:51200
	ds_read_b128 v[192:195], v151 offset:52224
	ds_read_b128 v[196:199], v151 offset:53248
	ds_read_b128 v[200:203], v151 offset:54272
	ds_read_b128 v[204:207], v151 offset:55296
	ds_read_b128 v[208:211], v151 offset:56320
	global_load_lds_dwordx4 v[212:213], off
	v_lshl_add_u64 v[212:213], v[214:215], 0, s[18:19]
	s_add_i32 m0, s30, 0x2000
	s_add_i32 s30, s67, s38
	global_load_lds_dwordx4 v[212:213], off
	v_lshl_add_u64 v[212:213], v[216:217], 0, s[18:19]
	s_mov_b32 m0, s30
	s_nop 0
	global_load_lds_dwordx4 v[212:213], off
	v_lshl_add_u64 v[212:213], v[218:219], 0, s[18:19]
	s_add_i32 m0, s30, 0x2000
	s_nop 0
	global_load_lds_dwordx4 v[212:213], off
	v_lshl_add_u64 v[212:213], v[220:221], 0, s[18:19]
	s_mov_b32 m0, s52
	s_nop 0
	global_load_lds_dwordx4 v[212:213], off
	v_lshl_add_u64 v[212:213], v[222:223], 0, s[18:19]
	s_mov_b32 m0, s53
	s_nop 0
	global_load_lds_dwordx4 v[212:213], off
	s_waitcnt vmcnt(8)
	s_waitcnt lgkmcnt(0)
	s_setprio 0
	s_barrier
	v_mfma_f32_16x16x32_bf16 v[60:63], v[142:145], v[180:183], v[60:63]
	v_mfma_f32_16x16x32_bf16 v[56:59], v[156:159], v[180:183], v[56:59]
	v_mfma_f32_16x16x32_bf16 v[44:47], v[142:145], v[188:191], v[44:47]
	v_mfma_f32_16x16x32_bf16 v[40:43], v[156:159], v[188:191], v[40:43]
	v_mfma_f32_16x16x32_bf16 v[28:31], v[142:145], v[196:199], v[28:31]
	v_mfma_f32_16x16x32_bf16 v[24:27], v[156:159], v[196:199], v[24:27]
	v_mfma_f32_16x16x32_bf16 v[12:15], v[142:145], v[204:207], v[12:15]
	v_mfma_f32_16x16x32_bf16 v[8:11], v[156:159], v[204:207], v[8:11]
	v_mfma_f32_16x16x32_bf16 v[60:63], v[152:155], v[184:187], v[60:63]
	v_mfma_f32_16x16x32_bf16 v[56:59], v[160:163], v[184:187], v[56:59]
	v_mfma_f32_16x16x32_bf16 v[44:47], v[152:155], v[192:195], v[44:47]
	v_mfma_f32_16x16x32_bf16 v[40:43], v[160:163], v[192:195], v[40:43]
	v_mfma_f32_16x16x32_bf16 v[28:31], v[152:155], v[200:203], v[28:31]
	v_mfma_f32_16x16x32_bf16 v[24:27], v[160:163], v[200:203], v[24:27]
	v_mfma_f32_16x16x32_bf16 v[12:15], v[152:155], v[208:211], v[12:15]
	v_mfma_f32_16x16x32_bf16 v[8:11], v[160:163], v[208:211], v[8:11]
	v_mfma_f32_16x16x32_bf16 v[52:55], v[164:167], v[180:183], v[52:55]
	v_mfma_f32_16x16x32_bf16 v[48:51], v[172:175], v[180:183], v[48:51]
	v_mfma_f32_16x16x32_bf16 v[36:39], v[164:167], v[188:191], v[36:39]
	v_mfma_f32_16x16x32_bf16 v[32:35], v[172:175], v[188:191], v[32:35]
	v_mfma_f32_16x16x32_bf16 v[20:23], v[164:167], v[196:199], v[20:23]
	v_mfma_f32_16x16x32_bf16 v[16:19], v[172:175], v[196:199], v[16:19]
	v_mfma_f32_16x16x32_bf16 v[4:7], v[164:167], v[204:207], v[4:7]
	v_mfma_f32_16x16x32_bf16 v[0:3], v[172:175], v[204:207], v[0:3]
	v_mfma_f32_16x16x32_bf16 v[52:55], v[168:171], v[184:187], v[52:55]
	v_mfma_f32_16x16x32_bf16 v[48:51], v[176:179], v[184:187], v[48:51]
	v_mfma_f32_16x16x32_bf16 v[36:39], v[168:171], v[192:195], v[36:39]
	v_mfma_f32_16x16x32_bf16 v[32:35], v[176:179], v[192:195], v[32:35]
	v_mfma_f32_16x16x32_bf16 v[20:23], v[168:171], v[200:203], v[20:23]
	v_mfma_f32_16x16x32_bf16 v[16:19], v[176:179], v[200:203], v[16:19]
	v_mfma_f32_16x16x32_bf16 v[4:7], v[168:171], v[208:211], v[4:7]
	v_mfma_f32_16x16x32_bf16 v[0:3], v[176:179], v[208:211], v[0:3]
	s_barrier
	s_setprio 1
	s_add_u32 s28, s28, 0x100
	s_addc_u32 s29, s29, 0
	s_add_u32 s0, s0, 0x100
	s_addc_u32 s1, s1, 0
	s_cmp_ge_i32 s66, s54
	s_mov_b32 s30, s66
	s_cbranch_scc0 .LBB0_1258

; #define PG8_STAGE(bufoff, gbase, voff) do { _Pragma("unroll") for (int _i = 0; _i < 2; ++_i) \
;         __builtin_amdgcn_global_load_lds((const unsigned*)((const char*)(gbase) + (voff)[_i]), (PG8_LAS unsigned*)(lds + (bufoff) + ldsw + _i * 8192), 16, 0, 0); } while (0)
; #define PG8_WAIT_V(n) asm volatile("s_waitcnt vmcnt(" #n ")" ::: "memory")
; #define PG8_WAIT_L(n) asm volatile("s_waitcnt lgkmcnt(" #n ")" ::: "memory")
; #define PG8_BAR __builtin_amdgcn_s_barrier()
; template <class Epi, class Sched, bool ALIGN_EPI = false, bool SP2 = false>
; __device__ __forceinline__ void gemm_phase(PG8_LAS unsigned char* lds, const Gemm g, const Sched& S, const Epi& E, const int wid) {
;     ...
;     for (;;) {
;         const bool has_next = S.next(ui + 1, nxt);
;         const char* nA = has_next ? (const char*)g.A + (size_t)nxt.pm * tstep : cA; const char* nB = has_next ? (const char*)g.Bt + (size_t)nxt.pn * tstep : cB;
;         for (int t = 0; t < nt; t += 2) {
;             const bool last = (t == nt - 2);
;             const char* a1 = cA + (size_t)(t + 1) * kstep;
;             const char* a2 = last ? nA : cA + (size_t)(t + 2) * kstep; const char* b2 = last ? nB : cB + (size_t)(t + 2) * kstep;
;             const char* a3 = a2 + kstep; const char* b3 = b2 + kstep;
;             if (last && has_next) S.a_ready(nxt);
;             if constexpr (SP2) {
;             PG8_LDB(B0, 0, 0); PG8_LDB(B1, 0, 1); PG8_SCHED; PG8_LDA(At, 0, 0); PG8_STAGE(PG8_SA(1, 1), a1 + hstep, voffA);
;             PG8_WAIT_V(8); PG8_WAIT_L(0); PG8_BAR; PG8_MMA(0, 0, At, B0); PG8_MMA(0, 1, At, B1); PG8_BAR; PG8_SCHED;
;             PG8_LDA(At, 0, 1); PG8_STAGE(PG8_SB(0, 0), b2, voffB); PG8_STAGE(PG8_SB(0, 1), b2 + hstep, voffB); PG8_STAGE(PG8_SA(0, 0), a2, voffA);
;             PG8_WAIT_V(8); PG8_WAIT_L(0); PG8_BAR; PG8_MMA(1, 0, At, B0); PG8_MMA(1, 1, At, B1); PG8_BAR; PG8_SCHED;
;             PG8_LDB(B0, 1, 0); PG8_LDB(B1, 1, 1); PG8_SCHED; PG8_LDA(At, 1, 0); PG8_STAGE(PG8_SA(0, 1), a2 + hstep, voffA);
;             PG8_WAIT_V(8); PG8_WAIT_L(0); PG8_BAR; PG8_MMA(0, 0, At, B0); PG8_MMA(0, 1, At, B1); PG8_BAR; PG8_SCHED;
;             PG8_LDA(At, 1, 1); PG8_STAGE(PG8_SB(1, 0), b3, voffB); PG8_STAGE(PG8_SB(1, 1), b3 + hstep, voffB); PG8_STAGE(PG8_SA(1, 0), a3, voffA);
;             PG8_WAIT_V(8); PG8_WAIT_L(0); PG8_BAR; PG8_MMA(1, 0, At, B0); PG8_MMA(1, 1, At, B1); PG8_BAR; PG8_SCHED;
.LBB0_1337:
	s_andn2_b64 vcc, exec, s[24:25]
	s_waitcnt lgkmcnt(0)
	s_cbranch_vccnz .Lz_GOUT
	s_add_u32 s4, s36, 0x80
	s_addc_u32 s5, s37, 0
	s_add_u32 s0, s34, 0x100
	s_addc_u32 s1, s35, 0
	s_mov_b32 s34, 0
	ds_read_b128 v[142:145], v149
	ds_read_b128 v[154:157], v149 offset:1024
	ds_read_b128 v[158:161], v149 offset:2048
	ds_read_b128 v[162:165], v149 offset:3072
	ds_read_b128 v[166:169], v150
	ds_read_b128 v[170:173], v150 offset:1024
	ds_read_b128 v[174:177], v150 offset:2048
	ds_read_b128 v[178:181], v150 offset:3072
	s_add_i32 s36, s34, 2
	s_add_u32 s33, s4, 0x80
	s_addc_u32 s35, s5, 0
	s_cmp_eq_u32 s54, s34
	s_cselect_b32 s34, s28, s33
	s_cselect_b32 s35, s29, s35
	s_cselect_b32 s69, s31, s1
	s_cselect_b32 s68, s30, s0
	v_lshl_add_u64 v[214:215], s[4:5], 0, v[136:137]
	s_add_i32 m0, s43, 0xc000
	ds_read_b128 v[182:185], v151
	ds_read_b128 v[186:189], v151 offset:1024
	ds_read_b128 v[190:193], v151 offset:2048
	ds_read_b128 v[194:197], v151 offset:3072
	ds_read_b128 v[198:201], v151 offset:4096
	ds_read_b128 v[202:205], v151 offset:5120
	ds_read_b128 v[206:209], v151 offset:6144
	ds_read_b128 v[210:213], v151 offset:7168
	global_load_lds_dwordx4 v[214:215], off
	v_lshl_add_u64 v[214:215], s[4:5], 0, v[138:139]
	s_add_i32 m0, s43, 0xe000
	s_nop 0
	global_load_lds_dwordx4 v[214:215], off
	s_waitcnt vmcnt(8)
	s_waitcnt lgkmcnt(0)
	s_setprio 0
	s_barrier
	v_mfma_f32_16x16x32_bf16 v[120:123], v[142:145], v[182:185], 0
	v_mfma_f32_16x16x32_bf16 v[124:127], v[158:161], v[182:185], 0
	v_mfma_f32_16x16x32_bf16 v[108:111], v[142:145], v[190:193], 0
	v_mfma_f32_16x16x32_bf16 v[104:107], v[158:161], v[190:193], 0
	v_mfma_f32_16x16x32_bf16 v[92:95], v[142:145], v[198:201], 0
	v_mfma_f32_16x16x32_bf16 v[88:91], v[158:161], v[198:201], 0
	v_mfma_f32_16x16x32_bf16 v[76:79], v[142:145], v[206:209], 0
	v_mfma_f32_16x16x32_bf16 v[72:75], v[158:161], v[206:209], 0
	v_mfma_f32_16x16x32_bf16 v[120:123], v[154:157], v[186:189], v[120:123]
	v_mfma_f32_16x16x32_bf16 v[124:127], v[162:165], v[186:189], v[124:127]
	v_mfma_f32_16x16x32_bf16 v[108:111], v[154:157], v[194:197], v[108:111]
	v_mfma_f32_16x16x32_bf16 v[104:107], v[162:165], v[194:197], v[104:107]
	v_mfma_f32_16x16x32_bf16 v[92:95], v[154:157], v[202:205], v[92:95]
	v_mfma_f32_16x16x32_bf16 v[88:91], v[162:165], v[202:205], v[88:91]
	v_mfma_f32_16x16x32_bf16 v[76:79], v[154:157], v[210:213], v[76:79]
	v_mfma_f32_16x16x32_bf16 v[72:75], v[162:165], v[210:213], v[72:75]
	v_mfma_f32_16x16x32_bf16 v[116:119], v[166:169], v[182:185], 0
	v_mfma_f32_16x16x32_bf16 v[112:115], v[174:177], v[182:185], 0
	v_mfma_f32_16x16x32_bf16 v[100:103], v[166:169], v[190:193], 0
	v_mfma_f32_16x16x32_bf16 v[96:99], v[174:177], v[190:193], 0
	v_mfma_f32_16x16x32_bf16 v[84:87], v[166:169], v[198:201], 0
	v_mfma_f32_16x16x32_bf16 v[80:83], v[174:177], v[198:201], 0
	v_mfma_f32_16x16x32_bf16 v[68:71], v[166:169], v[206:209], 0
	v_mfma_f32_16x16x32_bf16 v[64:67], v[174:177], v[206:209], 0
	v_mfma_f32_16x16x32_bf16 v[116:119], v[170:173], v[186:189], v[116:119]
	v_mfma_f32_16x16x32_bf16 v[112:115], v[178:181], v[186:189], v[112:115]
	v_mfma_f32_16x16x32_bf16 v[100:103], v[170:173], v[194:197], v[100:103]
	v_mfma_f32_16x16x32_bf16 v[96:99], v[178:181], v[194:197], v[96:99]
	v_mfma_f32_16x16x32_bf16 v[84:87], v[170:173], v[202:205], v[84:87]
	v_mfma_f32_16x16x32_bf16 v[80:83], v[178:181], v[202:205], v[80:83]
	v_mfma_f32_16x16x32_bf16 v[68:71], v[170:173], v[210:213], v[68:71]
	v_mfma_f32_16x16x32_bf16 v[64:67], v[178:181], v[210:213], v[64:67]
	s_barrier
	s_setprio 1
	s_add_i32 s33, s62, s42
	v_lshl_add_u64 v[214:215], s[68:69], 0, v[130:131]
	s_mov_b32 m0, s33
	ds_read_b128 v[182:185], v151 offset:16384
	ds_read_b128 v[186:189], v151 offset:17408
	ds_read_b128 v[190:193], v151 offset:18432
	ds_read_b128 v[194:197], v151 offset:19456
	ds_read_b128 v[198:201], v151 offset:20480
	ds_read_b128 v[202:205], v151 offset:21504
	ds_read_b128 v[206:209], v151 offset:22528
	ds_read_b128 v[210:213], v151 offset:23552
	global_load_lds_dwordx4 v[214:215], off
	s_add_i32 m0, s33, 0x2000
	v_lshl_add_u64 v[216:217], s[68:69], 0, v[134:135]
	s_add_u32 s68, s68, s8
	s_addc_u32 s69, s69, s9
	s_add_i32 s33, s63, s42
	global_load_lds_dwordx4 v[216:217], off
	v_lshl_add_u64 v[218:219], s[68:69], 0, v[130:131]
	s_mov_b32 m0, s33
	v_lshl_add_u64 v[220:221], s[68:69], 0, v[134:135]
	global_load_lds_dwordx4 v[218:219], off
	s_add_i32 m0, s33, 0x2000
	v_lshl_add_u64 v[222:223], s[34:35], 0, v[128:129]
	global_load_lds_dwordx4 v[220:221], off
	s_mov_b32 m0, s43
	v_lshl_add_u64 v[224:225], s[34:35], 0, v[132:133]
	global_load_lds_dwordx4 v[222:223], off
	s_mov_b32 m0, s44
	s_nop 0
	global_load_lds_dwordx4 v[224:225], off
	s_waitcnt vmcnt(8)
	s_waitcnt lgkmcnt(0)
	s_setprio 0
	s_barrier
; #define PG8_STAGE(bufoff, gbase, voff) do { _Pragma("unroll") for (int _i = 0; _i < 2; ++_i) \
;         __builtin_amdgcn_global_load_lds((const unsigned*)((const char*)(gbase) + (voff)[_i]), (PG8_LAS unsigned*)(lds + (bufoff) + ldsw + _i * 8192), 16, 0, 0); } while (0)
; #define PG8_LDA(dst, b, h) do { _Pragma("unroll") for (int m = 0; m < 4; ++m) _Pragma("unroll") for (int k = 0; k < 2; ++k) dst[m][k] = *(const PG8_LAS bf16x8*)(lds + PG8_SA(b, h) + aoff + m * 2048 + k * 1024); } while (0)
; #define PG8_LDB(dst, b, h) do { _Pragma("unroll") for (int n = 0; n < 2; ++n) _Pragma("unroll") for (int k = 0; k < 2; ++k) dst[n][k] = *(const PG8_LAS bf16x8*)(lds + PG8_SB(b, h) + boff + n * 2048 + k * 1024); } while (0)
; #define PG8_MMA(ai, bj, At, Bt) do { __builtin_amdgcn_s_setprio(1); _Pragma("unroll") for (int m = 0; m < 4; ++m) _Pragma("unroll") for (int n = 0; n < 2; ++n) _Pragma("unroll") for (int k = 0; k < 2; ++k) \
;         acc[ai][bj][m][n] = __builtin_amdgcn_mfma_f32_16x16x32_bf16(Bt[n][k], At[m][k], acc[ai][bj][m][n], 0, 0, 0); __builtin_amdgcn_s_setprio(0); } while (0)
; #define PG8_BAR __builtin_amdgcn_s_barrier()
; template <class Epi, class Sched, bool ALIGN_EPI = false, bool SP2 = false>
; __device__ __forceinline__ void gemm_phase(PG8_LAS unsigned char* lds, const Gemm g, const Sched& S, const Epi& E, const int wid) {
;     ...
;             PG8_LDB(B0, 0, 0); PG8_LDB(B1, 0, 1); PG8_SCHED; PG8_LDA(At, 0, 0); PG8_STAGE(PG8_SA(1, 1), a1 + hstep, voffA);
;             PG8_WAIT_V(8); PG8_WAIT_L(0); PG8_BAR; PG8_MMA(0, 0, At, B0); PG8_MMA(0, 1, At, B1); PG8_BAR; PG8_SCHED;
;             PG8_LDA(At, 0, 1); PG8_STAGE(PG8_SB(0, 0), b2, voffB); PG8_STAGE(PG8_SB(0, 1), b2 + hstep, voffB); PG8_STAGE(PG8_SA(0, 0), a2, voffA);
;             PG8_WAIT_V(8); PG8_WAIT_L(0); PG8_BAR; PG8_MMA(1, 0, At, B0); PG8_MMA(1, 1, At, B1); PG8_BAR; PG8_SCHED;
;             PG8_LDB(B0, 1, 0); PG8_LDB(B1, 1, 1); PG8_SCHED; PG8_LDA(At, 1, 0); PG8_STAGE(PG8_SA(0, 1), a2 + hstep, voffA);
;             PG8_WAIT_V(8); PG8_WAIT_L(0); PG8_BAR; PG8_MMA(0, 0, At, B0); PG8_MMA(0, 1, At, B1); PG8_BAR; PG8_SCHED;
;             PG8_LDA(At, 1, 1); PG8_STAGE(PG8_SB(1, 0), b3, voffB); PG8_STAGE(PG8_SB(1, 1), b3 + hstep, voffB); PG8_STAGE(PG8_SA(1, 0), a3, voffA);
;             PG8_WAIT_V(8); PG8_WAIT_L(0); PG8_BAR; PG8_MMA(1, 0, At, B0); PG8_MMA(1, 1, At, B1); PG8_BAR; PG8_SCHED;
	v_mfma_f32_16x16x32_bf16 v[60:63], v[142:145], v[182:185], 0
	v_mfma_f32_16x16x32_bf16 v[56:59], v[158:161], v[182:185], 0
	v_mfma_f32_16x16x32_bf16 v[44:47], v[142:145], v[190:193], 0
	v_mfma_f32_16x16x32_bf16 v[40:43], v[158:161], v[190:193], 0
	v_mfma_f32_16x16x32_bf16 v[28:31], v[142:145], v[198:201], 0
	v_mfma_f32_16x16x32_bf16 v[24:27], v[158:161], v[198:201], 0
	v_mfma_f32_16x16x32_bf16 v[12:15], v[142:145], v[206:209], 0
	v_mfma_f32_16x16x32_bf16 v[8:11], v[158:161], v[206:209], 0
	v_mfma_f32_16x16x32_bf16 v[60:63], v[154:157], v[186:189], v[60:63]
	v_mfma_f32_16x16x32_bf16 v[56:59], v[162:165], v[186:189], v[56:59]
	v_mfma_f32_16x16x32_bf16 v[44:47], v[154:157], v[194:197], v[44:47]
	v_mfma_f32_16x16x32_bf16 v[40:43], v[162:165], v[194:197], v[40:43]
	v_mfma_f32_16x16x32_bf16 v[28:31], v[154:157], v[202:205], v[28:31]
	v_mfma_f32_16x16x32_bf16 v[24:27], v[162:165], v[202:205], v[24:27]
	v_mfma_f32_16x16x32_bf16 v[12:15], v[154:157], v[210:213], v[12:15]
	v_mfma_f32_16x16x32_bf16 v[8:11], v[162:165], v[210:213], v[8:11]
	v_mfma_f32_16x16x32_bf16 v[52:55], v[166:169], v[182:185], 0
	v_mfma_f32_16x16x32_bf16 v[48:51], v[174:177], v[182:185], 0
	v_mfma_f32_16x16x32_bf16 v[36:39], v[166:169], v[190:193], 0
	v_mfma_f32_16x16x32_bf16 v[32:35], v[174:177], v[190:193], 0
	v_mfma_f32_16x16x32_bf16 v[20:23], v[166:169], v[198:201], 0
	v_mfma_f32_16x16x32_bf16 v[16:19], v[174:177], v[198:201], 0
	v_mfma_f32_16x16x32_bf16 v[4:7], v[166:169], v[206:209], 0
	v_mfma_f32_16x16x32_bf16 v[0:3], v[174:177], v[206:209], 0
	v_mfma_f32_16x16x32_bf16 v[52:55], v[170:173], v[186:189], v[52:55]
	v_mfma_f32_16x16x32_bf16 v[48:51], v[178:181], v[186:189], v[48:51]
	v_mfma_f32_16x16x32_bf16 v[36:39], v[170:173], v[194:197], v[36:39]
	v_mfma_f32_16x16x32_bf16 v[32:35], v[178:181], v[194:197], v[32:35]
	v_mfma_f32_16x16x32_bf16 v[20:23], v[170:173], v[202:205], v[20:23]
	v_mfma_f32_16x16x32_bf16 v[16:19], v[178:181], v[202:205], v[16:19]
	v_mfma_f32_16x16x32_bf16 v[4:7], v[170:173], v[210:213], v[4:7]
	v_mfma_f32_16x16x32_bf16 v[0:3], v[178:181], v[210:213], v[0:3]
	s_barrier
	s_setprio 1
	s_add_i32 s33, 0, 0x18000
	v_add_u32_e32 v153, s33, v148
	s_add_i32 s37, 0, 0x1c000
	ds_read_b128 v[142:145], v153
	ds_read_b128 v[154:157], v153 offset:1024
	ds_read_b128 v[158:161], v153 offset:2048
	ds_read_b128 v[162:165], v153 offset:3072
	v_add_u32_e32 v153, s37, v148
	ds_read_b128 v[166:169], v153
	ds_read_b128 v[170:173], v153 offset:1024
	ds_read_b128 v[174:177], v153 offset:2048
	ds_read_b128 v[178:181], v153 offset:3072
	s_add_u32 s34, s34, s8
	s_addc_u32 s35, s35, s9
	s_mov_b32 m0, s45
	v_lshl_add_u64 v[226:227], s[34:35], 0, v[128:129]
	ds_read_b128 v[182:185], v151 offset:32768
	ds_read_b128 v[186:189], v151 offset:33792
	ds_read_b128 v[190:193], v151 offset:34816
	ds_read_b128 v[194:197], v151 offset:35840
	ds_read_b128 v[198:201], v151 offset:36864
	ds_read_b128 v[202:205], v151 offset:37888
	ds_read_b128 v[206:209], v151 offset:38912
	ds_read_b128 v[210:213], v151 offset:39936
	global_load_lds_dwordx4 v[226:227], off
	v_lshl_add_u64 v[226:227], s[34:35], 0, v[132:133]
	s_mov_b32 m0, s46
	s_nop 0
	global_load_lds_dwordx4 v[226:227], off
	s_waitcnt vmcnt(8)
	s_waitcnt lgkmcnt(0)
	s_setprio 0
	s_barrier
	v_mfma_f32_16x16x32_bf16 v[120:123], v[142:145], v[182:185], v[120:123]
	v_mfma_f32_16x16x32_bf16 v[124:127], v[158:161], v[182:185], v[124:127]
	v_mfma_f32_16x16x32_bf16 v[108:111], v[142:145], v[190:193], v[108:111]
	v_mfma_f32_16x16x32_bf16 v[104:107], v[158:161], v[190:193], v[104:107]
	v_mfma_f32_16x16x32_bf16 v[92:95], v[142:145], v[198:201], v[92:95]
	v_mfma_f32_16x16x32_bf16 v[88:91], v[158:161], v[198:201], v[88:91]
	v_mfma_f32_16x16x32_bf16 v[76:79], v[142:145], v[206:209], v[76:79]
	v_mfma_f32_16x16x32_bf16 v[72:75], v[158:161], v[206:209], v[72:75]
	v_mfma_f32_16x16x32_bf16 v[120:123], v[154:157], v[186:189], v[120:123]
	v_mfma_f32_16x16x32_bf16 v[124:127], v[162:165], v[186:189], v[124:127]
	v_mfma_f32_16x16x32_bf16 v[108:111], v[154:157], v[194:197], v[108:111]
	v_mfma_f32_16x16x32_bf16 v[104:107], v[162:165], v[194:197], v[104:107]
	v_mfma_f32_16x16x32_bf16 v[92:95], v[154:157], v[202:205], v[92:95]
	v_mfma_f32_16x16x32_bf16 v[88:91], v[162:165], v[202:205], v[88:91]
	v_mfma_f32_16x16x32_bf16 v[76:79], v[154:157], v[210:213], v[76:79]
	v_mfma_f32_16x16x32_bf16 v[72:75], v[162:165], v[210:213], v[72:75]
	v_mfma_f32_16x16x32_bf16 v[116:119], v[166:169], v[182:185], v[116:119]
	v_mfma_f32_16x16x32_bf16 v[112:115], v[174:177], v[182:185], v[112:115]
	v_mfma_f32_16x16x32_bf16 v[100:103], v[166:169], v[190:193], v[100:103]
	v_mfma_f32_16x16x32_bf16 v[96:99], v[174:177], v[190:193], v[96:99]
	v_mfma_f32_16x16x32_bf16 v[84:87], v[166:169], v[198:201], v[84:87]
	v_mfma_f32_16x16x32_bf16 v[80:83], v[174:177], v[198:201], v[80:83]
	v_mfma_f32_16x16x32_bf16 v[68:71], v[166:169], v[206:209], v[68:71]
	v_mfma_f32_16x16x32_bf16 v[64:67], v[174:177], v[206:209], v[64:67]
	v_mfma_f32_16x16x32_bf16 v[116:119], v[170:173], v[186:189], v[116:119]
	v_mfma_f32_16x16x32_bf16 v[112:115], v[178:181], v[186:189], v[112:115]
	v_mfma_f32_16x16x32_bf16 v[100:103], v[170:173], v[194:197], v[100:103]
	v_mfma_f32_16x16x32_bf16 v[96:99], v[178:181], v[194:197], v[96:99]
	v_mfma_f32_16x16x32_bf16 v[84:87], v[170:173], v[202:205], v[84:87]
	v_mfma_f32_16x16x32_bf16 v[80:83], v[178:181], v[202:205], v[80:83]
	v_mfma_f32_16x16x32_bf16 v[68:71], v[170:173], v[210:213], v[68:71]
	v_mfma_f32_16x16x32_bf16 v[64:67], v[178:181], v[210:213], v[64:67]
	s_barrier
; #define PG8_STAGE(bufoff, gbase, voff) do { _Pragma("unroll") for (int _i = 0; _i < 2; ++_i) \
;         __builtin_amdgcn_global_load_lds((const unsigned*)((const char*)(gbase) + (voff)[_i]), (PG8_LAS unsigned*)(lds + (bufoff) + ldsw + _i * 8192), 16, 0, 0); } while (0)
; #define PG8_LDA(dst, b, h) do { _Pragma("unroll") for (int m = 0; m < 4; ++m) _Pragma("unroll") for (int k = 0; k < 2; ++k) dst[m][k] = *(const PG8_LAS bf16x8*)(lds + PG8_SA(b, h) + aoff + m * 2048 + k * 1024); } while (0)
; #define PG8_WAIT_V(n) asm volatile("s_waitcnt vmcnt(" #n ")" ::: "memory")
; #define PG8_WAIT_L(n) asm volatile("s_waitcnt lgkmcnt(" #n ")" ::: "memory")
; #define PG8_BAR __builtin_amdgcn_s_barrier()
; template <class Epi, class Sched, bool ALIGN_EPI = false, bool SP2 = false>
; __device__ __forceinline__ void gemm_phase(PG8_LAS unsigned char* lds, const Gemm g, const Sched& S, const Epi& E, const int wid) {
;     ...
;         for (int t = 0; t < nt; t += 2) {
;             const bool last = (t == nt - 2);
;             const char* a1 = cA + (size_t)(t + 1) * kstep;
;             const char* a2 = last ? nA : cA + (size_t)(t + 2) * kstep; const char* b2 = last ? nB : cB + (size_t)(t + 2) * kstep;
;             const char* a3 = a2 + kstep; const char* b3 = b2 + kstep;
;             if (last && has_next) S.a_ready(nxt);
;             if constexpr (SP2) {
;             PG8_LDB(B0, 0, 0); PG8_LDB(B1, 0, 1); PG8_SCHED; PG8_LDA(At, 0, 0); PG8_STAGE(PG8_SA(1, 1), a1 + hstep, voffA);
;             PG8_WAIT_V(8); PG8_WAIT_L(0); PG8_BAR; PG8_MMA(0, 0, At, B0); PG8_MMA(0, 1, At, B1); PG8_BAR; PG8_SCHED;
;             PG8_LDA(At, 0, 1); PG8_STAGE(PG8_SB(0, 0), b2, voffB); PG8_STAGE(PG8_SB(0, 1), b2 + hstep, voffB); PG8_STAGE(PG8_SA(0, 0), a2, voffA);
;             PG8_WAIT_V(8); PG8_WAIT_L(0); PG8_BAR; PG8_MMA(1, 0, At, B0); PG8_MMA(1, 1, At, B1); PG8_BAR; PG8_SCHED;
;             PG8_LDB(B0, 1, 0); PG8_LDB(B1, 1, 1); PG8_SCHED; PG8_LDA(At, 1, 0); PG8_STAGE(PG8_SA(0, 1), a2 + hstep, voffA);
;             PG8_WAIT_V(8); PG8_WAIT_L(0); PG8_BAR; PG8_MMA(0, 0, At, B0); PG8_MMA(0, 1, At, B1); PG8_BAR; PG8_SCHED;
;             PG8_LDA(At, 1, 1); PG8_STAGE(PG8_SB(1, 0), b3, voffB); PG8_STAGE(PG8_SB(1, 1), b3 + hstep, voffB); PG8_STAGE(PG8_SA(1, 0), a3, voffA);
;             PG8_WAIT_V(8); PG8_WAIT_L(0); PG8_BAR; PG8_MMA(1, 0, At, B0); PG8_MMA(1, 1, At, B1); PG8_BAR; PG8_SCHED;
	s_setprio 1
	s_add_i32 s33, s33, s42
	v_lshl_add_u64 v[214:215], v[214:215], 0, s[22:23]
	s_mov_b32 m0, s33
	ds_read_b128 v[182:185], v151 offset:49152
	ds_read_b128 v[186:189], v151 offset:50176
	ds_read_b128 v[190:193], v151 offset:51200
	ds_read_b128 v[194:197], v151 offset:52224
	ds_read_b128 v[198:201], v151 offset:53248
	ds_read_b128 v[202:205], v151 offset:54272
	ds_read_b128 v[206:209], v151 offset:55296
	ds_read_b128 v[210:213], v151 offset:56320
	global_load_lds_dwordx4 v[214:215], off
	v_lshl_add_u64 v[214:215], v[216:217], 0, s[22:23]
	s_add_i32 m0, s33, 0x2000
	s_add_i32 s33, s37, s42
	global_load_lds_dwordx4 v[214:215], off
	v_lshl_add_u64 v[214:215], v[218:219], 0, s[22:23]
	s_mov_b32 m0, s33
	s_nop 0
	global_load_lds_dwordx4 v[214:215], off
	v_lshl_add_u64 v[214:215], v[220:221], 0, s[22:23]
	s_add_i32 m0, s33, 0x2000
	s_nop 0
	global_load_lds_dwordx4 v[214:215], off
	v_lshl_add_u64 v[214:215], v[222:223], 0, s[22:23]
	s_mov_b32 m0, s47
	s_nop 0
	global_load_lds_dwordx4 v[214:215], off
	v_lshl_add_u64 v[214:215], v[224:225], 0, s[22:23]
	s_mov_b32 m0, s49
	s_nop 0
	global_load_lds_dwordx4 v[214:215], off
	s_waitcnt vmcnt(8)
	s_waitcnt lgkmcnt(0)
	s_setprio 0
	s_barrier
	v_mfma_f32_16x16x32_bf16 v[60:63], v[142:145], v[182:185], v[60:63]
	v_mfma_f32_16x16x32_bf16 v[56:59], v[158:161], v[182:185], v[56:59]
	v_mfma_f32_16x16x32_bf16 v[44:47], v[142:145], v[190:193], v[44:47]
	v_mfma_f32_16x16x32_bf16 v[40:43], v[158:161], v[190:193], v[40:43]
	v_mfma_f32_16x16x32_bf16 v[28:31], v[142:145], v[198:201], v[28:31]
	v_mfma_f32_16x16x32_bf16 v[24:27], v[158:161], v[198:201], v[24:27]
	v_mfma_f32_16x16x32_bf16 v[12:15], v[142:145], v[206:209], v[12:15]
	v_mfma_f32_16x16x32_bf16 v[8:11], v[158:161], v[206:209], v[8:11]
	v_mfma_f32_16x16x32_bf16 v[60:63], v[154:157], v[186:189], v[60:63]
	v_mfma_f32_16x16x32_bf16 v[56:59], v[162:165], v[186:189], v[56:59]
	v_mfma_f32_16x16x32_bf16 v[44:47], v[154:157], v[194:197], v[44:47]
	v_mfma_f32_16x16x32_bf16 v[40:43], v[162:165], v[194:197], v[40:43]
	v_mfma_f32_16x16x32_bf16 v[28:31], v[154:157], v[202:205], v[28:31]
	v_mfma_f32_16x16x32_bf16 v[24:27], v[162:165], v[202:205], v[24:27]
	v_mfma_f32_16x16x32_bf16 v[12:15], v[154:157], v[210:213], v[12:15]
	v_mfma_f32_16x16x32_bf16 v[8:11], v[162:165], v[210:213], v[8:11]
	v_mfma_f32_16x16x32_bf16 v[52:55], v[166:169], v[182:185], v[52:55]
	v_mfma_f32_16x16x32_bf16 v[48:51], v[174:177], v[182:185], v[48:51]
	v_mfma_f32_16x16x32_bf16 v[36:39], v[166:169], v[190:193], v[36:39]
	v_mfma_f32_16x16x32_bf16 v[32:35], v[174:177], v[190:193], v[32:35]
	v_mfma_f32_16x16x32_bf16 v[20:23], v[166:169], v[198:201], v[20:23]
	v_mfma_f32_16x16x32_bf16 v[16:19], v[174:177], v[198:201], v[16:19]
	v_mfma_f32_16x16x32_bf16 v[4:7], v[166:169], v[206:209], v[4:7]
	v_mfma_f32_16x16x32_bf16 v[0:3], v[174:177], v[206:209], v[0:3]
	v_mfma_f32_16x16x32_bf16 v[52:55], v[170:173], v[186:189], v[52:55]
	v_mfma_f32_16x16x32_bf16 v[48:51], v[178:181], v[186:189], v[48:51]
	v_mfma_f32_16x16x32_bf16 v[36:39], v[170:173], v[194:197], v[36:39]
	v_mfma_f32_16x16x32_bf16 v[32:35], v[178:181], v[194:197], v[32:35]
	v_mfma_f32_16x16x32_bf16 v[20:23], v[170:173], v[202:205], v[20:23]
	v_mfma_f32_16x16x32_bf16 v[16:19], v[178:181], v[202:205], v[16:19]
	v_mfma_f32_16x16x32_bf16 v[4:7], v[170:173], v[210:213], v[4:7]
	v_mfma_f32_16x16x32_bf16 v[0:3], v[178:181], v[210:213], v[0:3]
	s_barrier
	s_setprio 1
	s_add_u32 s4, s4, 0x100
	s_addc_u32 s5, s5, 0
	s_add_u32 s0, s0, 0x100
	s_addc_u32 s1, s1, 0
	s_cmp_ge_i32 s36, s51
	s_mov_b32 s34, s36
	s_cbranch_scc1 .LBB0_1340
.LBB0_1339:
	ds_read_b128 v[142:145], v149
	ds_read_b128 v[154:157], v149 offset:1024
	ds_read_b128 v[158:161], v149 offset:2048
	ds_read_b128 v[162:165], v149 offset:3072
	ds_read_b128 v[166:169], v150
	ds_read_b128 v[170:173], v150 offset:1024
	ds_read_b128 v[174:177], v150 offset:2048
	ds_read_b128 v[178:181], v150 offset:3072
	s_add_i32 s36, s34, 2
	s_add_u32 s33, s4, 0x80
	s_addc_u32 s35, s5, 0
	s_cmp_eq_u32 s54, s34
	s_cselect_b32 s34, s28, s33
	s_cselect_b32 s35, s29, s35
	s_cselect_b32 s69, s31, s1
	s_cselect_b32 s68, s30, s0
	v_lshl_add_u64 v[214:215], s[4:5], 0, v[136:137]
	s_add_i32 m0, s43, 0xc000
	ds_read_b128 v[182:185], v151
	ds_read_b128 v[186:189], v151 offset:1024
	ds_read_b128 v[190:193], v151 offset:2048
	ds_read_b128 v[194:197], v151 offset:3072
	ds_read_b128 v[198:201], v151 offset:4096
	ds_read_b128 v[202:205], v151 offset:5120
	ds_read_b128 v[206:209], v151 offset:6144
	ds_read_b128 v[210:213], v151 offset:7168
	global_load_lds_dwordx4 v[214:215], off
	v_lshl_add_u64 v[214:215], s[4:5], 0, v[138:139]
	s_add_i32 m0, s43, 0xe000
	s_nop 0
	global_load_lds_dwordx4 v[214:215], off
	s_waitcnt vmcnt(8)
	s_waitcnt lgkmcnt(0)
	s_setprio 0
	s_barrier
; #define PG8_STAGE(bufoff, gbase, voff) do { _Pragma("unroll") for (int _i = 0; _i < 2; ++_i) \
;         __builtin_amdgcn_global_load_lds((const unsigned*)((const char*)(gbase) + (voff)[_i]), (PG8_LAS unsigned*)(lds + (bufoff) + ldsw + _i * 8192), 16, 0, 0); } while (0)
; #define PG8_LDA(dst, b, h) do { _Pragma("unroll") for (int m = 0; m < 4; ++m) _Pragma("unroll") for (int k = 0; k < 2; ++k) dst[m][k] = *(const PG8_LAS bf16x8*)(lds + PG8_SA(b, h) + aoff + m * 2048 + k * 1024); } while (0)
; #define PG8_LDB(dst, b, h) do { _Pragma("unroll") for (int n = 0; n < 2; ++n) _Pragma("unroll") for (int k = 0; k < 2; ++k) dst[n][k] = *(const PG8_LAS bf16x8*)(lds + PG8_SB(b, h) + boff + n * 2048 + k * 1024); } while (0)
; #define PG8_MMA(ai, bj, At, Bt) do { __builtin_amdgcn_s_setprio(1); _Pragma("unroll") for (int m = 0; m < 4; ++m) _Pragma("unroll") for (int n = 0; n < 2; ++n) _Pragma("unroll") for (int k = 0; k < 2; ++k) \
;         acc[ai][bj][m][n] = __builtin_amdgcn_mfma_f32_16x16x32_bf16(Bt[n][k], At[m][k], acc[ai][bj][m][n], 0, 0, 0); __builtin_amdgcn_s_setprio(0); } while (0)
; #define PG8_BAR __builtin_amdgcn_s_barrier()
; template <class Epi, class Sched, bool ALIGN_EPI = false, bool SP2 = false>
; __device__ __forceinline__ void gemm_phase(PG8_LAS unsigned char* lds, const Gemm g, const Sched& S, const Epi& E, const int wid) {
;     ...
;             PG8_LDB(B0, 0, 0); PG8_LDB(B1, 0, 1); PG8_SCHED; PG8_LDA(At, 0, 0); PG8_STAGE(PG8_SA(1, 1), a1 + hstep, voffA);
;             PG8_WAIT_V(8); PG8_WAIT_L(0); PG8_BAR; PG8_MMA(0, 0, At, B0); PG8_MMA(0, 1, At, B1); PG8_BAR; PG8_SCHED;
;             PG8_LDA(At, 0, 1); PG8_STAGE(PG8_SB(0, 0), b2, voffB); PG8_STAGE(PG8_SB(0, 1), b2 + hstep, voffB); PG8_STAGE(PG8_SA(0, 0), a2, voffA);
;             PG8_WAIT_V(8); PG8_WAIT_L(0); PG8_BAR; PG8_MMA(1, 0, At, B0); PG8_MMA(1, 1, At, B1); PG8_BAR; PG8_SCHED;
;             PG8_LDB(B0, 1, 0); PG8_LDB(B1, 1, 1); PG8_SCHED; PG8_LDA(At, 1, 0); PG8_STAGE(PG8_SA(0, 1), a2 + hstep, voffA);
;             PG8_WAIT_V(8); PG8_WAIT_L(0); PG8_BAR; PG8_MMA(0, 0, At, B0); PG8_MMA(0, 1, At, B1); PG8_BAR; PG8_SCHED;
;             PG8_LDA(At, 1, 1); PG8_STAGE(PG8_SB(1, 0), b3, voffB); PG8_STAGE(PG8_SB(1, 1), b3 + hstep, voffB); PG8_STAGE(PG8_SA(1, 0), a3, voffA);
;             PG8_WAIT_V(8); PG8_WAIT_L(0); PG8_BAR; PG8_MMA(1, 0, At, B0); PG8_MMA(1, 1, At, B1); PG8_BAR; PG8_SCHED;
	v_mfma_f32_16x16x32_bf16 v[120:123], v[142:145], v[182:185], v[120:123]
	v_mfma_f32_16x16x32_bf16 v[124:127], v[158:161], v[182:185], v[124:127]
	v_mfma_f32_16x16x32_bf16 v[108:111], v[142:145], v[190:193], v[108:111]
	v_mfma_f32_16x16x32_bf16 v[104:107], v[158:161], v[190:193], v[104:107]
	v_mfma_f32_16x16x32_bf16 v[92:95], v[142:145], v[198:201], v[92:95]
	v_mfma_f32_16x16x32_bf16 v[88:91], v[158:161], v[198:201], v[88:91]
	v_mfma_f32_16x16x32_bf16 v[76:79], v[142:145], v[206:209], v[76:79]
	v_mfma_f32_16x16x32_bf16 v[72:75], v[158:161], v[206:209], v[72:75]
	v_mfma_f32_16x16x32_bf16 v[120:123], v[154:157], v[186:189], v[120:123]
	v_mfma_f32_16x16x32_bf16 v[124:127], v[162:165], v[186:189], v[124:127]
	v_mfma_f32_16x16x32_bf16 v[108:111], v[154:157], v[194:197], v[108:111]
	v_mfma_f32_16x16x32_bf16 v[104:107], v[162:165], v[194:197], v[104:107]
	v_mfma_f32_16x16x32_bf16 v[92:95], v[154:157], v[202:205], v[92:95]
	v_mfma_f32_16x16x32_bf16 v[88:91], v[162:165], v[202:205], v[88:91]
	v_mfma_f32_16x16x32_bf16 v[76:79], v[154:157], v[210:213], v[76:79]
	v_mfma_f32_16x16x32_bf16 v[72:75], v[162:165], v[210:213], v[72:75]
	v_mfma_f32_16x16x32_bf16 v[116:119], v[166:169], v[182:185], v[116:119]
	v_mfma_f32_16x16x32_bf16 v[112:115], v[174:177], v[182:185], v[112:115]
	v_mfma_f32_16x16x32_bf16 v[100:103], v[166:169], v[190:193], v[100:103]
	v_mfma_f32_16x16x32_bf16 v[96:99], v[174:177], v[190:193], v[96:99]
	v_mfma_f32_16x16x32_bf16 v[84:87], v[166:169], v[198:201], v[84:87]
	v_mfma_f32_16x16x32_bf16 v[80:83], v[174:177], v[198:201], v[80:83]
	v_mfma_f32_16x16x32_bf16 v[68:71], v[166:169], v[206:209], v[68:71]
	v_mfma_f32_16x16x32_bf16 v[64:67], v[174:177], v[206:209], v[64:67]
	v_mfma_f32_16x16x32_bf16 v[116:119], v[170:173], v[186:189], v[116:119]
	v_mfma_f32_16x16x32_bf16 v[112:115], v[178:181], v[186:189], v[112:115]
	v_mfma_f32_16x16x32_bf16 v[100:103], v[170:173], v[194:197], v[100:103]
	v_mfma_f32_16x16x32_bf16 v[96:99], v[178:181], v[194:197], v[96:99]
	v_mfma_f32_16x16x32_bf16 v[84:87], v[170:173], v[202:205], v[84:87]
	v_mfma_f32_16x16x32_bf16 v[80:83], v[178:181], v[202:205], v[80:83]
	v_mfma_f32_16x16x32_bf16 v[68:71], v[170:173], v[210:213], v[68:71]
	v_mfma_f32_16x16x32_bf16 v[64:67], v[178:181], v[210:213], v[64:67]
	s_barrier
	s_setprio 1
	s_add_i32 s33, s62, s42
	v_lshl_add_u64 v[214:215], s[68:69], 0, v[130:131]
	s_mov_b32 m0, s33
	ds_read_b128 v[182:185], v151 offset:16384
	ds_read_b128 v[186:189], v151 offset:17408
	ds_read_b128 v[190:193], v151 offset:18432
	ds_read_b128 v[194:197], v151 offset:19456
	ds_read_b128 v[198:201], v151 offset:20480
	ds_read_b128 v[202:205], v151 offset:21504
	ds_read_b128 v[206:209], v151 offset:22528
	ds_read_b128 v[210:213], v151 offset:23552
	global_load_lds_dwordx4 v[214:215], off
	s_add_i32 m0, s33, 0x2000
	v_lshl_add_u64 v[216:217], s[68:69], 0, v[134:135]
	s_add_u32 s68, s68, s8
	s_addc_u32 s69, s69, s9
	s_add_i32 s33, s63, s42
	global_load_lds_dwordx4 v[216:217], off
	v_lshl_add_u64 v[218:219], s[68:69], 0, v[130:131]
	s_mov_b32 m0, s33
	v_lshl_add_u64 v[220:221], s[68:69], 0, v[134:135]
	global_load_lds_dwordx4 v[218:219], off
	s_add_i32 m0, s33, 0x2000
	v_lshl_add_u64 v[222:223], s[34:35], 0, v[128:129]
	global_load_lds_dwordx4 v[220:221], off
	s_mov_b32 m0, s43
	v_lshl_add_u64 v[224:225], s[34:35], 0, v[132:133]
	global_load_lds_dwordx4 v[222:223], off
	s_mov_b32 m0, s44
	s_nop 0
	global_load_lds_dwordx4 v[224:225], off
	s_waitcnt vmcnt(8)
	s_waitcnt lgkmcnt(0)
	s_setprio 0
	s_barrier
	v_mfma_f32_16x16x32_bf16 v[60:63], v[142:145], v[182:185], v[60:63]
	v_mfma_f32_16x16x32_bf16 v[56:59], v[158:161], v[182:185], v[56:59]
	v_mfma_f32_16x16x32_bf16 v[44:47], v[142:145], v[190:193], v[44:47]
	v_mfma_f32_16x16x32_bf16 v[40:43], v[158:161], v[190:193], v[40:43]
	v_mfma_f32_16x16x32_bf16 v[28:31], v[142:145], v[198:201], v[28:31]
	v_mfma_f32_16x16x32_bf16 v[24:27], v[158:161], v[198:201], v[24:27]
	v_mfma_f32_16x16x32_bf16 v[12:15], v[142:145], v[206:209], v[12:15]
	v_mfma_f32_16x16x32_bf16 v[8:11], v[158:161], v[206:209], v[8:11]
	v_mfma_f32_16x16x32_bf16 v[60:63], v[154:157], v[186:189], v[60:63]
	v_mfma_f32_16x16x32_bf16 v[56:59], v[162:165], v[186:189], v[56:59]
	v_mfma_f32_16x16x32_bf16 v[44:47], v[154:157], v[194:197], v[44:47]
	v_mfma_f32_16x16x32_bf16 v[40:43], v[162:165], v[194:197], v[40:43]
	v_mfma_f32_16x16x32_bf16 v[28:31], v[154:157], v[202:205], v[28:31]
	v_mfma_f32_16x16x32_bf16 v[24:27], v[162:165], v[202:205], v[24:27]
	v_mfma_f32_16x16x32_bf16 v[12:15], v[154:157], v[210:213], v[12:15]
	v_mfma_f32_16x16x32_bf16 v[8:11], v[162:165], v[210:213], v[8:11]
	v_mfma_f32_16x16x32_bf16 v[52:55], v[166:169], v[182:185], v[52:55]
	v_mfma_f32_16x16x32_bf16 v[48:51], v[174:177], v[182:185], v[48:51]
	v_mfma_f32_16x16x32_bf16 v[36:39], v[166:169], v[190:193], v[36:39]
	v_mfma_f32_16x16x32_bf16 v[32:35], v[174:177], v[190:193], v[32:35]
	v_mfma_f32_16x16x32_bf16 v[20:23], v[166:169], v[198:201], v[20:23]
	v_mfma_f32_16x16x32_bf16 v[16:19], v[174:177], v[198:201], v[16:19]
	v_mfma_f32_16x16x32_bf16 v[4:7], v[166:169], v[206:209], v[4:7]
	v_mfma_f32_16x16x32_bf16 v[0:3], v[174:177], v[206:209], v[0:3]
	v_mfma_f32_16x16x32_bf16 v[52:55], v[170:173], v[186:189], v[52:55]
	v_mfma_f32_16x16x32_bf16 v[48:51], v[178:181], v[186:189], v[48:51]
	v_mfma_f32_16x16x32_bf16 v[36:39], v[170:173], v[194:197], v[36:39]
	v_mfma_f32_16x16x32_bf16 v[32:35], v[178:181], v[194:197], v[32:35]
	v_mfma_f32_16x16x32_bf16 v[20:23], v[170:173], v[202:205], v[20:23]
	v_mfma_f32_16x16x32_bf16 v[16:19], v[178:181], v[202:205], v[16:19]
	v_mfma_f32_16x16x32_bf16 v[4:7], v[170:173], v[210:213], v[4:7]
	v_mfma_f32_16x16x32_bf16 v[0:3], v[178:181], v[210:213], v[0:3]
	s_barrier
; #define PG8_STAGE(bufoff, gbase, voff) do { _Pragma("unroll") for (int _i = 0; _i < 2; ++_i) \
;         __builtin_amdgcn_global_load_lds((const unsigned*)((const char*)(gbase) + (voff)[_i]), (PG8_LAS unsigned*)(lds + (bufoff) + ldsw + _i * 8192), 16, 0, 0); } while (0)
; #define PG8_LDA(dst, b, h) do { _Pragma("unroll") for (int m = 0; m < 4; ++m) _Pragma("unroll") for (int k = 0; k < 2; ++k) dst[m][k] = *(const PG8_LAS bf16x8*)(lds + PG8_SA(b, h) + aoff + m * 2048 + k * 1024); } while (0)
; #define PG8_WAIT_V(n) asm volatile("s_waitcnt vmcnt(" #n ")" ::: "memory")
; #define PG8_WAIT_L(n) asm volatile("s_waitcnt lgkmcnt(" #n ")" ::: "memory")
; #define PG8_BAR __builtin_amdgcn_s_barrier()
; template <class Epi, class Sched, bool ALIGN_EPI = false, bool SP2 = false>
; __device__ __forceinline__ void gemm_phase(PG8_LAS unsigned char* lds, const Gemm g, const Sched& S, const Epi& E, const int wid) {
;     ...
;         for (int t = 0; t < nt; t += 2) {
;             const bool last = (t == nt - 2);
;             const char* a1 = cA + (size_t)(t + 1) * kstep;
;             const char* a2 = last ? nA : cA + (size_t)(t + 2) * kstep; const char* b2 = last ? nB : cB + (size_t)(t + 2) * kstep;
;             const char* a3 = a2 + kstep; const char* b3 = b2 + kstep;
;             if (last && has_next) S.a_ready(nxt);
;             if constexpr (SP2) {
;             PG8_LDB(B0, 0, 0); PG8_LDB(B1, 0, 1); PG8_SCHED; PG8_LDA(At, 0, 0); PG8_STAGE(PG8_SA(1, 1), a1 + hstep, voffA);
;             PG8_WAIT_V(8); PG8_WAIT_L(0); PG8_BAR; PG8_MMA(0, 0, At, B0); PG8_MMA(0, 1, At, B1); PG8_BAR; PG8_SCHED;
;             PG8_LDA(At, 0, 1); PG8_STAGE(PG8_SB(0, 0), b2, voffB); PG8_STAGE(PG8_SB(0, 1), b2 + hstep, voffB); PG8_STAGE(PG8_SA(0, 0), a2, voffA);
;             PG8_WAIT_V(8); PG8_WAIT_L(0); PG8_BAR; PG8_MMA(1, 0, At, B0); PG8_MMA(1, 1, At, B1); PG8_BAR; PG8_SCHED;
;             PG8_LDB(B0, 1, 0); PG8_LDB(B1, 1, 1); PG8_SCHED; PG8_LDA(At, 1, 0); PG8_STAGE(PG8_SA(0, 1), a2 + hstep, voffA);
;             PG8_WAIT_V(8); PG8_WAIT_L(0); PG8_BAR; PG8_MMA(0, 0, At, B0); PG8_MMA(0, 1, At, B1); PG8_BAR; PG8_SCHED;
;             PG8_LDA(At, 1, 1); PG8_STAGE(PG8_SB(1, 0), b3, voffB); PG8_STAGE(PG8_SB(1, 1), b3 + hstep, voffB); PG8_STAGE(PG8_SA(1, 0), a3, voffA);
;             PG8_WAIT_V(8); PG8_WAIT_L(0); PG8_BAR; PG8_MMA(1, 0, At, B0); PG8_MMA(1, 1, At, B1); PG8_BAR; PG8_SCHED;
	s_setprio 1
	s_add_i32 s33, 0, 0x18000
	v_add_u32_e32 v153, s33, v148
	s_add_i32 s37, 0, 0x1c000
	ds_read_b128 v[142:145], v153
	ds_read_b128 v[154:157], v153 offset:1024
	ds_read_b128 v[158:161], v153 offset:2048
	ds_read_b128 v[162:165], v153 offset:3072
	v_add_u32_e32 v153, s37, v148
	ds_read_b128 v[166:169], v153
	ds_read_b128 v[170:173], v153 offset:1024
	ds_read_b128 v[174:177], v153 offset:2048
	ds_read_b128 v[178:181], v153 offset:3072
	s_add_u32 s34, s34, s8
	s_addc_u32 s35, s35, s9
	s_mov_b32 m0, s45
	v_lshl_add_u64 v[226:227], s[34:35], 0, v[128:129]
	ds_read_b128 v[182:185], v151 offset:32768
	ds_read_b128 v[186:189], v151 offset:33792
	ds_read_b128 v[190:193], v151 offset:34816
	ds_read_b128 v[194:197], v151 offset:35840
	ds_read_b128 v[198:201], v151 offset:36864
	ds_read_b128 v[202:205], v151 offset:37888
	ds_read_b128 v[206:209], v151 offset:38912
	ds_read_b128 v[210:213], v151 offset:39936
	global_load_lds_dwordx4 v[226:227], off
	v_lshl_add_u64 v[226:227], s[34:35], 0, v[132:133]
	s_mov_b32 m0, s46
	s_nop 0
	global_load_lds_dwordx4 v[226:227], off
	s_waitcnt vmcnt(8)
	s_waitcnt lgkmcnt(0)
	s_setprio 0
	s_barrier
	v_mfma_f32_16x16x32_bf16 v[120:123], v[142:145], v[182:185], v[120:123]
	v_mfma_f32_16x16x32_bf16 v[124:127], v[158:161], v[182:185], v[124:127]
	v_mfma_f32_16x16x32_bf16 v[108:111], v[142:145], v[190:193], v[108:111]
	v_mfma_f32_16x16x32_bf16 v[104:107], v[158:161], v[190:193], v[104:107]
	v_mfma_f32_16x16x32_bf16 v[92:95], v[142:145], v[198:201], v[92:95]
	v_mfma_f32_16x16x32_bf16 v[88:91], v[158:161], v[198:201], v[88:91]
	v_mfma_f32_16x16x32_bf16 v[76:79], v[142:145], v[206:209], v[76:79]
	v_mfma_f32_16x16x32_bf16 v[72:75], v[158:161], v[206:209], v[72:75]
	v_mfma_f32_16x16x32_bf16 v[120:123], v[154:157], v[186:189], v[120:123]
	v_mfma_f32_16x16x32_bf16 v[124:127], v[162:165], v[186:189], v[124:127]
	v_mfma_f32_16x16x32_bf16 v[108:111], v[154:157], v[194:197], v[108:111]
	v_mfma_f32_16x16x32_bf16 v[104:107], v[162:165], v[194:197], v[104:107]
	v_mfma_f32_16x16x32_bf16 v[92:95], v[154:157], v[202:205], v[92:95]
	v_mfma_f32_16x16x32_bf16 v[88:91], v[162:165], v[202:205], v[88:91]
	v_mfma_f32_16x16x32_bf16 v[76:79], v[154:157], v[210:213], v[76:79]
	v_mfma_f32_16x16x32_bf16 v[72:75], v[162:165], v[210:213], v[72:75]
	v_mfma_f32_16x16x32_bf16 v[116:119], v[166:169], v[182:185], v[116:119]
	v_mfma_f32_16x16x32_bf16 v[112:115], v[174:177], v[182:185], v[112:115]
	v_mfma_f32_16x16x32_bf16 v[100:103], v[166:169], v[190:193], v[100:103]
	v_mfma_f32_16x16x32_bf16 v[96:99], v[174:177], v[190:193], v[96:99]
	v_mfma_f32_16x16x32_bf16 v[84:87], v[166:169], v[198:201], v[84:87]
	v_mfma_f32_16x16x32_bf16 v[80:83], v[174:177], v[198:201], v[80:83]
	v_mfma_f32_16x16x32_bf16 v[68:71], v[166:169], v[206:209], v[68:71]
	v_mfma_f32_16x16x32_bf16 v[64:67], v[174:177], v[206:209], v[64:67]
	v_mfma_f32_16x16x32_bf16 v[116:119], v[170:173], v[186:189], v[116:119]
	v_mfma_f32_16x16x32_bf16 v[112:115], v[178:181], v[186:189], v[112:115]
	v_mfma_f32_16x16x32_bf16 v[100:103], v[170:173], v[194:197], v[100:103]
	v_mfma_f32_16x16x32_bf16 v[96:99], v[178:181], v[194:197], v[96:99]
	v_mfma_f32_16x16x32_bf16 v[84:87], v[170:173], v[202:205], v[84:87]
	v_mfma_f32_16x16x32_bf16 v[80:83], v[178:181], v[202:205], v[80:83]
	v_mfma_f32_16x16x32_bf16 v[68:71], v[170:173], v[210:213], v[68:71]
	v_mfma_f32_16x16x32_bf16 v[64:67], v[178:181], v[210:213], v[64:67]
	s_barrier
	s_setprio 1
	s_add_i32 s33, s33, s42
	v_lshl_add_u64 v[214:215], v[214:215], 0, s[22:23]
	s_mov_b32 m0, s33
	ds_read_b128 v[182:185], v151 offset:49152
	ds_read_b128 v[186:189], v151 offset:50176
	ds_read_b128 v[190:193], v151 offset:51200
	ds_read_b128 v[194:197], v151 offset:52224
	ds_read_b128 v[198:201], v151 offset:53248
	ds_read_b128 v[202:205], v151 offset:54272
	ds_read_b128 v[206:209], v151 offset:55296
	ds_read_b128 v[210:213], v151 offset:56320
	global_load_lds_dwordx4 v[214:215], off
	v_lshl_add_u64 v[214:215], v[216:217], 0, s[22:23]
	s_add_i32 m0, s33, 0x2000
	s_add_i32 s33, s37, s42
	global_load_lds_dwordx4 v[214:215], off
	v_lshl_add_u64 v[214:215], v[218:219], 0, s[22:23]
	s_mov_b32 m0, s33
	s_nop 0
	global_load_lds_dwordx4 v[214:215], off
	v_lshl_add_u64 v[214:215], v[220:221], 0, s[22:23]
	s_add_i32 m0, s33, 0x2000
	s_nop 0
	global_load_lds_dwordx4 v[214:215], off
	v_lshl_add_u64 v[214:215], v[222:223], 0, s[22:23]
	s_mov_b32 m0, s47
	s_nop 0
	global_load_lds_dwordx4 v[214:215], off
	v_lshl_add_u64 v[214:215], v[224:225], 0, s[22:23]
	s_mov_b32 m0, s49
	s_nop 0
	global_load_lds_dwordx4 v[214:215], off
	s_waitcnt vmcnt(8)
	s_waitcnt lgkmcnt(0)
	s_setprio 0
	s_barrier
	v_mfma_f32_16x16x32_bf16 v[60:63], v[142:145], v[182:185], v[60:63]
	v_mfma_f32_16x16x32_bf16 v[56:59], v[158:161], v[182:185], v[56:59]
	v_mfma_f32_16x16x32_bf16 v[44:47], v[142:145], v[190:193], v[44:47]
	v_mfma_f32_16x16x32_bf16 v[40:43], v[158:161], v[190:193], v[40:43]
	v_mfma_f32_16x16x32_bf16 v[28:31], v[142:145], v[198:201], v[28:31]
	v_mfma_f32_16x16x32_bf16 v[24:27], v[158:161], v[198:201], v[24:27]
	v_mfma_f32_16x16x32_bf16 v[12:15], v[142:145], v[206:209], v[12:15]
	v_mfma_f32_16x16x32_bf16 v[8:11], v[158:161], v[206:209], v[8:11]
	v_mfma_f32_16x16x32_bf16 v[60:63], v[154:157], v[186:189], v[60:63]
	v_mfma_f32_16x16x32_bf16 v[56:59], v[162:165], v[186:189], v[56:59]
	v_mfma_f32_16x16x32_bf16 v[44:47], v[154:157], v[194:197], v[44:47]
	v_mfma_f32_16x16x32_bf16 v[40:43], v[162:165], v[194:197], v[40:43]
	v_mfma_f32_16x16x32_bf16 v[28:31], v[154:157], v[202:205], v[28:31]
	v_mfma_f32_16x16x32_bf16 v[24:27], v[162:165], v[202:205], v[24:27]
	v_mfma_f32_16x16x32_bf16 v[12:15], v[154:157], v[210:213], v[12:15]
	v_mfma_f32_16x16x32_bf16 v[8:11], v[162:165], v[210:213], v[8:11]
	v_mfma_f32_16x16x32_bf16 v[52:55], v[166:169], v[182:185], v[52:55]
	v_mfma_f32_16x16x32_bf16 v[48:51], v[174:177], v[182:185], v[48:51]
	v_mfma_f32_16x16x32_bf16 v[36:39], v[166:169], v[190:193], v[36:39]
	v_mfma_f32_16x16x32_bf16 v[32:35], v[174:177], v[190:193], v[32:35]
	v_mfma_f32_16x16x32_bf16 v[20:23], v[166:169], v[198:201], v[20:23]
	v_mfma_f32_16x16x32_bf16 v[16:19], v[174:177], v[198:201], v[16:19]
	v_mfma_f32_16x16x32_bf16 v[4:7], v[166:169], v[206:209], v[4:7]
	v_mfma_f32_16x16x32_bf16 v[0:3], v[174:177], v[206:209], v[0:3]
	v_mfma_f32_16x16x32_bf16 v[52:55], v[170:173], v[186:189], v[52:55]
	v_mfma_f32_16x16x32_bf16 v[48:51], v[178:181], v[186:189], v[48:51]
	v_mfma_f32_16x16x32_bf16 v[36:39], v[170:173], v[194:197], v[36:39]
	v_mfma_f32_16x16x32_bf16 v[32:35], v[178:181], v[194:197], v[32:35]
	v_mfma_f32_16x16x32_bf16 v[20:23], v[170:173], v[202:205], v[20:23]
	v_mfma_f32_16x16x32_bf16 v[16:19], v[178:181], v[202:205], v[16:19]
	v_mfma_f32_16x16x32_bf16 v[4:7], v[170:173], v[210:213], v[4:7]
	v_mfma_f32_16x16x32_bf16 v[0:3], v[178:181], v[210:213], v[0:3]
	s_barrier
	s_setprio 1
	s_add_u32 s4, s4, 0x100
	s_addc_u32 s5, s5, 0
	s_add_u32 s0, s0, 0x100
	s_addc_u32 s1, s1, 0
	s_cmp_ge_i32 s36, s51
	s_mov_b32 s34, s36
	s_cbranch_scc0 .LBB0_1339

; #define PG8_STAGE(bufoff, gbase, voff) do { _Pragma("unroll") for (int _i = 0; _i < 2; ++_i) \
;         __builtin_amdgcn_global_load_lds((const unsigned*)((const char*)(gbase) + (voff)[_i]), (PG8_LAS unsigned*)(lds + (bufoff) + ldsw + _i * 8192), 16, 0, 0); } while (0)
; #define PG8_WAIT_V(n) asm volatile("s_waitcnt vmcnt(" #n ")" ::: "memory")
; #define PG8_WAIT_L(n) asm volatile("s_waitcnt lgkmcnt(" #n ")" ::: "memory")
; #define PG8_BAR __builtin_amdgcn_s_barrier()
; template <class Epi, class Sched, bool ALIGN_EPI = false, bool SP2 = false>
; __device__ __forceinline__ void gemm_phase(PG8_LAS unsigned char* lds, const Gemm g, const Sched& S, const Epi& E, const int wid) {
;     ...
;     for (;;) {
;         const bool has_next = S.next(ui + 1, nxt);
;         const char* nA = has_next ? (const char*)g.A + (size_t)nxt.pm * tstep : cA; const char* nB = has_next ? (const char*)g.Bt + (size_t)nxt.pn * tstep : cB;
;         for (int t = 0; t < nt; t += 2) {
;             const bool last = (t == nt - 2);
;             const char* a1 = cA + (size_t)(t + 1) * kstep;
;             const char* a2 = last ? nA : cA + (size_t)(t + 2) * kstep; const char* b2 = last ? nB : cB + (size_t)(t + 2) * kstep;
;             const char* a3 = a2 + kstep; const char* b3 = b2 + kstep;
;             if (last && has_next) S.a_ready(nxt);
;             if constexpr (SP2) {
;             PG8_LDB(B0, 0, 0); PG8_LDB(B1, 0, 1); PG8_SCHED; PG8_LDA(At, 0, 0); PG8_STAGE(PG8_SA(1, 1), a1 + hstep, voffA);
;             PG8_WAIT_V(8); PG8_WAIT_L(0); PG8_BAR; PG8_MMA(0, 0, At, B0); PG8_MMA(0, 1, At, B1); PG8_BAR; PG8_SCHED;
;             PG8_LDA(At, 0, 1); PG8_STAGE(PG8_SB(0, 0), b2, voffB); PG8_STAGE(PG8_SB(0, 1), b2 + hstep, voffB); PG8_STAGE(PG8_SA(0, 0), a2, voffA);
;             PG8_WAIT_V(8); PG8_WAIT_L(0); PG8_BAR; PG8_MMA(1, 0, At, B0); PG8_MMA(1, 1, At, B1); PG8_BAR; PG8_SCHED;
;             PG8_LDB(B0, 1, 0); PG8_LDB(B1, 1, 1); PG8_SCHED; PG8_LDA(At, 1, 0); PG8_STAGE(PG8_SA(0, 1), a2 + hstep, voffA);
;             PG8_WAIT_V(8); PG8_WAIT_L(0); PG8_BAR; PG8_MMA(0, 0, At, B0); PG8_MMA(0, 1, At, B1); PG8_BAR; PG8_SCHED;
;             PG8_LDA(At, 1, 1); PG8_STAGE(PG8_SB(1, 0), b3, voffB); PG8_STAGE(PG8_SB(1, 1), b3 + hstep, voffB); PG8_STAGE(PG8_SA(1, 0), a3, voffA);
;             PG8_WAIT_V(8); PG8_WAIT_L(0); PG8_BAR; PG8_MMA(1, 0, At, B0); PG8_MMA(1, 1, At, B1); PG8_BAR; PG8_SCHED;
.LBB0_1493:
	s_andn2_b64 vcc, exec, s[22:23]
	s_cbranch_vccnz .Lz_FFN1
	s_add_u32 s4, s8, 0x80
	s_addc_u32 s5, s9, 0
	s_add_u32 s0, s6, 0x100
	s_addc_u32 s1, s7, 0
	s_mov_b32 s6, 0
	ds_read_b128 v[142:145], v149
	ds_read_b128 v[152:155], v149 offset:1024
	ds_read_b128 v[156:159], v149 offset:2048
	ds_read_b128 v[160:163], v149 offset:3072
	ds_read_b128 v[164:167], v150
	ds_read_b128 v[168:171], v150 offset:1024
	ds_read_b128 v[172:175], v150 offset:2048
	ds_read_b128 v[176:179], v150 offset:3072
	s_add_i32 s8, s6, 2
	s_add_u32 s9, s4, 0x80
	s_addc_u32 s7, s5, 0
	s_cmp_eq_u32 s55, s6
	s_cselect_b32 s6, s26, s9
	s_cselect_b32 s7, s27, s7
	s_cselect_b32 s65, s29, s1
	s_cselect_b32 s64, s28, s0
	v_lshl_add_u64 v[212:213], s[4:5], 0, v[136:137]
	s_add_i32 m0, s44, 0xc000
	ds_read_b128 v[180:183], v151
	ds_read_b128 v[184:187], v151 offset:1024
	ds_read_b128 v[188:191], v151 offset:2048
	ds_read_b128 v[192:195], v151 offset:3072
	ds_read_b128 v[196:199], v151 offset:4096
	ds_read_b128 v[200:203], v151 offset:5120
	ds_read_b128 v[204:207], v151 offset:6144
	ds_read_b128 v[208:211], v151 offset:7168
	global_load_lds_dwordx4 v[212:213], off
	v_lshl_add_u64 v[212:213], s[4:5], 0, v[138:139]
	s_add_i32 m0, s44, 0xe000
	s_nop 0
	global_load_lds_dwordx4 v[212:213], off
	s_waitcnt vmcnt(8)
	s_waitcnt lgkmcnt(0)
	s_setprio 0
	s_barrier
	v_mfma_f32_16x16x32_bf16 v[120:123], v[142:145], v[180:183], 0
	v_mfma_f32_16x16x32_bf16 v[112:115], v[156:159], v[180:183], 0
	v_mfma_f32_16x16x32_bf16 v[104:107], v[142:145], v[188:191], 0
	v_mfma_f32_16x16x32_bf16 v[96:99], v[156:159], v[188:191], 0
	v_mfma_f32_16x16x32_bf16 v[88:91], v[142:145], v[196:199], 0
	v_mfma_f32_16x16x32_bf16 v[80:83], v[156:159], v[196:199], 0
	v_mfma_f32_16x16x32_bf16 v[72:75], v[142:145], v[204:207], 0
	v_mfma_f32_16x16x32_bf16 v[64:67], v[156:159], v[204:207], 0
	v_mfma_f32_16x16x32_bf16 v[120:123], v[152:155], v[184:187], v[120:123]
	v_mfma_f32_16x16x32_bf16 v[112:115], v[160:163], v[184:187], v[112:115]
	v_mfma_f32_16x16x32_bf16 v[104:107], v[152:155], v[192:195], v[104:107]
	v_mfma_f32_16x16x32_bf16 v[96:99], v[160:163], v[192:195], v[96:99]
	v_mfma_f32_16x16x32_bf16 v[88:91], v[152:155], v[200:203], v[88:91]
	v_mfma_f32_16x16x32_bf16 v[80:83], v[160:163], v[200:203], v[80:83]
	v_mfma_f32_16x16x32_bf16 v[72:75], v[152:155], v[208:211], v[72:75]
	v_mfma_f32_16x16x32_bf16 v[64:67], v[160:163], v[208:211], v[64:67]
	v_mfma_f32_16x16x32_bf16 v[124:127], v[164:167], v[180:183], 0
	v_mfma_f32_16x16x32_bf16 v[116:119], v[172:175], v[180:183], 0
	v_mfma_f32_16x16x32_bf16 v[108:111], v[164:167], v[188:191], 0
	v_mfma_f32_16x16x32_bf16 v[100:103], v[172:175], v[188:191], 0
	v_mfma_f32_16x16x32_bf16 v[92:95], v[164:167], v[196:199], 0
	v_mfma_f32_16x16x32_bf16 v[84:87], v[172:175], v[196:199], 0
	v_mfma_f32_16x16x32_bf16 v[76:79], v[164:167], v[204:207], 0
	v_mfma_f32_16x16x32_bf16 v[68:71], v[172:175], v[204:207], 0
	v_mfma_f32_16x16x32_bf16 v[124:127], v[168:171], v[184:187], v[124:127]
	v_mfma_f32_16x16x32_bf16 v[116:119], v[176:179], v[184:187], v[116:119]
	v_mfma_f32_16x16x32_bf16 v[108:111], v[168:171], v[192:195], v[108:111]
	v_mfma_f32_16x16x32_bf16 v[100:103], v[176:179], v[192:195], v[100:103]
	v_mfma_f32_16x16x32_bf16 v[92:95], v[168:171], v[200:203], v[92:95]
	v_mfma_f32_16x16x32_bf16 v[84:87], v[176:179], v[200:203], v[84:87]
	v_mfma_f32_16x16x32_bf16 v[76:79], v[168:171], v[208:211], v[76:79]
	v_mfma_f32_16x16x32_bf16 v[68:71], v[176:179], v[208:211], v[68:71]
	s_barrier
	s_setprio 1
	s_add_i32 s9, s57, s36
	v_lshl_add_u64 v[212:213], s[64:65], 0, v[132:133]
	s_mov_b32 m0, s9
	ds_read_b128 v[180:183], v151 offset:16384
	ds_read_b128 v[184:187], v151 offset:17408
	ds_read_b128 v[188:191], v151 offset:18432
	ds_read_b128 v[192:195], v151 offset:19456
	ds_read_b128 v[196:199], v151 offset:20480
	ds_read_b128 v[200:203], v151 offset:21504
	ds_read_b128 v[204:207], v151 offset:22528
	ds_read_b128 v[208:211], v151 offset:23552
	global_load_lds_dwordx4 v[212:213], off
	s_add_i32 m0, s9, 0x2000
	v_lshl_add_u64 v[214:215], s[64:65], 0, v[128:129]
	s_add_u32 s64, s64, s12
	s_addc_u32 s65, s65, s13
	s_add_i32 s9, s58, s36
	global_load_lds_dwordx4 v[214:215], off
	v_lshl_add_u64 v[216:217], s[64:65], 0, v[132:133]
	s_mov_b32 m0, s9
	v_lshl_add_u64 v[218:219], s[64:65], 0, v[128:129]
	global_load_lds_dwordx4 v[216:217], off
	s_add_i32 m0, s9, 0x2000
	v_lshl_add_u64 v[220:221], s[6:7], 0, v[134:135]
	global_load_lds_dwordx4 v[218:219], off
	s_mov_b32 m0, s44
	v_lshl_add_u64 v[222:223], s[6:7], 0, v[130:131]
	global_load_lds_dwordx4 v[220:221], off
	s_mov_b32 m0, s45
	s_nop 0
	global_load_lds_dwordx4 v[222:223], off
	s_waitcnt vmcnt(8)
	s_waitcnt lgkmcnt(0)
	s_setprio 0
	s_barrier
; #define PG8_STAGE(bufoff, gbase, voff) do { _Pragma("unroll") for (int _i = 0; _i < 2; ++_i) \
;         __builtin_amdgcn_global_load_lds((const unsigned*)((const char*)(gbase) + (voff)[_i]), (PG8_LAS unsigned*)(lds + (bufoff) + ldsw + _i * 8192), 16, 0, 0); } while (0)
; #define PG8_LDA(dst, b, h) do { _Pragma("unroll") for (int m = 0; m < 4; ++m) _Pragma("unroll") for (int k = 0; k < 2; ++k) dst[m][k] = *(const PG8_LAS bf16x8*)(lds + PG8_SA(b, h) + aoff + m * 2048 + k * 1024); } while (0)
; #define PG8_LDB(dst, b, h) do { _Pragma("unroll") for (int n = 0; n < 2; ++n) _Pragma("unroll") for (int k = 0; k < 2; ++k) dst[n][k] = *(const PG8_LAS bf16x8*)(lds + PG8_SB(b, h) + boff + n * 2048 + k * 1024); } while (0)
; #define PG8_MMA(ai, bj, At, Bt) do { __builtin_amdgcn_s_setprio(1); _Pragma("unroll") for (int m = 0; m < 4; ++m) _Pragma("unroll") for (int n = 0; n < 2; ++n) _Pragma("unroll") for (int k = 0; k < 2; ++k) \
;         acc[ai][bj][m][n] = __builtin_amdgcn_mfma_f32_16x16x32_bf16(Bt[n][k], At[m][k], acc[ai][bj][m][n], 0, 0, 0); __builtin_amdgcn_s_setprio(0); } while (0)
; #define PG8_BAR __builtin_amdgcn_s_barrier()
; template <class Epi, class Sched, bool ALIGN_EPI = false, bool SP2 = false>
; __device__ __forceinline__ void gemm_phase(PG8_LAS unsigned char* lds, const Gemm g, const Sched& S, const Epi& E, const int wid) {
;     ...
;             PG8_LDB(B0, 0, 0); PG8_LDB(B1, 0, 1); PG8_SCHED; PG8_LDA(At, 0, 0); PG8_STAGE(PG8_SA(1, 1), a1 + hstep, voffA);
;             PG8_WAIT_V(8); PG8_WAIT_L(0); PG8_BAR; PG8_MMA(0, 0, At, B0); PG8_MMA(0, 1, At, B1); PG8_BAR; PG8_SCHED;
;             PG8_LDA(At, 0, 1); PG8_STAGE(PG8_SB(0, 0), b2, voffB); PG8_STAGE(PG8_SB(0, 1), b2 + hstep, voffB); PG8_STAGE(PG8_SA(0, 0), a2, voffA);
;             PG8_WAIT_V(8); PG8_WAIT_L(0); PG8_BAR; PG8_MMA(1, 0, At, B0); PG8_MMA(1, 1, At, B1); PG8_BAR; PG8_SCHED;
;             PG8_LDB(B0, 1, 0); PG8_LDB(B1, 1, 1); PG8_SCHED; PG8_LDA(At, 1, 0); PG8_STAGE(PG8_SA(0, 1), a2 + hstep, voffA);
;             PG8_WAIT_V(8); PG8_WAIT_L(0); PG8_BAR; PG8_MMA(0, 0, At, B0); PG8_MMA(0, 1, At, B1); PG8_BAR; PG8_SCHED;
;             PG8_LDA(At, 1, 1); PG8_STAGE(PG8_SB(1, 0), b3, voffB); PG8_STAGE(PG8_SB(1, 1), b3 + hstep, voffB); PG8_STAGE(PG8_SA(1, 0), a3, voffA);
;             PG8_WAIT_V(8); PG8_WAIT_L(0); PG8_BAR; PG8_MMA(1, 0, At, B0); PG8_MMA(1, 1, At, B1); PG8_BAR; PG8_SCHED;
	v_mfma_f32_16x16x32_bf16 v[56:59], v[142:145], v[180:183], 0
	v_mfma_f32_16x16x32_bf16 v[48:51], v[156:159], v[180:183], 0
	v_mfma_f32_16x16x32_bf16 v[40:43], v[142:145], v[188:191], 0
	v_mfma_f32_16x16x32_bf16 v[32:35], v[156:159], v[188:191], 0
	v_mfma_f32_16x16x32_bf16 v[24:27], v[142:145], v[196:199], 0
	v_mfma_f32_16x16x32_bf16 v[16:19], v[156:159], v[196:199], 0
	v_mfma_f32_16x16x32_bf16 v[8:11], v[142:145], v[204:207], 0
	v_mfma_f32_16x16x32_bf16 v[4:7], v[156:159], v[204:207], 0
	v_mfma_f32_16x16x32_bf16 v[56:59], v[152:155], v[184:187], v[56:59]
	v_mfma_f32_16x16x32_bf16 v[48:51], v[160:163], v[184:187], v[48:51]
	v_mfma_f32_16x16x32_bf16 v[40:43], v[152:155], v[192:195], v[40:43]
	v_mfma_f32_16x16x32_bf16 v[32:35], v[160:163], v[192:195], v[32:35]
	v_mfma_f32_16x16x32_bf16 v[24:27], v[152:155], v[200:203], v[24:27]
	v_mfma_f32_16x16x32_bf16 v[16:19], v[160:163], v[200:203], v[16:19]
	v_mfma_f32_16x16x32_bf16 v[8:11], v[152:155], v[208:211], v[8:11]
	v_mfma_f32_16x16x32_bf16 v[4:7], v[160:163], v[208:211], v[4:7]
	v_mfma_f32_16x16x32_bf16 v[60:63], v[164:167], v[180:183], 0
	v_mfma_f32_16x16x32_bf16 v[52:55], v[172:175], v[180:183], 0
	v_mfma_f32_16x16x32_bf16 v[44:47], v[164:167], v[188:191], 0
	v_mfma_f32_16x16x32_bf16 v[36:39], v[172:175], v[188:191], 0
	v_mfma_f32_16x16x32_bf16 v[28:31], v[164:167], v[196:199], 0
	v_mfma_f32_16x16x32_bf16 v[20:23], v[172:175], v[196:199], 0
	v_mfma_f32_16x16x32_bf16 v[12:15], v[164:167], v[204:207], 0
	v_mfma_f32_16x16x32_bf16 v[0:3], v[172:175], v[204:207], 0
	v_mfma_f32_16x16x32_bf16 v[60:63], v[168:171], v[184:187], v[60:63]
	v_mfma_f32_16x16x32_bf16 v[52:55], v[176:179], v[184:187], v[52:55]
	v_mfma_f32_16x16x32_bf16 v[44:47], v[168:171], v[192:195], v[44:47]
	v_mfma_f32_16x16x32_bf16 v[36:39], v[176:179], v[192:195], v[36:39]
	v_mfma_f32_16x16x32_bf16 v[28:31], v[168:171], v[200:203], v[28:31]
	v_mfma_f32_16x16x32_bf16 v[20:23], v[176:179], v[200:203], v[20:23]
	v_mfma_f32_16x16x32_bf16 v[12:15], v[168:171], v[208:211], v[12:15]
	v_mfma_f32_16x16x32_bf16 v[0:3], v[176:179], v[208:211], v[0:3]
	s_barrier
	s_setprio 1
	s_add_i32 s9, 0, 0x18000
	s_add_i32 s33, 0, 0x1c000
	v_add_u32_e32 v160, s9, v148
	v_add_u32_e32 v176, s33, v148
	ds_read_b128 v[142:145], v160
	ds_read_b128 v[152:155], v160 offset:1024
	ds_read_b128 v[156:159], v160 offset:2048
	ds_read_b128 v[160:163], v160 offset:3072
	ds_read_b128 v[164:167], v176
	ds_read_b128 v[168:171], v176 offset:1024
	ds_read_b128 v[172:175], v176 offset:2048
	ds_read_b128 v[176:179], v176 offset:3072
	s_add_u32 s6, s6, s12
	s_addc_u32 s7, s7, s13
	s_mov_b32 m0, s46
	v_lshl_add_u64 v[224:225], s[6:7], 0, v[134:135]
	ds_read_b128 v[180:183], v151 offset:32768
	ds_read_b128 v[184:187], v151 offset:33792
	ds_read_b128 v[188:191], v151 offset:34816
	ds_read_b128 v[192:195], v151 offset:35840
	ds_read_b128 v[196:199], v151 offset:36864
	ds_read_b128 v[200:203], v151 offset:37888
	ds_read_b128 v[204:207], v151 offset:38912
	ds_read_b128 v[208:211], v151 offset:39936
	global_load_lds_dwordx4 v[224:225], off
	v_lshl_add_u64 v[224:225], s[6:7], 0, v[130:131]
	s_mov_b32 m0, s47
	s_nop 0
	global_load_lds_dwordx4 v[224:225], off
	s_waitcnt vmcnt(8)
	s_waitcnt lgkmcnt(0)
	s_setprio 0
	s_barrier
	v_mfma_f32_16x16x32_bf16 v[120:123], v[142:145], v[180:183], v[120:123]
	v_mfma_f32_16x16x32_bf16 v[112:115], v[156:159], v[180:183], v[112:115]
	v_mfma_f32_16x16x32_bf16 v[104:107], v[142:145], v[188:191], v[104:107]
	v_mfma_f32_16x16x32_bf16 v[96:99], v[156:159], v[188:191], v[96:99]
	v_mfma_f32_16x16x32_bf16 v[88:91], v[142:145], v[196:199], v[88:91]
	v_mfma_f32_16x16x32_bf16 v[80:83], v[156:159], v[196:199], v[80:83]
	v_mfma_f32_16x16x32_bf16 v[72:75], v[142:145], v[204:207], v[72:75]
	v_mfma_f32_16x16x32_bf16 v[64:67], v[156:159], v[204:207], v[64:67]
	v_mfma_f32_16x16x32_bf16 v[120:123], v[152:155], v[184:187], v[120:123]
	v_mfma_f32_16x16x32_bf16 v[112:115], v[160:163], v[184:187], v[112:115]
	v_mfma_f32_16x16x32_bf16 v[104:107], v[152:155], v[192:195], v[104:107]
	v_mfma_f32_16x16x32_bf16 v[96:99], v[160:163], v[192:195], v[96:99]
	v_mfma_f32_16x16x32_bf16 v[88:91], v[152:155], v[200:203], v[88:91]
	v_mfma_f32_16x16x32_bf16 v[80:83], v[160:163], v[200:203], v[80:83]
	v_mfma_f32_16x16x32_bf16 v[72:75], v[152:155], v[208:211], v[72:75]
	v_mfma_f32_16x16x32_bf16 v[64:67], v[160:163], v[208:211], v[64:67]
	v_mfma_f32_16x16x32_bf16 v[124:127], v[164:167], v[180:183], v[124:127]
	v_mfma_f32_16x16x32_bf16 v[116:119], v[172:175], v[180:183], v[116:119]
	v_mfma_f32_16x16x32_bf16 v[108:111], v[164:167], v[188:191], v[108:111]
	v_mfma_f32_16x16x32_bf16 v[100:103], v[172:175], v[188:191], v[100:103]
	v_mfma_f32_16x16x32_bf16 v[92:95], v[164:167], v[196:199], v[92:95]
	v_mfma_f32_16x16x32_bf16 v[84:87], v[172:175], v[196:199], v[84:87]
	v_mfma_f32_16x16x32_bf16 v[76:79], v[164:167], v[204:207], v[76:79]
	v_mfma_f32_16x16x32_bf16 v[68:71], v[172:175], v[204:207], v[68:71]
	v_mfma_f32_16x16x32_bf16 v[124:127], v[168:171], v[184:187], v[124:127]
	v_mfma_f32_16x16x32_bf16 v[116:119], v[176:179], v[184:187], v[116:119]
	v_mfma_f32_16x16x32_bf16 v[108:111], v[168:171], v[192:195], v[108:111]
	v_mfma_f32_16x16x32_bf16 v[100:103], v[176:179], v[192:195], v[100:103]
	v_mfma_f32_16x16x32_bf16 v[92:95], v[168:171], v[200:203], v[92:95]
	v_mfma_f32_16x16x32_bf16 v[84:87], v[176:179], v[200:203], v[84:87]
	v_mfma_f32_16x16x32_bf16 v[76:79], v[168:171], v[208:211], v[76:79]
	v_mfma_f32_16x16x32_bf16 v[68:71], v[176:179], v[208:211], v[68:71]
	s_barrier
; #define PG8_STAGE(bufoff, gbase, voff) do { _Pragma("unroll") for (int _i = 0; _i < 2; ++_i) \
;         __builtin_amdgcn_global_load_lds((const unsigned*)((const char*)(gbase) + (voff)[_i]), (PG8_LAS unsigned*)(lds + (bufoff) + ldsw + _i * 8192), 16, 0, 0); } while (0)
; #define PG8_LDA(dst, b, h) do { _Pragma("unroll") for (int m = 0; m < 4; ++m) _Pragma("unroll") for (int k = 0; k < 2; ++k) dst[m][k] = *(const PG8_LAS bf16x8*)(lds + PG8_SA(b, h) + aoff + m * 2048 + k * 1024); } while (0)
; #define PG8_WAIT_V(n) asm volatile("s_waitcnt vmcnt(" #n ")" ::: "memory")
; #define PG8_WAIT_L(n) asm volatile("s_waitcnt lgkmcnt(" #n ")" ::: "memory")
; #define PG8_BAR __builtin_amdgcn_s_barrier()
; template <class Epi, class Sched, bool ALIGN_EPI = false, bool SP2 = false>
; __device__ __forceinline__ void gemm_phase(PG8_LAS unsigned char* lds, const Gemm g, const Sched& S, const Epi& E, const int wid) {
;     ...
;         for (int t = 0; t < nt; t += 2) {
;             const bool last = (t == nt - 2);
;             const char* a1 = cA + (size_t)(t + 1) * kstep;
;             const char* a2 = last ? nA : cA + (size_t)(t + 2) * kstep; const char* b2 = last ? nB : cB + (size_t)(t + 2) * kstep;
;             const char* a3 = a2 + kstep; const char* b3 = b2 + kstep;
;             if (last && has_next) S.a_ready(nxt);
;             if constexpr (SP2) {
;             PG8_LDB(B0, 0, 0); PG8_LDB(B1, 0, 1); PG8_SCHED; PG8_LDA(At, 0, 0); PG8_STAGE(PG8_SA(1, 1), a1 + hstep, voffA);
;             PG8_WAIT_V(8); PG8_WAIT_L(0); PG8_BAR; PG8_MMA(0, 0, At, B0); PG8_MMA(0, 1, At, B1); PG8_BAR; PG8_SCHED;
;             PG8_LDA(At, 0, 1); PG8_STAGE(PG8_SB(0, 0), b2, voffB); PG8_STAGE(PG8_SB(0, 1), b2 + hstep, voffB); PG8_STAGE(PG8_SA(0, 0), a2, voffA);
;             PG8_WAIT_V(8); PG8_WAIT_L(0); PG8_BAR; PG8_MMA(1, 0, At, B0); PG8_MMA(1, 1, At, B1); PG8_BAR; PG8_SCHED;
;             PG8_LDB(B0, 1, 0); PG8_LDB(B1, 1, 1); PG8_SCHED; PG8_LDA(At, 1, 0); PG8_STAGE(PG8_SA(0, 1), a2 + hstep, voffA);
;             PG8_WAIT_V(8); PG8_WAIT_L(0); PG8_BAR; PG8_MMA(0, 0, At, B0); PG8_MMA(0, 1, At, B1); PG8_BAR; PG8_SCHED;
;             PG8_LDA(At, 1, 1); PG8_STAGE(PG8_SB(1, 0), b3, voffB); PG8_STAGE(PG8_SB(1, 1), b3 + hstep, voffB); PG8_STAGE(PG8_SA(1, 0), a3, voffA);
;             PG8_WAIT_V(8); PG8_WAIT_L(0); PG8_BAR; PG8_MMA(1, 0, At, B0); PG8_MMA(1, 1, At, B1); PG8_BAR; PG8_SCHED;
	s_setprio 1
	s_add_i32 s6, s9, s36
	v_lshl_add_u64 v[212:213], v[212:213], 0, s[20:21]
	s_mov_b32 m0, s6
	ds_read_b128 v[180:183], v151 offset:49152
	ds_read_b128 v[184:187], v151 offset:50176
	ds_read_b128 v[188:191], v151 offset:51200
	ds_read_b128 v[192:195], v151 offset:52224
	ds_read_b128 v[196:199], v151 offset:53248
	ds_read_b128 v[200:203], v151 offset:54272
	ds_read_b128 v[204:207], v151 offset:55296
	ds_read_b128 v[208:211], v151 offset:56320
	global_load_lds_dwordx4 v[212:213], off
	v_lshl_add_u64 v[212:213], v[214:215], 0, s[20:21]
	s_add_i32 m0, s6, 0x2000
	s_add_i32 s6, s33, s36
	global_load_lds_dwordx4 v[212:213], off
	v_lshl_add_u64 v[212:213], v[216:217], 0, s[20:21]
	s_mov_b32 m0, s6
	s_nop 0
	global_load_lds_dwordx4 v[212:213], off
	v_lshl_add_u64 v[212:213], v[218:219], 0, s[20:21]
	s_add_i32 m0, s6, 0x2000
	s_nop 0
	global_load_lds_dwordx4 v[212:213], off
	v_lshl_add_u64 v[212:213], v[220:221], 0, s[20:21]
	s_mov_b32 m0, s50
	s_nop 0
	global_load_lds_dwordx4 v[212:213], off
	v_lshl_add_u64 v[212:213], v[222:223], 0, s[20:21]
	s_mov_b32 m0, s51
	s_nop 0
	global_load_lds_dwordx4 v[212:213], off
	s_waitcnt vmcnt(8)
	s_waitcnt lgkmcnt(0)
	s_setprio 0
	s_barrier
	v_mfma_f32_16x16x32_bf16 v[56:59], v[142:145], v[180:183], v[56:59]
	v_mfma_f32_16x16x32_bf16 v[48:51], v[156:159], v[180:183], v[48:51]
	v_mfma_f32_16x16x32_bf16 v[40:43], v[142:145], v[188:191], v[40:43]
	v_mfma_f32_16x16x32_bf16 v[32:35], v[156:159], v[188:191], v[32:35]
	v_mfma_f32_16x16x32_bf16 v[24:27], v[142:145], v[196:199], v[24:27]
	v_mfma_f32_16x16x32_bf16 v[16:19], v[156:159], v[196:199], v[16:19]
	v_mfma_f32_16x16x32_bf16 v[8:11], v[142:145], v[204:207], v[8:11]
	v_mfma_f32_16x16x32_bf16 v[4:7], v[156:159], v[204:207], v[4:7]
	v_mfma_f32_16x16x32_bf16 v[56:59], v[152:155], v[184:187], v[56:59]
	v_mfma_f32_16x16x32_bf16 v[48:51], v[160:163], v[184:187], v[48:51]
	v_mfma_f32_16x16x32_bf16 v[40:43], v[152:155], v[192:195], v[40:43]
	v_mfma_f32_16x16x32_bf16 v[32:35], v[160:163], v[192:195], v[32:35]
	v_mfma_f32_16x16x32_bf16 v[24:27], v[152:155], v[200:203], v[24:27]
	v_mfma_f32_16x16x32_bf16 v[16:19], v[160:163], v[200:203], v[16:19]
	v_mfma_f32_16x16x32_bf16 v[8:11], v[152:155], v[208:211], v[8:11]
	v_mfma_f32_16x16x32_bf16 v[4:7], v[160:163], v[208:211], v[4:7]
	v_mfma_f32_16x16x32_bf16 v[60:63], v[164:167], v[180:183], v[60:63]
	v_mfma_f32_16x16x32_bf16 v[52:55], v[172:175], v[180:183], v[52:55]
	v_mfma_f32_16x16x32_bf16 v[44:47], v[164:167], v[188:191], v[44:47]
	v_mfma_f32_16x16x32_bf16 v[36:39], v[172:175], v[188:191], v[36:39]
	v_mfma_f32_16x16x32_bf16 v[28:31], v[164:167], v[196:199], v[28:31]
	v_mfma_f32_16x16x32_bf16 v[20:23], v[172:175], v[196:199], v[20:23]
	v_mfma_f32_16x16x32_bf16 v[12:15], v[164:167], v[204:207], v[12:15]
	v_mfma_f32_16x16x32_bf16 v[0:3], v[172:175], v[204:207], v[0:3]
	v_mfma_f32_16x16x32_bf16 v[60:63], v[168:171], v[184:187], v[60:63]
	v_mfma_f32_16x16x32_bf16 v[52:55], v[176:179], v[184:187], v[52:55]
	v_mfma_f32_16x16x32_bf16 v[44:47], v[168:171], v[192:195], v[44:47]
	v_mfma_f32_16x16x32_bf16 v[36:39], v[176:179], v[192:195], v[36:39]
	v_mfma_f32_16x16x32_bf16 v[28:31], v[168:171], v[200:203], v[28:31]
	v_mfma_f32_16x16x32_bf16 v[20:23], v[176:179], v[200:203], v[20:23]
	v_mfma_f32_16x16x32_bf16 v[12:15], v[168:171], v[208:211], v[12:15]
	v_mfma_f32_16x16x32_bf16 v[0:3], v[176:179], v[208:211], v[0:3]
	s_barrier
	s_setprio 1
	s_add_u32 s4, s4, 0x100
	s_addc_u32 s5, s5, 0
	s_add_u32 s0, s0, 0x100
	s_addc_u32 s1, s1, 0
	s_cmp_ge_i32 s8, s52
	s_mov_b32 s6, s8
	s_cbranch_scc1 .LBB0_1496
.LBB0_1495:
	ds_read_b128 v[142:145], v149
	ds_read_b128 v[152:155], v149 offset:1024
	ds_read_b128 v[156:159], v149 offset:2048
	ds_read_b128 v[160:163], v149 offset:3072
	ds_read_b128 v[164:167], v150
	ds_read_b128 v[168:171], v150 offset:1024
	ds_read_b128 v[172:175], v150 offset:2048
	ds_read_b128 v[176:179], v150 offset:3072
	s_add_i32 s8, s6, 2
	s_add_u32 s9, s4, 0x80
	s_addc_u32 s7, s5, 0
	s_cmp_eq_u32 s55, s6
	s_cselect_b32 s6, s26, s9
	s_cselect_b32 s7, s27, s7
	s_cselect_b32 s65, s29, s1
	s_cselect_b32 s64, s28, s0
	v_lshl_add_u64 v[212:213], s[4:5], 0, v[136:137]
	s_add_i32 m0, s44, 0xc000
	ds_read_b128 v[180:183], v151
	ds_read_b128 v[184:187], v151 offset:1024
	ds_read_b128 v[188:191], v151 offset:2048
	ds_read_b128 v[192:195], v151 offset:3072
	ds_read_b128 v[196:199], v151 offset:4096
	ds_read_b128 v[200:203], v151 offset:5120
	ds_read_b128 v[204:207], v151 offset:6144
	ds_read_b128 v[208:211], v151 offset:7168
	global_load_lds_dwordx4 v[212:213], off
	v_lshl_add_u64 v[212:213], s[4:5], 0, v[138:139]
	s_add_i32 m0, s44, 0xe000
	s_nop 0
	global_load_lds_dwordx4 v[212:213], off
	s_waitcnt vmcnt(8)
	s_waitcnt lgkmcnt(0)
	s_setprio 0
	s_barrier
; #define PG8_STAGE(bufoff, gbase, voff) do { _Pragma("unroll") for (int _i = 0; _i < 2; ++_i) \
;         __builtin_amdgcn_global_load_lds((const unsigned*)((const char*)(gbase) + (voff)[_i]), (PG8_LAS unsigned*)(lds + (bufoff) + ldsw + _i * 8192), 16, 0, 0); } while (0)
; #define PG8_LDA(dst, b, h) do { _Pragma("unroll") for (int m = 0; m < 4; ++m) _Pragma("unroll") for (int k = 0; k < 2; ++k) dst[m][k] = *(const PG8_LAS bf16x8*)(lds + PG8_SA(b, h) + aoff + m * 2048 + k * 1024); } while (0)
; #define PG8_LDB(dst, b, h) do { _Pragma("unroll") for (int n = 0; n < 2; ++n) _Pragma("unroll") for (int k = 0; k < 2; ++k) dst[n][k] = *(const PG8_LAS bf16x8*)(lds + PG8_SB(b, h) + boff + n * 2048 + k * 1024); } while (0)
; #define PG8_MMA(ai, bj, At, Bt) do { __builtin_amdgcn_s_setprio(1); _Pragma("unroll") for (int m = 0; m < 4; ++m) _Pragma("unroll") for (int n = 0; n < 2; ++n) _Pragma("unroll") for (int k = 0; k < 2; ++k) \
;         acc[ai][bj][m][n] = __builtin_amdgcn_mfma_f32_16x16x32_bf16(Bt[n][k], At[m][k], acc[ai][bj][m][n], 0, 0, 0); __builtin_amdgcn_s_setprio(0); } while (0)
; #define PG8_BAR __builtin_amdgcn_s_barrier()
; template <class Epi, class Sched, bool ALIGN_EPI = false, bool SP2 = false>
; __device__ __forceinline__ void gemm_phase(PG8_LAS unsigned char* lds, const Gemm g, const Sched& S, const Epi& E, const int wid) {
;     ...
;             PG8_LDB(B0, 0, 0); PG8_LDB(B1, 0, 1); PG8_SCHED; PG8_LDA(At, 0, 0); PG8_STAGE(PG8_SA(1, 1), a1 + hstep, voffA);
;             PG8_WAIT_V(8); PG8_WAIT_L(0); PG8_BAR; PG8_MMA(0, 0, At, B0); PG8_MMA(0, 1, At, B1); PG8_BAR; PG8_SCHED;
;             PG8_LDA(At, 0, 1); PG8_STAGE(PG8_SB(0, 0), b2, voffB); PG8_STAGE(PG8_SB(0, 1), b2 + hstep, voffB); PG8_STAGE(PG8_SA(0, 0), a2, voffA);
;             PG8_WAIT_V(8); PG8_WAIT_L(0); PG8_BAR; PG8_MMA(1, 0, At, B0); PG8_MMA(1, 1, At, B1); PG8_BAR; PG8_SCHED;
;             PG8_LDB(B0, 1, 0); PG8_LDB(B1, 1, 1); PG8_SCHED; PG8_LDA(At, 1, 0); PG8_STAGE(PG8_SA(0, 1), a2 + hstep, voffA);
;             PG8_WAIT_V(8); PG8_WAIT_L(0); PG8_BAR; PG8_MMA(0, 0, At, B0); PG8_MMA(0, 1, At, B1); PG8_BAR; PG8_SCHED;
;             PG8_LDA(At, 1, 1); PG8_STAGE(PG8_SB(1, 0), b3, voffB); PG8_STAGE(PG8_SB(1, 1), b3 + hstep, voffB); PG8_STAGE(PG8_SA(1, 0), a3, voffA);
;             PG8_WAIT_V(8); PG8_WAIT_L(0); PG8_BAR; PG8_MMA(1, 0, At, B0); PG8_MMA(1, 1, At, B1); PG8_BAR; PG8_SCHED;
	v_mfma_f32_16x16x32_bf16 v[120:123], v[142:145], v[180:183], v[120:123]
	v_mfma_f32_16x16x32_bf16 v[112:115], v[156:159], v[180:183], v[112:115]
	v_mfma_f32_16x16x32_bf16 v[104:107], v[142:145], v[188:191], v[104:107]
	v_mfma_f32_16x16x32_bf16 v[96:99], v[156:159], v[188:191], v[96:99]
	v_mfma_f32_16x16x32_bf16 v[88:91], v[142:145], v[196:199], v[88:91]
	v_mfma_f32_16x16x32_bf16 v[80:83], v[156:159], v[196:199], v[80:83]
	v_mfma_f32_16x16x32_bf16 v[72:75], v[142:145], v[204:207], v[72:75]
	v_mfma_f32_16x16x32_bf16 v[64:67], v[156:159], v[204:207], v[64:67]
	v_mfma_f32_16x16x32_bf16 v[120:123], v[152:155], v[184:187], v[120:123]
	v_mfma_f32_16x16x32_bf16 v[112:115], v[160:163], v[184:187], v[112:115]
	v_mfma_f32_16x16x32_bf16 v[104:107], v[152:155], v[192:195], v[104:107]
	v_mfma_f32_16x16x32_bf16 v[96:99], v[160:163], v[192:195], v[96:99]
	v_mfma_f32_16x16x32_bf16 v[88:91], v[152:155], v[200:203], v[88:91]
	v_mfma_f32_16x16x32_bf16 v[80:83], v[160:163], v[200:203], v[80:83]
	v_mfma_f32_16x16x32_bf16 v[72:75], v[152:155], v[208:211], v[72:75]
	v_mfma_f32_16x16x32_bf16 v[64:67], v[160:163], v[208:211], v[64:67]
	v_mfma_f32_16x16x32_bf16 v[124:127], v[164:167], v[180:183], v[124:127]
	v_mfma_f32_16x16x32_bf16 v[116:119], v[172:175], v[180:183], v[116:119]
	v_mfma_f32_16x16x32_bf16 v[108:111], v[164:167], v[188:191], v[108:111]
	v_mfma_f32_16x16x32_bf16 v[100:103], v[172:175], v[188:191], v[100:103]
	v_mfma_f32_16x16x32_bf16 v[92:95], v[164:167], v[196:199], v[92:95]
	v_mfma_f32_16x16x32_bf16 v[84:87], v[172:175], v[196:199], v[84:87]
	v_mfma_f32_16x16x32_bf16 v[76:79], v[164:167], v[204:207], v[76:79]
	v_mfma_f32_16x16x32_bf16 v[68:71], v[172:175], v[204:207], v[68:71]
	v_mfma_f32_16x16x32_bf16 v[124:127], v[168:171], v[184:187], v[124:127]
	v_mfma_f32_16x16x32_bf16 v[116:119], v[176:179], v[184:187], v[116:119]
	v_mfma_f32_16x16x32_bf16 v[108:111], v[168:171], v[192:195], v[108:111]
	v_mfma_f32_16x16x32_bf16 v[100:103], v[176:179], v[192:195], v[100:103]
	v_mfma_f32_16x16x32_bf16 v[92:95], v[168:171], v[200:203], v[92:95]
	v_mfma_f32_16x16x32_bf16 v[84:87], v[176:179], v[200:203], v[84:87]
	v_mfma_f32_16x16x32_bf16 v[76:79], v[168:171], v[208:211], v[76:79]
	v_mfma_f32_16x16x32_bf16 v[68:71], v[176:179], v[208:211], v[68:71]
	s_barrier
	s_setprio 1
	s_add_i32 s9, s57, s36
	v_lshl_add_u64 v[212:213], s[64:65], 0, v[132:133]
	s_mov_b32 m0, s9
	ds_read_b128 v[180:183], v151 offset:16384
	ds_read_b128 v[184:187], v151 offset:17408
	ds_read_b128 v[188:191], v151 offset:18432
	ds_read_b128 v[192:195], v151 offset:19456
	ds_read_b128 v[196:199], v151 offset:20480
	ds_read_b128 v[200:203], v151 offset:21504
	ds_read_b128 v[204:207], v151 offset:22528
	ds_read_b128 v[208:211], v151 offset:23552
	global_load_lds_dwordx4 v[212:213], off
	s_add_i32 m0, s9, 0x2000
	v_lshl_add_u64 v[214:215], s[64:65], 0, v[128:129]
	s_add_u32 s64, s64, s12
	s_addc_u32 s65, s65, s13
	s_add_i32 s9, s58, s36
	global_load_lds_dwordx4 v[214:215], off
	v_lshl_add_u64 v[216:217], s[64:65], 0, v[132:133]
	s_mov_b32 m0, s9
	v_lshl_add_u64 v[218:219], s[64:65], 0, v[128:129]
	global_load_lds_dwordx4 v[216:217], off
	s_add_i32 m0, s9, 0x2000
	v_lshl_add_u64 v[220:221], s[6:7], 0, v[134:135]
	global_load_lds_dwordx4 v[218:219], off
	s_mov_b32 m0, s44
	v_lshl_add_u64 v[222:223], s[6:7], 0, v[130:131]
	global_load_lds_dwordx4 v[220:221], off
	s_mov_b32 m0, s45
	s_nop 0
	global_load_lds_dwordx4 v[222:223], off
	s_waitcnt vmcnt(8)
	s_waitcnt lgkmcnt(0)
	s_setprio 0
	s_barrier
	v_mfma_f32_16x16x32_bf16 v[56:59], v[142:145], v[180:183], v[56:59]
	v_mfma_f32_16x16x32_bf16 v[48:51], v[156:159], v[180:183], v[48:51]
	v_mfma_f32_16x16x32_bf16 v[40:43], v[142:145], v[188:191], v[40:43]
	v_mfma_f32_16x16x32_bf16 v[32:35], v[156:159], v[188:191], v[32:35]
	v_mfma_f32_16x16x32_bf16 v[24:27], v[142:145], v[196:199], v[24:27]
	v_mfma_f32_16x16x32_bf16 v[16:19], v[156:159], v[196:199], v[16:19]
	v_mfma_f32_16x16x32_bf16 v[8:11], v[142:145], v[204:207], v[8:11]
	v_mfma_f32_16x16x32_bf16 v[4:7], v[156:159], v[204:207], v[4:7]
	v_mfma_f32_16x16x32_bf16 v[56:59], v[152:155], v[184:187], v[56:59]
	v_mfma_f32_16x16x32_bf16 v[48:51], v[160:163], v[184:187], v[48:51]
	v_mfma_f32_16x16x32_bf16 v[40:43], v[152:155], v[192:195], v[40:43]
	v_mfma_f32_16x16x32_bf16 v[32:35], v[160:163], v[192:195], v[32:35]
	v_mfma_f32_16x16x32_bf16 v[24:27], v[152:155], v[200:203], v[24:27]
	v_mfma_f32_16x16x32_bf16 v[16:19], v[160:163], v[200:203], v[16:19]
	v_mfma_f32_16x16x32_bf16 v[8:11], v[152:155], v[208:211], v[8:11]
	v_mfma_f32_16x16x32_bf16 v[4:7], v[160:163], v[208:211], v[4:7]
	v_mfma_f32_16x16x32_bf16 v[60:63], v[164:167], v[180:183], v[60:63]
	v_mfma_f32_16x16x32_bf16 v[52:55], v[172:175], v[180:183], v[52:55]
	v_mfma_f32_16x16x32_bf16 v[44:47], v[164:167], v[188:191], v[44:47]
	v_mfma_f32_16x16x32_bf16 v[36:39], v[172:175], v[188:191], v[36:39]
	v_mfma_f32_16x16x32_bf16 v[28:31], v[164:167], v[196:199], v[28:31]
	v_mfma_f32_16x16x32_bf16 v[20:23], v[172:175], v[196:199], v[20:23]
	v_mfma_f32_16x16x32_bf16 v[12:15], v[164:167], v[204:207], v[12:15]
	v_mfma_f32_16x16x32_bf16 v[0:3], v[172:175], v[204:207], v[0:3]
	v_mfma_f32_16x16x32_bf16 v[60:63], v[168:171], v[184:187], v[60:63]
	v_mfma_f32_16x16x32_bf16 v[52:55], v[176:179], v[184:187], v[52:55]
	v_mfma_f32_16x16x32_bf16 v[44:47], v[168:171], v[192:195], v[44:47]
	v_mfma_f32_16x16x32_bf16 v[36:39], v[176:179], v[192:195], v[36:39]
	v_mfma_f32_16x16x32_bf16 v[28:31], v[168:171], v[200:203], v[28:31]
	v_mfma_f32_16x16x32_bf16 v[20:23], v[176:179], v[200:203], v[20:23]
	v_mfma_f32_16x16x32_bf16 v[12:15], v[168:171], v[208:211], v[12:15]
	v_mfma_f32_16x16x32_bf16 v[0:3], v[176:179], v[208:211], v[0:3]
	s_barrier
; #define PG8_STAGE(bufoff, gbase, voff) do { _Pragma("unroll") for (int _i = 0; _i < 2; ++_i) \
;         __builtin_amdgcn_global_load_lds((const unsigned*)((const char*)(gbase) + (voff)[_i]), (PG8_LAS unsigned*)(lds + (bufoff) + ldsw + _i * 8192), 16, 0, 0); } while (0)
; #define PG8_LDA(dst, b, h) do { _Pragma("unroll") for (int m = 0; m < 4; ++m) _Pragma("unroll") for (int k = 0; k < 2; ++k) dst[m][k] = *(const PG8_LAS bf16x8*)(lds + PG8_SA(b, h) + aoff + m * 2048 + k * 1024); } while (0)
; #define PG8_WAIT_V(n) asm volatile("s_waitcnt vmcnt(" #n ")" ::: "memory")
; #define PG8_WAIT_L(n) asm volatile("s_waitcnt lgkmcnt(" #n ")" ::: "memory")
; #define PG8_BAR __builtin_amdgcn_s_barrier()
; template <class Epi, class Sched, bool ALIGN_EPI = false, bool SP2 = false>
; __device__ __forceinline__ void gemm_phase(PG8_LAS unsigned char* lds, const Gemm g, const Sched& S, const Epi& E, const int wid) {
;     ...
;         for (int t = 0; t < nt; t += 2) {
;             const bool last = (t == nt - 2);
;             const char* a1 = cA + (size_t)(t + 1) * kstep;
;             const char* a2 = last ? nA : cA + (size_t)(t + 2) * kstep; const char* b2 = last ? nB : cB + (size_t)(t + 2) * kstep;
;             const char* a3 = a2 + kstep; const char* b3 = b2 + kstep;
;             if (last && has_next) S.a_ready(nxt);
;             if constexpr (SP2) {
;             PG8_LDB(B0, 0, 0); PG8_LDB(B1, 0, 1); PG8_SCHED; PG8_LDA(At, 0, 0); PG8_STAGE(PG8_SA(1, 1), a1 + hstep, voffA);
;             PG8_WAIT_V(8); PG8_WAIT_L(0); PG8_BAR; PG8_MMA(0, 0, At, B0); PG8_MMA(0, 1, At, B1); PG8_BAR; PG8_SCHED;
;             PG8_LDA(At, 0, 1); PG8_STAGE(PG8_SB(0, 0), b2, voffB); PG8_STAGE(PG8_SB(0, 1), b2 + hstep, voffB); PG8_STAGE(PG8_SA(0, 0), a2, voffA);
;             PG8_WAIT_V(8); PG8_WAIT_L(0); PG8_BAR; PG8_MMA(1, 0, At, B0); PG8_MMA(1, 1, At, B1); PG8_BAR; PG8_SCHED;
;             PG8_LDB(B0, 1, 0); PG8_LDB(B1, 1, 1); PG8_SCHED; PG8_LDA(At, 1, 0); PG8_STAGE(PG8_SA(0, 1), a2 + hstep, voffA);
;             PG8_WAIT_V(8); PG8_WAIT_L(0); PG8_BAR; PG8_MMA(0, 0, At, B0); PG8_MMA(0, 1, At, B1); PG8_BAR; PG8_SCHED;
;             PG8_LDA(At, 1, 1); PG8_STAGE(PG8_SB(1, 0), b3, voffB); PG8_STAGE(PG8_SB(1, 1), b3 + hstep, voffB); PG8_STAGE(PG8_SA(1, 0), a3, voffA);
;             PG8_WAIT_V(8); PG8_WAIT_L(0); PG8_BAR; PG8_MMA(1, 0, At, B0); PG8_MMA(1, 1, At, B1); PG8_BAR; PG8_SCHED;
	s_setprio 1
	s_add_i32 s9, 0, 0x18000
	s_add_i32 s33, 0, 0x1c000
	v_add_u32_e32 v160, s9, v148
	v_add_u32_e32 v176, s33, v148
	ds_read_b128 v[142:145], v160
	ds_read_b128 v[152:155], v160 offset:1024
	ds_read_b128 v[156:159], v160 offset:2048
	ds_read_b128 v[160:163], v160 offset:3072
	ds_read_b128 v[164:167], v176
	ds_read_b128 v[168:171], v176 offset:1024
	ds_read_b128 v[172:175], v176 offset:2048
	ds_read_b128 v[176:179], v176 offset:3072
	s_add_u32 s6, s6, s12
	s_addc_u32 s7, s7, s13
	s_mov_b32 m0, s46
	v_lshl_add_u64 v[224:225], s[6:7], 0, v[134:135]
	ds_read_b128 v[180:183], v151 offset:32768
	ds_read_b128 v[184:187], v151 offset:33792
	ds_read_b128 v[188:191], v151 offset:34816
	ds_read_b128 v[192:195], v151 offset:35840
	ds_read_b128 v[196:199], v151 offset:36864
	ds_read_b128 v[200:203], v151 offset:37888
	ds_read_b128 v[204:207], v151 offset:38912
	ds_read_b128 v[208:211], v151 offset:39936
	global_load_lds_dwordx4 v[224:225], off
	v_lshl_add_u64 v[224:225], s[6:7], 0, v[130:131]
	s_mov_b32 m0, s47
	s_nop 0
	global_load_lds_dwordx4 v[224:225], off
	s_waitcnt vmcnt(8)
	s_waitcnt lgkmcnt(0)
	s_setprio 0
	s_barrier
	v_mfma_f32_16x16x32_bf16 v[120:123], v[142:145], v[180:183], v[120:123]
	v_mfma_f32_16x16x32_bf16 v[112:115], v[156:159], v[180:183], v[112:115]
	v_mfma_f32_16x16x32_bf16 v[104:107], v[142:145], v[188:191], v[104:107]
	v_mfma_f32_16x16x32_bf16 v[96:99], v[156:159], v[188:191], v[96:99]
	v_mfma_f32_16x16x32_bf16 v[88:91], v[142:145], v[196:199], v[88:91]
	v_mfma_f32_16x16x32_bf16 v[80:83], v[156:159], v[196:199], v[80:83]
	v_mfma_f32_16x16x32_bf16 v[72:75], v[142:145], v[204:207], v[72:75]
	v_mfma_f32_16x16x32_bf16 v[64:67], v[156:159], v[204:207], v[64:67]
	v_mfma_f32_16x16x32_bf16 v[120:123], v[152:155], v[184:187], v[120:123]
	v_mfma_f32_16x16x32_bf16 v[112:115], v[160:163], v[184:187], v[112:115]
	v_mfma_f32_16x16x32_bf16 v[104:107], v[152:155], v[192:195], v[104:107]
	v_mfma_f32_16x16x32_bf16 v[96:99], v[160:163], v[192:195], v[96:99]
	v_mfma_f32_16x16x32_bf16 v[88:91], v[152:155], v[200:203], v[88:91]
	v_mfma_f32_16x16x32_bf16 v[80:83], v[160:163], v[200:203], v[80:83]
	v_mfma_f32_16x16x32_bf16 v[72:75], v[152:155], v[208:211], v[72:75]
	v_mfma_f32_16x16x32_bf16 v[64:67], v[160:163], v[208:211], v[64:67]
	v_mfma_f32_16x16x32_bf16 v[124:127], v[164:167], v[180:183], v[124:127]
	v_mfma_f32_16x16x32_bf16 v[116:119], v[172:175], v[180:183], v[116:119]
	v_mfma_f32_16x16x32_bf16 v[108:111], v[164:167], v[188:191], v[108:111]
	v_mfma_f32_16x16x32_bf16 v[100:103], v[172:175], v[188:191], v[100:103]
	v_mfma_f32_16x16x32_bf16 v[92:95], v[164:167], v[196:199], v[92:95]
	v_mfma_f32_16x16x32_bf16 v[84:87], v[172:175], v[196:199], v[84:87]
	v_mfma_f32_16x16x32_bf16 v[76:79], v[164:167], v[204:207], v[76:79]
	v_mfma_f32_16x16x32_bf16 v[68:71], v[172:175], v[204:207], v[68:71]
	v_mfma_f32_16x16x32_bf16 v[124:127], v[168:171], v[184:187], v[124:127]
	v_mfma_f32_16x16x32_bf16 v[116:119], v[176:179], v[184:187], v[116:119]
	v_mfma_f32_16x16x32_bf16 v[108:111], v[168:171], v[192:195], v[108:111]
	v_mfma_f32_16x16x32_bf16 v[100:103], v[176:179], v[192:195], v[100:103]
	v_mfma_f32_16x16x32_bf16 v[92:95], v[168:171], v[200:203], v[92:95]
	v_mfma_f32_16x16x32_bf16 v[84:87], v[176:179], v[200:203], v[84:87]
	v_mfma_f32_16x16x32_bf16 v[76:79], v[168:171], v[208:211], v[76:79]
	v_mfma_f32_16x16x32_bf16 v[68:71], v[176:179], v[208:211], v[68:71]
	s_barrier
	s_setprio 1
	s_add_i32 s6, s9, s36
	v_lshl_add_u64 v[212:213], v[212:213], 0, s[20:21]
	s_mov_b32 m0, s6
	ds_read_b128 v[180:183], v151 offset:49152
	ds_read_b128 v[184:187], v151 offset:50176
	ds_read_b128 v[188:191], v151 offset:51200
	ds_read_b128 v[192:195], v151 offset:52224
	ds_read_b128 v[196:199], v151 offset:53248
	ds_read_b128 v[200:203], v151 offset:54272
	ds_read_b128 v[204:207], v151 offset:55296
	ds_read_b128 v[208:211], v151 offset:56320
	global_load_lds_dwordx4 v[212:213], off
	v_lshl_add_u64 v[212:213], v[214:215], 0, s[20:21]
	s_add_i32 m0, s6, 0x2000
	s_add_i32 s6, s33, s36
	global_load_lds_dwordx4 v[212:213], off
	v_lshl_add_u64 v[212:213], v[216:217], 0, s[20:21]
	s_mov_b32 m0, s6
	s_nop 0
	global_load_lds_dwordx4 v[212:213], off
	v_lshl_add_u64 v[212:213], v[218:219], 0, s[20:21]
	s_add_i32 m0, s6, 0x2000
	s_nop 0
	global_load_lds_dwordx4 v[212:213], off
	v_lshl_add_u64 v[212:213], v[220:221], 0, s[20:21]
	s_mov_b32 m0, s50
	s_nop 0
	global_load_lds_dwordx4 v[212:213], off
	v_lshl_add_u64 v[212:213], v[222:223], 0, s[20:21]
	s_mov_b32 m0, s51
	s_nop 0
	global_load_lds_dwordx4 v[212:213], off
	s_waitcnt vmcnt(8)
	s_waitcnt lgkmcnt(0)
	s_setprio 0
	s_barrier
	v_mfma_f32_16x16x32_bf16 v[56:59], v[142:145], v[180:183], v[56:59]
	v_mfma_f32_16x16x32_bf16 v[48:51], v[156:159], v[180:183], v[48:51]
	v_mfma_f32_16x16x32_bf16 v[40:43], v[142:145], v[188:191], v[40:43]
	v_mfma_f32_16x16x32_bf16 v[32:35], v[156:159], v[188:191], v[32:35]
	v_mfma_f32_16x16x32_bf16 v[24:27], v[142:145], v[196:199], v[24:27]
	v_mfma_f32_16x16x32_bf16 v[16:19], v[156:159], v[196:199], v[16:19]
	v_mfma_f32_16x16x32_bf16 v[8:11], v[142:145], v[204:207], v[8:11]
	v_mfma_f32_16x16x32_bf16 v[4:7], v[156:159], v[204:207], v[4:7]
	v_mfma_f32_16x16x32_bf16 v[56:59], v[152:155], v[184:187], v[56:59]
	v_mfma_f32_16x16x32_bf16 v[48:51], v[160:163], v[184:187], v[48:51]
	v_mfma_f32_16x16x32_bf16 v[40:43], v[152:155], v[192:195], v[40:43]
	v_mfma_f32_16x16x32_bf16 v[32:35], v[160:163], v[192:195], v[32:35]
	v_mfma_f32_16x16x32_bf16 v[24:27], v[152:155], v[200:203], v[24:27]
	v_mfma_f32_16x16x32_bf16 v[16:19], v[160:163], v[200:203], v[16:19]
	v_mfma_f32_16x16x32_bf16 v[8:11], v[152:155], v[208:211], v[8:11]
	v_mfma_f32_16x16x32_bf16 v[4:7], v[160:163], v[208:211], v[4:7]
	v_mfma_f32_16x16x32_bf16 v[60:63], v[164:167], v[180:183], v[60:63]
	v_mfma_f32_16x16x32_bf16 v[52:55], v[172:175], v[180:183], v[52:55]
	v_mfma_f32_16x16x32_bf16 v[44:47], v[164:167], v[188:191], v[44:47]
	v_mfma_f32_16x16x32_bf16 v[36:39], v[172:175], v[188:191], v[36:39]
	v_mfma_f32_16x16x32_bf16 v[28:31], v[164:167], v[196:199], v[28:31]
	v_mfma_f32_16x16x32_bf16 v[20:23], v[172:175], v[196:199], v[20:23]
	v_mfma_f32_16x16x32_bf16 v[12:15], v[164:167], v[204:207], v[12:15]
	v_mfma_f32_16x16x32_bf16 v[0:3], v[172:175], v[204:207], v[0:3]
	v_mfma_f32_16x16x32_bf16 v[60:63], v[168:171], v[184:187], v[60:63]
	v_mfma_f32_16x16x32_bf16 v[52:55], v[176:179], v[184:187], v[52:55]
	v_mfma_f32_16x16x32_bf16 v[44:47], v[168:171], v[192:195], v[44:47]
	v_mfma_f32_16x16x32_bf16 v[36:39], v[176:179], v[192:195], v[36:39]
	v_mfma_f32_16x16x32_bf16 v[28:31], v[168:171], v[200:203], v[28:31]
	v_mfma_f32_16x16x32_bf16 v[20:23], v[176:179], v[200:203], v[20:23]
	v_mfma_f32_16x16x32_bf16 v[12:15], v[168:171], v[208:211], v[12:15]
	v_mfma_f32_16x16x32_bf16 v[0:3], v[176:179], v[208:211], v[0:3]
	s_barrier
	s_setprio 1
	s_add_u32 s4, s4, 0x100
	s_addc_u32 s5, s5, 0
	s_add_u32 s0, s0, 0x100
	s_addc_u32 s1, s1, 0
	s_cmp_ge_i32 s8, s52
	s_mov_b32 s6, s8
	s_cbranch_scc0 .LBB0_1495

; #define PG8_STAGE(bufoff, gbase, voff) do { _Pragma("unroll") for (int _i = 0; _i < 2; ++_i) \
;         __builtin_amdgcn_global_load_lds((const unsigned*)((const char*)(gbase) + (voff)[_i]), (PG8_LAS unsigned*)(lds + (bufoff) + ldsw + _i * 8192), 16, 0, 0); } while (0)
; #define PG8_WAIT_V(n) asm volatile("s_waitcnt vmcnt(" #n ")" ::: "memory")
; #define PG8_WAIT_L(n) asm volatile("s_waitcnt lgkmcnt(" #n ")" ::: "memory")
; #define PG8_BAR __builtin_amdgcn_s_barrier()
; template <class Epi, class Sched, bool ALIGN_EPI = false, bool SP2 = false>
; __device__ __forceinline__ void gemm_phase(PG8_LAS unsigned char* lds, const Gemm g, const Sched& S, const Epi& E, const int wid) {
;     ...
;     for (;;) {
;         const bool has_next = S.next(ui + 1, nxt);
;         const char* nA = has_next ? (const char*)g.A + (size_t)nxt.pm * tstep : cA; const char* nB = has_next ? (const char*)g.Bt + (size_t)nxt.pn * tstep : cB;
;         for (int t = 0; t < nt; t += 2) {
;             const bool last = (t == nt - 2);
;             const char* a1 = cA + (size_t)(t + 1) * kstep;
;             const char* a2 = last ? nA : cA + (size_t)(t + 2) * kstep; const char* b2 = last ? nB : cB + (size_t)(t + 2) * kstep;
;             const char* a3 = a2 + kstep; const char* b3 = b2 + kstep;
;             if (last && has_next) S.a_ready(nxt);
;             if constexpr (SP2) {
;             PG8_LDB(B0, 0, 0); PG8_LDB(B1, 0, 1); PG8_SCHED; PG8_LDA(At, 0, 0); PG8_STAGE(PG8_SA(1, 1), a1 + hstep, voffA);
;             PG8_WAIT_V(8); PG8_WAIT_L(0); PG8_BAR; PG8_MMA(0, 0, At, B0); PG8_MMA(0, 1, At, B1); PG8_BAR; PG8_SCHED;
;             PG8_LDA(At, 0, 1); PG8_STAGE(PG8_SB(0, 0), b2, voffB); PG8_STAGE(PG8_SB(0, 1), b2 + hstep, voffB); PG8_STAGE(PG8_SA(0, 0), a2, voffA);
;             PG8_WAIT_V(8); PG8_WAIT_L(0); PG8_BAR; PG8_MMA(1, 0, At, B0); PG8_MMA(1, 1, At, B1); PG8_BAR; PG8_SCHED;
;             PG8_LDB(B0, 1, 0); PG8_LDB(B1, 1, 1); PG8_SCHED; PG8_LDA(At, 1, 0); PG8_STAGE(PG8_SA(0, 1), a2 + hstep, voffA);
;             PG8_WAIT_V(8); PG8_WAIT_L(0); PG8_BAR; PG8_MMA(0, 0, At, B0); PG8_MMA(0, 1, At, B1); PG8_BAR; PG8_SCHED;
;             PG8_LDA(At, 1, 1); PG8_STAGE(PG8_SB(1, 0), b3, voffB); PG8_STAGE(PG8_SB(1, 1), b3 + hstep, voffB); PG8_STAGE(PG8_SA(1, 0), a3, voffA);
;             PG8_WAIT_V(8); PG8_WAIT_L(0); PG8_BAR; PG8_MMA(1, 0, At, B0); PG8_MMA(1, 1, At, B1); PG8_BAR; PG8_SCHED;
.LBB0_1572:
	s_andn2_b64 vcc, exec, s[18:19]
	s_cbranch_vccnz .Lz_FFN2
	s_add_u32 s40, s40, 0x80
	s_addc_u32 s41, s41, 0
	s_add_u32 s73, s42, 0x100
	s_addc_u32 s74, s43, 0
	s_mov_b32 s42, 0
	ds_read_b128 v[146:149], v143
	ds_read_b128 v[150:153], v143 offset:1024
	ds_read_b128 v[154:157], v143 offset:2048
	ds_read_b128 v[158:161], v143 offset:3072
	ds_read_b128 v[162:165], v144
	ds_read_b128 v[166:169], v144 offset:1024
	ds_read_b128 v[170:173], v144 offset:2048
	ds_read_b128 v[174:177], v144 offset:3072
	s_add_i32 s75, s42, 2
	s_add_u32 s33, s40, 0x80
	s_addc_u32 s43, s41, 0
	s_cmp_eq_u32 s65, s42
	s_cselect_b32 s42, s2, s33
	s_cselect_b32 s43, s3, s43
	s_cselect_b32 s77, s39, s74
	s_cselect_b32 s76, s38, s73
	v_lshl_add_u64 v[138:139], s[40:41], 0, v[132:133]
	s_add_i32 m0, s55, 0xc000
	ds_read_b128 v[178:181], v145
	ds_read_b128 v[182:185], v145 offset:1024
	ds_read_b128 v[186:189], v145 offset:2048
	ds_read_b128 v[190:193], v145 offset:3072
	ds_read_b128 v[194:197], v145 offset:4096
	ds_read_b128 v[198:201], v145 offset:5120
	ds_read_b128 v[202:205], v145 offset:6144
	ds_read_b128 v[206:209], v145 offset:7168
	global_load_lds_dwordx4 v[138:139], off
	v_lshl_add_u64 v[138:139], s[40:41], 0, v[134:135]
	s_add_i32 m0, s55, 0xe000
	s_nop 0
	global_load_lds_dwordx4 v[138:139], off
	s_waitcnt vmcnt(8)
	s_waitcnt lgkmcnt(0)
	s_setprio 0
	s_barrier
	v_mfma_f32_16x16x32_bf16 v[124:127], v[146:149], v[178:181], 0
	v_mfma_f32_16x16x32_bf16 v[120:123], v[154:157], v[178:181], 0
	v_mfma_f32_16x16x32_bf16 v[108:111], v[146:149], v[186:189], 0
	v_mfma_f32_16x16x32_bf16 v[104:107], v[154:157], v[186:189], 0
	v_mfma_f32_16x16x32_bf16 v[92:95], v[146:149], v[194:197], 0
	v_mfma_f32_16x16x32_bf16 v[88:91], v[154:157], v[194:197], 0
	v_mfma_f32_16x16x32_bf16 v[76:79], v[146:149], v[202:205], 0
	v_mfma_f32_16x16x32_bf16 v[72:75], v[154:157], v[202:205], 0
	v_mfma_f32_16x16x32_bf16 v[124:127], v[150:153], v[182:185], v[124:127]
	v_mfma_f32_16x16x32_bf16 v[120:123], v[158:161], v[182:185], v[120:123]
	v_mfma_f32_16x16x32_bf16 v[108:111], v[150:153], v[190:193], v[108:111]
	v_mfma_f32_16x16x32_bf16 v[104:107], v[158:161], v[190:193], v[104:107]
	v_mfma_f32_16x16x32_bf16 v[92:95], v[150:153], v[198:201], v[92:95]
	v_mfma_f32_16x16x32_bf16 v[88:91], v[158:161], v[198:201], v[88:91]
	v_mfma_f32_16x16x32_bf16 v[76:79], v[150:153], v[206:209], v[76:79]
	v_mfma_f32_16x16x32_bf16 v[72:75], v[158:161], v[206:209], v[72:75]
	v_mfma_f32_16x16x32_bf16 v[116:119], v[162:165], v[178:181], 0
	v_mfma_f32_16x16x32_bf16 v[112:115], v[170:173], v[178:181], 0
	v_mfma_f32_16x16x32_bf16 v[100:103], v[162:165], v[186:189], 0
	v_mfma_f32_16x16x32_bf16 v[96:99], v[170:173], v[186:189], 0
	v_mfma_f32_16x16x32_bf16 v[84:87], v[162:165], v[194:197], 0
	v_mfma_f32_16x16x32_bf16 v[80:83], v[170:173], v[194:197], 0
	v_mfma_f32_16x16x32_bf16 v[68:71], v[162:165], v[202:205], 0
	v_mfma_f32_16x16x32_bf16 v[64:67], v[170:173], v[202:205], 0
	v_mfma_f32_16x16x32_bf16 v[116:119], v[166:169], v[182:185], v[116:119]
	v_mfma_f32_16x16x32_bf16 v[112:115], v[174:177], v[182:185], v[112:115]
	v_mfma_f32_16x16x32_bf16 v[100:103], v[166:169], v[190:193], v[100:103]
	v_mfma_f32_16x16x32_bf16 v[96:99], v[174:177], v[190:193], v[96:99]
	v_mfma_f32_16x16x32_bf16 v[84:87], v[166:169], v[198:201], v[84:87]
	v_mfma_f32_16x16x32_bf16 v[80:83], v[174:177], v[198:201], v[80:83]
	v_mfma_f32_16x16x32_bf16 v[68:71], v[166:169], v[206:209], v[68:71]
	v_mfma_f32_16x16x32_bf16 v[64:67], v[174:177], v[206:209], v[64:67]
	s_barrier
	s_setprio 1
	s_add_i32 s33, s67, s47
	v_lshl_add_u64 v[138:139], s[76:77], 0, v[130:131]
	s_mov_b32 m0, s33
	ds_read_b128 v[178:181], v145 offset:16384
	ds_read_b128 v[182:185], v145 offset:17408
	ds_read_b128 v[186:189], v145 offset:18432
	ds_read_b128 v[190:193], v145 offset:19456
	ds_read_b128 v[194:197], v145 offset:20480
	ds_read_b128 v[198:201], v145 offset:21504
	ds_read_b128 v[202:205], v145 offset:22528
	ds_read_b128 v[206:209], v145 offset:23552
	global_load_lds_dwordx4 v[138:139], off
	s_add_i32 m0, s33, 0x2000
	v_lshl_add_u64 v[210:211], s[76:77], 0, v[128:129]
	s_add_u32 s76, s76, s8
	s_addc_u32 s77, s77, s9
	s_add_i32 s33, s68, s47
	global_load_lds_dwordx4 v[210:211], off
	v_lshl_add_u64 v[212:213], s[76:77], 0, v[130:131]
	s_mov_b32 m0, s33
	v_lshl_add_u64 v[214:215], s[76:77], 0, v[128:129]
	global_load_lds_dwordx4 v[212:213], off
	s_add_i32 m0, s33, 0x2000
	v_lshl_add_u64 v[216:217], s[42:43], 0, v[130:131]
	global_load_lds_dwordx4 v[214:215], off
	s_mov_b32 m0, s55
	v_lshl_add_u64 v[218:219], s[42:43], 0, v[128:129]
	global_load_lds_dwordx4 v[216:217], off
	s_mov_b32 m0, s56
	s_nop 0
	global_load_lds_dwordx4 v[218:219], off
	s_waitcnt vmcnt(8)
	s_waitcnt lgkmcnt(0)
	s_setprio 0
	s_barrier
; #define PG8_STAGE(bufoff, gbase, voff) do { _Pragma("unroll") for (int _i = 0; _i < 2; ++_i) \
;         __builtin_amdgcn_global_load_lds((const unsigned*)((const char*)(gbase) + (voff)[_i]), (PG8_LAS unsigned*)(lds + (bufoff) + ldsw + _i * 8192), 16, 0, 0); } while (0)
; #define PG8_LDA(dst, b, h) do { _Pragma("unroll") for (int m = 0; m < 4; ++m) _Pragma("unroll") for (int k = 0; k < 2; ++k) dst[m][k] = *(const PG8_LAS bf16x8*)(lds + PG8_SA(b, h) + aoff + m * 2048 + k * 1024); } while (0)
; #define PG8_LDB(dst, b, h) do { _Pragma("unroll") for (int n = 0; n < 2; ++n) _Pragma("unroll") for (int k = 0; k < 2; ++k) dst[n][k] = *(const PG8_LAS bf16x8*)(lds + PG8_SB(b, h) + boff + n * 2048 + k * 1024); } while (0)
; #define PG8_MMA(ai, bj, At, Bt) do { __builtin_amdgcn_s_setprio(1); _Pragma("unroll") for (int m = 0; m < 4; ++m) _Pragma("unroll") for (int n = 0; n < 2; ++n) _Pragma("unroll") for (int k = 0; k < 2; ++k) \
;         acc[ai][bj][m][n] = __builtin_amdgcn_mfma_f32_16x16x32_bf16(Bt[n][k], At[m][k], acc[ai][bj][m][n], 0, 0, 0); __builtin_amdgcn_s_setprio(0); } while (0)
; #define PG8_BAR __builtin_amdgcn_s_barrier()
; template <class Epi, class Sched, bool ALIGN_EPI = false, bool SP2 = false>
; __device__ __forceinline__ void gemm_phase(PG8_LAS unsigned char* lds, const Gemm g, const Sched& S, const Epi& E, const int wid) {
;     ...
;             PG8_LDB(B0, 0, 0); PG8_LDB(B1, 0, 1); PG8_SCHED; PG8_LDA(At, 0, 0); PG8_STAGE(PG8_SA(1, 1), a1 + hstep, voffA);
;             PG8_WAIT_V(8); PG8_WAIT_L(0); PG8_BAR; PG8_MMA(0, 0, At, B0); PG8_MMA(0, 1, At, B1); PG8_BAR; PG8_SCHED;
;             PG8_LDA(At, 0, 1); PG8_STAGE(PG8_SB(0, 0), b2, voffB); PG8_STAGE(PG8_SB(0, 1), b2 + hstep, voffB); PG8_STAGE(PG8_SA(0, 0), a2, voffA);
;             PG8_WAIT_V(8); PG8_WAIT_L(0); PG8_BAR; PG8_MMA(1, 0, At, B0); PG8_MMA(1, 1, At, B1); PG8_BAR; PG8_SCHED;
;             PG8_LDB(B0, 1, 0); PG8_LDB(B1, 1, 1); PG8_SCHED; PG8_LDA(At, 1, 0); PG8_STAGE(PG8_SA(0, 1), a2 + hstep, voffA);
;             PG8_WAIT_V(8); PG8_WAIT_L(0); PG8_BAR; PG8_MMA(0, 0, At, B0); PG8_MMA(0, 1, At, B1); PG8_BAR; PG8_SCHED;
;             PG8_LDA(At, 1, 1); PG8_STAGE(PG8_SB(1, 0), b3, voffB); PG8_STAGE(PG8_SB(1, 1), b3 + hstep, voffB); PG8_STAGE(PG8_SA(1, 0), a3, voffA);
;             PG8_WAIT_V(8); PG8_WAIT_L(0); PG8_BAR; PG8_MMA(1, 0, At, B0); PG8_MMA(1, 1, At, B1); PG8_BAR; PG8_SCHED;
	v_mfma_f32_16x16x32_bf16 v[60:63], v[146:149], v[178:181], 0
	v_mfma_f32_16x16x32_bf16 v[56:59], v[154:157], v[178:181], 0
	v_mfma_f32_16x16x32_bf16 v[44:47], v[146:149], v[186:189], 0
	v_mfma_f32_16x16x32_bf16 v[40:43], v[154:157], v[186:189], 0
	v_mfma_f32_16x16x32_bf16 v[28:31], v[146:149], v[194:197], 0
	v_mfma_f32_16x16x32_bf16 v[24:27], v[154:157], v[194:197], 0
	v_mfma_f32_16x16x32_bf16 v[12:15], v[146:149], v[202:205], 0
	v_mfma_f32_16x16x32_bf16 v[8:11], v[154:157], v[202:205], 0
	v_mfma_f32_16x16x32_bf16 v[60:63], v[150:153], v[182:185], v[60:63]
	v_mfma_f32_16x16x32_bf16 v[56:59], v[158:161], v[182:185], v[56:59]
	v_mfma_f32_16x16x32_bf16 v[44:47], v[150:153], v[190:193], v[44:47]
	v_mfma_f32_16x16x32_bf16 v[40:43], v[158:161], v[190:193], v[40:43]
	v_mfma_f32_16x16x32_bf16 v[28:31], v[150:153], v[198:201], v[28:31]
	v_mfma_f32_16x16x32_bf16 v[24:27], v[158:161], v[198:201], v[24:27]
	v_mfma_f32_16x16x32_bf16 v[12:15], v[150:153], v[206:209], v[12:15]
	v_mfma_f32_16x16x32_bf16 v[8:11], v[158:161], v[206:209], v[8:11]
	v_mfma_f32_16x16x32_bf16 v[52:55], v[162:165], v[178:181], 0
	v_mfma_f32_16x16x32_bf16 v[48:51], v[170:173], v[178:181], 0
	v_mfma_f32_16x16x32_bf16 v[36:39], v[162:165], v[186:189], 0
	v_mfma_f32_16x16x32_bf16 v[32:35], v[170:173], v[186:189], 0
	v_mfma_f32_16x16x32_bf16 v[20:23], v[162:165], v[194:197], 0
	v_mfma_f32_16x16x32_bf16 v[16:19], v[170:173], v[194:197], 0
	v_mfma_f32_16x16x32_bf16 v[4:7], v[162:165], v[202:205], 0
	v_mfma_f32_16x16x32_bf16 v[0:3], v[170:173], v[202:205], 0
	v_mfma_f32_16x16x32_bf16 v[52:55], v[166:169], v[182:185], v[52:55]
	v_mfma_f32_16x16x32_bf16 v[48:51], v[174:177], v[182:185], v[48:51]
	v_mfma_f32_16x16x32_bf16 v[36:39], v[166:169], v[190:193], v[36:39]
	v_mfma_f32_16x16x32_bf16 v[32:35], v[174:177], v[190:193], v[32:35]
	v_mfma_f32_16x16x32_bf16 v[20:23], v[166:169], v[198:201], v[20:23]
	v_mfma_f32_16x16x32_bf16 v[16:19], v[174:177], v[198:201], v[16:19]
	v_mfma_f32_16x16x32_bf16 v[4:7], v[166:169], v[206:209], v[4:7]
	v_mfma_f32_16x16x32_bf16 v[0:3], v[174:177], v[206:209], v[0:3]
	s_barrier
	s_setprio 1
	s_add_i32 s33, 0, 0x18000
	s_add_i32 s76, 0, 0x1c000
	v_add_u32_e32 v158, s33, v142
	v_add_u32_e32 v174, s76, v142
	ds_read_b128 v[146:149], v158
	ds_read_b128 v[150:153], v158 offset:1024
	ds_read_b128 v[154:157], v158 offset:2048
	ds_read_b128 v[158:161], v158 offset:3072
	ds_read_b128 v[162:165], v174
	ds_read_b128 v[166:169], v174 offset:1024
	ds_read_b128 v[170:173], v174 offset:2048
	ds_read_b128 v[174:177], v174 offset:3072
	s_add_u32 s42, s42, s8
	s_addc_u32 s43, s43, s9
	s_mov_b32 m0, s57
	v_lshl_add_u64 v[220:221], s[42:43], 0, v[130:131]
	ds_read_b128 v[178:181], v145 offset:32768
	ds_read_b128 v[182:185], v145 offset:33792
	ds_read_b128 v[186:189], v145 offset:34816
	ds_read_b128 v[190:193], v145 offset:35840
	ds_read_b128 v[194:197], v145 offset:36864
	ds_read_b128 v[198:201], v145 offset:37888
	ds_read_b128 v[202:205], v145 offset:38912
	ds_read_b128 v[206:209], v145 offset:39936
	global_load_lds_dwordx4 v[220:221], off
	v_lshl_add_u64 v[220:221], s[42:43], 0, v[128:129]
	s_mov_b32 m0, s58
	s_nop 0
	global_load_lds_dwordx4 v[220:221], off
	s_waitcnt vmcnt(8)
	s_waitcnt lgkmcnt(0)
	s_setprio 0
	s_barrier
	v_mfma_f32_16x16x32_bf16 v[124:127], v[146:149], v[178:181], v[124:127]
	v_mfma_f32_16x16x32_bf16 v[120:123], v[154:157], v[178:181], v[120:123]
	v_mfma_f32_16x16x32_bf16 v[108:111], v[146:149], v[186:189], v[108:111]
	v_mfma_f32_16x16x32_bf16 v[104:107], v[154:157], v[186:189], v[104:107]
	v_mfma_f32_16x16x32_bf16 v[92:95], v[146:149], v[194:197], v[92:95]
	v_mfma_f32_16x16x32_bf16 v[88:91], v[154:157], v[194:197], v[88:91]
	v_mfma_f32_16x16x32_bf16 v[76:79], v[146:149], v[202:205], v[76:79]
	v_mfma_f32_16x16x32_bf16 v[72:75], v[154:157], v[202:205], v[72:75]
	v_mfma_f32_16x16x32_bf16 v[124:127], v[150:153], v[182:185], v[124:127]
	v_mfma_f32_16x16x32_bf16 v[120:123], v[158:161], v[182:185], v[120:123]
	v_mfma_f32_16x16x32_bf16 v[108:111], v[150:153], v[190:193], v[108:111]
	v_mfma_f32_16x16x32_bf16 v[104:107], v[158:161], v[190:193], v[104:107]
	v_mfma_f32_16x16x32_bf16 v[92:95], v[150:153], v[198:201], v[92:95]
	v_mfma_f32_16x16x32_bf16 v[88:91], v[158:161], v[198:201], v[88:91]
	v_mfma_f32_16x16x32_bf16 v[76:79], v[150:153], v[206:209], v[76:79]
	v_mfma_f32_16x16x32_bf16 v[72:75], v[158:161], v[206:209], v[72:75]
	v_mfma_f32_16x16x32_bf16 v[116:119], v[162:165], v[178:181], v[116:119]
	v_mfma_f32_16x16x32_bf16 v[112:115], v[170:173], v[178:181], v[112:115]
	v_mfma_f32_16x16x32_bf16 v[100:103], v[162:165], v[186:189], v[100:103]
	v_mfma_f32_16x16x32_bf16 v[96:99], v[170:173], v[186:189], v[96:99]
	v_mfma_f32_16x16x32_bf16 v[84:87], v[162:165], v[194:197], v[84:87]
	v_mfma_f32_16x16x32_bf16 v[80:83], v[170:173], v[194:197], v[80:83]
	v_mfma_f32_16x16x32_bf16 v[68:71], v[162:165], v[202:205], v[68:71]
	v_mfma_f32_16x16x32_bf16 v[64:67], v[170:173], v[202:205], v[64:67]
	v_mfma_f32_16x16x32_bf16 v[116:119], v[166:169], v[182:185], v[116:119]
	v_mfma_f32_16x16x32_bf16 v[112:115], v[174:177], v[182:185], v[112:115]
	v_mfma_f32_16x16x32_bf16 v[100:103], v[166:169], v[190:193], v[100:103]
	v_mfma_f32_16x16x32_bf16 v[96:99], v[174:177], v[190:193], v[96:99]
	v_mfma_f32_16x16x32_bf16 v[84:87], v[166:169], v[198:201], v[84:87]
	v_mfma_f32_16x16x32_bf16 v[80:83], v[174:177], v[198:201], v[80:83]
	v_mfma_f32_16x16x32_bf16 v[68:71], v[166:169], v[206:209], v[68:71]
	v_mfma_f32_16x16x32_bf16 v[64:67], v[174:177], v[206:209], v[64:67]
	s_barrier
; #define PG8_STAGE(bufoff, gbase, voff) do { _Pragma("unroll") for (int _i = 0; _i < 2; ++_i) \
;         __builtin_amdgcn_global_load_lds((const unsigned*)((const char*)(gbase) + (voff)[_i]), (PG8_LAS unsigned*)(lds + (bufoff) + ldsw + _i * 8192), 16, 0, 0); } while (0)
; #define PG8_LDA(dst, b, h) do { _Pragma("unroll") for (int m = 0; m < 4; ++m) _Pragma("unroll") for (int k = 0; k < 2; ++k) dst[m][k] = *(const PG8_LAS bf16x8*)(lds + PG8_SA(b, h) + aoff + m * 2048 + k * 1024); } while (0)
; #define PG8_WAIT_V(n) asm volatile("s_waitcnt vmcnt(" #n ")" ::: "memory")
; #define PG8_WAIT_L(n) asm volatile("s_waitcnt lgkmcnt(" #n ")" ::: "memory")
; #define PG8_BAR __builtin_amdgcn_s_barrier()
; template <class Epi, class Sched, bool ALIGN_EPI = false, bool SP2 = false>
; __device__ __forceinline__ void gemm_phase(PG8_LAS unsigned char* lds, const Gemm g, const Sched& S, const Epi& E, const int wid) {
;     ...
;         for (int t = 0; t < nt; t += 2) {
;             const bool last = (t == nt - 2);
;             const char* a1 = cA + (size_t)(t + 1) * kstep;
;             const char* a2 = last ? nA : cA + (size_t)(t + 2) * kstep; const char* b2 = last ? nB : cB + (size_t)(t + 2) * kstep;
;             const char* a3 = a2 + kstep; const char* b3 = b2 + kstep;
;             if (last && has_next) S.a_ready(nxt);
;             if constexpr (SP2) {
;             PG8_LDB(B0, 0, 0); PG8_LDB(B1, 0, 1); PG8_SCHED; PG8_LDA(At, 0, 0); PG8_STAGE(PG8_SA(1, 1), a1 + hstep, voffA);
;             PG8_WAIT_V(8); PG8_WAIT_L(0); PG8_BAR; PG8_MMA(0, 0, At, B0); PG8_MMA(0, 1, At, B1); PG8_BAR; PG8_SCHED;
;             PG8_LDA(At, 0, 1); PG8_STAGE(PG8_SB(0, 0), b2, voffB); PG8_STAGE(PG8_SB(0, 1), b2 + hstep, voffB); PG8_STAGE(PG8_SA(0, 0), a2, voffA);
;             PG8_WAIT_V(8); PG8_WAIT_L(0); PG8_BAR; PG8_MMA(1, 0, At, B0); PG8_MMA(1, 1, At, B1); PG8_BAR; PG8_SCHED;
;             PG8_LDB(B0, 1, 0); PG8_LDB(B1, 1, 1); PG8_SCHED; PG8_LDA(At, 1, 0); PG8_STAGE(PG8_SA(0, 1), a2 + hstep, voffA);
;             PG8_WAIT_V(8); PG8_WAIT_L(0); PG8_BAR; PG8_MMA(0, 0, At, B0); PG8_MMA(0, 1, At, B1); PG8_BAR; PG8_SCHED;
;             PG8_LDA(At, 1, 1); PG8_STAGE(PG8_SB(1, 0), b3, voffB); PG8_STAGE(PG8_SB(1, 1), b3 + hstep, voffB); PG8_STAGE(PG8_SA(1, 0), a3, voffA);
;             PG8_WAIT_V(8); PG8_WAIT_L(0); PG8_BAR; PG8_MMA(1, 0, At, B0); PG8_MMA(1, 1, At, B1); PG8_BAR; PG8_SCHED;
	s_setprio 1
	s_add_i32 s33, s33, s47
	v_lshl_add_u64 v[138:139], v[138:139], 0, s[16:17]
	s_mov_b32 m0, s33
	ds_read_b128 v[178:181], v145 offset:49152
	ds_read_b128 v[182:185], v145 offset:50176
	ds_read_b128 v[186:189], v145 offset:51200
	ds_read_b128 v[190:193], v145 offset:52224
	ds_read_b128 v[194:197], v145 offset:53248
	ds_read_b128 v[198:201], v145 offset:54272
	ds_read_b128 v[202:205], v145 offset:55296
	ds_read_b128 v[206:209], v145 offset:56320
	global_load_lds_dwordx4 v[138:139], off
	v_lshl_add_u64 v[138:139], v[210:211], 0, s[16:17]
	s_add_i32 m0, s33, 0x2000
	s_add_i32 s33, s76, s47
	global_load_lds_dwordx4 v[138:139], off
	v_lshl_add_u64 v[138:139], v[212:213], 0, s[16:17]
	s_mov_b32 m0, s33
	s_nop 0
	global_load_lds_dwordx4 v[138:139], off
	v_lshl_add_u64 v[138:139], v[214:215], 0, s[16:17]
	s_add_i32 m0, s33, 0x2000
	s_nop 0
	global_load_lds_dwordx4 v[138:139], off
	v_lshl_add_u64 v[138:139], v[216:217], 0, s[16:17]
	s_mov_b32 m0, s60
	s_nop 0
	global_load_lds_dwordx4 v[138:139], off
	v_lshl_add_u64 v[138:139], v[218:219], 0, s[16:17]
	s_mov_b32 m0, s61
	s_nop 0
	global_load_lds_dwordx4 v[138:139], off
	s_waitcnt vmcnt(8)
	s_waitcnt lgkmcnt(0)
	s_setprio 0
	s_barrier
	v_mfma_f32_16x16x32_bf16 v[60:63], v[146:149], v[178:181], v[60:63]
	v_mfma_f32_16x16x32_bf16 v[56:59], v[154:157], v[178:181], v[56:59]
	v_mfma_f32_16x16x32_bf16 v[44:47], v[146:149], v[186:189], v[44:47]
	v_mfma_f32_16x16x32_bf16 v[40:43], v[154:157], v[186:189], v[40:43]
	v_mfma_f32_16x16x32_bf16 v[28:31], v[146:149], v[194:197], v[28:31]
	v_mfma_f32_16x16x32_bf16 v[24:27], v[154:157], v[194:197], v[24:27]
	v_mfma_f32_16x16x32_bf16 v[12:15], v[146:149], v[202:205], v[12:15]
	v_mfma_f32_16x16x32_bf16 v[8:11], v[154:157], v[202:205], v[8:11]
	v_mfma_f32_16x16x32_bf16 v[60:63], v[150:153], v[182:185], v[60:63]
	v_mfma_f32_16x16x32_bf16 v[56:59], v[158:161], v[182:185], v[56:59]
	v_mfma_f32_16x16x32_bf16 v[44:47], v[150:153], v[190:193], v[44:47]
	v_mfma_f32_16x16x32_bf16 v[40:43], v[158:161], v[190:193], v[40:43]
	v_mfma_f32_16x16x32_bf16 v[28:31], v[150:153], v[198:201], v[28:31]
	v_mfma_f32_16x16x32_bf16 v[24:27], v[158:161], v[198:201], v[24:27]
	v_mfma_f32_16x16x32_bf16 v[12:15], v[150:153], v[206:209], v[12:15]
	v_mfma_f32_16x16x32_bf16 v[8:11], v[158:161], v[206:209], v[8:11]
	v_mfma_f32_16x16x32_bf16 v[52:55], v[162:165], v[178:181], v[52:55]
	v_mfma_f32_16x16x32_bf16 v[48:51], v[170:173], v[178:181], v[48:51]
	v_mfma_f32_16x16x32_bf16 v[36:39], v[162:165], v[186:189], v[36:39]
	v_mfma_f32_16x16x32_bf16 v[32:35], v[170:173], v[186:189], v[32:35]
	v_mfma_f32_16x16x32_bf16 v[20:23], v[162:165], v[194:197], v[20:23]
	v_mfma_f32_16x16x32_bf16 v[16:19], v[170:173], v[194:197], v[16:19]
	v_mfma_f32_16x16x32_bf16 v[4:7], v[162:165], v[202:205], v[4:7]
	v_mfma_f32_16x16x32_bf16 v[0:3], v[170:173], v[202:205], v[0:3]
	v_mfma_f32_16x16x32_bf16 v[52:55], v[166:169], v[182:185], v[52:55]
	v_mfma_f32_16x16x32_bf16 v[48:51], v[174:177], v[182:185], v[48:51]
	v_mfma_f32_16x16x32_bf16 v[36:39], v[166:169], v[190:193], v[36:39]
	v_mfma_f32_16x16x32_bf16 v[32:35], v[174:177], v[190:193], v[32:35]
	v_mfma_f32_16x16x32_bf16 v[20:23], v[166:169], v[198:201], v[20:23]
	v_mfma_f32_16x16x32_bf16 v[16:19], v[174:177], v[198:201], v[16:19]
	v_mfma_f32_16x16x32_bf16 v[4:7], v[166:169], v[206:209], v[4:7]
	v_mfma_f32_16x16x32_bf16 v[0:3], v[174:177], v[206:209], v[0:3]
	s_barrier
	s_setprio 1
	s_add_u32 s40, s40, 0x100
	s_addc_u32 s41, s41, 0
	s_add_u32 s73, s73, 0x100
	s_addc_u32 s74, s74, 0
	s_cmp_ge_i32 s75, s62
	s_mov_b32 s42, s75
	s_cbranch_scc1 .LBB0_1575
.LBB0_1574:
	ds_read_b128 v[146:149], v143
	ds_read_b128 v[150:153], v143 offset:1024
	ds_read_b128 v[154:157], v143 offset:2048
	ds_read_b128 v[158:161], v143 offset:3072
	ds_read_b128 v[162:165], v144
	ds_read_b128 v[166:169], v144 offset:1024
	ds_read_b128 v[170:173], v144 offset:2048
	ds_read_b128 v[174:177], v144 offset:3072
	s_add_i32 s75, s42, 2
	s_add_u32 s33, s40, 0x80
	s_addc_u32 s43, s41, 0
	s_cmp_eq_u32 s65, s42
	s_cselect_b32 s42, s2, s33
	s_cselect_b32 s43, s3, s43
	s_cselect_b32 s77, s39, s74
	s_cselect_b32 s76, s38, s73
	v_lshl_add_u64 v[138:139], s[40:41], 0, v[132:133]
	s_add_i32 m0, s55, 0xc000
	ds_read_b128 v[178:181], v145
	ds_read_b128 v[182:185], v145 offset:1024
	ds_read_b128 v[186:189], v145 offset:2048
	ds_read_b128 v[190:193], v145 offset:3072
	ds_read_b128 v[194:197], v145 offset:4096
	ds_read_b128 v[198:201], v145 offset:5120
	ds_read_b128 v[202:205], v145 offset:6144
	ds_read_b128 v[206:209], v145 offset:7168
	global_load_lds_dwordx4 v[138:139], off
	v_lshl_add_u64 v[138:139], s[40:41], 0, v[134:135]
	s_add_i32 m0, s55, 0xe000
	s_nop 0
	global_load_lds_dwordx4 v[138:139], off
	s_waitcnt vmcnt(8)
	s_waitcnt lgkmcnt(0)
	s_setprio 0
	s_barrier
; #define PG8_STAGE(bufoff, gbase, voff) do { _Pragma("unroll") for (int _i = 0; _i < 2; ++_i) \
;         __builtin_amdgcn_global_load_lds((const unsigned*)((const char*)(gbase) + (voff)[_i]), (PG8_LAS unsigned*)(lds + (bufoff) + ldsw + _i * 8192), 16, 0, 0); } while (0)
; #define PG8_LDA(dst, b, h) do { _Pragma("unroll") for (int m = 0; m < 4; ++m) _Pragma("unroll") for (int k = 0; k < 2; ++k) dst[m][k] = *(const PG8_LAS bf16x8*)(lds + PG8_SA(b, h) + aoff + m * 2048 + k * 1024); } while (0)
; #define PG8_LDB(dst, b, h) do { _Pragma("unroll") for (int n = 0; n < 2; ++n) _Pragma("unroll") for (int k = 0; k < 2; ++k) dst[n][k] = *(const PG8_LAS bf16x8*)(lds + PG8_SB(b, h) + boff + n * 2048 + k * 1024); } while (0)
; #define PG8_MMA(ai, bj, At, Bt) do { __builtin_amdgcn_s_setprio(1); _Pragma("unroll") for (int m = 0; m < 4; ++m) _Pragma("unroll") for (int n = 0; n < 2; ++n) _Pragma("unroll") for (int k = 0; k < 2; ++k) \
;         acc[ai][bj][m][n] = __builtin_amdgcn_mfma_f32_16x16x32_bf16(Bt[n][k], At[m][k], acc[ai][bj][m][n], 0, 0, 0); __builtin_amdgcn_s_setprio(0); } while (0)
; #define PG8_BAR __builtin_amdgcn_s_barrier()
; template <class Epi, class Sched, bool ALIGN_EPI = false, bool SP2 = false>
; __device__ __forceinline__ void gemm_phase(PG8_LAS unsigned char* lds, const Gemm g, const Sched& S, const Epi& E, const int wid) {
;     ...
;             PG8_LDB(B0, 0, 0); PG8_LDB(B1, 0, 1); PG8_SCHED; PG8_LDA(At, 0, 0); PG8_STAGE(PG8_SA(1, 1), a1 + hstep, voffA);
;             PG8_WAIT_V(8); PG8_WAIT_L(0); PG8_BAR; PG8_MMA(0, 0, At, B0); PG8_MMA(0, 1, At, B1); PG8_BAR; PG8_SCHED;
;             PG8_LDA(At, 0, 1); PG8_STAGE(PG8_SB(0, 0), b2, voffB); PG8_STAGE(PG8_SB(0, 1), b2 + hstep, voffB); PG8_STAGE(PG8_SA(0, 0), a2, voffA);
;             PG8_WAIT_V(8); PG8_WAIT_L(0); PG8_BAR; PG8_MMA(1, 0, At, B0); PG8_MMA(1, 1, At, B1); PG8_BAR; PG8_SCHED;
;             PG8_LDB(B0, 1, 0); PG8_LDB(B1, 1, 1); PG8_SCHED; PG8_LDA(At, 1, 0); PG8_STAGE(PG8_SA(0, 1), a2 + hstep, voffA);
;             PG8_WAIT_V(8); PG8_WAIT_L(0); PG8_BAR; PG8_MMA(0, 0, At, B0); PG8_MMA(0, 1, At, B1); PG8_BAR; PG8_SCHED;
;             PG8_LDA(At, 1, 1); PG8_STAGE(PG8_SB(1, 0), b3, voffB); PG8_STAGE(PG8_SB(1, 1), b3 + hstep, voffB); PG8_STAGE(PG8_SA(1, 0), a3, voffA);
;             PG8_WAIT_V(8); PG8_WAIT_L(0); PG8_BAR; PG8_MMA(1, 0, At, B0); PG8_MMA(1, 1, At, B1); PG8_BAR; PG8_SCHED;
	v_mfma_f32_16x16x32_bf16 v[124:127], v[146:149], v[178:181], v[124:127]
	v_mfma_f32_16x16x32_bf16 v[120:123], v[154:157], v[178:181], v[120:123]
	v_mfma_f32_16x16x32_bf16 v[108:111], v[146:149], v[186:189], v[108:111]
	v_mfma_f32_16x16x32_bf16 v[104:107], v[154:157], v[186:189], v[104:107]
	v_mfma_f32_16x16x32_bf16 v[92:95], v[146:149], v[194:197], v[92:95]
	v_mfma_f32_16x16x32_bf16 v[88:91], v[154:157], v[194:197], v[88:91]
	v_mfma_f32_16x16x32_bf16 v[76:79], v[146:149], v[202:205], v[76:79]
	v_mfma_f32_16x16x32_bf16 v[72:75], v[154:157], v[202:205], v[72:75]
	v_mfma_f32_16x16x32_bf16 v[124:127], v[150:153], v[182:185], v[124:127]
	v_mfma_f32_16x16x32_bf16 v[120:123], v[158:161], v[182:185], v[120:123]
	v_mfma_f32_16x16x32_bf16 v[108:111], v[150:153], v[190:193], v[108:111]
	v_mfma_f32_16x16x32_bf16 v[104:107], v[158:161], v[190:193], v[104:107]
	v_mfma_f32_16x16x32_bf16 v[92:95], v[150:153], v[198:201], v[92:95]
	v_mfma_f32_16x16x32_bf16 v[88:91], v[158:161], v[198:201], v[88:91]
	v_mfma_f32_16x16x32_bf16 v[76:79], v[150:153], v[206:209], v[76:79]
	v_mfma_f32_16x16x32_bf16 v[72:75], v[158:161], v[206:209], v[72:75]
	v_mfma_f32_16x16x32_bf16 v[116:119], v[162:165], v[178:181], v[116:119]
	v_mfma_f32_16x16x32_bf16 v[112:115], v[170:173], v[178:181], v[112:115]
	v_mfma_f32_16x16x32_bf16 v[100:103], v[162:165], v[186:189], v[100:103]
	v_mfma_f32_16x16x32_bf16 v[96:99], v[170:173], v[186:189], v[96:99]
	v_mfma_f32_16x16x32_bf16 v[84:87], v[162:165], v[194:197], v[84:87]
	v_mfma_f32_16x16x32_bf16 v[80:83], v[170:173], v[194:197], v[80:83]
	v_mfma_f32_16x16x32_bf16 v[68:71], v[162:165], v[202:205], v[68:71]
	v_mfma_f32_16x16x32_bf16 v[64:67], v[170:173], v[202:205], v[64:67]
	v_mfma_f32_16x16x32_bf16 v[116:119], v[166:169], v[182:185], v[116:119]
	v_mfma_f32_16x16x32_bf16 v[112:115], v[174:177], v[182:185], v[112:115]
	v_mfma_f32_16x16x32_bf16 v[100:103], v[166:169], v[190:193], v[100:103]
	v_mfma_f32_16x16x32_bf16 v[96:99], v[174:177], v[190:193], v[96:99]
	v_mfma_f32_16x16x32_bf16 v[84:87], v[166:169], v[198:201], v[84:87]
	v_mfma_f32_16x16x32_bf16 v[80:83], v[174:177], v[198:201], v[80:83]
	v_mfma_f32_16x16x32_bf16 v[68:71], v[166:169], v[206:209], v[68:71]
	v_mfma_f32_16x16x32_bf16 v[64:67], v[174:177], v[206:209], v[64:67]
	s_barrier
	s_setprio 1
	s_add_i32 s33, s67, s47
	v_lshl_add_u64 v[138:139], s[76:77], 0, v[130:131]
	s_mov_b32 m0, s33
	ds_read_b128 v[178:181], v145 offset:16384
	ds_read_b128 v[182:185], v145 offset:17408
	ds_read_b128 v[186:189], v145 offset:18432
	ds_read_b128 v[190:193], v145 offset:19456
	ds_read_b128 v[194:197], v145 offset:20480
	ds_read_b128 v[198:201], v145 offset:21504
	ds_read_b128 v[202:205], v145 offset:22528
	ds_read_b128 v[206:209], v145 offset:23552
	global_load_lds_dwordx4 v[138:139], off
	s_add_i32 m0, s33, 0x2000
	v_lshl_add_u64 v[210:211], s[76:77], 0, v[128:129]
	s_add_u32 s76, s76, s8
	s_addc_u32 s77, s77, s9
	s_add_i32 s33, s68, s47
	global_load_lds_dwordx4 v[210:211], off
	v_lshl_add_u64 v[212:213], s[76:77], 0, v[130:131]
	s_mov_b32 m0, s33
	v_lshl_add_u64 v[214:215], s[76:77], 0, v[128:129]
	global_load_lds_dwordx4 v[212:213], off
	s_add_i32 m0, s33, 0x2000
	v_lshl_add_u64 v[216:217], s[42:43], 0, v[130:131]
	global_load_lds_dwordx4 v[214:215], off
	s_mov_b32 m0, s55
	v_lshl_add_u64 v[218:219], s[42:43], 0, v[128:129]
	global_load_lds_dwordx4 v[216:217], off
	s_mov_b32 m0, s56
	s_nop 0
	global_load_lds_dwordx4 v[218:219], off
	s_waitcnt vmcnt(8)
	s_waitcnt lgkmcnt(0)
	s_setprio 0
	s_barrier
	v_mfma_f32_16x16x32_bf16 v[60:63], v[146:149], v[178:181], v[60:63]
	v_mfma_f32_16x16x32_bf16 v[56:59], v[154:157], v[178:181], v[56:59]
	v_mfma_f32_16x16x32_bf16 v[44:47], v[146:149], v[186:189], v[44:47]
	v_mfma_f32_16x16x32_bf16 v[40:43], v[154:157], v[186:189], v[40:43]
	v_mfma_f32_16x16x32_bf16 v[28:31], v[146:149], v[194:197], v[28:31]
	v_mfma_f32_16x16x32_bf16 v[24:27], v[154:157], v[194:197], v[24:27]
	v_mfma_f32_16x16x32_bf16 v[12:15], v[146:149], v[202:205], v[12:15]
	v_mfma_f32_16x16x32_bf16 v[8:11], v[154:157], v[202:205], v[8:11]
	v_mfma_f32_16x16x32_bf16 v[60:63], v[150:153], v[182:185], v[60:63]
	v_mfma_f32_16x16x32_bf16 v[56:59], v[158:161], v[182:185], v[56:59]
	v_mfma_f32_16x16x32_bf16 v[44:47], v[150:153], v[190:193], v[44:47]
	v_mfma_f32_16x16x32_bf16 v[40:43], v[158:161], v[190:193], v[40:43]
	v_mfma_f32_16x16x32_bf16 v[28:31], v[150:153], v[198:201], v[28:31]
	v_mfma_f32_16x16x32_bf16 v[24:27], v[158:161], v[198:201], v[24:27]
	v_mfma_f32_16x16x32_bf16 v[12:15], v[150:153], v[206:209], v[12:15]
	v_mfma_f32_16x16x32_bf16 v[8:11], v[158:161], v[206:209], v[8:11]
	v_mfma_f32_16x16x32_bf16 v[52:55], v[162:165], v[178:181], v[52:55]
	v_mfma_f32_16x16x32_bf16 v[48:51], v[170:173], v[178:181], v[48:51]
	v_mfma_f32_16x16x32_bf16 v[36:39], v[162:165], v[186:189], v[36:39]
	v_mfma_f32_16x16x32_bf16 v[32:35], v[170:173], v[186:189], v[32:35]
	v_mfma_f32_16x16x32_bf16 v[20:23], v[162:165], v[194:197], v[20:23]
	v_mfma_f32_16x16x32_bf16 v[16:19], v[170:173], v[194:197], v[16:19]
	v_mfma_f32_16x16x32_bf16 v[4:7], v[162:165], v[202:205], v[4:7]
	v_mfma_f32_16x16x32_bf16 v[0:3], v[170:173], v[202:205], v[0:3]
	v_mfma_f32_16x16x32_bf16 v[52:55], v[166:169], v[182:185], v[52:55]
	v_mfma_f32_16x16x32_bf16 v[48:51], v[174:177], v[182:185], v[48:51]
	v_mfma_f32_16x16x32_bf16 v[36:39], v[166:169], v[190:193], v[36:39]
	v_mfma_f32_16x16x32_bf16 v[32:35], v[174:177], v[190:193], v[32:35]
	v_mfma_f32_16x16x32_bf16 v[20:23], v[166:169], v[198:201], v[20:23]
	v_mfma_f32_16x16x32_bf16 v[16:19], v[174:177], v[198:201], v[16:19]
	v_mfma_f32_16x16x32_bf16 v[4:7], v[166:169], v[206:209], v[4:7]
	v_mfma_f32_16x16x32_bf16 v[0:3], v[174:177], v[206:209], v[0:3]
	s_barrier
; #define PG8_STAGE(bufoff, gbase, voff) do { _Pragma("unroll") for (int _i = 0; _i < 2; ++_i) \
;         __builtin_amdgcn_global_load_lds((const unsigned*)((const char*)(gbase) + (voff)[_i]), (PG8_LAS unsigned*)(lds + (bufoff) + ldsw + _i * 8192), 16, 0, 0); } while (0)
; #define PG8_LDA(dst, b, h) do { _Pragma("unroll") for (int m = 0; m < 4; ++m) _Pragma("unroll") for (int k = 0; k < 2; ++k) dst[m][k] = *(const PG8_LAS bf16x8*)(lds + PG8_SA(b, h) + aoff + m * 2048 + k * 1024); } while (0)
; #define PG8_LDB(dst, b, h) do { _Pragma("unroll") for (int n = 0; n < 2; ++n) _Pragma("unroll") for (int k = 0; k < 2; ++k) dst[n][k] = *(const PG8_LAS bf16x8*)(lds + PG8_SB(b, h) + boff + n * 2048 + k * 1024); } while (0)
; #define PG8_MMA(ai, bj, At, Bt) do { __builtin_amdgcn_s_setprio(1); _Pragma("unroll") for (int m = 0; m < 4; ++m) _Pragma("unroll") for (int n = 0; n < 2; ++n) _Pragma("unroll") for (int k = 0; k < 2; ++k) \
;         acc[ai][bj][m][n] = __builtin_amdgcn_mfma_f32_16x16x32_bf16(Bt[n][k], At[m][k], acc[ai][bj][m][n], 0, 0, 0); __builtin_amdgcn_s_setprio(0); } while (0)
; template <class Epi, class Sched, bool ALIGN_EPI = false, bool SP2 = false>
; __device__ __forceinline__ void gemm_phase(PG8_LAS unsigned char* lds, const Gemm g, const Sched& S, const Epi& E, const int wid) {
;     ...
;             if constexpr (SP2) {
;             PG8_LDB(B0, 0, 0); PG8_LDB(B1, 0, 1); PG8_SCHED; PG8_LDA(At, 0, 0); PG8_STAGE(PG8_SA(1, 1), a1 + hstep, voffA);
;             PG8_WAIT_V(8); PG8_WAIT_L(0); PG8_BAR; PG8_MMA(0, 0, At, B0); PG8_MMA(0, 1, At, B1); PG8_BAR; PG8_SCHED;
;             PG8_LDA(At, 0, 1); PG8_STAGE(PG8_SB(0, 0), b2, voffB); PG8_STAGE(PG8_SB(0, 1), b2 + hstep, voffB); PG8_STAGE(PG8_SA(0, 0), a2, voffA);
;             PG8_WAIT_V(8); PG8_WAIT_L(0); PG8_BAR; PG8_MMA(1, 0, At, B0); PG8_MMA(1, 1, At, B1); PG8_BAR; PG8_SCHED;
;             PG8_LDB(B0, 1, 0); PG8_LDB(B1, 1, 1); PG8_SCHED; PG8_LDA(At, 1, 0); PG8_STAGE(PG8_SA(0, 1), a2 + hstep, voffA);
;             PG8_WAIT_V(8); PG8_WAIT_L(0); PG8_BAR; PG8_MMA(0, 0, At, B0); PG8_MMA(0, 1, At, B1); PG8_BAR; PG8_SCHED;
;             PG8_LDA(At, 1, 1); PG8_STAGE(PG8_SB(1, 0), b3, voffB); PG8_STAGE(PG8_SB(1, 1), b3 + hstep, voffB); PG8_STAGE(PG8_SA(1, 0), a3, voffA);
;             PG8_WAIT_V(8); PG8_WAIT_L(0); PG8_BAR; PG8_MMA(1, 0, At, B0); PG8_MMA(1, 1, At, B1); PG8_BAR; PG8_SCHED;
	s_setprio 1
	s_add_i32 s33, 0, 0x18000
	s_add_i32 s76, 0, 0x1c000
	v_add_u32_e32 v158, s33, v142
	v_add_u32_e32 v174, s76, v142
	ds_read_b128 v[146:149], v158
	ds_read_b128 v[150:153], v158 offset:1024
	ds_read_b128 v[154:157], v158 offset:2048
	ds_read_b128 v[158:161], v158 offset:3072
	ds_read_b128 v[162:165], v174
	ds_read_b128 v[166:169], v174 offset:1024
	ds_read_b128 v[170:173], v174 offset:2048
	ds_read_b128 v[174:177], v174 offset:3072
	s_add_u32 s42, s42, s8
	s_addc_u32 s43, s43, s9
	s_mov_b32 m0, s57
	v_lshl_add_u64 v[220:221], s[42:43], 0, v[130:131]
	ds_read_b128 v[178:181], v145 offset:32768
	ds_read_b128 v[182:185], v145 offset:33792
	ds_read_b128 v[186:189], v145 offset:34816
	ds_read_b128 v[190:193], v145 offset:35840
	ds_read_b128 v[194:197], v145 offset:36864
	ds_read_b128 v[198:201], v145 offset:37888
	ds_read_b128 v[202:205], v145 offset:38912
	ds_read_b128 v[206:209], v145 offset:39936
	global_load_lds_dwordx4 v[220:221], off
	v_lshl_add_u64 v[220:221], s[42:43], 0, v[128:129]
	s_mov_b32 m0, s58
	s_nop 0
	global_load_lds_dwordx4 v[220:221], off
	s_waitcnt vmcnt(8)
	s_waitcnt lgkmcnt(0)
	s_setprio 0
	s_barrier
	v_mfma_f32_16x16x32_bf16 v[124:127], v[146:149], v[178:181], v[124:127]
	v_mfma_f32_16x16x32_bf16 v[120:123], v[154:157], v[178:181], v[120:123]
	v_mfma_f32_16x16x32_bf16 v[108:111], v[146:149], v[186:189], v[108:111]
	v_mfma_f32_16x16x32_bf16 v[104:107], v[154:157], v[186:189], v[104:107]
	v_mfma_f32_16x16x32_bf16 v[92:95], v[146:149], v[194:197], v[92:95]
	v_mfma_f32_16x16x32_bf16 v[88:91], v[154:157], v[194:197], v[88:91]
	v_mfma_f32_16x16x32_bf16 v[76:79], v[146:149], v[202:205], v[76:79]
	v_mfma_f32_16x16x32_bf16 v[72:75], v[154:157], v[202:205], v[72:75]
	v_mfma_f32_16x16x32_bf16 v[124:127], v[150:153], v[182:185], v[124:127]
	v_mfma_f32_16x16x32_bf16 v[120:123], v[158:161], v[182:185], v[120:123]
	v_mfma_f32_16x16x32_bf16 v[108:111], v[150:153], v[190:193], v[108:111]
	v_mfma_f32_16x16x32_bf16 v[104:107], v[158:161], v[190:193], v[104:107]
	v_mfma_f32_16x16x32_bf16 v[92:95], v[150:153], v[198:201], v[92:95]
	v_mfma_f32_16x16x32_bf16 v[88:91], v[158:161], v[198:201], v[88:91]
	v_mfma_f32_16x16x32_bf16 v[76:79], v[150:153], v[206:209], v[76:79]
	v_mfma_f32_16x16x32_bf16 v[72:75], v[158:161], v[206:209], v[72:75]
	v_mfma_f32_16x16x32_bf16 v[116:119], v[162:165], v[178:181], v[116:119]
	v_mfma_f32_16x16x32_bf16 v[112:115], v[170:173], v[178:181], v[112:115]
	v_mfma_f32_16x16x32_bf16 v[100:103], v[162:165], v[186:189], v[100:103]
	v_mfma_f32_16x16x32_bf16 v[96:99], v[170:173], v[186:189], v[96:99]
	v_mfma_f32_16x16x32_bf16 v[84:87], v[162:165], v[194:197], v[84:87]
	v_mfma_f32_16x16x32_bf16 v[80:83], v[170:173], v[194:197], v[80:83]
	v_mfma_f32_16x16x32_bf16 v[68:71], v[162:165], v[202:205], v[68:71]
	v_mfma_f32_16x16x32_bf16 v[64:67], v[170:173], v[202:205], v[64:67]
	v_mfma_f32_16x16x32_bf16 v[116:119], v[166:169], v[182:185], v[116:119]
	v_mfma_f32_16x16x32_bf16 v[112:115], v[174:177], v[182:185], v[112:115]
	v_mfma_f32_16x16x32_bf16 v[100:103], v[166:169], v[190:193], v[100:103]
	v_mfma_f32_16x16x32_bf16 v[96:99], v[174:177], v[190:193], v[96:99]
	v_mfma_f32_16x16x32_bf16 v[84:87], v[166:169], v[198:201], v[84:87]
	v_mfma_f32_16x16x32_bf16 v[80:83], v[174:177], v[198:201], v[80:83]
	v_mfma_f32_16x16x32_bf16 v[68:71], v[166:169], v[206:209], v[68:71]
	v_mfma_f32_16x16x32_bf16 v[64:67], v[174:177], v[206:209], v[64:67]
	s_barrier
	s_setprio 1
	s_add_i32 s33, s33, s47
	v_lshl_add_u64 v[138:139], v[138:139], 0, s[16:17]
	s_mov_b32 m0, s33
	ds_read_b128 v[178:181], v145 offset:49152
	ds_read_b128 v[182:185], v145 offset:50176
	ds_read_b128 v[186:189], v145 offset:51200
	ds_read_b128 v[190:193], v145 offset:52224
	ds_read_b128 v[194:197], v145 offset:53248
	ds_read_b128 v[198:201], v145 offset:54272
	ds_read_b128 v[202:205], v145 offset:55296
	ds_read_b128 v[206:209], v145 offset:56320
	global_load_lds_dwordx4 v[138:139], off
	v_lshl_add_u64 v[138:139], v[210:211], 0, s[16:17]
	s_add_i32 m0, s33, 0x2000
	s_add_i32 s33, s76, s47
	global_load_lds_dwordx4 v[138:139], off
	v_lshl_add_u64 v[138:139], v[212:213], 0, s[16:17]
	s_mov_b32 m0, s33
	s_nop 0
	global_load_lds_dwordx4 v[138:139], off
	v_lshl_add_u64 v[138:139], v[214:215], 0, s[16:17]
	s_add_i32 m0, s33, 0x2000
	s_nop 0
	global_load_lds_dwordx4 v[138:139], off
	v_lshl_add_u64 v[138:139], v[216:217], 0, s[16:17]
	s_mov_b32 m0, s60
	s_nop 0
	global_load_lds_dwordx4 v[138:139], off
	v_lshl_add_u64 v[138:139], v[218:219], 0, s[16:17]
	s_mov_b32 m0, s61
	s_nop 0
	global_load_lds_dwordx4 v[138:139], off
	s_waitcnt vmcnt(8)
	s_waitcnt lgkmcnt(0)
	s_setprio 0
	s_barrier
	v_mfma_f32_16x16x32_bf16 v[60:63], v[146:149], v[178:181], v[60:63]
	v_mfma_f32_16x16x32_bf16 v[56:59], v[154:157], v[178:181], v[56:59]
	v_mfma_f32_16x16x32_bf16 v[44:47], v[146:149], v[186:189], v[44:47]
	v_mfma_f32_16x16x32_bf16 v[40:43], v[154:157], v[186:189], v[40:43]
	v_mfma_f32_16x16x32_bf16 v[28:31], v[146:149], v[194:197], v[28:31]
	v_mfma_f32_16x16x32_bf16 v[24:27], v[154:157], v[194:197], v[24:27]
	v_mfma_f32_16x16x32_bf16 v[12:15], v[146:149], v[202:205], v[12:15]
	v_mfma_f32_16x16x32_bf16 v[8:11], v[154:157], v[202:205], v[8:11]
	v_mfma_f32_16x16x32_bf16 v[60:63], v[150:153], v[182:185], v[60:63]
	v_mfma_f32_16x16x32_bf16 v[56:59], v[158:161], v[182:185], v[56:59]
	v_mfma_f32_16x16x32_bf16 v[44:47], v[150:153], v[190:193], v[44:47]
	v_mfma_f32_16x16x32_bf16 v[40:43], v[158:161], v[190:193], v[40:43]
	v_mfma_f32_16x16x32_bf16 v[28:31], v[150:153], v[198:201], v[28:31]
	v_mfma_f32_16x16x32_bf16 v[24:27], v[158:161], v[198:201], v[24:27]
	v_mfma_f32_16x16x32_bf16 v[12:15], v[150:153], v[206:209], v[12:15]
	v_mfma_f32_16x16x32_bf16 v[8:11], v[158:161], v[206:209], v[8:11]
	v_mfma_f32_16x16x32_bf16 v[52:55], v[162:165], v[178:181], v[52:55]
	v_mfma_f32_16x16x32_bf16 v[48:51], v[170:173], v[178:181], v[48:51]
	v_mfma_f32_16x16x32_bf16 v[36:39], v[162:165], v[186:189], v[36:39]
	v_mfma_f32_16x16x32_bf16 v[32:35], v[170:173], v[186:189], v[32:35]
	v_mfma_f32_16x16x32_bf16 v[20:23], v[162:165], v[194:197], v[20:23]
	v_mfma_f32_16x16x32_bf16 v[16:19], v[170:173], v[194:197], v[16:19]
	v_mfma_f32_16x16x32_bf16 v[4:7], v[162:165], v[202:205], v[4:7]
	v_mfma_f32_16x16x32_bf16 v[0:3], v[170:173], v[202:205], v[0:3]
	v_mfma_f32_16x16x32_bf16 v[52:55], v[166:169], v[182:185], v[52:55]
	v_mfma_f32_16x16x32_bf16 v[48:51], v[174:177], v[182:185], v[48:51]
	v_mfma_f32_16x16x32_bf16 v[36:39], v[166:169], v[190:193], v[36:39]
	v_mfma_f32_16x16x32_bf16 v[32:35], v[174:177], v[190:193], v[32:35]
	v_mfma_f32_16x16x32_bf16 v[20:23], v[166:169], v[198:201], v[20:23]
	v_mfma_f32_16x16x32_bf16 v[16:19], v[174:177], v[198:201], v[16:19]
	v_mfma_f32_16x16x32_bf16 v[4:7], v[166:169], v[206:209], v[4:7]
	v_mfma_f32_16x16x32_bf16 v[0:3], v[174:177], v[206:209], v[0:3]
	s_barrier
	s_setprio 1
	s_add_u32 s40, s40, 0x100
	s_addc_u32 s41, s41, 0
	s_add_u32 s73, s73, 0x100
	s_addc_u32 s74, s74, 0
	s_cmp_ge_i32 s75, s62
	s_mov_b32 s42, s75
	s_cbranch_scc0 .LBB0_1574
